# fp8 attention walks (selected/window/dilated): counted vmcnt relaxed by 16 so two fragment sets stay in flight as the 3-set rotation intends; vmcnt(16) restored at loop exits
# baseline (speedup 1.0000x reference)
; template <bool SLC, bool NOMASK> ...
;     const int kq = lane >> 4;
;     const int pos0 = SLC ? (dcur & 0xfffff) : dcur;
;     const int lo = SLC ? ((((dcur >> 20) == qi) | ((dcur >> 20) == 4)) ? 0 : (1 << 30)) : lo_in;
;     load_frag8(nxt, KF, VF, SLC ? (dnext & 0xfffff) : dnext, lane);
;     f32x4 sa[2] = {(f32x4){0.f, 0.f, 0.f, 0.f}, (f32x4){0.f, 0.f, 0.f, 0.f}};
; #pragma unroll
;     for (int T = 0; T < 2; ++T)
; #pragma unroll
;         for (int s2 = 0; s2 < 4; ++s2) sa[T] = __builtin_amdgcn_mfma_f32_16x16x32_fp8_fp8(cur.k[T][s2], qf[s2], sa[T], 0, 0, 0);
;     float sc[8]; bool vd[8]; float mx = -1e30f;
;     const bool act = lo == 0 || !SLC;
;     if (NOMASK) {
; #pragma unroll
;         for (int j = 0; j < 8; ++j) { sc[j] = sa[j >> 2][j & 3]; vd[j] = act; }
;         mx = fmaxf(fmaxf(fmaxf(sc[0], sc[1]), fmaxf(sc[2], sc[3])), fmaxf(fmaxf(sc[4], sc[5]), fmaxf(sc[6], sc[7])));
;         mx = act ? mx : -1e30f;
;     } else {
; #pragma unroll
;         for (int T = 0; T < 2; ++T)
; #pragma unroll
;             for (int r = 0; r < 4; ++r) { const int p = pos0 + 16 * T + 4 * kq + r; const bool v = (p >= lo) & (p <= hi); const float x = sa[T][r];
;                 sc[4 * T + r] = x; vd[4 * T + r] = v; mx = v ? fmaxf(mx, x) : mx; }
;     }
;     if (__builtin_amdgcn_ballot_w64(mx > st.m + 4.f) != 0ull) {
;         mx = fmaxf(mx, __shfl_xor(mx, 16)); mx = fmaxf(mx, __shfl_xor(mx, 32));
;         const float mn = fmaxf(st.m, mx), alpha = __builtin_amdgcn_exp2f(st.m - mn); st.m = mn; st.l *= alpha;
; #pragma unroll
;         for (int j = 0; j < 8; ++j) st.o[j] = st.o[j] * alpha;
;     }
;     f32x4 pa, pb; float ps = 0.f;
;     const float mref = st.m - 4.f;
;     if (NOMASK) {
; #pragma unroll
;         for (int j = 0; j < 4; ++j) { pa[j] = __builtin_amdgcn_exp2f(sc[j] - mref); pb[j] = __builtin_amdgcn_exp2f(sc[4 + j] - mref); }
;         if (SLC) {
; #pragma unroll
;             for (int j = 0; j < 4; ++j) { pa[j] = act ? pa[j] : 0.f; pb[j] = act ? pb[j] : 0.f; }
;         }
; #pragma unroll
;         for (int j = 0; j < 4; ++j) ps += pa[j] + pb[j];
;     } else {
; #pragma unroll
;         for (int j = 0; j < 4; ++j) { pa[j] = vd[j] ? __builtin_amdgcn_exp2f(sc[j] - mref) : 0.f; pb[j] = vd[4 + j] ? __builtin_amdgcn_exp2f(sc[4 + j] - mref) : 0.f; ps += pa[j] + pb[j]; }
;     }
;     st.l += ps;
;     const u32x2 pw = pack8_fp8(pa, pb);
.LBB0_704:
	global_load_dwordx2 v[190:191], v[198:199], off
	global_load_dwordx2 v[194:195], v[198:199], off offset:512
	global_load_dwordx2 v[192:193], v[198:199], off offset:1024
	global_load_dwordx2 v[186:187], v[198:199], off offset:1536
	global_load_dwordx2 v[188:189], v[198:199], off offset:2048
	global_load_dwordx2 v[184:185], v[198:199], off offset:2560
	global_load_dwordx2 v[182:183], v[198:199], off offset:3072
	global_load_dwordx2 v[180:181], v[198:199], off offset:3584
	global_load_dwordx2 v[164:165], v[196:197], off
	global_load_dwordx2 v[166:167], v[196:197], off offset:512
	global_load_dwordx2 v[168:169], v[196:197], off offset:1024
	global_load_dwordx2 v[170:171], v[196:197], off offset:1536
	global_load_dwordx2 v[178:179], v[196:197], off offset:2048
	global_load_dwordx2 v[176:177], v[196:197], off offset:2560
	global_load_dwordx2 v[174:175], v[196:197], off offset:3072
	global_load_dwordx2 v[172:173], v[196:197], off offset:3584
	s_waitcnt vmcnt(47)
	v_mfma_f32_16x16x32_fp8_fp8 v[2:5], v[142:143], v[74:75], 0
	v_mov_b64_e32 v[72:73], v[48:49]
	v_mov_b64_e32 v[68:69], v[52:53]
	v_mov_b64_e32 v[30:31], v[58:59]
	s_waitcnt vmcnt(43)
	v_mfma_f32_16x16x32_fp8_fp8 v[6:9], v[140:141], v[74:75], 0
	v_mov_b64_e32 v[26:27], v[62:63]
	v_mov_b64_e32 v[22:23], v[54:55]
	v_mov_b64_e32 v[18:19], v[42:43]
	v_mfma_f32_16x16x32_fp8_fp8 v[2:5], v[146:147], v[76:77], v[2:5]
	v_mov_b64_e32 v[14:15], v[38:39]
	v_mov_b32_e32 v207, v210
	v_mov_b64_e32 v[70:71], v[46:47]
	s_waitcnt vmcnt(42)
	v_mfma_f32_16x16x32_fp8_fp8 v[6:9], v[136:137], v[76:77], v[6:9]
	v_mov_b64_e32 v[66:67], v[50:51]
	v_mov_b64_e32 v[32:33], v[60:61]
	v_mov_b64_e32 v[28:29], v[64:65]
	v_mfma_f32_16x16x32_fp8_fp8 v[2:5], v[144:145], v[78:79], v[2:5]
	v_mov_b64_e32 v[24:25], v[56:57]
	v_mov_b64_e32 v[20:21], v[44:45]
	v_mov_b64_e32 v[16:17], v[40:41]
	s_waitcnt vmcnt(41)
	v_mfma_f32_16x16x32_fp8_fp8 v[6:9], v[134:135], v[78:79], v[6:9]
	v_mov_b32_e32 v208, v209
	v_mfma_f32_16x16x32_fp8_fp8 v[2:5], v[138:139], v[80:81], v[2:5]
	s_waitcnt vmcnt(40)
	v_mfma_f32_16x16x32_fp8_fp8 v[6:9], v[132:133], v[80:81], v[6:9]
	s_nop 5
	v_max_f32_e32 v0, v3, v3
	v_max_f32_e32 v10, v2, v2
	v_max_f32_e32 v0, v10, v0
	v_max_f32_e32 v10, v5, v5
	v_max_f32_e32 v11, v4, v4
	v_max_f32_e32 v10, v11, v10
	v_max_f32_e32 v11, v9, v9
	v_max_f32_e32 v12, v8, v8
	v_max_f32_e32 v11, v12, v11
	v_max3_f32 v11, v6, v7, v11
	v_max3_f32 v0, v0, v10, v11
	v_mov_b64_e32 v[10:11], v[34:35]
	v_cmp_gt_f32_e32 vcc, v0, v211
	v_mov_b64_e32 v[12:13], v[36:37]
	s_cbranch_vccz .LBB0_706
	v_and_b32_e32 v11, 64, v204
	v_xor_b32_e32 v10, 16, v204
	v_add_u32_e32 v11, 64, v11
	v_cmp_lt_i32_e32 vcc, v10, v11
	v_xor_b32_e32 v12, 32, v204
	s_nop 0
	v_cndmask_b32_e32 v10, v204, v10, vcc
	v_lshlrev_b32_e32 v10, 2, v10
	ds_bpermute_b32 v10, v10, v0
	v_max_f32_e32 v0, v0, v0
	v_cmp_lt_i32_e32 vcc, v12, v11
	s_waitcnt lgkmcnt(0)
	v_max_f32_e32 v10, v10, v10
	v_max_f32_e32 v0, v0, v10
	v_cndmask_b32_e32 v10, v204, v12, vcc
	v_lshlrev_b32_e32 v10, 2, v10
	ds_bpermute_b32 v10, v10, v0
	s_waitcnt lgkmcnt(0)
	v_max3_f32 v207, v210, v0, v10
	v_sub_f32_e32 v0, v210, v207
	v_exp_f32_e32 v0, v0
	s_nop 0
	v_mul_f32_e32 v208, v209, v0
	v_pk_mul_f32 v[12:13], v[36:37], v[0:1] op_sel_hi:[1,0]
	v_pk_mul_f32 v[10:11], v[34:35], v[0:1] op_sel_hi:[1,0]
	v_pk_mul_f32 v[16:17], v[40:41], v[0:1] op_sel_hi:[1,0]
	v_pk_mul_f32 v[14:15], v[38:39], v[0:1] op_sel_hi:[1,0]
	v_pk_mul_f32 v[20:21], v[44:45], v[0:1] op_sel_hi:[1,0]
	v_pk_mul_f32 v[18:19], v[42:43], v[0:1] op_sel_hi:[1,0]
	v_pk_mul_f32 v[24:25], v[56:57], v[0:1] op_sel_hi:[1,0]
	v_pk_mul_f32 v[22:23], v[54:55], v[0:1] op_sel_hi:[1,0]
	v_pk_mul_f32 v[28:29], v[64:65], v[0:1] op_sel_hi:[1,0]
	v_pk_mul_f32 v[26:27], v[62:63], v[0:1] op_sel_hi:[1,0]
	v_pk_mul_f32 v[32:33], v[60:61], v[0:1] op_sel_hi:[1,0]
	v_pk_mul_f32 v[30:31], v[58:59], v[0:1] op_sel_hi:[1,0]
	v_pk_mul_f32 v[68:69], v[52:53], v[0:1] op_sel_hi:[1,0]
	v_pk_mul_f32 v[66:67], v[50:51], v[0:1] op_sel_hi:[1,0]
	v_pk_mul_f32 v[72:73], v[48:49], v[0:1] op_sel_hi:[1,0]
	v_pk_mul_f32 v[70:71], v[46:47], v[0:1] op_sel_hi:[1,0]
.LBB0_706:
	v_add_f32_e32 v213, -4.0, v207
	v_sub_f32_e32 v0, v2, v213
	v_exp_f32_e32 v215, v0
	v_sub_f32_e32 v0, v6, v213
	v_exp_f32_e32 v217, v0
	v_sub_f32_e32 v0, v3, v213
	v_exp_f32_e32 v212, v0
	v_sub_f32_e32 v0, v7, v213
	v_exp_f32_e32 v0, v0
	v_sub_f32_e32 v2, v4, v213
	v_exp_f32_e32 v220, v2
	v_sub_f32_e32 v2, v8, v213
	v_exp_f32_e32 v221, v2
	v_sub_f32_e32 v2, v5, v213
	v_exp_f32_e32 v214, v2
	v_sub_f32_e32 v2, v9, v213
	v_mov_b32_e32 v218, v1
	v_mov_b32_e32 v219, v1
	v_exp_f32_e32 v216, v2
	v_cvt_pk_fp8_f32 v218, v215, v212
	v_cvt_pk_fp8_f32 v219, v217, v0
	v_add_f32_e32 v213, v215, v217
	v_add_f32_e32 v215, v220, v221
	v_cvt_pk_fp8_f32 v218, v220, v214 op_sel:[0,0,1]
	v_cvt_pk_fp8_f32 v219, v221, v216 op_sel:[0,0,1]
	s_waitcnt vmcnt(39)
	s_nop 0
	v_mfma_f32_16x16x32_fp8_fp8 v[2:5], v[86:87], v[218:219], v[10:13]
	s_waitcnt vmcnt(37)
	v_mfma_f32_16x16x32_fp8_fp8 v[10:13], v[90:91], v[218:219], v[18:21]
	s_waitcnt vmcnt(35)
	v_mfma_f32_16x16x32_fp8_fp8 v[18:21], v[114:115], v[218:219], v[26:29]
	s_nop 2
	v_add_f32_e64 v26, v212, v0
	v_add_f32_e64 v27, v213, v1
	v_mfma_f32_16x16x32_fp8_fp8 v[6:9], v[88:89], v[218:219], v[14:17]
	v_pk_add_f32 v[26:27], v[26:27], v[26:27] op_sel_hi:[0,1]
	v_mov_b32_e32 v217, v27
	v_pk_add_f32 v[26:27], v[214:215], v[216:217]
	v_mfma_f32_16x16x32_fp8_fp8 v[14:17], v[92:93], v[218:219], v[22:25]
	v_add_f32_e32 v0, v26, v27
	v_add_f32_e32 v208, v0, v208
	s_waitcnt vmcnt(34)
	v_mfma_f32_16x16x32_fp8_fp8 v[22:25], v[112:113], v[218:219], v[30:33]
	s_waitcnt vmcnt(33)
	v_mfma_f32_16x16x32_fp8_fp8 v[30:33], v[96:97], v[218:219], v[66:69]
	s_waitcnt vmcnt(32)
	v_mfma_f32_16x16x32_fp8_fp8 v[26:29], v[94:95], v[218:219], v[70:73]
	s_branch .LBB0_700
; template <bool SLC, bool NOMASK> ...
;     const int kq = lane >> 4;
;     const int pos0 = SLC ? (dcur & 0xfffff) : dcur;
;     const int lo = SLC ? ((((dcur >> 20) == qi) | ((dcur >> 20) == 4)) ? 0 : (1 << 30)) : lo_in;
;     load_frag8(nxt, KF, VF, SLC ? (dnext & 0xfffff) : dnext, lane);
;     f32x4 sa[2] = {(f32x4){0.f, 0.f, 0.f, 0.f}, (f32x4){0.f, 0.f, 0.f, 0.f}};
; #pragma unroll
;     for (int T = 0; T < 2; ++T)
; #pragma unroll
;         for (int s2 = 0; s2 < 4; ++s2) sa[T] = __builtin_amdgcn_mfma_f32_16x16x32_fp8_fp8(cur.k[T][s2], qf[s2], sa[T], 0, 0, 0);
;     float sc[8]; bool vd[8]; float mx = -1e30f;
;     const bool act = lo == 0 || !SLC;
;     if (NOMASK) {
; #pragma unroll
;         for (int j = 0; j < 8; ++j) { sc[j] = sa[j >> 2][j & 3]; vd[j] = act; }
;         mx = fmaxf(fmaxf(fmaxf(sc[0], sc[1]), fmaxf(sc[2], sc[3])), fmaxf(fmaxf(sc[4], sc[5]), fmaxf(sc[6], sc[7])));
;         mx = act ? mx : -1e30f;
;     } else {
; #pragma unroll
;         for (int T = 0; T < 2; ++T)
; #pragma unroll
;             for (int r = 0; r < 4; ++r) { const int p = pos0 + 16 * T + 4 * kq + r; const bool v = (p >= lo) & (p <= hi); const float x = sa[T][r];
;                 sc[4 * T + r] = x; vd[4 * T + r] = v; mx = v ? fmaxf(mx, x) : mx; }
;     }
;     if (__builtin_amdgcn_ballot_w64(mx > st.m + 4.f) != 0ull) {
.LBB0_707:
	global_load_dwordx2 v[190:191], v[198:199], off
	global_load_dwordx2 v[194:195], v[198:199], off offset:512
	global_load_dwordx2 v[192:193], v[198:199], off offset:1024
	global_load_dwordx2 v[186:187], v[198:199], off offset:1536
	global_load_dwordx2 v[188:189], v[198:199], off offset:2048
	global_load_dwordx2 v[184:185], v[198:199], off offset:2560
	global_load_dwordx2 v[182:183], v[198:199], off offset:3072
	global_load_dwordx2 v[180:181], v[198:199], off offset:3584
	global_load_dwordx2 v[164:165], v[196:197], off
	global_load_dwordx2 v[166:167], v[196:197], off offset:512
	global_load_dwordx2 v[168:169], v[196:197], off offset:1024
	global_load_dwordx2 v[170:171], v[196:197], off offset:1536
	global_load_dwordx2 v[178:179], v[196:197], off offset:2048
	global_load_dwordx2 v[176:177], v[196:197], off offset:2560
	global_load_dwordx2 v[174:175], v[196:197], off offset:3072
	global_load_dwordx2 v[172:173], v[196:197], off offset:3584
	s_waitcnt vmcnt(47)
	v_mfma_f32_16x16x32_fp8_fp8 v[2:5], v[142:143], v[74:75], 0
	v_or_b32_e32 v0, s75, v203
	v_cmp_ge_i32_e32 vcc, v0, v105
	v_cmp_le_i32_e64 s[4:5], v0, v206
	s_waitcnt vmcnt(46)
	v_mfma_f32_16x16x32_fp8_fp8 v[2:5], v[146:147], v[76:77], v[2:5]
	s_and_b64 s[10:11], vcc, s[4:5]
	v_or_b32_e32 v11, 1, v0
	v_cmp_ge_i32_e32 vcc, v11, v105
	s_waitcnt vmcnt(45)
	v_mfma_f32_16x16x32_fp8_fp8 v[2:5], v[144:145], v[78:79], v[2:5]
	v_cmp_lt_i32_e64 s[4:5], v0, v206
	s_and_b64 s[6:7], s[4:5], vcc
	s_waitcnt vmcnt(43)
	v_mfma_f32_16x16x32_fp8_fp8 v[6:9], v[140:141], v[74:75], 0
	v_mfma_f32_16x16x32_fp8_fp8 v[2:5], v[138:139], v[80:81], v[2:5]
	s_waitcnt vmcnt(42)
	v_mfma_f32_16x16x32_fp8_fp8 v[6:9], v[136:137], v[76:77], v[6:9]
	s_waitcnt vmcnt(41)
	v_mfma_f32_16x16x32_fp8_fp8 v[6:9], v[134:135], v[78:79], v[6:9]
	s_nop 3
	v_max_f32_e32 v10, v2, v2
	v_max_f32_e32 v10, 0xf149f2ca, v10
	v_cndmask_b32_e64 v10, v205, v10, s[10:11]
	v_max_f32_e32 v11, v3, v3
	v_max_f32_e32 v11, v10, v11
	v_cndmask_b32_e64 v10, v10, v11, s[6:7]
	v_or_b32_e32 v11, 2, v0
	v_cmp_ge_i32_e32 vcc, v11, v105
	v_cmp_le_i32_e64 s[4:5], v11, v206
	v_max_f32_e32 v11, v4, v4
	v_max_f32_e32 v11, v10, v11
	s_and_b64 s[8:9], vcc, s[4:5]
	s_waitcnt vmcnt(40)
	v_mfma_f32_16x16x32_fp8_fp8 v[6:9], v[132:133], v[80:81], v[6:9]
	v_cndmask_b32_e64 v10, v10, v11, s[8:9]
	v_or_b32_e32 v11, 3, v0
	v_cmp_ge_i32_e32 vcc, v11, v105
	v_cmp_le_i32_e64 s[4:5], v11, v206
	v_max_f32_e32 v11, v5, v5
	v_max_f32_e32 v11, v10, v11
	s_and_b64 s[4:5], vcc, s[4:5]
	v_cndmask_b32_e64 v10, v10, v11, s[4:5]
	v_or_b32_e32 v11, 16, v0
	v_cmp_ge_i32_e32 vcc, v11, v105
	v_cmp_le_i32_e64 s[12:13], v11, v206
	v_max_f32_e32 v11, v6, v6
	v_max_f32_e32 v11, v10, v11
	s_and_b64 s[18:19], vcc, s[12:13]
	v_cndmask_b32_e64 v10, v10, v11, s[18:19]
	v_or_b32_e32 v11, 17, v0
	v_cmp_ge_i32_e32 vcc, v11, v105
	v_cmp_le_i32_e64 s[12:13], v11, v206
	v_max_f32_e32 v11, v10, v10
	v_max_f32_e32 v12, v7, v7
	v_max_f32_e32 v11, v11, v12
	s_and_b64 s[14:15], vcc, s[12:13]
	v_cndmask_b32_e64 v10, v10, v11, s[14:15]
	v_or_b32_e32 v11, 18, v0
	v_cmp_ge_i32_e32 vcc, v11, v105
	v_cmp_le_i32_e64 s[12:13], v11, v206
	v_max_f32_e32 v11, v10, v10
	v_max_f32_e32 v12, v8, v8
	v_max_f32_e32 v11, v11, v12
	s_and_b64 s[16:17], vcc, s[12:13]
	v_cndmask_b32_e64 v10, v10, v11, s[16:17]
	v_or_b32_e32 v0, 19, v0
	v_cmp_ge_i32_e32 vcc, v0, v105
	v_cmp_le_i32_e64 s[12:13], v0, v206
	v_max_f32_e32 v0, v10, v10
	v_max_f32_e32 v11, v9, v9
	v_max_f32_e32 v0, v0, v11
	s_and_b64 s[12:13], vcc, s[12:13]
	v_cndmask_b32_e64 v0, v10, v0, s[12:13]
	v_cmp_gt_f32_e32 vcc, v0, v211
	s_cbranch_vccz .LBB0_709
	v_and_b32_e32 v11, 64, v204
	v_xor_b32_e32 v10, 16, v204
	v_add_u32_e32 v11, 64, v11
	v_cmp_lt_i32_e32 vcc, v10, v11
	v_xor_b32_e32 v12, 32, v204
	s_nop 0
	v_cndmask_b32_e32 v10, v204, v10, vcc
	v_lshlrev_b32_e32 v10, 2, v10
	ds_bpermute_b32 v10, v10, v0
	v_max_f32_e32 v0, v0, v0
	v_cmp_lt_i32_e32 vcc, v12, v11
	s_waitcnt lgkmcnt(0)
	v_max_f32_e32 v10, v10, v10
	v_max_f32_e32 v0, v0, v10
	v_cndmask_b32_e32 v10, v204, v12, vcc
	v_lshlrev_b32_e32 v10, 2, v10
	ds_bpermute_b32 v10, v10, v0
	s_waitcnt lgkmcnt(0)
	v_max3_f32 v10, v210, v0, v10
	v_sub_f32_e32 v0, v210, v10
	v_exp_f32_e32 v0, v0
	v_mov_b32_e32 v210, v10
	v_mul_f32_e32 v209, v209, v0
	v_pk_mul_f32 v[36:37], v[36:37], v[0:1] op_sel_hi:[1,0]
	v_pk_mul_f32 v[34:35], v[34:35], v[0:1] op_sel_hi:[1,0]
	v_pk_mul_f32 v[40:41], v[40:41], v[0:1] op_sel_hi:[1,0]
	v_pk_mul_f32 v[38:39], v[38:39], v[0:1] op_sel_hi:[1,0]
	v_pk_mul_f32 v[44:45], v[44:45], v[0:1] op_sel_hi:[1,0]
	v_pk_mul_f32 v[42:43], v[42:43], v[0:1] op_sel_hi:[1,0]
	v_pk_mul_f32 v[56:57], v[56:57], v[0:1] op_sel_hi:[1,0]
	v_pk_mul_f32 v[54:55], v[54:55], v[0:1] op_sel_hi:[1,0]
	v_pk_mul_f32 v[64:65], v[64:65], v[0:1] op_sel_hi:[1,0]
	v_pk_mul_f32 v[62:63], v[62:63], v[0:1] op_sel_hi:[1,0]
	v_pk_mul_f32 v[60:61], v[60:61], v[0:1] op_sel_hi:[1,0]
	v_pk_mul_f32 v[58:59], v[58:59], v[0:1] op_sel_hi:[1,0]
	v_pk_mul_f32 v[52:53], v[52:53], v[0:1] op_sel_hi:[1,0]
	v_pk_mul_f32 v[50:51], v[50:51], v[0:1] op_sel_hi:[1,0]
	v_pk_mul_f32 v[48:49], v[48:49], v[0:1] op_sel_hi:[1,0]
	v_pk_mul_f32 v[46:47], v[46:47], v[0:1] op_sel_hi:[1,0]
; template <bool SLC, bool NOMASK> ...
;     ...
;     } else {
; #pragma unroll
;         for (int j = 0; j < 4; ++j) { pa[j] = vd[j] ? __builtin_amdgcn_exp2f(sc[j] - mref) : 0.f; pb[j] = vd[4 + j] ? __builtin_amdgcn_exp2f(sc[4 + j] - mref) : 0.f; ps += pa[j] + pb[j]; }
;     }
;     st.l += ps;
;     const u32x2 pw = pack8_fp8(pa, pb);
;     const i64_t pf = __builtin_bit_cast(i64_t, pw);
; #pragma unroll
;     for (int db = 0; db < 8; ++db) st.o[db] = __builtin_amdgcn_mfma_f32_16x16x32_fp8_fp8(cur.v[db], pf, st.o[db], 0, 0, 0);
.LBB0_709:
	v_add_f32_e32 v0, -4.0, v210
	v_sub_f32_e32 v2, v2, v0
	v_exp_f32_e32 v2, v2
	v_sub_f32_e32 v6, v6, v0
	v_exp_f32_e32 v6, v6
	v_sub_f32_e32 v4, v4, v0
	v_cndmask_b32_e64 v22, 0, v2, s[10:11]
	v_sub_f32_e32 v2, v3, v0
	v_exp_f32_e32 v2, v2
	v_sub_f32_e32 v3, v7, v0
	v_exp_f32_e32 v3, v3
	v_cndmask_b32_e64 v23, 0, v6, s[18:19]
	v_sub_f32_e32 v6, v8, v0
	v_cndmask_b32_e64 v24, 0, v2, s[6:7]
	v_sub_f32_e32 v2, v5, v0
	v_sub_f32_e32 v0, v9, v0
	v_exp_f32_e32 v4, v4
	v_exp_f32_e32 v6, v6
	v_cndmask_b32_e64 v25, 0, v3, s[14:15]
	v_exp_f32_e32 v2, v2
	v_exp_f32_e32 v0, v0
	v_mov_b32_e32 v26, v1
	v_mov_b32_e32 v27, v1
	v_cvt_pk_fp8_f32 v26, v22, v24
	v_cvt_pk_fp8_f32 v27, v23, v25
	v_cndmask_b32_e64 v28, 0, v4, s[8:9]
	v_cndmask_b32_e64 v29, 0, v6, s[16:17]
	v_cndmask_b32_e64 v66, 0, v2, s[4:5]
	v_cndmask_b32_e64 v0, 0, v0, s[12:13]
	v_cvt_pk_fp8_f32 v26, v28, v66 op_sel:[0,0,1]
	v_cvt_pk_fp8_f32 v27, v29, v0 op_sel:[0,0,1]
	v_add_f32_e32 v22, v22, v23
	v_add_f32_e32 v30, 0, v22
	v_add_f32_e32 v31, v24, v25
	v_add_f32_e32 v30, v31, v30
	v_add_f32_e32 v28, v28, v29
	v_add_f32_e32 v28, v28, v30
	v_add_f32_e32 v0, v66, v0
	s_waitcnt vmcnt(39)
	v_mfma_f32_16x16x32_fp8_fp8 v[2:5], v[86:87], v[26:27], v[34:37]
	v_add_f32_e32 v0, v0, v28
	v_add_f32_e32 v208, v209, v0
	v_mov_b32_e32 v207, v210
	s_waitcnt vmcnt(38)
	v_mfma_f32_16x16x32_fp8_fp8 v[6:9], v[88:89], v[26:27], v[38:41]
	s_waitcnt vmcnt(37)
	v_mfma_f32_16x16x32_fp8_fp8 v[10:13], v[90:91], v[26:27], v[42:45]
	s_waitcnt vmcnt(36)
	v_mfma_f32_16x16x32_fp8_fp8 v[14:17], v[92:93], v[26:27], v[54:57]
	s_waitcnt vmcnt(35)
	v_mfma_f32_16x16x32_fp8_fp8 v[18:21], v[114:115], v[26:27], v[62:65]
	s_waitcnt vmcnt(34)
	v_mfma_f32_16x16x32_fp8_fp8 v[22:25], v[112:113], v[26:27], v[58:61]
	s_waitcnt vmcnt(33)
	v_mfma_f32_16x16x32_fp8_fp8 v[30:33], v[96:97], v[26:27], v[50:53]
	s_waitcnt vmcnt(32)
	v_mfma_f32_16x16x32_fp8_fp8 v[26:29], v[94:95], v[26:27], v[46:49]
	s_cmp_ge_i32 s66, s74
	s_mov_b64 s[4:5], -1
	s_cbranch_scc0 .LBB0_701

; template <bool SLC, bool NOMASK> ...
;     const int kq = lane >> 4;
;     const int pos0 = SLC ? (dcur & 0xfffff) : dcur;
;     const int lo = SLC ? ((((dcur >> 20) == qi) | ((dcur >> 20) == 4)) ? 0 : (1 << 30)) : lo_in;
;     load_frag8(nxt, KF, VF, SLC ? (dnext & 0xfffff) : dnext, lane);
;     f32x4 sa[2] = {(f32x4){0.f, 0.f, 0.f, 0.f}, (f32x4){0.f, 0.f, 0.f, 0.f}};
; #pragma unroll
;     for (int T = 0; T < 2; ++T)
; #pragma unroll
;         for (int s2 = 0; s2 < 4; ++s2) sa[T] = __builtin_amdgcn_mfma_f32_16x16x32_fp8_fp8(cur.k[T][s2], qf[s2], sa[T], 0, 0, 0);
;     float sc[8]; bool vd[8]; float mx = -1e30f;
;     const bool act = lo == 0 || !SLC;
;     if (NOMASK) {
; #pragma unroll
;         for (int j = 0; j < 8; ++j) { sc[j] = sa[j >> 2][j & 3]; vd[j] = act; }
;         mx = fmaxf(fmaxf(fmaxf(sc[0], sc[1]), fmaxf(sc[2], sc[3])), fmaxf(fmaxf(sc[4], sc[5]), fmaxf(sc[6], sc[7])));
;         mx = act ? mx : -1e30f;
;     } else {
; #pragma unroll
;         for (int T = 0; T < 2; ++T)
; #pragma unroll
;             for (int r = 0; r < 4; ++r) { const int p = pos0 + 16 * T + 4 * kq + r; const bool v = (p >= lo) & (p <= hi); const float x = sa[T][r];
;                 sc[4 * T + r] = x; vd[4 * T + r] = v; mx = v ? fmaxf(mx, x) : mx; }
;     }
;     if (__builtin_amdgcn_ballot_w64(mx > st.m + 4.f) != 0ull) {
;         mx = fmaxf(mx, __shfl_xor(mx, 16)); mx = fmaxf(mx, __shfl_xor(mx, 32));
;         const float mn = fmaxf(st.m, mx), alpha = __builtin_amdgcn_exp2f(st.m - mn); st.m = mn; st.l *= alpha;
; #pragma unroll
;         for (int j = 0; j < 8; ++j) st.o[j] = st.o[j] * alpha;
;     }
;     f32x4 pa, pb; float ps = 0.f;
;     const float mref = st.m - 4.f;
;     if (NOMASK) {
; #pragma unroll
;         for (int j = 0; j < 4; ++j) { pa[j] = __builtin_amdgcn_exp2f(sc[j] - mref); pb[j] = __builtin_amdgcn_exp2f(sc[4 + j] - mref); }
;         if (SLC) {
; #pragma unroll
;             for (int j = 0; j < 4; ++j) { pa[j] = act ? pa[j] : 0.f; pb[j] = act ? pb[j] : 0.f; }
;         }
; #pragma unroll
;         for (int j = 0; j < 4; ++j) ps += pa[j] + pb[j];
;     } else {
; #pragma unroll
;         for (int j = 0; j < 4; ++j) { pa[j] = vd[j] ? __builtin_amdgcn_exp2f(sc[j] - mref) : 0.f; pb[j] = vd[4 + j] ? __builtin_amdgcn_exp2f(sc[4 + j] - mref) : 0.f; ps += pa[j] + pb[j]; }
;     }
;     st.l += ps;
;     const u32x2 pw = pack8_fp8(pa, pb);
.LBB0_711:
	global_load_dwordx2 v[142:143], v[198:199], off
	global_load_dwordx2 v[146:147], v[198:199], off offset:512
	global_load_dwordx2 v[144:145], v[198:199], off offset:1024
	global_load_dwordx2 v[138:139], v[198:199], off offset:1536
	global_load_dwordx2 v[140:141], v[198:199], off offset:2048
	global_load_dwordx2 v[136:137], v[198:199], off offset:2560
	global_load_dwordx2 v[134:135], v[198:199], off offset:3072
	global_load_dwordx2 v[132:133], v[198:199], off offset:3584
	global_load_dwordx2 v[86:87], v[196:197], off
	global_load_dwordx2 v[88:89], v[196:197], off offset:512
	global_load_dwordx2 v[90:91], v[196:197], off offset:1024
	global_load_dwordx2 v[92:93], v[196:197], off offset:1536
	global_load_dwordx2 v[114:115], v[196:197], off offset:2048
	global_load_dwordx2 v[112:113], v[196:197], off offset:2560
	global_load_dwordx2 v[96:97], v[196:197], off offset:3072
	global_load_dwordx2 v[94:95], v[196:197], off offset:3584
	s_waitcnt vmcnt(47)
	v_mfma_f32_16x16x32_fp8_fp8 v[34:37], v[160:161], v[74:75], 0
	v_mov_b64_e32 v[72:73], v[28:29]
	v_mov_b64_e32 v[68:69], v[32:33]
	v_mov_b64_e32 v[64:65], v[24:25]
	s_waitcnt vmcnt(43)
	v_mfma_f32_16x16x32_fp8_fp8 v[38:41], v[154:155], v[74:75], 0
	v_mov_b64_e32 v[60:61], v[20:21]
	v_mov_b64_e32 v[56:57], v[16:17]
	v_mov_b64_e32 v[52:53], v[12:13]
	v_mfma_f32_16x16x32_fp8_fp8 v[34:37], v[162:163], v[76:77], v[34:37]
	v_mov_b64_e32 v[48:49], v[8:9]
	v_mov_b32_e32 v209, v207
	v_mov_b64_e32 v[70:71], v[26:27]
	s_waitcnt vmcnt(42)
	v_mfma_f32_16x16x32_fp8_fp8 v[38:41], v[152:153], v[76:77], v[38:41]
	v_mov_b64_e32 v[66:67], v[30:31]
	v_mov_b64_e32 v[62:63], v[22:23]
	v_mov_b64_e32 v[58:59], v[18:19]
	v_mfma_f32_16x16x32_fp8_fp8 v[34:37], v[158:159], v[78:79], v[34:37]
	v_mov_b64_e32 v[54:55], v[14:15]
	v_mov_b64_e32 v[50:51], v[10:11]
	v_mov_b64_e32 v[46:47], v[6:7]
	s_waitcnt vmcnt(41)
	v_mfma_f32_16x16x32_fp8_fp8 v[38:41], v[150:151], v[78:79], v[38:41]
	v_mov_b32_e32 v210, v208
	v_mfma_f32_16x16x32_fp8_fp8 v[34:37], v[156:157], v[80:81], v[34:37]
	s_waitcnt vmcnt(40)
	v_mfma_f32_16x16x32_fp8_fp8 v[38:41], v[148:149], v[80:81], v[38:41]
	s_nop 5
	v_max_f32_e32 v0, v35, v35
	v_max_f32_e32 v42, v34, v34
	v_max_f32_e32 v0, v42, v0
	v_max_f32_e32 v42, v37, v37
	v_max_f32_e32 v43, v36, v36
	v_max_f32_e32 v42, v43, v42
	v_max_f32_e32 v43, v41, v41
	v_max_f32_e32 v44, v40, v40
	v_max_f32_e32 v43, v44, v43
	v_max3_f32 v43, v38, v39, v43
	v_max3_f32 v0, v0, v42, v43
	v_mov_b64_e32 v[44:45], v[4:5]
	v_cmp_gt_f32_e32 vcc, v0, v211
	v_mov_b64_e32 v[42:43], v[2:3]
	s_cbranch_vccz .LBB0_713
	v_and_b32_e32 v43, 64, v204
	v_xor_b32_e32 v42, 16, v204
	v_add_u32_e32 v43, 64, v43
	v_cmp_lt_i32_e32 vcc, v42, v43
	v_xor_b32_e32 v44, 32, v204
	s_nop 0
	v_cndmask_b32_e32 v42, v204, v42, vcc
	v_lshlrev_b32_e32 v42, 2, v42
	ds_bpermute_b32 v42, v42, v0
	v_max_f32_e32 v0, v0, v0
	v_cmp_lt_i32_e32 vcc, v44, v43
	s_waitcnt lgkmcnt(0)
	v_max_f32_e32 v42, v42, v42
	v_max_f32_e32 v0, v0, v42
	v_cndmask_b32_e32 v42, v204, v44, vcc
	v_lshlrev_b32_e32 v42, 2, v42
	ds_bpermute_b32 v42, v42, v0
	s_waitcnt lgkmcnt(0)
	v_max3_f32 v209, v207, v0, v42
	v_sub_f32_e32 v0, v207, v209
	v_exp_f32_e32 v0, v0
	s_nop 0
	v_mul_f32_e32 v210, v208, v0
	v_pk_mul_f32 v[44:45], v[4:5], v[0:1] op_sel_hi:[1,0]
	v_pk_mul_f32 v[42:43], v[2:3], v[0:1] op_sel_hi:[1,0]
	v_pk_mul_f32 v[48:49], v[8:9], v[0:1] op_sel_hi:[1,0]
	v_pk_mul_f32 v[46:47], v[6:7], v[0:1] op_sel_hi:[1,0]
	v_pk_mul_f32 v[52:53], v[12:13], v[0:1] op_sel_hi:[1,0]
	v_pk_mul_f32 v[50:51], v[10:11], v[0:1] op_sel_hi:[1,0]
	v_pk_mul_f32 v[56:57], v[16:17], v[0:1] op_sel_hi:[1,0]
	v_pk_mul_f32 v[54:55], v[14:15], v[0:1] op_sel_hi:[1,0]
	v_pk_mul_f32 v[60:61], v[20:21], v[0:1] op_sel_hi:[1,0]
	v_pk_mul_f32 v[58:59], v[18:19], v[0:1] op_sel_hi:[1,0]
	v_pk_mul_f32 v[64:65], v[24:25], v[0:1] op_sel_hi:[1,0]
	v_pk_mul_f32 v[62:63], v[22:23], v[0:1] op_sel_hi:[1,0]
	v_pk_mul_f32 v[68:69], v[32:33], v[0:1] op_sel_hi:[1,0]
	v_pk_mul_f32 v[66:67], v[30:31], v[0:1] op_sel_hi:[1,0]
	v_pk_mul_f32 v[72:73], v[28:29], v[0:1] op_sel_hi:[1,0]
	v_pk_mul_f32 v[70:71], v[26:27], v[0:1] op_sel_hi:[1,0]
.LBB0_713:
	v_add_f32_e32 v213, -4.0, v209
	v_sub_f32_e32 v0, v34, v213
	v_exp_f32_e32 v215, v0
	v_sub_f32_e32 v0, v38, v213
	v_exp_f32_e32 v217, v0
	v_sub_f32_e32 v0, v35, v213
	v_exp_f32_e32 v212, v0
	v_sub_f32_e32 v0, v39, v213
	v_exp_f32_e32 v0, v0
	v_sub_f32_e32 v34, v36, v213
	v_exp_f32_e32 v220, v34
	v_sub_f32_e32 v34, v40, v213
	v_exp_f32_e32 v221, v34
	v_sub_f32_e32 v34, v37, v213
	v_exp_f32_e32 v214, v34
	v_sub_f32_e32 v34, v41, v213
	v_mov_b32_e32 v218, v1
	v_mov_b32_e32 v219, v1
	v_exp_f32_e32 v216, v34
	v_cvt_pk_fp8_f32 v218, v215, v212
	v_cvt_pk_fp8_f32 v219, v217, v0
	v_add_f32_e32 v213, v215, v217
	v_add_f32_e32 v215, v220, v221
	v_cvt_pk_fp8_f32 v218, v220, v214 op_sel:[0,0,1]
	v_cvt_pk_fp8_f32 v219, v221, v216 op_sel:[0,0,1]
	s_waitcnt vmcnt(39)
	s_nop 0
	v_mfma_f32_16x16x32_fp8_fp8 v[34:37], v[116:117], v[218:219], v[42:45]
	s_waitcnt vmcnt(37)
	v_mfma_f32_16x16x32_fp8_fp8 v[42:45], v[122:123], v[218:219], v[50:53]
	s_waitcnt vmcnt(35)
	v_mfma_f32_16x16x32_fp8_fp8 v[50:53], v[130:131], v[218:219], v[58:61]
	s_nop 2
	v_add_f32_e64 v58, v212, v0
	v_add_f32_e64 v59, v213, v1
	v_mfma_f32_16x16x32_fp8_fp8 v[38:41], v[120:121], v[218:219], v[46:49]
	v_pk_add_f32 v[58:59], v[58:59], v[58:59] op_sel_hi:[0,1]
	v_mov_b32_e32 v217, v59
	v_mfma_f32_16x16x32_fp8_fp8 v[46:49], v[126:127], v[218:219], v[54:57]
	s_waitcnt vmcnt(34)
	v_mfma_f32_16x16x32_fp8_fp8 v[54:57], v[128:129], v[218:219], v[62:65]
	s_nop 2
	v_add_f32_e64 v62, v214, v216
	v_add_f32_e64 v63, v215, v217
	s_waitcnt vmcnt(33)
	v_mfma_f32_16x16x32_fp8_fp8 v[58:61], v[124:125], v[218:219], v[66:69]
	v_add_f32_e32 v0, v62, v63
	v_add_f32_e32 v210, v0, v210
	s_waitcnt vmcnt(32)
	v_mfma_f32_16x16x32_fp8_fp8 v[62:65], v[118:119], v[218:219], v[70:73]
	s_branch .LBB0_703
; template <bool SLC, bool NOMASK> ...
;     const int kq = lane >> 4;
;     const int pos0 = SLC ? (dcur & 0xfffff) : dcur;
;     const int lo = SLC ? ((((dcur >> 20) == qi) | ((dcur >> 20) == 4)) ? 0 : (1 << 30)) : lo_in;
;     load_frag8(nxt, KF, VF, SLC ? (dnext & 0xfffff) : dnext, lane);
;     f32x4 sa[2] = {(f32x4){0.f, 0.f, 0.f, 0.f}, (f32x4){0.f, 0.f, 0.f, 0.f}};
; #pragma unroll
;     for (int T = 0; T < 2; ++T)
; #pragma unroll
;         for (int s2 = 0; s2 < 4; ++s2) sa[T] = __builtin_amdgcn_mfma_f32_16x16x32_fp8_fp8(cur.k[T][s2], qf[s2], sa[T], 0, 0, 0);
;     float sc[8]; bool vd[8]; float mx = -1e30f;
;     const bool act = lo == 0 || !SLC;
;     if (NOMASK) {
; #pragma unroll
;         for (int j = 0; j < 8; ++j) { sc[j] = sa[j >> 2][j & 3]; vd[j] = act; }
;         mx = fmaxf(fmaxf(fmaxf(sc[0], sc[1]), fmaxf(sc[2], sc[3])), fmaxf(fmaxf(sc[4], sc[5]), fmaxf(sc[6], sc[7])));
;         mx = act ? mx : -1e30f;
;     } else {
; #pragma unroll
;         for (int T = 0; T < 2; ++T)
; #pragma unroll
;             for (int r = 0; r < 4; ++r) { const int p = pos0 + 16 * T + 4 * kq + r; const bool v = (p >= lo) & (p <= hi); const float x = sa[T][r];
;                 sc[4 * T + r] = x; vd[4 * T + r] = v; mx = v ? fmaxf(mx, x) : mx; }
;     }
;     if (__builtin_amdgcn_ballot_w64(mx > st.m + 4.f) != 0ull) {
.LBB0_714:
	global_load_dwordx2 v[142:143], v[198:199], off
	global_load_dwordx2 v[146:147], v[198:199], off offset:512
	global_load_dwordx2 v[144:145], v[198:199], off offset:1024
	global_load_dwordx2 v[138:139], v[198:199], off offset:1536
	global_load_dwordx2 v[140:141], v[198:199], off offset:2048
	global_load_dwordx2 v[136:137], v[198:199], off offset:2560
	global_load_dwordx2 v[134:135], v[198:199], off offset:3072
	global_load_dwordx2 v[132:133], v[198:199], off offset:3584
	global_load_dwordx2 v[86:87], v[196:197], off
	global_load_dwordx2 v[88:89], v[196:197], off offset:512
	global_load_dwordx2 v[90:91], v[196:197], off offset:1024
	global_load_dwordx2 v[92:93], v[196:197], off offset:1536
	global_load_dwordx2 v[114:115], v[196:197], off offset:2048
	global_load_dwordx2 v[112:113], v[196:197], off offset:2560
	global_load_dwordx2 v[96:97], v[196:197], off offset:3072
	global_load_dwordx2 v[94:95], v[196:197], off offset:3584
	s_waitcnt vmcnt(47)
	v_mfma_f32_16x16x32_fp8_fp8 v[34:37], v[160:161], v[74:75], 0
	v_or_b32_e32 v0, s76, v203
	v_cmp_ge_i32_e32 vcc, v0, v105
	v_cmp_le_i32_e64 s[4:5], v0, v206
	s_waitcnt vmcnt(46)
	v_mfma_f32_16x16x32_fp8_fp8 v[34:37], v[162:163], v[76:77], v[34:37]
	s_and_b64 s[10:11], vcc, s[4:5]
	v_or_b32_e32 v43, 1, v0
	v_cmp_ge_i32_e32 vcc, v43, v105
	s_waitcnt vmcnt(45)
	v_mfma_f32_16x16x32_fp8_fp8 v[34:37], v[158:159], v[78:79], v[34:37]
	v_cmp_lt_i32_e64 s[4:5], v0, v206
	s_and_b64 s[6:7], s[4:5], vcc
	s_waitcnt vmcnt(43)
	v_mfma_f32_16x16x32_fp8_fp8 v[38:41], v[154:155], v[74:75], 0
	v_mfma_f32_16x16x32_fp8_fp8 v[34:37], v[156:157], v[80:81], v[34:37]
	s_waitcnt vmcnt(42)
	v_mfma_f32_16x16x32_fp8_fp8 v[38:41], v[152:153], v[76:77], v[38:41]
	s_waitcnt vmcnt(41)
	v_mfma_f32_16x16x32_fp8_fp8 v[38:41], v[150:151], v[78:79], v[38:41]
	s_nop 3
	v_max_f32_e32 v42, v34, v34
	v_max_f32_e32 v42, 0xf149f2ca, v42
	v_cndmask_b32_e64 v42, v205, v42, s[10:11]
	v_max_f32_e32 v43, v35, v35
	v_max_f32_e32 v43, v42, v43
	v_cndmask_b32_e64 v42, v42, v43, s[6:7]
	v_or_b32_e32 v43, 2, v0
	v_cmp_ge_i32_e32 vcc, v43, v105
	v_cmp_le_i32_e64 s[4:5], v43, v206
	v_max_f32_e32 v43, v36, v36
	v_max_f32_e32 v43, v42, v43
	s_and_b64 s[8:9], vcc, s[4:5]
	s_waitcnt vmcnt(40)
	v_mfma_f32_16x16x32_fp8_fp8 v[38:41], v[148:149], v[80:81], v[38:41]
	v_cndmask_b32_e64 v42, v42, v43, s[8:9]
	v_or_b32_e32 v43, 3, v0
	v_cmp_ge_i32_e32 vcc, v43, v105
	v_cmp_le_i32_e64 s[4:5], v43, v206
	v_max_f32_e32 v43, v37, v37
	v_max_f32_e32 v43, v42, v43
	s_and_b64 s[4:5], vcc, s[4:5]
	v_cndmask_b32_e64 v42, v42, v43, s[4:5]
	v_or_b32_e32 v43, 16, v0
	v_cmp_ge_i32_e32 vcc, v43, v105
	v_cmp_le_i32_e64 s[12:13], v43, v206
	v_max_f32_e32 v43, v38, v38
	v_max_f32_e32 v43, v42, v43
	s_and_b64 s[18:19], vcc, s[12:13]
	v_cndmask_b32_e64 v42, v42, v43, s[18:19]
	v_or_b32_e32 v43, 17, v0
	v_cmp_ge_i32_e32 vcc, v43, v105
	v_cmp_le_i32_e64 s[12:13], v43, v206
	v_max_f32_e32 v43, v42, v42
	v_max_f32_e32 v44, v39, v39
	v_max_f32_e32 v43, v43, v44
	s_and_b64 s[14:15], vcc, s[12:13]
	v_cndmask_b32_e64 v42, v42, v43, s[14:15]
	v_or_b32_e32 v43, 18, v0
	v_cmp_ge_i32_e32 vcc, v43, v105
	v_cmp_le_i32_e64 s[12:13], v43, v206
	v_max_f32_e32 v43, v42, v42
	v_max_f32_e32 v44, v40, v40
	v_max_f32_e32 v43, v43, v44
	s_and_b64 s[16:17], vcc, s[12:13]
	v_cndmask_b32_e64 v42, v42, v43, s[16:17]
	v_or_b32_e32 v0, 19, v0
	v_cmp_ge_i32_e32 vcc, v0, v105
	v_cmp_le_i32_e64 s[12:13], v0, v206
	v_max_f32_e32 v0, v42, v42
	v_max_f32_e32 v43, v41, v41
	v_max_f32_e32 v0, v0, v43
	s_and_b64 s[12:13], vcc, s[12:13]
	v_cndmask_b32_e64 v0, v42, v0, s[12:13]
	v_cmp_gt_f32_e32 vcc, v0, v211
	s_cbranch_vccz .LBB0_716
	v_and_b32_e32 v43, 64, v204
	v_xor_b32_e32 v42, 16, v204
	v_add_u32_e32 v43, 64, v43
	v_cmp_lt_i32_e32 vcc, v42, v43
	v_xor_b32_e32 v44, 32, v204
	s_nop 0
	v_cndmask_b32_e32 v42, v204, v42, vcc
	v_lshlrev_b32_e32 v42, 2, v42
	ds_bpermute_b32 v42, v42, v0
	v_max_f32_e32 v0, v0, v0
	v_cmp_lt_i32_e32 vcc, v44, v43
	s_waitcnt lgkmcnt(0)
	v_max_f32_e32 v42, v42, v42
	v_max_f32_e32 v0, v0, v42
	v_cndmask_b32_e32 v42, v204, v44, vcc
	v_lshlrev_b32_e32 v42, 2, v42
	ds_bpermute_b32 v42, v42, v0
	s_waitcnt lgkmcnt(0)
	v_max3_f32 v42, v207, v0, v42
	v_sub_f32_e32 v0, v207, v42
	v_exp_f32_e32 v0, v0
	v_mov_b32_e32 v207, v42
	v_mul_f32_e32 v208, v208, v0
	v_pk_mul_f32 v[4:5], v[4:5], v[0:1] op_sel_hi:[1,0]
	v_pk_mul_f32 v[2:3], v[2:3], v[0:1] op_sel_hi:[1,0]
	v_pk_mul_f32 v[8:9], v[8:9], v[0:1] op_sel_hi:[1,0]
	v_pk_mul_f32 v[6:7], v[6:7], v[0:1] op_sel_hi:[1,0]
	v_pk_mul_f32 v[12:13], v[12:13], v[0:1] op_sel_hi:[1,0]
	v_pk_mul_f32 v[10:11], v[10:11], v[0:1] op_sel_hi:[1,0]
	v_pk_mul_f32 v[16:17], v[16:17], v[0:1] op_sel_hi:[1,0]
	v_pk_mul_f32 v[14:15], v[14:15], v[0:1] op_sel_hi:[1,0]
	v_pk_mul_f32 v[20:21], v[20:21], v[0:1] op_sel_hi:[1,0]
	v_pk_mul_f32 v[18:19], v[18:19], v[0:1] op_sel_hi:[1,0]
	v_pk_mul_f32 v[24:25], v[24:25], v[0:1] op_sel_hi:[1,0]
	v_pk_mul_f32 v[22:23], v[22:23], v[0:1] op_sel_hi:[1,0]
	v_pk_mul_f32 v[32:33], v[32:33], v[0:1] op_sel_hi:[1,0]
	v_pk_mul_f32 v[30:31], v[30:31], v[0:1] op_sel_hi:[1,0]
	v_pk_mul_f32 v[28:29], v[28:29], v[0:1] op_sel_hi:[1,0]
	v_pk_mul_f32 v[26:27], v[26:27], v[0:1] op_sel_hi:[1,0]
; #define F8_STEP(CUR, NXT2, DC, DN2) do { \
;         if ((DC) & (1 << 30)) step_frag8<SLC, true>(qf, CUR, NXT2, KF, VF, (DC) & NM, (DN2) & NM, lo_in, hi, qi, st, lane); \
;         else step_frag8<SLC, false>(qf, CUR, NXT2, KF, VF, (DC), (DN2) & NM, lo_in, hi, qi, st, lane); } while (0)
; template <bool SLC, bool NOMASK> ...
;     ...
;     } else {
; #pragma unroll
;         for (int j = 0; j < 4; ++j) { pa[j] = vd[j] ? __builtin_amdgcn_exp2f(sc[j] - mref) : 0.f; pb[j] = vd[4 + j] ? __builtin_amdgcn_exp2f(sc[4 + j] - mref) : 0.f; ps += pa[j] + pb[j]; }
;     }
;     st.l += ps;
;     const u32x2 pw = pack8_fp8(pa, pb);
;     const i64_t pf = __builtin_bit_cast(i64_t, pw);
; #pragma unroll
;     for (int db = 0; db < 8; ++db) st.o[db] = __builtin_amdgcn_mfma_f32_16x16x32_fp8_fp8(cur.v[db], pf, st.o[db], 0, 0, 0);
; template <bool SLC, class Desc>
; __device__ __forceinline__ void attn_run_frag8(const i64_t (&qf)[4], const unsigned char* __restrict__ KF, const unsigned char* __restrict__ VF, const Desc& desc, int n,
;                                                int lo_in, int hi, int qi, AState& st, int lane) {
;     ...
;     for (int i = 0; i < n; i += 3) {
;         const int d2 = desc(i + 2 < n ? i + 2 : n - 1);
;         F8_STEP(fa, fc, d0, d2);
;         if (i + 1 >= n) break;
;         const int d3 = desc(i + 3 < n ? i + 3 : n - 1);
;         F8_STEP(fb, fa, d1, d3);
;         if (i + 2 >= n) break;
;         const int d4 = desc(i + 4 < n ? i + 4 : n - 1);
;         F8_STEP(fc, fb, d2, d4);
;         d0 = d3; d1 = d4;
.LBB0_716:
	v_add_f32_e32 v0, -4.0, v207
	v_sub_f32_e32 v34, v34, v0
	v_exp_f32_e32 v34, v34
	v_sub_f32_e32 v38, v38, v0
	v_exp_f32_e32 v38, v38
	v_sub_f32_e32 v36, v36, v0
	v_cndmask_b32_e64 v54, 0, v34, s[10:11]
	v_sub_f32_e32 v34, v35, v0
	v_exp_f32_e32 v34, v34
	v_sub_f32_e32 v35, v39, v0
	v_exp_f32_e32 v35, v35
	v_cndmask_b32_e64 v55, 0, v38, s[18:19]
	v_sub_f32_e32 v38, v40, v0
	v_cndmask_b32_e64 v56, 0, v34, s[6:7]
	v_sub_f32_e32 v34, v37, v0
	v_sub_f32_e32 v0, v41, v0
	v_exp_f32_e32 v36, v36
	v_exp_f32_e32 v38, v38
	v_cndmask_b32_e64 v57, 0, v35, s[14:15]
	v_exp_f32_e32 v34, v34
	v_exp_f32_e32 v0, v0
	v_mov_b32_e32 v62, v1
	v_mov_b32_e32 v63, v1
	v_cvt_pk_fp8_f32 v62, v54, v56
	v_cvt_pk_fp8_f32 v63, v55, v57
	v_cndmask_b32_e64 v58, 0, v36, s[8:9]
	v_cndmask_b32_e64 v59, 0, v38, s[16:17]
	v_cndmask_b32_e64 v64, 0, v34, s[4:5]
	v_cndmask_b32_e64 v0, 0, v0, s[12:13]
	v_cvt_pk_fp8_f32 v62, v58, v64 op_sel:[0,0,1]
	v_cvt_pk_fp8_f32 v63, v59, v0 op_sel:[0,0,1]
	v_add_f32_e32 v0, v64, v0
	v_mov_b32_e32 v209, v207
	s_waitcnt vmcnt(39)
	v_mfma_f32_16x16x32_fp8_fp8 v[34:37], v[116:117], v[62:63], v[2:5]
	s_nop 2
	v_add_f32_e32 v2, v54, v55
	v_add_f32_e32 v2, 0, v2
	v_add_f32_e32 v3, v56, v57
	s_waitcnt vmcnt(38)
	v_mfma_f32_16x16x32_fp8_fp8 v[38:41], v[120:121], v[62:63], v[6:9]
	v_add_f32_e32 v2, v3, v2
	v_add_f32_e32 v3, v58, v59
	v_add_f32_e32 v2, v3, v2
	s_waitcnt vmcnt(37)
	v_mfma_f32_16x16x32_fp8_fp8 v[42:45], v[122:123], v[62:63], v[10:13]
	v_add_f32_e32 v0, v0, v2
	v_add_f32_e32 v210, v208, v0
	s_waitcnt vmcnt(36)
	v_mfma_f32_16x16x32_fp8_fp8 v[46:49], v[126:127], v[62:63], v[14:17]
	s_waitcnt vmcnt(35)
	v_mfma_f32_16x16x32_fp8_fp8 v[50:53], v[130:131], v[62:63], v[18:21]
	s_waitcnt vmcnt(34)
	v_mfma_f32_16x16x32_fp8_fp8 v[54:57], v[128:129], v[62:63], v[22:25]
	s_waitcnt vmcnt(33)
	v_mfma_f32_16x16x32_fp8_fp8 v[58:61], v[124:125], v[62:63], v[30:33]
	s_waitcnt vmcnt(32)
	v_mfma_f32_16x16x32_fp8_fp8 v[62:65], v[118:119], v[62:63], v[26:29]
	s_cmp_gt_i32 s77, s74
	s_mov_b64 s[4:5], -1
	s_cbranch_scc1 .LBB0_696
.LBB0_717:
	s_add_i32 s66, s66, 4
	s_min_i32 s4, s66, s74
	s_add_i32 s6, s4, s73
	s_lshl_b32 s76, s6, 5
	s_and_b32 s4, s76, 0x3fffffe0
	s_lshr_b32 s26, s4, 4
	s_lshl_b64 s[4:5], s[26:27], 11
	s_and_b32 s26, s6, 0x1ffffff
	s_and_b32 s8, s42, 0x2000000
	s_lshl_b64 s[6:7], s[26:27], 12
	s_cmp_eq_u32 s8, 0
	v_lshl_add_u64 v[198:199], v[82:83], 0, s[4:5]
	v_lshl_add_u64 v[196:197], v[84:85], 0, s[6:7]
	s_mov_b64 s[4:5], -1
	v_add_f32_e32 v211, 4.0, v209
	s_cbranch_scc1 .LBB0_721
	global_load_dwordx2 v[160:161], v[198:199], off
	global_load_dwordx2 v[162:163], v[198:199], off offset:512
	global_load_dwordx2 v[158:159], v[198:199], off offset:1024
	global_load_dwordx2 v[156:157], v[198:199], off offset:1536
	global_load_dwordx2 v[154:155], v[198:199], off offset:2048
	global_load_dwordx2 v[152:153], v[198:199], off offset:2560
	global_load_dwordx2 v[150:151], v[198:199], off offset:3072
	global_load_dwordx2 v[148:149], v[198:199], off offset:3584
	global_load_dwordx2 v[116:117], v[196:197], off
	global_load_dwordx2 v[120:121], v[196:197], off offset:512
	global_load_dwordx2 v[122:123], v[196:197], off offset:1024
	global_load_dwordx2 v[126:127], v[196:197], off offset:1536
	global_load_dwordx2 v[130:131], v[196:197], off offset:2048
	global_load_dwordx2 v[128:129], v[196:197], off offset:2560
	global_load_dwordx2 v[124:125], v[196:197], off offset:3072
	global_load_dwordx2 v[118:119], v[196:197], off offset:3584
	s_waitcnt vmcnt(47)
	v_mfma_f32_16x16x32_fp8_fp8 v[2:5], v[190:191], v[74:75], 0
	v_mov_b64_e32 v[72:73], v[64:65]
	v_mov_b64_e32 v[68:69], v[60:61]
	v_mov_b64_e32 v[30:31], v[54:55]
	s_waitcnt vmcnt(43)
	v_mfma_f32_16x16x32_fp8_fp8 v[6:9], v[188:189], v[74:75], 0
	v_mov_b64_e32 v[26:27], v[50:51]
	v_mov_b64_e32 v[22:23], v[46:47]
	v_mov_b64_e32 v[18:19], v[42:43]
	v_mfma_f32_16x16x32_fp8_fp8 v[2:5], v[194:195], v[76:77], v[2:5]
	v_mov_b64_e32 v[14:15], v[38:39]
	v_mov_b32_e32 v207, v209
	v_mov_b64_e32 v[70:71], v[62:63]
	s_waitcnt vmcnt(42)
	v_mfma_f32_16x16x32_fp8_fp8 v[6:9], v[184:185], v[76:77], v[6:9]
	v_mov_b64_e32 v[66:67], v[58:59]
	v_mov_b64_e32 v[32:33], v[56:57]
	v_mov_b64_e32 v[28:29], v[52:53]
	v_mfma_f32_16x16x32_fp8_fp8 v[2:5], v[192:193], v[78:79], v[2:5]
	v_mov_b64_e32 v[24:25], v[48:49]
	v_mov_b64_e32 v[20:21], v[44:45]
	v_mov_b64_e32 v[16:17], v[40:41]
	s_waitcnt vmcnt(41)
	v_mfma_f32_16x16x32_fp8_fp8 v[6:9], v[182:183], v[78:79], v[6:9]
	v_mov_b32_e32 v208, v210
	v_mfma_f32_16x16x32_fp8_fp8 v[2:5], v[186:187], v[80:81], v[2:5]
	s_waitcnt vmcnt(40)
	v_mfma_f32_16x16x32_fp8_fp8 v[6:9], v[180:181], v[80:81], v[6:9]
	s_nop 5
	v_max_f32_e32 v0, v3, v3
	v_max_f32_e32 v10, v2, v2
	v_max_f32_e32 v0, v10, v0
	v_max_f32_e32 v10, v5, v5
	v_max_f32_e32 v11, v4, v4
	v_max_f32_e32 v10, v11, v10
	v_max_f32_e32 v11, v9, v9
	v_max_f32_e32 v12, v8, v8
	v_max_f32_e32 v11, v12, v11
	v_max3_f32 v11, v6, v7, v11
	v_max3_f32 v0, v0, v10, v11
	v_mov_b64_e32 v[10:11], v[34:35]
	v_cmp_gt_f32_e32 vcc, v0, v211
	v_mov_b64_e32 v[12:13], v[36:37]
	s_cbranch_vccz .LBB0_720
	v_and_b32_e32 v11, 64, v204
	v_xor_b32_e32 v10, 16, v204
	v_add_u32_e32 v11, 64, v11
	v_cmp_lt_i32_e32 vcc, v10, v11
	v_xor_b32_e32 v12, 32, v204
	s_nop 0
	v_cndmask_b32_e32 v10, v204, v10, vcc
	v_lshlrev_b32_e32 v10, 2, v10
	ds_bpermute_b32 v10, v10, v0
	v_max_f32_e32 v0, v0, v0
	v_cmp_lt_i32_e32 vcc, v12, v11
	s_waitcnt lgkmcnt(0)
	v_max_f32_e32 v10, v10, v10
	v_max_f32_e32 v0, v0, v10
	v_cndmask_b32_e32 v10, v204, v12, vcc
	v_lshlrev_b32_e32 v10, 2, v10
	ds_bpermute_b32 v10, v10, v0
	s_waitcnt lgkmcnt(0)
	v_max3_f32 v207, v209, v0, v10
	v_sub_f32_e32 v0, v209, v207
	v_exp_f32_e32 v0, v0
	s_nop 0
	v_mul_f32_e32 v208, v210, v0
	v_pk_mul_f32 v[12:13], v[36:37], v[0:1] op_sel_hi:[1,0]
	v_pk_mul_f32 v[10:11], v[34:35], v[0:1] op_sel_hi:[1,0]
	v_pk_mul_f32 v[16:17], v[40:41], v[0:1] op_sel_hi:[1,0]
	v_pk_mul_f32 v[14:15], v[38:39], v[0:1] op_sel_hi:[1,0]
	v_pk_mul_f32 v[20:21], v[44:45], v[0:1] op_sel_hi:[1,0]
	v_pk_mul_f32 v[18:19], v[42:43], v[0:1] op_sel_hi:[1,0]
	v_pk_mul_f32 v[24:25], v[48:49], v[0:1] op_sel_hi:[1,0]
	v_pk_mul_f32 v[22:23], v[46:47], v[0:1] op_sel_hi:[1,0]
	v_pk_mul_f32 v[28:29], v[52:53], v[0:1] op_sel_hi:[1,0]
	v_pk_mul_f32 v[26:27], v[50:51], v[0:1] op_sel_hi:[1,0]
	v_pk_mul_f32 v[32:33], v[56:57], v[0:1] op_sel_hi:[1,0]
	v_pk_mul_f32 v[30:31], v[54:55], v[0:1] op_sel_hi:[1,0]
	v_pk_mul_f32 v[68:69], v[60:61], v[0:1] op_sel_hi:[1,0]
	v_pk_mul_f32 v[66:67], v[58:59], v[0:1] op_sel_hi:[1,0]
	v_pk_mul_f32 v[72:73], v[64:65], v[0:1] op_sel_hi:[1,0]
	v_pk_mul_f32 v[70:71], v[62:63], v[0:1] op_sel_hi:[1,0]
; template <bool SLC, bool NOMASK> ...
;     const int kq = lane >> 4;
;     const int pos0 = SLC ? (dcur & 0xfffff) : dcur;
;     const int lo = SLC ? ((((dcur >> 20) == qi) | ((dcur >> 20) == 4)) ? 0 : (1 << 30)) : lo_in;
;     load_frag8(nxt, KF, VF, SLC ? (dnext & 0xfffff) : dnext, lane);
;     f32x4 sa[2] = {(f32x4){0.f, 0.f, 0.f, 0.f}, (f32x4){0.f, 0.f, 0.f, 0.f}};
; #pragma unroll
;     for (int T = 0; T < 2; ++T)
; #pragma unroll
;         for (int s2 = 0; s2 < 4; ++s2) sa[T] = __builtin_amdgcn_mfma_f32_16x16x32_fp8_fp8(cur.k[T][s2], qf[s2], sa[T], 0, 0, 0);
;     float sc[8]; bool vd[8]; float mx = -1e30f;
;     const bool act = lo == 0 || !SLC;
;     if (NOMASK) {
; #pragma unroll
;         for (int j = 0; j < 8; ++j) { sc[j] = sa[j >> 2][j & 3]; vd[j] = act; }
;         mx = fmaxf(fmaxf(fmaxf(sc[0], sc[1]), fmaxf(sc[2], sc[3])), fmaxf(fmaxf(sc[4], sc[5]), fmaxf(sc[6], sc[7])));
;         mx = act ? mx : -1e30f;
;     } else {
; #pragma unroll
;         for (int T = 0; T < 2; ++T)
; #pragma unroll
;             for (int r = 0; r < 4; ++r) { const int p = pos0 + 16 * T + 4 * kq + r; const bool v = (p >= lo) & (p <= hi); const float x = sa[T][r];
;                 sc[4 * T + r] = x; vd[4 * T + r] = v; mx = v ? fmaxf(mx, x) : mx; }
;     }
;     if (__builtin_amdgcn_ballot_w64(mx > st.m + 4.f) != 0ull) {
;     ...
;     } else {
; #pragma unroll
;         for (int j = 0; j < 4; ++j) { pa[j] = vd[j] ? __builtin_amdgcn_exp2f(sc[j] - mref) : 0.f; pb[j] = vd[4 + j] ? __builtin_amdgcn_exp2f(sc[4 + j] - mref) : 0.f; ps += pa[j] + pb[j]; }
;     }
;     st.l += ps;
;     const u32x2 pw = pack8_fp8(pa, pb);
;     const i64_t pf = __builtin_bit_cast(i64_t, pw);
; #pragma unroll
;     for (int db = 0; db < 8; ++db) st.o[db] = __builtin_amdgcn_mfma_f32_16x16x32_fp8_fp8(cur.v[db], pf, st.o[db], 0, 0, 0);
.LBB0_720:
	v_add_f32_e32 v213, -4.0, v207
	v_sub_f32_e32 v0, v2, v213
	v_exp_f32_e32 v215, v0
	v_sub_f32_e32 v0, v6, v213
	v_exp_f32_e32 v217, v0
	v_sub_f32_e32 v0, v3, v213
	v_exp_f32_e32 v212, v0
	v_sub_f32_e32 v0, v7, v213
	v_exp_f32_e32 v0, v0
	v_sub_f32_e32 v2, v4, v213
	v_exp_f32_e32 v220, v2
	v_sub_f32_e32 v2, v8, v213
	v_exp_f32_e32 v221, v2
	v_sub_f32_e32 v2, v5, v213
	v_exp_f32_e32 v214, v2
	v_sub_f32_e32 v2, v9, v213
	v_mov_b32_e32 v218, v1
	v_mov_b32_e32 v219, v1
	v_exp_f32_e32 v216, v2
	v_cvt_pk_fp8_f32 v218, v215, v212
	v_cvt_pk_fp8_f32 v219, v217, v0
	v_add_f32_e32 v213, v215, v217
	v_add_f32_e32 v215, v220, v221
	v_cvt_pk_fp8_f32 v218, v220, v214 op_sel:[0,0,1]
	v_cvt_pk_fp8_f32 v219, v221, v216 op_sel:[0,0,1]
	s_mov_b64 s[4:5], 0
	s_waitcnt vmcnt(39)
	v_mfma_f32_16x16x32_fp8_fp8 v[2:5], v[164:165], v[218:219], v[10:13]
	s_waitcnt vmcnt(37)
	v_mfma_f32_16x16x32_fp8_fp8 v[10:13], v[168:169], v[218:219], v[18:21]
	s_waitcnt vmcnt(35)
	v_mfma_f32_16x16x32_fp8_fp8 v[18:21], v[178:179], v[218:219], v[26:29]
	s_nop 2
	v_add_f32_e64 v26, v212, v0
	v_add_f32_e64 v27, v213, v1
	v_mfma_f32_16x16x32_fp8_fp8 v[6:9], v[166:167], v[218:219], v[14:17]
	v_pk_add_f32 v[26:27], v[26:27], v[26:27] op_sel_hi:[0,1]
	v_mov_b32_e32 v217, v27
	v_pk_add_f32 v[26:27], v[214:215], v[216:217]
	v_mfma_f32_16x16x32_fp8_fp8 v[14:17], v[170:171], v[218:219], v[22:25]
	v_add_f32_e32 v0, v26, v27
	v_add_f32_e32 v208, v0, v208
	s_waitcnt vmcnt(34)
	v_mfma_f32_16x16x32_fp8_fp8 v[22:25], v[176:177], v[218:219], v[30:33]
	s_waitcnt vmcnt(33)
	v_mfma_f32_16x16x32_fp8_fp8 v[30:33], v[174:175], v[218:219], v[66:69]
	s_waitcnt vmcnt(32)
	v_mfma_f32_16x16x32_fp8_fp8 v[26:29], v[172:173], v[218:219], v[70:73]
.LBB0_721:
	s_and_b64 vcc, exec, s[4:5]
	s_cbranch_vccz .LBB0_725
	global_load_dwordx2 v[160:161], v[198:199], off
	global_load_dwordx2 v[162:163], v[198:199], off offset:512
	global_load_dwordx2 v[158:159], v[198:199], off offset:1024
	global_load_dwordx2 v[156:157], v[198:199], off offset:1536
	global_load_dwordx2 v[154:155], v[198:199], off offset:2048
	global_load_dwordx2 v[152:153], v[198:199], off offset:2560
	global_load_dwordx2 v[150:151], v[198:199], off offset:3072
	global_load_dwordx2 v[148:149], v[198:199], off offset:3584
	global_load_dwordx2 v[116:117], v[196:197], off
	global_load_dwordx2 v[120:121], v[196:197], off offset:512
	global_load_dwordx2 v[122:123], v[196:197], off offset:1024
	global_load_dwordx2 v[126:127], v[196:197], off offset:1536
	global_load_dwordx2 v[130:131], v[196:197], off offset:2048
	global_load_dwordx2 v[128:129], v[196:197], off offset:2560
	global_load_dwordx2 v[124:125], v[196:197], off offset:3072
	global_load_dwordx2 v[118:119], v[196:197], off offset:3584
	s_waitcnt vmcnt(47)
	v_mfma_f32_16x16x32_fp8_fp8 v[2:5], v[190:191], v[74:75], 0
	v_or_b32_e32 v0, s78, v203
	v_cmp_ge_i32_e32 vcc, v0, v105
	v_cmp_le_i32_e64 s[4:5], v0, v206
	s_waitcnt vmcnt(46)
	v_mfma_f32_16x16x32_fp8_fp8 v[2:5], v[194:195], v[76:77], v[2:5]
	s_and_b64 s[10:11], vcc, s[4:5]
	v_or_b32_e32 v11, 1, v0
	v_cmp_ge_i32_e32 vcc, v11, v105
	s_waitcnt vmcnt(45)
	v_mfma_f32_16x16x32_fp8_fp8 v[2:5], v[192:193], v[78:79], v[2:5]
	v_cmp_lt_i32_e64 s[4:5], v0, v206
	s_and_b64 s[6:7], s[4:5], vcc
	s_waitcnt vmcnt(43)
	v_mfma_f32_16x16x32_fp8_fp8 v[6:9], v[188:189], v[74:75], 0
	v_mfma_f32_16x16x32_fp8_fp8 v[2:5], v[186:187], v[80:81], v[2:5]
	s_waitcnt vmcnt(42)
	v_mfma_f32_16x16x32_fp8_fp8 v[6:9], v[184:185], v[76:77], v[6:9]
	s_waitcnt vmcnt(41)
	v_mfma_f32_16x16x32_fp8_fp8 v[6:9], v[182:183], v[78:79], v[6:9]
	s_nop 3
	v_max_f32_e32 v10, v2, v2
	v_max_f32_e32 v10, 0xf149f2ca, v10
	v_cndmask_b32_e64 v10, v205, v10, s[10:11]
	v_max_f32_e32 v11, v3, v3
	v_max_f32_e32 v11, v10, v11
	v_cndmask_b32_e64 v10, v10, v11, s[6:7]
	v_or_b32_e32 v11, 2, v0
	v_cmp_ge_i32_e32 vcc, v11, v105
	v_cmp_le_i32_e64 s[4:5], v11, v206
	v_max_f32_e32 v11, v4, v4
	v_max_f32_e32 v11, v10, v11
	s_and_b64 s[8:9], vcc, s[4:5]
	s_waitcnt vmcnt(40)
	v_mfma_f32_16x16x32_fp8_fp8 v[6:9], v[180:181], v[80:81], v[6:9]
	v_cndmask_b32_e64 v10, v10, v11, s[8:9]
	v_or_b32_e32 v11, 3, v0
	v_cmp_ge_i32_e32 vcc, v11, v105
	v_cmp_le_i32_e64 s[4:5], v11, v206
	v_max_f32_e32 v11, v5, v5
	v_max_f32_e32 v11, v10, v11
	s_and_b64 s[4:5], vcc, s[4:5]
	v_cndmask_b32_e64 v10, v10, v11, s[4:5]
	v_or_b32_e32 v11, 16, v0
	v_cmp_ge_i32_e32 vcc, v11, v105
	v_cmp_le_i32_e64 s[12:13], v11, v206
	v_max_f32_e32 v11, v6, v6
	v_max_f32_e32 v11, v10, v11
	s_and_b64 s[18:19], vcc, s[12:13]
	v_cndmask_b32_e64 v10, v10, v11, s[18:19]
	v_or_b32_e32 v11, 17, v0
	v_cmp_ge_i32_e32 vcc, v11, v105
	v_cmp_le_i32_e64 s[12:13], v11, v206
	v_max_f32_e32 v11, v10, v10
	v_max_f32_e32 v12, v7, v7
	v_max_f32_e32 v11, v11, v12
	s_and_b64 s[14:15], vcc, s[12:13]
	v_cndmask_b32_e64 v10, v10, v11, s[14:15]
	v_or_b32_e32 v11, 18, v0
	v_cmp_ge_i32_e32 vcc, v11, v105
	v_cmp_le_i32_e64 s[12:13], v11, v206
	v_max_f32_e32 v11, v10, v10
	v_max_f32_e32 v12, v8, v8
	v_max_f32_e32 v11, v11, v12
	s_and_b64 s[16:17], vcc, s[12:13]
	v_cndmask_b32_e64 v10, v10, v11, s[16:17]
	v_or_b32_e32 v0, 19, v0
	v_cmp_ge_i32_e32 vcc, v0, v105
	v_cmp_le_i32_e64 s[12:13], v0, v206
	v_max_f32_e32 v0, v10, v10
	v_max_f32_e32 v11, v9, v9
	v_max_f32_e32 v0, v0, v11
	s_and_b64 s[12:13], vcc, s[12:13]
	v_cndmask_b32_e64 v0, v10, v0, s[12:13]
	v_cmp_gt_f32_e32 vcc, v0, v211
	s_cbranch_vccz .LBB0_724
	v_and_b32_e32 v11, 64, v204
	v_xor_b32_e32 v10, 16, v204
	v_add_u32_e32 v11, 64, v11
	v_cmp_lt_i32_e32 vcc, v10, v11
	v_xor_b32_e32 v12, 32, v204
	s_nop 0
	v_cndmask_b32_e32 v10, v204, v10, vcc
	v_lshlrev_b32_e32 v10, 2, v10
	ds_bpermute_b32 v10, v10, v0
	v_max_f32_e32 v0, v0, v0
	v_cmp_lt_i32_e32 vcc, v12, v11
	s_waitcnt lgkmcnt(0)
	v_max_f32_e32 v10, v10, v10
	v_max_f32_e32 v0, v0, v10
	v_cndmask_b32_e32 v10, v204, v12, vcc
	v_lshlrev_b32_e32 v10, 2, v10
	ds_bpermute_b32 v10, v10, v0
	s_waitcnt lgkmcnt(0)
	v_max3_f32 v10, v209, v0, v10
	v_sub_f32_e32 v0, v209, v10
	v_exp_f32_e32 v0, v0
	v_mov_b32_e32 v209, v10
	v_mul_f32_e32 v210, v210, v0
	v_pk_mul_f32 v[36:37], v[36:37], v[0:1] op_sel_hi:[1,0]
	v_pk_mul_f32 v[34:35], v[34:35], v[0:1] op_sel_hi:[1,0]
	v_pk_mul_f32 v[40:41], v[40:41], v[0:1] op_sel_hi:[1,0]
	v_pk_mul_f32 v[38:39], v[38:39], v[0:1] op_sel_hi:[1,0]
	v_pk_mul_f32 v[44:45], v[44:45], v[0:1] op_sel_hi:[1,0]
	v_pk_mul_f32 v[42:43], v[42:43], v[0:1] op_sel_hi:[1,0]
	v_pk_mul_f32 v[48:49], v[48:49], v[0:1] op_sel_hi:[1,0]
	v_pk_mul_f32 v[46:47], v[46:47], v[0:1] op_sel_hi:[1,0]
	v_pk_mul_f32 v[52:53], v[52:53], v[0:1] op_sel_hi:[1,0]
	v_pk_mul_f32 v[50:51], v[50:51], v[0:1] op_sel_hi:[1,0]
	v_pk_mul_f32 v[56:57], v[56:57], v[0:1] op_sel_hi:[1,0]
	v_pk_mul_f32 v[54:55], v[54:55], v[0:1] op_sel_hi:[1,0]
	v_pk_mul_f32 v[60:61], v[60:61], v[0:1] op_sel_hi:[1,0]
	v_pk_mul_f32 v[58:59], v[58:59], v[0:1] op_sel_hi:[1,0]
	v_pk_mul_f32 v[64:65], v[64:65], v[0:1] op_sel_hi:[1,0]
	v_pk_mul_f32 v[62:63], v[62:63], v[0:1] op_sel_hi:[1,0]
; template <bool SLC, bool NOMASK> ...
;     ...
;     } else {
; #pragma unroll
;         for (int j = 0; j < 4; ++j) { pa[j] = vd[j] ? __builtin_amdgcn_exp2f(sc[j] - mref) : 0.f; pb[j] = vd[4 + j] ? __builtin_amdgcn_exp2f(sc[4 + j] - mref) : 0.f; ps += pa[j] + pb[j]; }
;     }
;     st.l += ps;
;     const u32x2 pw = pack8_fp8(pa, pb);
;     const i64_t pf = __builtin_bit_cast(i64_t, pw);
; #pragma unroll
;     for (int db = 0; db < 8; ++db) st.o[db] = __builtin_amdgcn_mfma_f32_16x16x32_fp8_fp8(cur.v[db], pf, st.o[db], 0, 0, 0);
.LBB0_724:
	v_add_f32_e32 v0, -4.0, v209
	v_sub_f32_e32 v2, v2, v0
	v_exp_f32_e32 v2, v2
	v_sub_f32_e32 v6, v6, v0
	v_exp_f32_e32 v6, v6
	v_sub_f32_e32 v4, v4, v0
	v_cndmask_b32_e64 v22, 0, v2, s[10:11]
	v_sub_f32_e32 v2, v3, v0
	v_exp_f32_e32 v2, v2
	v_sub_f32_e32 v3, v7, v0
	v_exp_f32_e32 v3, v3
	v_cndmask_b32_e64 v23, 0, v6, s[18:19]
	v_sub_f32_e32 v6, v8, v0
	v_cndmask_b32_e64 v24, 0, v2, s[6:7]
	v_sub_f32_e32 v2, v5, v0
	v_sub_f32_e32 v0, v9, v0
	v_exp_f32_e32 v4, v4
	v_exp_f32_e32 v6, v6
	v_cndmask_b32_e64 v25, 0, v3, s[14:15]
	v_exp_f32_e32 v2, v2
	v_exp_f32_e32 v0, v0
	v_mov_b32_e32 v26, v1
	v_mov_b32_e32 v27, v1
	v_cvt_pk_fp8_f32 v26, v22, v24
	v_cvt_pk_fp8_f32 v27, v23, v25
	v_cndmask_b32_e64 v28, 0, v4, s[8:9]
	v_cndmask_b32_e64 v29, 0, v6, s[16:17]
	v_cndmask_b32_e64 v66, 0, v2, s[4:5]
	v_cndmask_b32_e64 v0, 0, v0, s[12:13]
	v_cvt_pk_fp8_f32 v26, v28, v66 op_sel:[0,0,1]
	v_cvt_pk_fp8_f32 v27, v29, v0 op_sel:[0,0,1]
	v_add_f32_e32 v22, v22, v23
	v_add_f32_e32 v30, 0, v22
	v_add_f32_e32 v31, v24, v25
	v_add_f32_e32 v30, v31, v30
	v_add_f32_e32 v28, v28, v29
	v_add_f32_e32 v28, v28, v30
	v_add_f32_e32 v0, v66, v0
	s_waitcnt vmcnt(39)
	v_mfma_f32_16x16x32_fp8_fp8 v[2:5], v[164:165], v[26:27], v[34:37]
	v_add_f32_e32 v0, v0, v28
	v_add_f32_e32 v208, v210, v0
	v_mov_b32_e32 v207, v209
	s_waitcnt vmcnt(38)
	v_mfma_f32_16x16x32_fp8_fp8 v[6:9], v[166:167], v[26:27], v[38:41]
	s_waitcnt vmcnt(37)
	v_mfma_f32_16x16x32_fp8_fp8 v[10:13], v[168:169], v[26:27], v[42:45]
	s_waitcnt vmcnt(36)
	v_mfma_f32_16x16x32_fp8_fp8 v[14:17], v[170:171], v[26:27], v[46:49]
	s_waitcnt vmcnt(35)
	v_mfma_f32_16x16x32_fp8_fp8 v[18:21], v[178:179], v[26:27], v[50:53]
	s_waitcnt vmcnt(34)
	v_mfma_f32_16x16x32_fp8_fp8 v[22:25], v[176:177], v[26:27], v[54:57]
	s_waitcnt vmcnt(33)
	v_mfma_f32_16x16x32_fp8_fp8 v[30:33], v[174:175], v[26:27], v[58:61]
	s_waitcnt vmcnt(32)
	v_mfma_f32_16x16x32_fp8_fp8 v[26:29], v[172:173], v[26:27], v[62:65]

; __device__ __forceinline__ float bf2f(unsigned short b) { return __uint_as_float(((unsigned)b) << 16); }
; __device__ __forceinline__ void dilated_unit(int unit, const bf16_t* proj, const bf16_t* kbf, bf16_t* nsaout, int lane) {
;     ...
;     for (int pt = 0; pt < 3; ++pt) {
;         const int sh = 2 * pt, head = 4 * pt + hg;
;         const bf16_t* qrow = proj + (size_t)tc * PLD + PC_QB + head * 128 + 8 * kq;
;         i64_t q8[4];
; #pragma unroll
;         for (int s = 0; s < 4; ++s) { const bf16x8 qv = *(const bf16x8*)(qrow + 32 * s); f32x4 a, b;
; #pragma unroll
;             for (int j = 0; j < 4; ++j) { a[j] = bf2f((unsigned short)qv[j]) * SL2; b[j] = bf2f((unsigned short)qv[4 + j]) * SL2; }
;             q8[s] = __builtin_bit_cast(i64_t, pack8_fp8(a, b)); }
;         const int base = (r16 & ((1 << sh) - 1)) << (14 - sh), u0 = t0 >> sh, ui = u0 + (16 >> sh) * l16;
;         const int lo = base + (ui - 128 < 0 ? 0 : ui - 128), hi = base + ui;
;         const int first = (base + (u0 - 128 < 0 ? 0 : u0 - 128)) >> 5, last = (base + u0 + 15 * (16 >> sh)) >> 5;
;         unsigned long long hoff = (unsigned long long)head * S * 128; asm volatile("" : "+s"(hoff));
;         auto desc = [&](int i) { return 32 * (first + i); };
;         attn_run_frag8<false>(q8, kb8 + hoff, vb8 + hoff, desc, last - first + 1, lo, hi, 0, st, lane);
;     }
.LBB0_727:
	s_waitcnt vmcnt(16)
	s_nop 1
	v_mov_b64_e32 v[68:69], v[28:29]
	s_waitcnt vmcnt(0)
	v_mov_b64_e32 v[96:97], v[4:5]
	v_mov_b64_e32 v[92:93], v[8:9]
	v_mov_b64_e32 v[88:89], v[12:13]
	v_mov_b64_e32 v[84:85], v[16:17]
	v_mov_b64_e32 v[80:81], v[20:21]
	v_mov_b64_e32 v[76:77], v[24:25]
	v_mov_b64_e32 v[72:73], v[32:33]
	v_mov_b64_e32 v[66:67], v[26:27]
	v_mov_b64_e32 v[94:95], v[2:3]
	v_mov_b64_e32 v[90:91], v[6:7]
	v_mov_b64_e32 v[86:87], v[10:11]
	v_mov_b64_e32 v[82:83], v[14:15]
	v_mov_b64_e32 v[78:79], v[18:19]
	v_mov_b64_e32 v[74:75], v[22:23]
	v_mov_b64_e32 v[70:71], v[30:31]
	s_add_i32 s72, s72, 1
	s_cmp_lg_u32 s72, 3
	s_cbranch_scc0 .LBB0_692

; template <bool SLC, bool NOMASK> ...
;     const int kq = lane >> 4;
;     const int pos0 = SLC ? (dcur & 0xfffff) : dcur;
;     const int lo = SLC ? ((((dcur >> 20) == qi) | ((dcur >> 20) == 4)) ? 0 : (1 << 30)) : lo_in;
;     load_frag8(nxt, KF, VF, SLC ? (dnext & 0xfffff) : dnext, lane);
;     f32x4 sa[2] = {(f32x4){0.f, 0.f, 0.f, 0.f}, (f32x4){0.f, 0.f, 0.f, 0.f}};
; #pragma unroll
;     for (int T = 0; T < 2; ++T)
; #pragma unroll
;         for (int s2 = 0; s2 < 4; ++s2) sa[T] = __builtin_amdgcn_mfma_f32_16x16x32_fp8_fp8(cur.k[T][s2], qf[s2], sa[T], 0, 0, 0);
;     float sc[8]; bool vd[8]; float mx = -1e30f;
;     const bool act = lo == 0 || !SLC;
;     if (NOMASK) {
; #pragma unroll
;         for (int j = 0; j < 8; ++j) { sc[j] = sa[j >> 2][j & 3]; vd[j] = act; }
;         mx = fmaxf(fmaxf(fmaxf(sc[0], sc[1]), fmaxf(sc[2], sc[3])), fmaxf(fmaxf(sc[4], sc[5]), fmaxf(sc[6], sc[7])));
;         mx = act ? mx : -1e30f;
;     } else {
; #pragma unroll
;         for (int T = 0; T < 2; ++T)
; #pragma unroll
;             for (int r = 0; r < 4; ++r) { const int p = pos0 + 16 * T + 4 * kq + r; const bool v = (p >= lo) & (p <= hi); const float x = sa[T][r];
;                 sc[4 * T + r] = x; vd[4 * T + r] = v; mx = v ? fmaxf(mx, x) : mx; }
;     }
;     if (__builtin_amdgcn_ballot_w64(mx > st.m + 4.f) != 0ull) {
;         mx = fmaxf(mx, __shfl_xor(mx, 16)); mx = fmaxf(mx, __shfl_xor(mx, 32));
;         const float mn = fmaxf(st.m, mx), alpha = __builtin_amdgcn_exp2f(st.m - mn); st.m = mn; st.l *= alpha;
; #pragma unroll
;         for (int j = 0; j < 8; ++j) st.o[j] = st.o[j] * alpha;
;     }
;     f32x4 pa, pb; float ps = 0.f;
;     const float mref = st.m - 4.f;
;     if (NOMASK) {
; #pragma unroll
;         for (int j = 0; j < 4; ++j) { pa[j] = __builtin_amdgcn_exp2f(sc[j] - mref); pb[j] = __builtin_amdgcn_exp2f(sc[4 + j] - mref); }
;         if (SLC) {
; #pragma unroll
;             for (int j = 0; j < 4; ++j) { pa[j] = act ? pa[j] : 0.f; pb[j] = act ? pb[j] : 0.f; }
;         }
; #pragma unroll
;         for (int j = 0; j < 4; ++j) ps += pa[j] + pb[j];
;     } else {
; #pragma unroll
;         for (int j = 0; j < 4; ++j) { pa[j] = vd[j] ? __builtin_amdgcn_exp2f(sc[j] - mref) : 0.f; pb[j] = vd[4 + j] ? __builtin_amdgcn_exp2f(sc[4 + j] - mref) : 0.f; ps += pa[j] + pb[j]; }
;     }
;     st.l += ps;
;     const u32x2 pw = pack8_fp8(pa, pb);
.LBB0_745:
	global_load_dwordx2 v[190:191], v[198:199], off
	global_load_dwordx2 v[194:195], v[198:199], off offset:512
	global_load_dwordx2 v[192:193], v[198:199], off offset:1024
	global_load_dwordx2 v[186:187], v[198:199], off offset:1536
	global_load_dwordx2 v[188:189], v[198:199], off offset:2048
	global_load_dwordx2 v[184:185], v[198:199], off offset:2560
	global_load_dwordx2 v[182:183], v[198:199], off offset:3072
	global_load_dwordx2 v[180:181], v[198:199], off offset:3584
	global_load_dwordx2 v[164:165], v[196:197], off
	global_load_dwordx2 v[166:167], v[196:197], off offset:512
	global_load_dwordx2 v[168:169], v[196:197], off offset:1024
	global_load_dwordx2 v[170:171], v[196:197], off offset:1536
	global_load_dwordx2 v[178:179], v[196:197], off offset:2048
	global_load_dwordx2 v[176:177], v[196:197], off offset:2560
	global_load_dwordx2 v[174:175], v[196:197], off offset:3072
	global_load_dwordx2 v[172:173], v[196:197], off offset:3584
	s_waitcnt vmcnt(47)
	v_mfma_f32_16x16x32_fp8_fp8 v[2:5], v[142:143], v[74:75], 0
	v_mov_b64_e32 v[72:73], v[48:49]
	v_mov_b64_e32 v[68:69], v[52:53]
	v_mov_b64_e32 v[30:31], v[58:59]
	s_waitcnt vmcnt(43)
	v_mfma_f32_16x16x32_fp8_fp8 v[6:9], v[140:141], v[74:75], 0
	v_mov_b64_e32 v[26:27], v[62:63]
	v_mov_b64_e32 v[22:23], v[54:55]
	v_mov_b64_e32 v[18:19], v[42:43]
	v_mfma_f32_16x16x32_fp8_fp8 v[2:5], v[146:147], v[76:77], v[2:5]
	v_mov_b64_e32 v[14:15], v[38:39]
	v_mov_b32_e32 v205, v208
	v_mov_b64_e32 v[70:71], v[46:47]
	s_waitcnt vmcnt(42)
	v_mfma_f32_16x16x32_fp8_fp8 v[6:9], v[136:137], v[76:77], v[6:9]
	v_mov_b64_e32 v[66:67], v[50:51]
	v_mov_b64_e32 v[32:33], v[60:61]
	v_mov_b64_e32 v[28:29], v[64:65]
	v_mfma_f32_16x16x32_fp8_fp8 v[2:5], v[144:145], v[78:79], v[2:5]
	v_mov_b64_e32 v[24:25], v[56:57]
	v_mov_b64_e32 v[20:21], v[44:45]
	v_mov_b64_e32 v[16:17], v[40:41]
	s_waitcnt vmcnt(41)
	v_mfma_f32_16x16x32_fp8_fp8 v[6:9], v[134:135], v[78:79], v[6:9]
	v_mov_b32_e32 v206, v207
	v_mfma_f32_16x16x32_fp8_fp8 v[2:5], v[138:139], v[80:81], v[2:5]
	s_waitcnt vmcnt(40)
	v_mfma_f32_16x16x32_fp8_fp8 v[6:9], v[132:133], v[80:81], v[6:9]
	s_nop 5
	v_max_f32_e32 v0, v3, v3
	v_max_f32_e32 v10, v2, v2
	v_max_f32_e32 v0, v10, v0
	v_max_f32_e32 v10, v5, v5
	v_max_f32_e32 v11, v4, v4
	v_max_f32_e32 v10, v11, v10
	v_max_f32_e32 v11, v9, v9
	v_max_f32_e32 v12, v8, v8
	v_max_f32_e32 v11, v12, v11
	v_max3_f32 v11, v6, v7, v11
	v_max3_f32 v0, v0, v10, v11
	v_add_f32_e32 v10, 4.0, v208
	v_cmp_gt_f32_e32 vcc, v0, v10
	v_mov_b64_e32 v[10:11], v[34:35]
	v_mov_b64_e32 v[12:13], v[36:37]
	s_cbranch_vccz .LBB0_747
	v_and_b32_e32 v11, 64, v200
	v_xor_b32_e32 v10, 16, v200
	v_add_u32_e32 v11, 64, v11
	v_cmp_lt_i32_e32 vcc, v10, v11
	v_xor_b32_e32 v12, 32, v200
	s_nop 0
	v_cndmask_b32_e32 v10, v200, v10, vcc
	v_lshlrev_b32_e32 v10, 2, v10
	ds_bpermute_b32 v10, v10, v0
	v_max_f32_e32 v0, v0, v0
	v_cmp_lt_i32_e32 vcc, v12, v11
	s_waitcnt lgkmcnt(0)
	v_max_f32_e32 v10, v10, v10
	v_max_f32_e32 v0, v0, v10
	v_cndmask_b32_e32 v10, v200, v12, vcc
	v_lshlrev_b32_e32 v10, 2, v10
	ds_bpermute_b32 v10, v10, v0
	s_waitcnt lgkmcnt(0)
	v_max3_f32 v205, v208, v0, v10
	v_sub_f32_e32 v0, v208, v205
	v_exp_f32_e32 v0, v0
	s_nop 0
	v_mul_f32_e32 v206, v207, v0
	v_pk_mul_f32 v[12:13], v[36:37], v[0:1] op_sel_hi:[1,0]
	v_pk_mul_f32 v[10:11], v[34:35], v[0:1] op_sel_hi:[1,0]
	v_pk_mul_f32 v[16:17], v[40:41], v[0:1] op_sel_hi:[1,0]
	v_pk_mul_f32 v[14:15], v[38:39], v[0:1] op_sel_hi:[1,0]
	v_pk_mul_f32 v[20:21], v[44:45], v[0:1] op_sel_hi:[1,0]
	v_pk_mul_f32 v[18:19], v[42:43], v[0:1] op_sel_hi:[1,0]
	v_pk_mul_f32 v[24:25], v[56:57], v[0:1] op_sel_hi:[1,0]
	v_pk_mul_f32 v[22:23], v[54:55], v[0:1] op_sel_hi:[1,0]
	v_pk_mul_f32 v[28:29], v[64:65], v[0:1] op_sel_hi:[1,0]
	v_pk_mul_f32 v[26:27], v[62:63], v[0:1] op_sel_hi:[1,0]
	v_pk_mul_f32 v[32:33], v[60:61], v[0:1] op_sel_hi:[1,0]
	v_pk_mul_f32 v[30:31], v[58:59], v[0:1] op_sel_hi:[1,0]
	v_pk_mul_f32 v[68:69], v[52:53], v[0:1] op_sel_hi:[1,0]
	v_pk_mul_f32 v[66:67], v[50:51], v[0:1] op_sel_hi:[1,0]
	v_pk_mul_f32 v[72:73], v[48:49], v[0:1] op_sel_hi:[1,0]
	v_pk_mul_f32 v[70:71], v[46:47], v[0:1] op_sel_hi:[1,0]
.LBB0_747:
	v_add_f32_e32 v209, -4.0, v205
	v_sub_f32_e32 v0, v2, v209
	v_exp_f32_e32 v211, v0
	v_sub_f32_e32 v0, v6, v209
	v_exp_f32_e32 v213, v0
	v_sub_f32_e32 v0, v3, v209
	v_exp_f32_e32 v210, v0
	v_sub_f32_e32 v0, v7, v209
	v_exp_f32_e32 v0, v0
	v_sub_f32_e32 v2, v4, v209
	v_exp_f32_e32 v215, v2
	v_sub_f32_e32 v2, v8, v209
	v_exp_f32_e32 v218, v2
	v_sub_f32_e32 v2, v5, v209
	v_exp_f32_e32 v212, v2
	v_sub_f32_e32 v2, v9, v209
	v_mov_b32_e32 v216, v1
	v_mov_b32_e32 v217, v1
	v_exp_f32_e32 v214, v2
	v_cvt_pk_fp8_f32 v216, v211, v210
	v_cvt_pk_fp8_f32 v217, v213, v0
	v_add_f32_e32 v211, v211, v213
	v_add_f32_e32 v213, v215, v218
	v_cvt_pk_fp8_f32 v216, v215, v212 op_sel:[0,0,1]
	v_cvt_pk_fp8_f32 v217, v218, v214 op_sel:[0,0,1]
	s_waitcnt vmcnt(39)
	s_nop 0
	v_mfma_f32_16x16x32_fp8_fp8 v[2:5], v[86:87], v[216:217], v[10:13]
	s_waitcnt vmcnt(37)
	v_mfma_f32_16x16x32_fp8_fp8 v[10:13], v[90:91], v[216:217], v[18:21]
	s_waitcnt vmcnt(35)
	v_mfma_f32_16x16x32_fp8_fp8 v[18:21], v[114:115], v[216:217], v[26:29]
	s_nop 2
	v_add_f32_e64 v26, v210, v0
	v_add_f32_e64 v27, v211, v1
	v_mfma_f32_16x16x32_fp8_fp8 v[6:9], v[88:89], v[216:217], v[14:17]
	v_pk_add_f32 v[26:27], v[26:27], v[26:27] op_sel_hi:[0,1]
	v_mov_b32_e32 v215, v27
	v_pk_add_f32 v[26:27], v[212:213], v[214:215]
	v_mfma_f32_16x16x32_fp8_fp8 v[14:17], v[92:93], v[216:217], v[22:25]
	v_add_f32_e32 v0, v26, v27
	v_add_f32_e32 v206, v0, v206
	s_waitcnt vmcnt(34)
	v_mfma_f32_16x16x32_fp8_fp8 v[22:25], v[112:113], v[216:217], v[30:33]
	s_waitcnt vmcnt(33)
	v_mfma_f32_16x16x32_fp8_fp8 v[30:33], v[96:97], v[216:217], v[66:69]
	s_waitcnt vmcnt(32)
	v_mfma_f32_16x16x32_fp8_fp8 v[26:29], v[94:95], v[216:217], v[70:73]
	s_branch .LBB0_741
; template <bool SLC, bool NOMASK> ...
;     const int kq = lane >> 4;
;     const int pos0 = SLC ? (dcur & 0xfffff) : dcur;
;     const int lo = SLC ? ((((dcur >> 20) == qi) | ((dcur >> 20) == 4)) ? 0 : (1 << 30)) : lo_in;
;     load_frag8(nxt, KF, VF, SLC ? (dnext & 0xfffff) : dnext, lane);
;     f32x4 sa[2] = {(f32x4){0.f, 0.f, 0.f, 0.f}, (f32x4){0.f, 0.f, 0.f, 0.f}};
; #pragma unroll
;     for (int T = 0; T < 2; ++T)
; #pragma unroll
;         for (int s2 = 0; s2 < 4; ++s2) sa[T] = __builtin_amdgcn_mfma_f32_16x16x32_fp8_fp8(cur.k[T][s2], qf[s2], sa[T], 0, 0, 0);
;     float sc[8]; bool vd[8]; float mx = -1e30f;
;     const bool act = lo == 0 || !SLC;
;     if (NOMASK) {
; #pragma unroll
;         for (int j = 0; j < 8; ++j) { sc[j] = sa[j >> 2][j & 3]; vd[j] = act; }
;         mx = fmaxf(fmaxf(fmaxf(sc[0], sc[1]), fmaxf(sc[2], sc[3])), fmaxf(fmaxf(sc[4], sc[5]), fmaxf(sc[6], sc[7])));
;         mx = act ? mx : -1e30f;
;     } else {
; #pragma unroll
;         for (int T = 0; T < 2; ++T)
; #pragma unroll
;             for (int r = 0; r < 4; ++r) { const int p = pos0 + 16 * T + 4 * kq + r; const bool v = (p >= lo) & (p <= hi); const float x = sa[T][r];
;                 sc[4 * T + r] = x; vd[4 * T + r] = v; mx = v ? fmaxf(mx, x) : mx; }
;     }
;     if (__builtin_amdgcn_ballot_w64(mx > st.m + 4.f) != 0ull) {
.LBB0_748:
	global_load_dwordx2 v[190:191], v[198:199], off
	global_load_dwordx2 v[194:195], v[198:199], off offset:512
	global_load_dwordx2 v[192:193], v[198:199], off offset:1024
	global_load_dwordx2 v[186:187], v[198:199], off offset:1536
	global_load_dwordx2 v[188:189], v[198:199], off offset:2048
	global_load_dwordx2 v[184:185], v[198:199], off offset:2560
	global_load_dwordx2 v[182:183], v[198:199], off offset:3072
	global_load_dwordx2 v[180:181], v[198:199], off offset:3584
	global_load_dwordx2 v[164:165], v[196:197], off
	global_load_dwordx2 v[166:167], v[196:197], off offset:512
	global_load_dwordx2 v[168:169], v[196:197], off offset:1024
	global_load_dwordx2 v[170:171], v[196:197], off offset:1536
	global_load_dwordx2 v[178:179], v[196:197], off offset:2048
	global_load_dwordx2 v[176:177], v[196:197], off offset:2560
	global_load_dwordx2 v[174:175], v[196:197], off offset:3072
	global_load_dwordx2 v[172:173], v[196:197], off offset:3584
	s_waitcnt vmcnt(47)
	v_mfma_f32_16x16x32_fp8_fp8 v[2:5], v[142:143], v[74:75], 0
	v_or_b32_e32 v0, s62, v107
	v_cmp_ge_i32_e32 vcc, v0, v105
	v_cmp_le_i32_e64 s[4:5], v0, v204
	s_waitcnt vmcnt(46)
	v_mfma_f32_16x16x32_fp8_fp8 v[2:5], v[146:147], v[76:77], v[2:5]
	s_and_b64 s[10:11], vcc, s[4:5]
	v_or_b32_e32 v11, 1, v0
	v_cmp_ge_i32_e32 vcc, v11, v105
	s_waitcnt vmcnt(45)
	v_mfma_f32_16x16x32_fp8_fp8 v[2:5], v[144:145], v[78:79], v[2:5]
	v_cmp_lt_i32_e64 s[4:5], v0, v204
	s_and_b64 s[6:7], s[4:5], vcc
	s_waitcnt vmcnt(43)
	v_mfma_f32_16x16x32_fp8_fp8 v[6:9], v[140:141], v[74:75], 0
	v_mfma_f32_16x16x32_fp8_fp8 v[2:5], v[138:139], v[80:81], v[2:5]
	s_waitcnt vmcnt(42)
	v_mfma_f32_16x16x32_fp8_fp8 v[6:9], v[136:137], v[76:77], v[6:9]
	s_waitcnt vmcnt(41)
	v_mfma_f32_16x16x32_fp8_fp8 v[6:9], v[134:135], v[78:79], v[6:9]
	s_nop 3
	v_max_f32_e32 v10, v2, v2
	v_max_f32_e32 v10, 0xf149f2ca, v10
	v_cndmask_b32_e64 v10, v203, v10, s[10:11]
	v_max_f32_e32 v11, v3, v3
	v_max_f32_e32 v11, v10, v11
	v_cndmask_b32_e64 v10, v10, v11, s[6:7]
	v_or_b32_e32 v11, 2, v0
	v_cmp_ge_i32_e32 vcc, v11, v105
	v_cmp_le_i32_e64 s[4:5], v11, v204
	v_max_f32_e32 v11, v4, v4
	v_max_f32_e32 v11, v10, v11
	s_and_b64 s[8:9], vcc, s[4:5]
	s_waitcnt vmcnt(40)
	v_mfma_f32_16x16x32_fp8_fp8 v[6:9], v[132:133], v[80:81], v[6:9]
	v_cndmask_b32_e64 v10, v10, v11, s[8:9]
	v_or_b32_e32 v11, 3, v0
	v_cmp_ge_i32_e32 vcc, v11, v105
	v_cmp_le_i32_e64 s[4:5], v11, v204
	v_max_f32_e32 v11, v5, v5
	v_max_f32_e32 v11, v10, v11
	s_and_b64 s[4:5], vcc, s[4:5]
	v_cndmask_b32_e64 v10, v10, v11, s[4:5]
	v_or_b32_e32 v11, 16, v0
	v_cmp_ge_i32_e32 vcc, v11, v105
	v_cmp_le_i32_e64 s[12:13], v11, v204
	v_max_f32_e32 v11, v6, v6
	v_max_f32_e32 v11, v10, v11
	s_and_b64 s[18:19], vcc, s[12:13]
	v_cndmask_b32_e64 v10, v10, v11, s[18:19]
	v_or_b32_e32 v11, 17, v0
	v_cmp_ge_i32_e32 vcc, v11, v105
	v_cmp_le_i32_e64 s[12:13], v11, v204
	v_max_f32_e32 v11, v10, v10
	v_max_f32_e32 v12, v7, v7
	v_max_f32_e32 v11, v11, v12
	s_and_b64 s[14:15], vcc, s[12:13]
	v_cndmask_b32_e64 v10, v10, v11, s[14:15]
	v_or_b32_e32 v11, 18, v0
	v_cmp_ge_i32_e32 vcc, v11, v105
	v_cmp_le_i32_e64 s[12:13], v11, v204
	v_max_f32_e32 v11, v10, v10
	v_max_f32_e32 v12, v8, v8
	v_max_f32_e32 v11, v11, v12
	s_and_b64 s[16:17], vcc, s[12:13]
	v_cndmask_b32_e64 v10, v10, v11, s[16:17]
	v_or_b32_e32 v0, 19, v0
	v_cmp_ge_i32_e32 vcc, v0, v105
	v_cmp_le_i32_e64 s[12:13], v0, v204
	v_max_f32_e32 v0, v10, v10
	v_max_f32_e32 v11, v9, v9
	v_max_f32_e32 v0, v0, v11
	s_and_b64 s[12:13], vcc, s[12:13]
	v_cndmask_b32_e64 v0, v10, v0, s[12:13]
	v_add_f32_e32 v10, 4.0, v208
	v_cmp_gt_f32_e32 vcc, v0, v10
	s_cbranch_vccz .LBB0_750
	v_and_b32_e32 v11, 64, v200
	v_xor_b32_e32 v10, 16, v200
	v_add_u32_e32 v11, 64, v11
	v_cmp_lt_i32_e32 vcc, v10, v11
	v_xor_b32_e32 v12, 32, v200
	s_nop 0
	v_cndmask_b32_e32 v10, v200, v10, vcc
	v_lshlrev_b32_e32 v10, 2, v10
	ds_bpermute_b32 v10, v10, v0
	v_max_f32_e32 v0, v0, v0
	v_cmp_lt_i32_e32 vcc, v12, v11
	s_waitcnt lgkmcnt(0)
	v_max_f32_e32 v10, v10, v10
	v_max_f32_e32 v0, v0, v10
	v_cndmask_b32_e32 v10, v200, v12, vcc
	v_lshlrev_b32_e32 v10, 2, v10
	ds_bpermute_b32 v10, v10, v0
	s_waitcnt lgkmcnt(0)
	v_max3_f32 v10, v208, v0, v10
	v_sub_f32_e32 v0, v208, v10
	v_exp_f32_e32 v0, v0
	v_mov_b32_e32 v208, v10
	v_mul_f32_e32 v207, v207, v0
	v_pk_mul_f32 v[36:37], v[36:37], v[0:1] op_sel_hi:[1,0]
	v_pk_mul_f32 v[34:35], v[34:35], v[0:1] op_sel_hi:[1,0]
	v_pk_mul_f32 v[40:41], v[40:41], v[0:1] op_sel_hi:[1,0]
	v_pk_mul_f32 v[38:39], v[38:39], v[0:1] op_sel_hi:[1,0]
	v_pk_mul_f32 v[44:45], v[44:45], v[0:1] op_sel_hi:[1,0]
	v_pk_mul_f32 v[42:43], v[42:43], v[0:1] op_sel_hi:[1,0]
	v_pk_mul_f32 v[56:57], v[56:57], v[0:1] op_sel_hi:[1,0]
	v_pk_mul_f32 v[54:55], v[54:55], v[0:1] op_sel_hi:[1,0]
	v_pk_mul_f32 v[64:65], v[64:65], v[0:1] op_sel_hi:[1,0]
	v_pk_mul_f32 v[62:63], v[62:63], v[0:1] op_sel_hi:[1,0]
	v_pk_mul_f32 v[60:61], v[60:61], v[0:1] op_sel_hi:[1,0]
	v_pk_mul_f32 v[58:59], v[58:59], v[0:1] op_sel_hi:[1,0]
	v_pk_mul_f32 v[52:53], v[52:53], v[0:1] op_sel_hi:[1,0]
	v_pk_mul_f32 v[50:51], v[50:51], v[0:1] op_sel_hi:[1,0]
	v_pk_mul_f32 v[48:49], v[48:49], v[0:1] op_sel_hi:[1,0]
	v_pk_mul_f32 v[46:47], v[46:47], v[0:1] op_sel_hi:[1,0]
; template <bool SLC, bool NOMASK> ...
;     ...
;     } else {
; #pragma unroll
;         for (int j = 0; j < 4; ++j) { pa[j] = vd[j] ? __builtin_amdgcn_exp2f(sc[j] - mref) : 0.f; pb[j] = vd[4 + j] ? __builtin_amdgcn_exp2f(sc[4 + j] - mref) : 0.f; ps += pa[j] + pb[j]; }
;     }
;     st.l += ps;
;     const u32x2 pw = pack8_fp8(pa, pb);
;     const i64_t pf = __builtin_bit_cast(i64_t, pw);
; #pragma unroll
;     for (int db = 0; db < 8; ++db) st.o[db] = __builtin_amdgcn_mfma_f32_16x16x32_fp8_fp8(cur.v[db], pf, st.o[db], 0, 0, 0);
.LBB0_750:
	v_add_f32_e32 v0, -4.0, v208
	v_sub_f32_e32 v2, v2, v0
	v_exp_f32_e32 v2, v2
	v_sub_f32_e32 v6, v6, v0
	v_exp_f32_e32 v6, v6
	v_sub_f32_e32 v4, v4, v0
	v_cndmask_b32_e64 v22, 0, v2, s[10:11]
	v_sub_f32_e32 v2, v3, v0
	v_exp_f32_e32 v2, v2
	v_sub_f32_e32 v3, v7, v0
	v_exp_f32_e32 v3, v3
	v_cndmask_b32_e64 v23, 0, v6, s[18:19]
	v_sub_f32_e32 v6, v8, v0
	v_cndmask_b32_e64 v24, 0, v2, s[6:7]
	v_sub_f32_e32 v2, v5, v0
	v_sub_f32_e32 v0, v9, v0
	v_exp_f32_e32 v4, v4
	v_exp_f32_e32 v6, v6
	v_cndmask_b32_e64 v25, 0, v3, s[14:15]
	v_exp_f32_e32 v2, v2
	v_exp_f32_e32 v0, v0
	v_mov_b32_e32 v26, v1
	v_mov_b32_e32 v27, v1
	v_cvt_pk_fp8_f32 v26, v22, v24
	v_cvt_pk_fp8_f32 v27, v23, v25
	v_cndmask_b32_e64 v28, 0, v4, s[8:9]
	v_cndmask_b32_e64 v29, 0, v6, s[16:17]
	v_cndmask_b32_e64 v66, 0, v2, s[4:5]
	v_cndmask_b32_e64 v0, 0, v0, s[12:13]
	v_cvt_pk_fp8_f32 v26, v28, v66 op_sel:[0,0,1]
	v_cvt_pk_fp8_f32 v27, v29, v0 op_sel:[0,0,1]
	v_add_f32_e32 v22, v22, v23
	v_add_f32_e32 v30, 0, v22
	v_add_f32_e32 v31, v24, v25
	v_add_f32_e32 v30, v31, v30
	v_add_f32_e32 v28, v28, v29
	v_add_f32_e32 v28, v28, v30
	v_add_f32_e32 v0, v66, v0
	s_waitcnt vmcnt(39)
	v_mfma_f32_16x16x32_fp8_fp8 v[2:5], v[86:87], v[26:27], v[34:37]
	v_add_f32_e32 v0, v0, v28
	v_add_f32_e32 v206, v207, v0
	v_mov_b32_e32 v205, v208
	s_waitcnt vmcnt(38)
	v_mfma_f32_16x16x32_fp8_fp8 v[6:9], v[88:89], v[26:27], v[38:41]
	s_waitcnt vmcnt(37)
	v_mfma_f32_16x16x32_fp8_fp8 v[10:13], v[90:91], v[26:27], v[42:45]
	s_waitcnt vmcnt(36)
	v_mfma_f32_16x16x32_fp8_fp8 v[14:17], v[92:93], v[26:27], v[54:57]
	s_waitcnt vmcnt(35)
	v_mfma_f32_16x16x32_fp8_fp8 v[18:21], v[114:115], v[26:27], v[62:65]
	s_waitcnt vmcnt(34)
	v_mfma_f32_16x16x32_fp8_fp8 v[22:25], v[112:113], v[26:27], v[58:61]
	s_waitcnt vmcnt(33)
	v_mfma_f32_16x16x32_fp8_fp8 v[30:33], v[96:97], v[26:27], v[50:53]
	s_waitcnt vmcnt(32)
	v_mfma_f32_16x16x32_fp8_fp8 v[26:29], v[94:95], v[26:27], v[46:49]
	s_cmp_ge_i32 s66, s61
	s_mov_b64 s[4:5], -1
	s_cbranch_scc0 .LBB0_742

; template <bool SLC, bool NOMASK> ...
;     const int kq = lane >> 4;
;     const int pos0 = SLC ? (dcur & 0xfffff) : dcur;
;     const int lo = SLC ? ((((dcur >> 20) == qi) | ((dcur >> 20) == 4)) ? 0 : (1 << 30)) : lo_in;
;     load_frag8(nxt, KF, VF, SLC ? (dnext & 0xfffff) : dnext, lane);
;     f32x4 sa[2] = {(f32x4){0.f, 0.f, 0.f, 0.f}, (f32x4){0.f, 0.f, 0.f, 0.f}};
; #pragma unroll
;     for (int T = 0; T < 2; ++T)
; #pragma unroll
;         for (int s2 = 0; s2 < 4; ++s2) sa[T] = __builtin_amdgcn_mfma_f32_16x16x32_fp8_fp8(cur.k[T][s2], qf[s2], sa[T], 0, 0, 0);
;     float sc[8]; bool vd[8]; float mx = -1e30f;
;     const bool act = lo == 0 || !SLC;
;     if (NOMASK) {
; #pragma unroll
;         for (int j = 0; j < 8; ++j) { sc[j] = sa[j >> 2][j & 3]; vd[j] = act; }
;         mx = fmaxf(fmaxf(fmaxf(sc[0], sc[1]), fmaxf(sc[2], sc[3])), fmaxf(fmaxf(sc[4], sc[5]), fmaxf(sc[6], sc[7])));
;         mx = act ? mx : -1e30f;
;     } else {
; #pragma unroll
;         for (int T = 0; T < 2; ++T)
; #pragma unroll
;             for (int r = 0; r < 4; ++r) { const int p = pos0 + 16 * T + 4 * kq + r; const bool v = (p >= lo) & (p <= hi); const float x = sa[T][r];
;                 sc[4 * T + r] = x; vd[4 * T + r] = v; mx = v ? fmaxf(mx, x) : mx; }
;     }
;     if (__builtin_amdgcn_ballot_w64(mx > st.m + 4.f) != 0ull) {
;         mx = fmaxf(mx, __shfl_xor(mx, 16)); mx = fmaxf(mx, __shfl_xor(mx, 32));
;         const float mn = fmaxf(st.m, mx), alpha = __builtin_amdgcn_exp2f(st.m - mn); st.m = mn; st.l *= alpha;
; #pragma unroll
;         for (int j = 0; j < 8; ++j) st.o[j] = st.o[j] * alpha;
;     }
;     f32x4 pa, pb; float ps = 0.f;
;     const float mref = st.m - 4.f;
;     if (NOMASK) {
; #pragma unroll
;         for (int j = 0; j < 4; ++j) { pa[j] = __builtin_amdgcn_exp2f(sc[j] - mref); pb[j] = __builtin_amdgcn_exp2f(sc[4 + j] - mref); }
;         if (SLC) {
; #pragma unroll
;             for (int j = 0; j < 4; ++j) { pa[j] = act ? pa[j] : 0.f; pb[j] = act ? pb[j] : 0.f; }
;         }
; #pragma unroll
;         for (int j = 0; j < 4; ++j) ps += pa[j] + pb[j];
;     } else {
; #pragma unroll
;         for (int j = 0; j < 4; ++j) { pa[j] = vd[j] ? __builtin_amdgcn_exp2f(sc[j] - mref) : 0.f; pb[j] = vd[4 + j] ? __builtin_amdgcn_exp2f(sc[4 + j] - mref) : 0.f; ps += pa[j] + pb[j]; }
;     }
;     st.l += ps;
;     const u32x2 pw = pack8_fp8(pa, pb);
.LBB0_752:
	global_load_dwordx2 v[142:143], v[198:199], off
	global_load_dwordx2 v[146:147], v[198:199], off offset:512
	global_load_dwordx2 v[144:145], v[198:199], off offset:1024
	global_load_dwordx2 v[138:139], v[198:199], off offset:1536
	global_load_dwordx2 v[140:141], v[198:199], off offset:2048
	global_load_dwordx2 v[136:137], v[198:199], off offset:2560
	global_load_dwordx2 v[134:135], v[198:199], off offset:3072
	global_load_dwordx2 v[132:133], v[198:199], off offset:3584
	global_load_dwordx2 v[86:87], v[196:197], off
	global_load_dwordx2 v[88:89], v[196:197], off offset:512
	global_load_dwordx2 v[90:91], v[196:197], off offset:1024
	global_load_dwordx2 v[92:93], v[196:197], off offset:1536
	global_load_dwordx2 v[114:115], v[196:197], off offset:2048
	global_load_dwordx2 v[112:113], v[196:197], off offset:2560
	global_load_dwordx2 v[96:97], v[196:197], off offset:3072
	global_load_dwordx2 v[94:95], v[196:197], off offset:3584
	s_waitcnt vmcnt(47)
	v_mfma_f32_16x16x32_fp8_fp8 v[34:37], v[160:161], v[74:75], 0
	v_mov_b64_e32 v[72:73], v[28:29]
	v_mov_b64_e32 v[68:69], v[32:33]
	v_mov_b64_e32 v[64:65], v[24:25]
	s_waitcnt vmcnt(43)
	v_mfma_f32_16x16x32_fp8_fp8 v[38:41], v[154:155], v[74:75], 0
	v_mov_b64_e32 v[60:61], v[20:21]
	v_mov_b64_e32 v[56:57], v[16:17]
	v_mov_b64_e32 v[52:53], v[12:13]
	v_mfma_f32_16x16x32_fp8_fp8 v[34:37], v[162:163], v[76:77], v[34:37]
	v_mov_b64_e32 v[48:49], v[8:9]
	v_mov_b32_e32 v207, v205
	v_mov_b64_e32 v[70:71], v[26:27]
	s_waitcnt vmcnt(42)
	v_mfma_f32_16x16x32_fp8_fp8 v[38:41], v[152:153], v[76:77], v[38:41]
	v_mov_b64_e32 v[66:67], v[30:31]
	v_mov_b64_e32 v[62:63], v[22:23]
	v_mov_b64_e32 v[58:59], v[18:19]
	v_mfma_f32_16x16x32_fp8_fp8 v[34:37], v[158:159], v[78:79], v[34:37]
	v_mov_b64_e32 v[54:55], v[14:15]
	v_mov_b64_e32 v[50:51], v[10:11]
	v_mov_b64_e32 v[46:47], v[6:7]
	s_waitcnt vmcnt(41)
	v_mfma_f32_16x16x32_fp8_fp8 v[38:41], v[150:151], v[78:79], v[38:41]
	v_mov_b32_e32 v208, v206
	v_mfma_f32_16x16x32_fp8_fp8 v[34:37], v[156:157], v[80:81], v[34:37]
	s_waitcnt vmcnt(40)
	v_mfma_f32_16x16x32_fp8_fp8 v[38:41], v[148:149], v[80:81], v[38:41]
	s_nop 5
	v_max_f32_e32 v0, v35, v35
	v_max_f32_e32 v42, v34, v34
	v_max_f32_e32 v0, v42, v0
	v_max_f32_e32 v42, v37, v37
	v_max_f32_e32 v43, v36, v36
	v_max_f32_e32 v42, v43, v42
	v_max_f32_e32 v43, v41, v41
	v_max_f32_e32 v44, v40, v40
	v_max_f32_e32 v43, v44, v43
	v_max3_f32 v43, v38, v39, v43
	v_max3_f32 v0, v0, v42, v43
	v_add_f32_e32 v42, 4.0, v205
	v_cmp_gt_f32_e32 vcc, v0, v42
	v_mov_b64_e32 v[44:45], v[4:5]
	v_mov_b64_e32 v[42:43], v[2:3]
	s_cbranch_vccz .LBB0_754
	v_and_b32_e32 v43, 64, v200
	v_xor_b32_e32 v42, 16, v200
	v_add_u32_e32 v43, 64, v43
	v_cmp_lt_i32_e32 vcc, v42, v43
	v_xor_b32_e32 v44, 32, v200
	s_nop 0
	v_cndmask_b32_e32 v42, v200, v42, vcc
	v_lshlrev_b32_e32 v42, 2, v42
	ds_bpermute_b32 v42, v42, v0
	v_max_f32_e32 v0, v0, v0
	v_cmp_lt_i32_e32 vcc, v44, v43
	s_waitcnt lgkmcnt(0)
	v_max_f32_e32 v42, v42, v42
	v_max_f32_e32 v0, v0, v42
	v_cndmask_b32_e32 v42, v200, v44, vcc
	v_lshlrev_b32_e32 v42, 2, v42
	ds_bpermute_b32 v42, v42, v0
	s_waitcnt lgkmcnt(0)
	v_max3_f32 v207, v205, v0, v42
	v_sub_f32_e32 v0, v205, v207
	v_exp_f32_e32 v0, v0
	s_nop 0
	v_mul_f32_e32 v208, v206, v0
	v_pk_mul_f32 v[44:45], v[4:5], v[0:1] op_sel_hi:[1,0]
	v_pk_mul_f32 v[42:43], v[2:3], v[0:1] op_sel_hi:[1,0]
	v_pk_mul_f32 v[48:49], v[8:9], v[0:1] op_sel_hi:[1,0]
	v_pk_mul_f32 v[46:47], v[6:7], v[0:1] op_sel_hi:[1,0]
	v_pk_mul_f32 v[52:53], v[12:13], v[0:1] op_sel_hi:[1,0]
	v_pk_mul_f32 v[50:51], v[10:11], v[0:1] op_sel_hi:[1,0]
	v_pk_mul_f32 v[56:57], v[16:17], v[0:1] op_sel_hi:[1,0]
	v_pk_mul_f32 v[54:55], v[14:15], v[0:1] op_sel_hi:[1,0]
	v_pk_mul_f32 v[60:61], v[20:21], v[0:1] op_sel_hi:[1,0]
	v_pk_mul_f32 v[58:59], v[18:19], v[0:1] op_sel_hi:[1,0]
	v_pk_mul_f32 v[64:65], v[24:25], v[0:1] op_sel_hi:[1,0]
	v_pk_mul_f32 v[62:63], v[22:23], v[0:1] op_sel_hi:[1,0]
	v_pk_mul_f32 v[68:69], v[32:33], v[0:1] op_sel_hi:[1,0]
	v_pk_mul_f32 v[66:67], v[30:31], v[0:1] op_sel_hi:[1,0]
	v_pk_mul_f32 v[72:73], v[28:29], v[0:1] op_sel_hi:[1,0]
	v_pk_mul_f32 v[70:71], v[26:27], v[0:1] op_sel_hi:[1,0]
.LBB0_754:
	v_add_f32_e32 v209, -4.0, v207
	v_sub_f32_e32 v0, v34, v209
	v_exp_f32_e32 v211, v0
	v_sub_f32_e32 v0, v38, v209
	v_exp_f32_e32 v213, v0
	v_sub_f32_e32 v0, v35, v209
	v_exp_f32_e32 v210, v0
	v_sub_f32_e32 v0, v39, v209
	v_exp_f32_e32 v0, v0
	v_sub_f32_e32 v34, v36, v209
	v_exp_f32_e32 v215, v34
	v_sub_f32_e32 v34, v40, v209
	v_exp_f32_e32 v218, v34
	v_sub_f32_e32 v34, v37, v209
	v_exp_f32_e32 v212, v34
	v_sub_f32_e32 v34, v41, v209
	v_mov_b32_e32 v216, v1
	v_mov_b32_e32 v217, v1
	v_exp_f32_e32 v214, v34
	v_cvt_pk_fp8_f32 v216, v211, v210
	v_cvt_pk_fp8_f32 v217, v213, v0
	v_add_f32_e32 v211, v211, v213
	v_add_f32_e32 v213, v215, v218
	v_cvt_pk_fp8_f32 v216, v215, v212 op_sel:[0,0,1]
	v_cvt_pk_fp8_f32 v217, v218, v214 op_sel:[0,0,1]
	s_waitcnt vmcnt(39)
	s_nop 0
	v_mfma_f32_16x16x32_fp8_fp8 v[34:37], v[116:117], v[216:217], v[42:45]
	s_waitcnt vmcnt(37)
	v_mfma_f32_16x16x32_fp8_fp8 v[42:45], v[122:123], v[216:217], v[50:53]
	s_waitcnt vmcnt(35)
	v_mfma_f32_16x16x32_fp8_fp8 v[50:53], v[130:131], v[216:217], v[58:61]
	s_nop 2
	v_add_f32_e64 v58, v210, v0
	v_add_f32_e64 v59, v211, v1
	v_mfma_f32_16x16x32_fp8_fp8 v[38:41], v[120:121], v[216:217], v[46:49]
	v_pk_add_f32 v[58:59], v[58:59], v[58:59] op_sel_hi:[0,1]
	v_mov_b32_e32 v215, v59
	v_mfma_f32_16x16x32_fp8_fp8 v[46:49], v[126:127], v[216:217], v[54:57]
	s_waitcnt vmcnt(34)
	v_mfma_f32_16x16x32_fp8_fp8 v[54:57], v[128:129], v[216:217], v[62:65]
	s_nop 2
	v_add_f32_e64 v62, v212, v214
	v_add_f32_e64 v63, v213, v215
	s_waitcnt vmcnt(33)
	v_mfma_f32_16x16x32_fp8_fp8 v[58:61], v[124:125], v[216:217], v[66:69]
	v_add_f32_e32 v0, v62, v63
	v_add_f32_e32 v208, v0, v208
	s_waitcnt vmcnt(32)
	v_mfma_f32_16x16x32_fp8_fp8 v[62:65], v[118:119], v[216:217], v[70:73]
	s_branch .LBB0_744
; template <bool SLC, bool NOMASK> ...
;     const int kq = lane >> 4;
;     const int pos0 = SLC ? (dcur & 0xfffff) : dcur;
;     const int lo = SLC ? ((((dcur >> 20) == qi) | ((dcur >> 20) == 4)) ? 0 : (1 << 30)) : lo_in;
;     load_frag8(nxt, KF, VF, SLC ? (dnext & 0xfffff) : dnext, lane);
;     f32x4 sa[2] = {(f32x4){0.f, 0.f, 0.f, 0.f}, (f32x4){0.f, 0.f, 0.f, 0.f}};
; #pragma unroll
;     for (int T = 0; T < 2; ++T)
; #pragma unroll
;         for (int s2 = 0; s2 < 4; ++s2) sa[T] = __builtin_amdgcn_mfma_f32_16x16x32_fp8_fp8(cur.k[T][s2], qf[s2], sa[T], 0, 0, 0);
;     float sc[8]; bool vd[8]; float mx = -1e30f;
;     const bool act = lo == 0 || !SLC;
;     if (NOMASK) {
; #pragma unroll
;         for (int j = 0; j < 8; ++j) { sc[j] = sa[j >> 2][j & 3]; vd[j] = act; }
;         mx = fmaxf(fmaxf(fmaxf(sc[0], sc[1]), fmaxf(sc[2], sc[3])), fmaxf(fmaxf(sc[4], sc[5]), fmaxf(sc[6], sc[7])));
;         mx = act ? mx : -1e30f;
;     } else {
; #pragma unroll
;         for (int T = 0; T < 2; ++T)
; #pragma unroll
;             for (int r = 0; r < 4; ++r) { const int p = pos0 + 16 * T + 4 * kq + r; const bool v = (p >= lo) & (p <= hi); const float x = sa[T][r];
;                 sc[4 * T + r] = x; vd[4 * T + r] = v; mx = v ? fmaxf(mx, x) : mx; }
;     }
;     if (__builtin_amdgcn_ballot_w64(mx > st.m + 4.f) != 0ull) {
.LBB0_755:
	global_load_dwordx2 v[142:143], v[198:199], off
	global_load_dwordx2 v[146:147], v[198:199], off offset:512
	global_load_dwordx2 v[144:145], v[198:199], off offset:1024
	global_load_dwordx2 v[138:139], v[198:199], off offset:1536
	global_load_dwordx2 v[140:141], v[198:199], off offset:2048
	global_load_dwordx2 v[136:137], v[198:199], off offset:2560
	global_load_dwordx2 v[134:135], v[198:199], off offset:3072
	global_load_dwordx2 v[132:133], v[198:199], off offset:3584
	global_load_dwordx2 v[86:87], v[196:197], off
	global_load_dwordx2 v[88:89], v[196:197], off offset:512
	global_load_dwordx2 v[90:91], v[196:197], off offset:1024
	global_load_dwordx2 v[92:93], v[196:197], off offset:1536
	global_load_dwordx2 v[114:115], v[196:197], off offset:2048
	global_load_dwordx2 v[112:113], v[196:197], off offset:2560
	global_load_dwordx2 v[96:97], v[196:197], off offset:3072
	global_load_dwordx2 v[94:95], v[196:197], off offset:3584
	s_waitcnt vmcnt(47)
	v_mfma_f32_16x16x32_fp8_fp8 v[34:37], v[160:161], v[74:75], 0
	v_or_b32_e32 v0, s63, v107
	v_cmp_ge_i32_e32 vcc, v0, v105
	v_cmp_le_i32_e64 s[4:5], v0, v204
	s_waitcnt vmcnt(46)
	v_mfma_f32_16x16x32_fp8_fp8 v[34:37], v[162:163], v[76:77], v[34:37]
	s_and_b64 s[10:11], vcc, s[4:5]
	v_or_b32_e32 v43, 1, v0
	v_cmp_ge_i32_e32 vcc, v43, v105
	s_waitcnt vmcnt(45)
	v_mfma_f32_16x16x32_fp8_fp8 v[34:37], v[158:159], v[78:79], v[34:37]
	v_cmp_lt_i32_e64 s[4:5], v0, v204
	s_and_b64 s[6:7], s[4:5], vcc
	s_waitcnt vmcnt(43)
	v_mfma_f32_16x16x32_fp8_fp8 v[38:41], v[154:155], v[74:75], 0
	v_mfma_f32_16x16x32_fp8_fp8 v[34:37], v[156:157], v[80:81], v[34:37]
	s_waitcnt vmcnt(42)
	v_mfma_f32_16x16x32_fp8_fp8 v[38:41], v[152:153], v[76:77], v[38:41]
	s_waitcnt vmcnt(41)
	v_mfma_f32_16x16x32_fp8_fp8 v[38:41], v[150:151], v[78:79], v[38:41]
	s_nop 3
	v_max_f32_e32 v42, v34, v34
	v_max_f32_e32 v42, 0xf149f2ca, v42
	v_cndmask_b32_e64 v42, v203, v42, s[10:11]
	v_max_f32_e32 v43, v35, v35
	v_max_f32_e32 v43, v42, v43
	v_cndmask_b32_e64 v42, v42, v43, s[6:7]
	v_or_b32_e32 v43, 2, v0
	v_cmp_ge_i32_e32 vcc, v43, v105
	v_cmp_le_i32_e64 s[4:5], v43, v204
	v_max_f32_e32 v43, v36, v36
	v_max_f32_e32 v43, v42, v43
	s_and_b64 s[8:9], vcc, s[4:5]
	s_waitcnt vmcnt(40)
	v_mfma_f32_16x16x32_fp8_fp8 v[38:41], v[148:149], v[80:81], v[38:41]
	v_cndmask_b32_e64 v42, v42, v43, s[8:9]
	v_or_b32_e32 v43, 3, v0
	v_cmp_ge_i32_e32 vcc, v43, v105
	v_cmp_le_i32_e64 s[4:5], v43, v204
	v_max_f32_e32 v43, v37, v37
	v_max_f32_e32 v43, v42, v43
	s_and_b64 s[4:5], vcc, s[4:5]
	v_cndmask_b32_e64 v42, v42, v43, s[4:5]
	v_or_b32_e32 v43, 16, v0
	v_cmp_ge_i32_e32 vcc, v43, v105
	v_cmp_le_i32_e64 s[12:13], v43, v204
	v_max_f32_e32 v43, v38, v38
	v_max_f32_e32 v43, v42, v43
	s_and_b64 s[18:19], vcc, s[12:13]
	v_cndmask_b32_e64 v42, v42, v43, s[18:19]
	v_or_b32_e32 v43, 17, v0
	v_cmp_ge_i32_e32 vcc, v43, v105
	v_cmp_le_i32_e64 s[12:13], v43, v204
	v_max_f32_e32 v43, v42, v42
	v_max_f32_e32 v44, v39, v39
	v_max_f32_e32 v43, v43, v44
	s_and_b64 s[14:15], vcc, s[12:13]
	v_cndmask_b32_e64 v42, v42, v43, s[14:15]
	v_or_b32_e32 v43, 18, v0
	v_cmp_ge_i32_e32 vcc, v43, v105
	v_cmp_le_i32_e64 s[12:13], v43, v204
	v_max_f32_e32 v43, v42, v42
	v_max_f32_e32 v44, v40, v40
	v_max_f32_e32 v43, v43, v44
	s_and_b64 s[16:17], vcc, s[12:13]
	v_cndmask_b32_e64 v42, v42, v43, s[16:17]
	v_or_b32_e32 v0, 19, v0
	v_cmp_ge_i32_e32 vcc, v0, v105
	v_cmp_le_i32_e64 s[12:13], v0, v204
	v_max_f32_e32 v0, v42, v42
	v_max_f32_e32 v43, v41, v41
	v_max_f32_e32 v0, v0, v43
	s_and_b64 s[12:13], vcc, s[12:13]
	v_cndmask_b32_e64 v0, v42, v0, s[12:13]
	v_add_f32_e32 v42, 4.0, v205
	v_cmp_gt_f32_e32 vcc, v0, v42
	s_cbranch_vccz .LBB0_757
	v_and_b32_e32 v43, 64, v200
	v_xor_b32_e32 v42, 16, v200
	v_add_u32_e32 v43, 64, v43
	v_cmp_lt_i32_e32 vcc, v42, v43
	v_xor_b32_e32 v44, 32, v200
	s_nop 0
	v_cndmask_b32_e32 v42, v200, v42, vcc
	v_lshlrev_b32_e32 v42, 2, v42
	ds_bpermute_b32 v42, v42, v0
	v_max_f32_e32 v0, v0, v0
	v_cmp_lt_i32_e32 vcc, v44, v43
	s_waitcnt lgkmcnt(0)
	v_max_f32_e32 v42, v42, v42
	v_max_f32_e32 v0, v0, v42
	v_cndmask_b32_e32 v42, v200, v44, vcc
	v_lshlrev_b32_e32 v42, 2, v42
	ds_bpermute_b32 v42, v42, v0
	s_waitcnt lgkmcnt(0)
	v_max3_f32 v42, v205, v0, v42
	v_sub_f32_e32 v0, v205, v42
	v_exp_f32_e32 v0, v0
	v_mov_b32_e32 v205, v42
	v_mul_f32_e32 v206, v206, v0
	v_pk_mul_f32 v[4:5], v[4:5], v[0:1] op_sel_hi:[1,0]
	v_pk_mul_f32 v[2:3], v[2:3], v[0:1] op_sel_hi:[1,0]
	v_pk_mul_f32 v[8:9], v[8:9], v[0:1] op_sel_hi:[1,0]
	v_pk_mul_f32 v[6:7], v[6:7], v[0:1] op_sel_hi:[1,0]
	v_pk_mul_f32 v[12:13], v[12:13], v[0:1] op_sel_hi:[1,0]
	v_pk_mul_f32 v[10:11], v[10:11], v[0:1] op_sel_hi:[1,0]
	v_pk_mul_f32 v[16:17], v[16:17], v[0:1] op_sel_hi:[1,0]
	v_pk_mul_f32 v[14:15], v[14:15], v[0:1] op_sel_hi:[1,0]
	v_pk_mul_f32 v[20:21], v[20:21], v[0:1] op_sel_hi:[1,0]
	v_pk_mul_f32 v[18:19], v[18:19], v[0:1] op_sel_hi:[1,0]
	v_pk_mul_f32 v[24:25], v[24:25], v[0:1] op_sel_hi:[1,0]
	v_pk_mul_f32 v[22:23], v[22:23], v[0:1] op_sel_hi:[1,0]
	v_pk_mul_f32 v[32:33], v[32:33], v[0:1] op_sel_hi:[1,0]
	v_pk_mul_f32 v[30:31], v[30:31], v[0:1] op_sel_hi:[1,0]
	v_pk_mul_f32 v[28:29], v[28:29], v[0:1] op_sel_hi:[1,0]
	v_pk_mul_f32 v[26:27], v[26:27], v[0:1] op_sel_hi:[1,0]
; #define F8_STEP(CUR, NXT2, DC, DN2) do { \
;         if ((DC) & (1 << 30)) step_frag8<SLC, true>(qf, CUR, NXT2, KF, VF, (DC) & NM, (DN2) & NM, lo_in, hi, qi, st, lane); \
;         else step_frag8<SLC, false>(qf, CUR, NXT2, KF, VF, (DC), (DN2) & NM, lo_in, hi, qi, st, lane); } while (0)
; template <bool SLC, bool NOMASK> ...
;     ...
;     } else {
; #pragma unroll
;         for (int j = 0; j < 4; ++j) { pa[j] = vd[j] ? __builtin_amdgcn_exp2f(sc[j] - mref) : 0.f; pb[j] = vd[4 + j] ? __builtin_amdgcn_exp2f(sc[4 + j] - mref) : 0.f; ps += pa[j] + pb[j]; }
;     }
;     st.l += ps;
;     const u32x2 pw = pack8_fp8(pa, pb);
;     const i64_t pf = __builtin_bit_cast(i64_t, pw);
; #pragma unroll
;     for (int db = 0; db < 8; ++db) st.o[db] = __builtin_amdgcn_mfma_f32_16x16x32_fp8_fp8(cur.v[db], pf, st.o[db], 0, 0, 0);
; template <bool SLC, class Desc>
; __device__ __forceinline__ void attn_run_frag8(const i64_t (&qf)[4], const unsigned char* __restrict__ KF, const unsigned char* __restrict__ VF, const Desc& desc, int n,
;                                                int lo_in, int hi, int qi, AState& st, int lane) {
;     ...
;     for (int i = 0; i < n; i += 3) {
;         const int d2 = desc(i + 2 < n ? i + 2 : n - 1);
;         F8_STEP(fa, fc, d0, d2);
;         if (i + 1 >= n) break;
;         const int d3 = desc(i + 3 < n ? i + 3 : n - 1);
;         F8_STEP(fb, fa, d1, d3);
;         if (i + 2 >= n) break;
;         const int d4 = desc(i + 4 < n ? i + 4 : n - 1);
;         F8_STEP(fc, fb, d2, d4);
;         d0 = d3; d1 = d4;
.LBB0_757:
	v_add_f32_e32 v0, -4.0, v205
	v_sub_f32_e32 v34, v34, v0
	v_exp_f32_e32 v34, v34
	v_sub_f32_e32 v38, v38, v0
	v_exp_f32_e32 v38, v38
	v_sub_f32_e32 v36, v36, v0
	v_cndmask_b32_e64 v54, 0, v34, s[10:11]
	v_sub_f32_e32 v34, v35, v0
	v_exp_f32_e32 v34, v34
	v_sub_f32_e32 v35, v39, v0
	v_exp_f32_e32 v35, v35
	v_cndmask_b32_e64 v55, 0, v38, s[18:19]
	v_sub_f32_e32 v38, v40, v0
	v_cndmask_b32_e64 v56, 0, v34, s[6:7]
	v_sub_f32_e32 v34, v37, v0
	v_sub_f32_e32 v0, v41, v0
	v_exp_f32_e32 v36, v36
	v_exp_f32_e32 v38, v38
	v_cndmask_b32_e64 v57, 0, v35, s[14:15]
	v_exp_f32_e32 v34, v34
	v_exp_f32_e32 v0, v0
	v_mov_b32_e32 v62, v1
	v_mov_b32_e32 v63, v1
	v_cvt_pk_fp8_f32 v62, v54, v56
	v_cvt_pk_fp8_f32 v63, v55, v57
	v_cndmask_b32_e64 v58, 0, v36, s[8:9]
	v_cndmask_b32_e64 v59, 0, v38, s[16:17]
	v_cndmask_b32_e64 v64, 0, v34, s[4:5]
	v_cndmask_b32_e64 v0, 0, v0, s[12:13]
	v_cvt_pk_fp8_f32 v62, v58, v64 op_sel:[0,0,1]
	v_cvt_pk_fp8_f32 v63, v59, v0 op_sel:[0,0,1]
	v_add_f32_e32 v0, v64, v0
	v_mov_b32_e32 v207, v205
	s_waitcnt vmcnt(39)
	v_mfma_f32_16x16x32_fp8_fp8 v[34:37], v[116:117], v[62:63], v[2:5]
	s_nop 2
	v_add_f32_e32 v2, v54, v55
	v_add_f32_e32 v2, 0, v2
	v_add_f32_e32 v3, v56, v57
	s_waitcnt vmcnt(38)
	v_mfma_f32_16x16x32_fp8_fp8 v[38:41], v[120:121], v[62:63], v[6:9]
	v_add_f32_e32 v2, v3, v2
	v_add_f32_e32 v3, v58, v59
	v_add_f32_e32 v2, v3, v2
	s_waitcnt vmcnt(37)
	v_mfma_f32_16x16x32_fp8_fp8 v[42:45], v[122:123], v[62:63], v[10:13]
	v_add_f32_e32 v0, v0, v2
	v_add_f32_e32 v208, v206, v0
	s_waitcnt vmcnt(36)
	v_mfma_f32_16x16x32_fp8_fp8 v[46:49], v[126:127], v[62:63], v[14:17]
	s_waitcnt vmcnt(35)
	v_mfma_f32_16x16x32_fp8_fp8 v[50:53], v[130:131], v[62:63], v[18:21]
	s_waitcnt vmcnt(34)
	v_mfma_f32_16x16x32_fp8_fp8 v[54:57], v[128:129], v[62:63], v[22:25]
	s_waitcnt vmcnt(33)
	v_mfma_f32_16x16x32_fp8_fp8 v[58:61], v[124:125], v[62:63], v[30:33]
	s_waitcnt vmcnt(32)
	v_mfma_f32_16x16x32_fp8_fp8 v[62:65], v[118:119], v[62:63], v[26:29]
	s_cmp_gt_i32 s67, s61
	s_mov_b64 s[4:5], -1
	s_cbranch_scc1 .LBB0_737
.LBB0_758:
	s_add_i32 s66, s66, 4
	s_min_i32 s4, s66, s61
	s_add_i32 s6, s4, s60
	s_lshl_b32 s63, s6, 5
	s_and_b32 s4, s63, 0x3fffffe0
	s_lshr_b32 s24, s4, 4
	s_lshl_b64 s[4:5], s[24:25], 11
	s_and_b32 s24, s6, 0x1ffffff
	s_and_b32 s8, s42, 0x2000000
	s_lshl_b64 s[6:7], s[24:25], 12
	s_cmp_eq_u32 s8, 0
	v_lshl_add_u64 v[198:199], v[82:83], 0, s[4:5]
	v_lshl_add_u64 v[196:197], v[84:85], 0, s[6:7]
	s_mov_b64 s[4:5], -1
	v_add_f32_e32 v209, 4.0, v207
	s_cbranch_scc1 .LBB0_762
	global_load_dwordx2 v[160:161], v[198:199], off
	global_load_dwordx2 v[162:163], v[198:199], off offset:512
	global_load_dwordx2 v[158:159], v[198:199], off offset:1024
	global_load_dwordx2 v[156:157], v[198:199], off offset:1536
	global_load_dwordx2 v[154:155], v[198:199], off offset:2048
	global_load_dwordx2 v[152:153], v[198:199], off offset:2560
	global_load_dwordx2 v[150:151], v[198:199], off offset:3072
	global_load_dwordx2 v[148:149], v[198:199], off offset:3584
	global_load_dwordx2 v[116:117], v[196:197], off
	global_load_dwordx2 v[120:121], v[196:197], off offset:512
	global_load_dwordx2 v[122:123], v[196:197], off offset:1024
	global_load_dwordx2 v[126:127], v[196:197], off offset:1536
	global_load_dwordx2 v[130:131], v[196:197], off offset:2048
	global_load_dwordx2 v[128:129], v[196:197], off offset:2560
	global_load_dwordx2 v[124:125], v[196:197], off offset:3072
	global_load_dwordx2 v[118:119], v[196:197], off offset:3584
	s_waitcnt vmcnt(47)
	v_mfma_f32_16x16x32_fp8_fp8 v[2:5], v[190:191], v[74:75], 0
	v_mov_b64_e32 v[72:73], v[64:65]
	v_mov_b64_e32 v[68:69], v[60:61]
	v_mov_b64_e32 v[30:31], v[54:55]
	s_waitcnt vmcnt(43)
	v_mfma_f32_16x16x32_fp8_fp8 v[6:9], v[188:189], v[74:75], 0
	v_mov_b64_e32 v[26:27], v[50:51]
	v_mov_b64_e32 v[22:23], v[46:47]
	v_mov_b64_e32 v[18:19], v[42:43]
	v_mfma_f32_16x16x32_fp8_fp8 v[2:5], v[194:195], v[76:77], v[2:5]
	v_mov_b64_e32 v[14:15], v[38:39]
	v_mov_b32_e32 v205, v207
	v_mov_b64_e32 v[70:71], v[62:63]
	s_waitcnt vmcnt(42)
	v_mfma_f32_16x16x32_fp8_fp8 v[6:9], v[184:185], v[76:77], v[6:9]
	v_mov_b64_e32 v[66:67], v[58:59]
	v_mov_b64_e32 v[32:33], v[56:57]
	v_mov_b64_e32 v[28:29], v[52:53]
	v_mfma_f32_16x16x32_fp8_fp8 v[2:5], v[192:193], v[78:79], v[2:5]
	v_mov_b64_e32 v[24:25], v[48:49]
	v_mov_b64_e32 v[20:21], v[44:45]
	v_mov_b64_e32 v[16:17], v[40:41]
	s_waitcnt vmcnt(41)
	v_mfma_f32_16x16x32_fp8_fp8 v[6:9], v[182:183], v[78:79], v[6:9]
	v_mov_b32_e32 v206, v208
	v_mfma_f32_16x16x32_fp8_fp8 v[2:5], v[186:187], v[80:81], v[2:5]
	s_waitcnt vmcnt(40)
	v_mfma_f32_16x16x32_fp8_fp8 v[6:9], v[180:181], v[80:81], v[6:9]
	s_nop 5
	v_max_f32_e32 v0, v3, v3
	v_max_f32_e32 v10, v2, v2
	v_max_f32_e32 v0, v10, v0
	v_max_f32_e32 v10, v5, v5
	v_max_f32_e32 v11, v4, v4
	v_max_f32_e32 v10, v11, v10
	v_max_f32_e32 v11, v9, v9
	v_max_f32_e32 v12, v8, v8
	v_max_f32_e32 v11, v12, v11
	v_max3_f32 v11, v6, v7, v11
	v_max3_f32 v0, v0, v10, v11
	v_mov_b64_e32 v[10:11], v[34:35]
	v_cmp_gt_f32_e32 vcc, v0, v209
	v_mov_b64_e32 v[12:13], v[36:37]
	s_cbranch_vccz .LBB0_761
	v_and_b32_e32 v11, 64, v200
	v_xor_b32_e32 v10, 16, v200
	v_add_u32_e32 v11, 64, v11
	v_cmp_lt_i32_e32 vcc, v10, v11
	v_xor_b32_e32 v12, 32, v200
	s_nop 0
	v_cndmask_b32_e32 v10, v200, v10, vcc
	v_lshlrev_b32_e32 v10, 2, v10
	ds_bpermute_b32 v10, v10, v0
	v_max_f32_e32 v0, v0, v0
	v_cmp_lt_i32_e32 vcc, v12, v11
	s_waitcnt lgkmcnt(0)
	v_max_f32_e32 v10, v10, v10
	v_max_f32_e32 v0, v0, v10
	v_cndmask_b32_e32 v10, v200, v12, vcc
	v_lshlrev_b32_e32 v10, 2, v10
	ds_bpermute_b32 v10, v10, v0
	s_waitcnt lgkmcnt(0)
	v_max3_f32 v205, v207, v0, v10
	v_sub_f32_e32 v0, v207, v205
	v_exp_f32_e32 v0, v0
	s_nop 0
	v_mul_f32_e32 v206, v208, v0
	v_pk_mul_f32 v[12:13], v[36:37], v[0:1] op_sel_hi:[1,0]
	v_pk_mul_f32 v[10:11], v[34:35], v[0:1] op_sel_hi:[1,0]
	v_pk_mul_f32 v[16:17], v[40:41], v[0:1] op_sel_hi:[1,0]
	v_pk_mul_f32 v[14:15], v[38:39], v[0:1] op_sel_hi:[1,0]
	v_pk_mul_f32 v[20:21], v[44:45], v[0:1] op_sel_hi:[1,0]
	v_pk_mul_f32 v[18:19], v[42:43], v[0:1] op_sel_hi:[1,0]
	v_pk_mul_f32 v[24:25], v[48:49], v[0:1] op_sel_hi:[1,0]
	v_pk_mul_f32 v[22:23], v[46:47], v[0:1] op_sel_hi:[1,0]
	v_pk_mul_f32 v[28:29], v[52:53], v[0:1] op_sel_hi:[1,0]
	v_pk_mul_f32 v[26:27], v[50:51], v[0:1] op_sel_hi:[1,0]
	v_pk_mul_f32 v[32:33], v[56:57], v[0:1] op_sel_hi:[1,0]
	v_pk_mul_f32 v[30:31], v[54:55], v[0:1] op_sel_hi:[1,0]
	v_pk_mul_f32 v[68:69], v[60:61], v[0:1] op_sel_hi:[1,0]
	v_pk_mul_f32 v[66:67], v[58:59], v[0:1] op_sel_hi:[1,0]
	v_pk_mul_f32 v[72:73], v[64:65], v[0:1] op_sel_hi:[1,0]
	v_pk_mul_f32 v[70:71], v[62:63], v[0:1] op_sel_hi:[1,0]
; template <bool SLC, bool NOMASK> ...
;     const int kq = lane >> 4;
;     const int pos0 = SLC ? (dcur & 0xfffff) : dcur;
;     const int lo = SLC ? ((((dcur >> 20) == qi) | ((dcur >> 20) == 4)) ? 0 : (1 << 30)) : lo_in;
;     load_frag8(nxt, KF, VF, SLC ? (dnext & 0xfffff) : dnext, lane);
;     f32x4 sa[2] = {(f32x4){0.f, 0.f, 0.f, 0.f}, (f32x4){0.f, 0.f, 0.f, 0.f}};
; #pragma unroll
;     for (int T = 0; T < 2; ++T)
; #pragma unroll
;         for (int s2 = 0; s2 < 4; ++s2) sa[T] = __builtin_amdgcn_mfma_f32_16x16x32_fp8_fp8(cur.k[T][s2], qf[s2], sa[T], 0, 0, 0);
;     float sc[8]; bool vd[8]; float mx = -1e30f;
;     const bool act = lo == 0 || !SLC;
;     if (NOMASK) {
; #pragma unroll
;         for (int j = 0; j < 8; ++j) { sc[j] = sa[j >> 2][j & 3]; vd[j] = act; }
;         mx = fmaxf(fmaxf(fmaxf(sc[0], sc[1]), fmaxf(sc[2], sc[3])), fmaxf(fmaxf(sc[4], sc[5]), fmaxf(sc[6], sc[7])));
;         mx = act ? mx : -1e30f;
;     } else {
; #pragma unroll
;         for (int T = 0; T < 2; ++T)
; #pragma unroll
;             for (int r = 0; r < 4; ++r) { const int p = pos0 + 16 * T + 4 * kq + r; const bool v = (p >= lo) & (p <= hi); const float x = sa[T][r];
;                 sc[4 * T + r] = x; vd[4 * T + r] = v; mx = v ? fmaxf(mx, x) : mx; }
;     }
;     if (__builtin_amdgcn_ballot_w64(mx > st.m + 4.f) != 0ull) {
;     ...
;     } else {
; #pragma unroll
;         for (int j = 0; j < 4; ++j) { pa[j] = vd[j] ? __builtin_amdgcn_exp2f(sc[j] - mref) : 0.f; pb[j] = vd[4 + j] ? __builtin_amdgcn_exp2f(sc[4 + j] - mref) : 0.f; ps += pa[j] + pb[j]; }
;     }
;     st.l += ps;
;     const u32x2 pw = pack8_fp8(pa, pb);
;     const i64_t pf = __builtin_bit_cast(i64_t, pw);
; #pragma unroll
;     for (int db = 0; db < 8; ++db) st.o[db] = __builtin_amdgcn_mfma_f32_16x16x32_fp8_fp8(cur.v[db], pf, st.o[db], 0, 0, 0);
.LBB0_761:
	v_add_f32_e32 v211, -4.0, v205
	v_sub_f32_e32 v0, v2, v211
	v_exp_f32_e32 v213, v0
	v_sub_f32_e32 v0, v6, v211
	v_exp_f32_e32 v215, v0
	v_sub_f32_e32 v0, v3, v211
	v_exp_f32_e32 v210, v0
	v_sub_f32_e32 v0, v7, v211
	v_exp_f32_e32 v0, v0
	v_sub_f32_e32 v2, v4, v211
	v_exp_f32_e32 v218, v2
	v_sub_f32_e32 v2, v8, v211
	v_exp_f32_e32 v219, v2
	v_sub_f32_e32 v2, v5, v211
	v_exp_f32_e32 v212, v2
	v_sub_f32_e32 v2, v9, v211
	v_mov_b32_e32 v216, v1
	v_mov_b32_e32 v217, v1
	v_exp_f32_e32 v214, v2
	v_cvt_pk_fp8_f32 v216, v213, v210
	v_cvt_pk_fp8_f32 v217, v215, v0
	v_add_f32_e32 v211, v213, v215
	v_add_f32_e32 v213, v218, v219
	v_cvt_pk_fp8_f32 v216, v218, v212 op_sel:[0,0,1]
	v_cvt_pk_fp8_f32 v217, v219, v214 op_sel:[0,0,1]
	s_mov_b64 s[4:5], 0
	s_waitcnt vmcnt(39)
	v_mfma_f32_16x16x32_fp8_fp8 v[2:5], v[164:165], v[216:217], v[10:13]
	s_waitcnt vmcnt(37)
	v_mfma_f32_16x16x32_fp8_fp8 v[10:13], v[168:169], v[216:217], v[18:21]
	s_waitcnt vmcnt(35)
	v_mfma_f32_16x16x32_fp8_fp8 v[18:21], v[178:179], v[216:217], v[26:29]
	s_nop 2
	v_add_f32_e64 v26, v210, v0
	v_add_f32_e64 v27, v211, v1
	v_mfma_f32_16x16x32_fp8_fp8 v[6:9], v[166:167], v[216:217], v[14:17]
	v_pk_add_f32 v[26:27], v[26:27], v[26:27] op_sel_hi:[0,1]
	v_mov_b32_e32 v215, v27
	v_pk_add_f32 v[26:27], v[212:213], v[214:215]
	v_mfma_f32_16x16x32_fp8_fp8 v[14:17], v[170:171], v[216:217], v[22:25]
	v_add_f32_e32 v0, v26, v27
	v_add_f32_e32 v206, v0, v206
	s_waitcnt vmcnt(34)
	v_mfma_f32_16x16x32_fp8_fp8 v[22:25], v[176:177], v[216:217], v[30:33]
	s_waitcnt vmcnt(33)
	v_mfma_f32_16x16x32_fp8_fp8 v[30:33], v[174:175], v[216:217], v[66:69]
	s_waitcnt vmcnt(32)
	v_mfma_f32_16x16x32_fp8_fp8 v[26:29], v[172:173], v[216:217], v[70:73]
.LBB0_762:
	s_and_b64 vcc, exec, s[4:5]
	s_cbranch_vccz .LBB0_766
	global_load_dwordx2 v[160:161], v[198:199], off
	global_load_dwordx2 v[162:163], v[198:199], off offset:512
	global_load_dwordx2 v[158:159], v[198:199], off offset:1024
	global_load_dwordx2 v[156:157], v[198:199], off offset:1536
	global_load_dwordx2 v[154:155], v[198:199], off offset:2048
	global_load_dwordx2 v[152:153], v[198:199], off offset:2560
	global_load_dwordx2 v[150:151], v[198:199], off offset:3072
	global_load_dwordx2 v[148:149], v[198:199], off offset:3584
	global_load_dwordx2 v[116:117], v[196:197], off
	global_load_dwordx2 v[120:121], v[196:197], off offset:512
	global_load_dwordx2 v[122:123], v[196:197], off offset:1024
	global_load_dwordx2 v[126:127], v[196:197], off offset:1536
	global_load_dwordx2 v[130:131], v[196:197], off offset:2048
	global_load_dwordx2 v[128:129], v[196:197], off offset:2560
	global_load_dwordx2 v[124:125], v[196:197], off offset:3072
	global_load_dwordx2 v[118:119], v[196:197], off offset:3584
	s_waitcnt vmcnt(47)
	v_mfma_f32_16x16x32_fp8_fp8 v[2:5], v[190:191], v[74:75], 0
	v_or_b32_e32 v0, s68, v107
	v_cmp_ge_i32_e32 vcc, v0, v105
	v_cmp_le_i32_e64 s[4:5], v0, v204
	s_waitcnt vmcnt(46)
	v_mfma_f32_16x16x32_fp8_fp8 v[2:5], v[194:195], v[76:77], v[2:5]
	s_and_b64 s[10:11], vcc, s[4:5]
	v_or_b32_e32 v11, 1, v0
	v_cmp_ge_i32_e32 vcc, v11, v105
	s_waitcnt vmcnt(45)
	v_mfma_f32_16x16x32_fp8_fp8 v[2:5], v[192:193], v[78:79], v[2:5]
	v_cmp_lt_i32_e64 s[4:5], v0, v204
	s_and_b64 s[6:7], s[4:5], vcc
	s_waitcnt vmcnt(43)
	v_mfma_f32_16x16x32_fp8_fp8 v[6:9], v[188:189], v[74:75], 0
	v_mfma_f32_16x16x32_fp8_fp8 v[2:5], v[186:187], v[80:81], v[2:5]
	s_waitcnt vmcnt(42)
	v_mfma_f32_16x16x32_fp8_fp8 v[6:9], v[184:185], v[76:77], v[6:9]
	s_waitcnt vmcnt(41)
	v_mfma_f32_16x16x32_fp8_fp8 v[6:9], v[182:183], v[78:79], v[6:9]
	s_nop 3
	v_max_f32_e32 v10, v2, v2
	v_max_f32_e32 v10, 0xf149f2ca, v10
	v_cndmask_b32_e64 v10, v203, v10, s[10:11]
	v_max_f32_e32 v11, v3, v3
	v_max_f32_e32 v11, v10, v11
	v_cndmask_b32_e64 v10, v10, v11, s[6:7]
	v_or_b32_e32 v11, 2, v0
	v_cmp_ge_i32_e32 vcc, v11, v105
	v_cmp_le_i32_e64 s[4:5], v11, v204
	v_max_f32_e32 v11, v4, v4
	v_max_f32_e32 v11, v10, v11
	s_and_b64 s[8:9], vcc, s[4:5]
	s_waitcnt vmcnt(40)
	v_mfma_f32_16x16x32_fp8_fp8 v[6:9], v[180:181], v[80:81], v[6:9]
	v_cndmask_b32_e64 v10, v10, v11, s[8:9]
	v_or_b32_e32 v11, 3, v0
	v_cmp_ge_i32_e32 vcc, v11, v105
	v_cmp_le_i32_e64 s[4:5], v11, v204
	v_max_f32_e32 v11, v5, v5
	v_max_f32_e32 v11, v10, v11
	s_and_b64 s[4:5], vcc, s[4:5]
	v_cndmask_b32_e64 v10, v10, v11, s[4:5]
	v_or_b32_e32 v11, 16, v0
	v_cmp_ge_i32_e32 vcc, v11, v105
	v_cmp_le_i32_e64 s[12:13], v11, v204
	v_max_f32_e32 v11, v6, v6
	v_max_f32_e32 v11, v10, v11
	s_and_b64 s[18:19], vcc, s[12:13]
	v_cndmask_b32_e64 v10, v10, v11, s[18:19]
	v_or_b32_e32 v11, 17, v0
	v_cmp_ge_i32_e32 vcc, v11, v105
	v_cmp_le_i32_e64 s[12:13], v11, v204
	v_max_f32_e32 v11, v10, v10
	v_max_f32_e32 v12, v7, v7
	v_max_f32_e32 v11, v11, v12
	s_and_b64 s[14:15], vcc, s[12:13]
	v_cndmask_b32_e64 v10, v10, v11, s[14:15]
	v_or_b32_e32 v11, 18, v0
	v_cmp_ge_i32_e32 vcc, v11, v105
	v_cmp_le_i32_e64 s[12:13], v11, v204
	v_max_f32_e32 v11, v10, v10
	v_max_f32_e32 v12, v8, v8
	v_max_f32_e32 v11, v11, v12
	s_and_b64 s[16:17], vcc, s[12:13]
	v_cndmask_b32_e64 v10, v10, v11, s[16:17]
	v_or_b32_e32 v0, 19, v0
	v_cmp_ge_i32_e32 vcc, v0, v105
	v_cmp_le_i32_e64 s[12:13], v0, v204
	v_max_f32_e32 v0, v10, v10
	v_max_f32_e32 v11, v9, v9
	v_max_f32_e32 v0, v0, v11
	s_and_b64 s[12:13], vcc, s[12:13]
	v_cndmask_b32_e64 v0, v10, v0, s[12:13]
	v_cmp_gt_f32_e32 vcc, v0, v209
	s_cbranch_vccz .LBB0_765
	v_and_b32_e32 v11, 64, v200
	v_xor_b32_e32 v10, 16, v200
	v_add_u32_e32 v11, 64, v11
	v_cmp_lt_i32_e32 vcc, v10, v11
	v_xor_b32_e32 v12, 32, v200
	s_nop 0
	v_cndmask_b32_e32 v10, v200, v10, vcc
	v_lshlrev_b32_e32 v10, 2, v10
	ds_bpermute_b32 v10, v10, v0
	v_max_f32_e32 v0, v0, v0
	v_cmp_lt_i32_e32 vcc, v12, v11
	s_waitcnt lgkmcnt(0)
	v_max_f32_e32 v10, v10, v10
	v_max_f32_e32 v0, v0, v10
	v_cndmask_b32_e32 v10, v200, v12, vcc
	v_lshlrev_b32_e32 v10, 2, v10
	ds_bpermute_b32 v10, v10, v0
	s_waitcnt lgkmcnt(0)
	v_max3_f32 v10, v207, v0, v10
	v_sub_f32_e32 v0, v207, v10
	v_exp_f32_e32 v0, v0
	v_mov_b32_e32 v207, v10
	v_mul_f32_e32 v208, v208, v0
	v_pk_mul_f32 v[36:37], v[36:37], v[0:1] op_sel_hi:[1,0]
	v_pk_mul_f32 v[34:35], v[34:35], v[0:1] op_sel_hi:[1,0]
	v_pk_mul_f32 v[40:41], v[40:41], v[0:1] op_sel_hi:[1,0]
	v_pk_mul_f32 v[38:39], v[38:39], v[0:1] op_sel_hi:[1,0]
	v_pk_mul_f32 v[44:45], v[44:45], v[0:1] op_sel_hi:[1,0]
	v_pk_mul_f32 v[42:43], v[42:43], v[0:1] op_sel_hi:[1,0]
	v_pk_mul_f32 v[48:49], v[48:49], v[0:1] op_sel_hi:[1,0]
	v_pk_mul_f32 v[46:47], v[46:47], v[0:1] op_sel_hi:[1,0]
	v_pk_mul_f32 v[52:53], v[52:53], v[0:1] op_sel_hi:[1,0]
	v_pk_mul_f32 v[50:51], v[50:51], v[0:1] op_sel_hi:[1,0]
	v_pk_mul_f32 v[56:57], v[56:57], v[0:1] op_sel_hi:[1,0]
	v_pk_mul_f32 v[54:55], v[54:55], v[0:1] op_sel_hi:[1,0]
	v_pk_mul_f32 v[60:61], v[60:61], v[0:1] op_sel_hi:[1,0]
	v_pk_mul_f32 v[58:59], v[58:59], v[0:1] op_sel_hi:[1,0]
	v_pk_mul_f32 v[64:65], v[64:65], v[0:1] op_sel_hi:[1,0]
	v_pk_mul_f32 v[62:63], v[62:63], v[0:1] op_sel_hi:[1,0]
; template <bool SLC, bool NOMASK> ...
;     ...
;     } else {
; #pragma unroll
;         for (int j = 0; j < 4; ++j) { pa[j] = vd[j] ? __builtin_amdgcn_exp2f(sc[j] - mref) : 0.f; pb[j] = vd[4 + j] ? __builtin_amdgcn_exp2f(sc[4 + j] - mref) : 0.f; ps += pa[j] + pb[j]; }
;     }
;     st.l += ps;
;     const u32x2 pw = pack8_fp8(pa, pb);
;     const i64_t pf = __builtin_bit_cast(i64_t, pw);
; #pragma unroll
;     for (int db = 0; db < 8; ++db) st.o[db] = __builtin_amdgcn_mfma_f32_16x16x32_fp8_fp8(cur.v[db], pf, st.o[db], 0, 0, 0);
.LBB0_765:
	v_add_f32_e32 v0, -4.0, v207
	v_sub_f32_e32 v2, v2, v0
	v_exp_f32_e32 v2, v2
	v_sub_f32_e32 v6, v6, v0
	v_exp_f32_e32 v6, v6
	v_sub_f32_e32 v4, v4, v0
	v_cndmask_b32_e64 v22, 0, v2, s[10:11]
	v_sub_f32_e32 v2, v3, v0
	v_exp_f32_e32 v2, v2
	v_sub_f32_e32 v3, v7, v0
	v_exp_f32_e32 v3, v3
	v_cndmask_b32_e64 v23, 0, v6, s[18:19]
	v_sub_f32_e32 v6, v8, v0
	v_cndmask_b32_e64 v24, 0, v2, s[6:7]
	v_sub_f32_e32 v2, v5, v0
	v_sub_f32_e32 v0, v9, v0
	v_exp_f32_e32 v4, v4
	v_exp_f32_e32 v6, v6
	v_cndmask_b32_e64 v25, 0, v3, s[14:15]
	v_exp_f32_e32 v2, v2
	v_exp_f32_e32 v0, v0
	v_mov_b32_e32 v26, v1
	v_mov_b32_e32 v27, v1
	v_cvt_pk_fp8_f32 v26, v22, v24
	v_cvt_pk_fp8_f32 v27, v23, v25
	v_cndmask_b32_e64 v28, 0, v4, s[8:9]
	v_cndmask_b32_e64 v29, 0, v6, s[16:17]
	v_cndmask_b32_e64 v66, 0, v2, s[4:5]
	v_cndmask_b32_e64 v0, 0, v0, s[12:13]
	v_cvt_pk_fp8_f32 v26, v28, v66 op_sel:[0,0,1]
	v_cvt_pk_fp8_f32 v27, v29, v0 op_sel:[0,0,1]
	v_add_f32_e32 v22, v22, v23
	v_add_f32_e32 v30, 0, v22
	v_add_f32_e32 v31, v24, v25
	v_add_f32_e32 v30, v31, v30
	v_add_f32_e32 v28, v28, v29
	v_add_f32_e32 v28, v28, v30
	v_add_f32_e32 v0, v66, v0
	s_waitcnt vmcnt(39)
	v_mfma_f32_16x16x32_fp8_fp8 v[2:5], v[164:165], v[26:27], v[34:37]
	v_add_f32_e32 v0, v0, v28
	v_add_f32_e32 v206, v208, v0
	v_mov_b32_e32 v205, v207
	s_waitcnt vmcnt(38)
	v_mfma_f32_16x16x32_fp8_fp8 v[6:9], v[166:167], v[26:27], v[38:41]
	s_waitcnt vmcnt(37)
	v_mfma_f32_16x16x32_fp8_fp8 v[10:13], v[168:169], v[26:27], v[42:45]
	s_waitcnt vmcnt(36)
	v_mfma_f32_16x16x32_fp8_fp8 v[14:17], v[170:171], v[26:27], v[46:49]
	s_waitcnt vmcnt(35)
	v_mfma_f32_16x16x32_fp8_fp8 v[18:21], v[178:179], v[26:27], v[50:53]
	s_waitcnt vmcnt(34)
	v_mfma_f32_16x16x32_fp8_fp8 v[22:25], v[176:177], v[26:27], v[54:57]
	s_waitcnt vmcnt(33)
	v_mfma_f32_16x16x32_fp8_fp8 v[30:33], v[174:175], v[26:27], v[58:61]
	s_waitcnt vmcnt(32)
	v_mfma_f32_16x16x32_fp8_fp8 v[26:29], v[172:173], v[26:27], v[62:65]

; __device__ __forceinline__ float bf2f(unsigned short b) { return __uint_as_float(((unsigned)b) << 16); }
; __device__ __forceinline__ void dilated_unit(int unit, const bf16_t* proj, const bf16_t* kbf, bf16_t* nsaout, int lane) {
;     ...
;     for (int pt = 0; pt < 3; ++pt) {
;         const int sh = 2 * pt, head = 4 * pt + hg;
;         const bf16_t* qrow = proj + (size_t)tc * PLD + PC_QB + head * 128 + 8 * kq;
;         i64_t q8[4];
; #pragma unroll
;         for (int s = 0; s < 4; ++s) { const bf16x8 qv = *(const bf16x8*)(qrow + 32 * s); f32x4 a, b;
; #pragma unroll
;             for (int j = 0; j < 4; ++j) { a[j] = bf2f((unsigned short)qv[j]) * SL2; b[j] = bf2f((unsigned short)qv[4 + j]) * SL2; }
;             q8[s] = __builtin_bit_cast(i64_t, pack8_fp8(a, b)); }
;         const int base = (r16 & ((1 << sh) - 1)) << (14 - sh), u0 = t0 >> sh, ui = u0 + (16 >> sh) * l16;
;         const int lo = base + (ui - 128 < 0 ? 0 : ui - 128), hi = base + ui;
;         const int first = (base + (u0 - 128 < 0 ? 0 : u0 - 128)) >> 5, last = (base + u0 + 15 * (16 >> sh)) >> 5;
;         unsigned long long hoff = (unsigned long long)head * S * 128; asm volatile("" : "+s"(hoff));
;         auto desc = [&](int i) { return 32 * (first + i); };
;         attn_run_frag8<false>(q8, kb8 + hoff, vb8 + hoff, desc, last - first + 1, lo, hi, 0, st, lane);
;     }
.LBB0_768:
	s_waitcnt vmcnt(16)
	s_nop 1
	v_mov_b64_e32 v[68:69], v[28:29]
	s_waitcnt vmcnt(0)
	v_mov_b64_e32 v[96:97], v[4:5]
	v_mov_b64_e32 v[92:93], v[8:9]
	v_mov_b64_e32 v[88:89], v[12:13]
	v_mov_b64_e32 v[84:85], v[16:17]
	v_mov_b64_e32 v[80:81], v[20:21]
	v_mov_b64_e32 v[76:77], v[24:25]
	v_mov_b64_e32 v[72:73], v[32:33]
	v_mov_b64_e32 v[66:67], v[26:27]
	v_mov_b64_e32 v[94:95], v[2:3]
	v_mov_b64_e32 v[90:91], v[6:7]
	v_mov_b64_e32 v[86:87], v[10:11]
	v_mov_b64_e32 v[82:83], v[14:15]
	v_mov_b64_e32 v[78:79], v[18:19]
	v_mov_b64_e32 v[74:75], v[22:23]
	v_mov_b64_e32 v[70:71], v[30:31]
	s_add_i32 s59, s59, 1
	s_cmp_lg_u32 s59, 3
	s_cbranch_scc0 .LBB0_733

; __device__ __forceinline__ unsigned cvt_pk_bf16(float lo, float hi) { f32x2 v = {lo, hi}; bf16x2_t b = __builtin_convertvector(v, bf16x2_t); return __builtin_bit_cast(unsigned, b); }
; __device__ __forceinline__ float bf2f(unsigned short b) { return __uint_as_float(((unsigned)b) << 16); }
; __device__ __forceinline__ float bflo(unsigned w) { return __uint_as_float(w << 16); }
; __device__ __forceinline__ float bfhi(unsigned w) { return __uint_as_float(w & 0xffff0000u); }
; __device__ __forceinline__ float quad_total(float v) { v += __shfl_xor(v, 16); v += __shfl_xor(v, 32); return v; }
; __device__ __forceinline__ void nsa_unit(int unit, const bf16_t* proj, const bf16_t* kc, const bf16_t* vc, const bf16_t* gn, const float* cs, const float* sn, ...
;     ...
;     { const float g2 = bf2f(gn[(size_t)tc * 32 + head * 3 + 2]); const float lt = quad_total(st.l), inv = (lt > 0.f ? 1.f / lt : 0.f) * g2;
; #pragma unroll
;         for (int i = 0; i < 8; ++i) { const f32x4 o = st.o[i] * inv; u32x2 w = outl[64 * i]; w.x = cvt_pk_bf16(bflo(w.x) + o[0], bfhi(w.x) + o[1]); w.y = cvt_pk_bf16(bflo(w.y) + o[2], bfhi(w.y) + o[3]); outl[64 * i] = w; } }
;     bf16_t* op = nsaout + (size_t)tc * NOLD + head * 128 + 4 * kq;
; #pragma unroll
;     for (int db = 0; db < 8; ++db) *(u32x2*)(op + 16 * db) = outl[64 * db];
.LBB0_826:
	s_waitcnt vmcnt(16)
	global_load_ushort v0, v[76:77], off offset:4
	ds_bpermute_b32 v35, v227, v34
	ds_read2st64_b64 v[36:39], v228 offset0:27 offset1:28
	ds_read2st64_b64 v[40:43], v228 offset0:29 offset1:30
	ds_read2st64_b64 v[44:47], v228 offset0:31 offset1:32
	ds_read2st64_b64 v[48:51], v228 offset0:33 offset1:34
	s_add_i32 s72, s72, s34
	s_waitcnt lgkmcnt(3)
	v_lshlrev_b32_e32 v52, 16, v38
	v_and_b32_e32 v53, 0xffff0000, v38
	v_add_f32_e32 v64, v34, v35
	ds_bpermute_b32 v65, v226, v64
	v_lshlrev_b32_e32 v34, 16, v36
	v_and_b32_e32 v35, 0xffff0000, v36
	v_lshlrev_b32_e32 v36, 16, v37
	v_and_b32_e32 v37, 0xffff0000, v37
	s_waitcnt lgkmcnt(0)
	v_add_f32_e32 v64, v64, v65
	v_div_scale_f32 v65, s[10:11], v64, v64, 1.0
	v_rcp_f32_e32 v66, v65
	v_div_scale_f32 v67, vcc, 1.0, v64, 1.0
	v_lshlrev_b32_e32 v38, 16, v39
	v_fma_f32 v68, -v65, v66, 1.0
	v_fmac_f32_e32 v66, v68, v66
	v_mul_f32_e32 v68, v67, v66
	v_fma_f32 v69, -v65, v68, v67
	v_fmac_f32_e32 v68, v69, v66
	v_fma_f32 v65, -v65, v68, v67
	v_div_fmas_f32 v65, v65, v66, v68
	v_div_fixup_f32 v65, v65, v64, 1.0
	v_cmp_lt_f32_e32 vcc, 0, v64
	v_and_b32_e32 v39, 0xffff0000, v39
	v_lshlrev_b32_e32 v56, 16, v42
	v_cndmask_b32_e32 v64, 0, v65, vcc
	v_and_b32_e32 v57, 0xffff0000, v42
	v_lshlrev_b32_e32 v42, 16, v43
	v_and_b32_e32 v43, 0xffff0000, v43
	v_lshlrev_b32_e32 v62, 16, v48
	v_and_b32_e32 v63, 0xffff0000, v48
	v_lshlrev_b32_e32 v48, 16, v49
	v_and_b32_e32 v49, 0xffff0000, v49
	v_lshlrev_b32_e32 v54, 16, v40
	v_and_b32_e32 v55, 0xffff0000, v40
	v_lshlrev_b32_e32 v40, 16, v41
	v_and_b32_e32 v41, 0xffff0000, v41
	v_lshlrev_b32_e32 v58, 16, v44
	v_and_b32_e32 v59, 0xffff0000, v44
	v_lshlrev_b32_e32 v44, 16, v45
	v_and_b32_e32 v45, 0xffff0000, v45
	v_lshlrev_b32_e32 v60, 16, v46
	v_and_b32_e32 v61, 0xffff0000, v46
	v_lshlrev_b32_e32 v46, 16, v47
	v_and_b32_e32 v47, 0xffff0000, v47
	s_movk_i32 s10, 0xc00
	s_cmpk_lt_i32 s72, 0x2000
	s_waitcnt vmcnt(0)
	v_lshlrev_b32_e32 v0, 16, v0
	v_mul_f32_e32 v0, v64, v0
	v_pk_fma_f32 v[6:7], v[6:7], v[0:1], v[34:35] op_sel_hi:[1,0,1]
	v_pk_fma_f32 v[8:9], v[8:9], v[0:1], v[36:37] op_sel_hi:[1,0,1]
	v_pk_fma_f32 v[12:13], v[12:13], v[0:1], v[38:39] op_sel_hi:[1,0,1]
	v_pk_fma_f32 v[20:21], v[20:21], v[0:1], v[42:43] op_sel_hi:[1,0,1]
	v_cvt_pk_bf16_f32 v6, v6, v7
	v_cvt_pk_bf16_f32 v7, v8, v9
	v_cvt_pk_bf16_f32 v9, v12, v13
	v_cvt_pk_bf16_f32 v13, v20, v21
	v_lshlrev_b32_e32 v20, 16, v50
	v_and_b32_e32 v21, 0xffff0000, v50
	v_pk_fma_f32 v[2:3], v[2:3], v[0:1], v[20:21] op_sel_hi:[1,0,1]
	v_lshlrev_b32_e32 v20, 16, v51
	v_and_b32_e32 v21, 0xffff0000, v51
	v_pk_fma_f32 v[10:11], v[10:11], v[0:1], v[52:53] op_sel_hi:[1,0,1]
	v_pk_fma_f32 v[18:19], v[18:19], v[0:1], v[56:57] op_sel_hi:[1,0,1]
	v_pk_fma_f32 v[30:31], v[30:31], v[0:1], v[62:63] op_sel_hi:[1,0,1]
	v_pk_fma_f32 v[32:33], v[32:33], v[0:1], v[48:49] op_sel_hi:[1,0,1]
	v_pk_fma_f32 v[4:5], v[4:5], v[0:1], v[20:21] op_sel_hi:[1,0,1]
	v_pk_fma_f32 v[14:15], v[14:15], v[0:1], v[54:55] op_sel_hi:[1,0,1]
	v_pk_fma_f32 v[16:17], v[16:17], v[0:1], v[40:41] op_sel_hi:[1,0,1]
	v_pk_fma_f32 v[22:23], v[22:23], v[0:1], v[58:59] op_sel_hi:[1,0,1]
	v_pk_fma_f32 v[24:25], v[24:25], v[0:1], v[44:45] op_sel_hi:[1,0,1]
	v_pk_fma_f32 v[26:27], v[26:27], v[0:1], v[60:61] op_sel_hi:[1,0,1]
	v_pk_fma_f32 v[28:29], v[28:29], v[0:1], v[46:47] op_sel_hi:[1,0,1]
	v_cvt_pk_bf16_f32 v8, v10, v11
	v_cvt_pk_bf16_f32 v12, v18, v19
	v_cvt_pk_bf16_f32 v18, v30, v31
	v_cvt_pk_bf16_f32 v19, v32, v33
	v_cvt_pk_bf16_f32 v2, v2, v3
	v_cvt_pk_bf16_f32 v3, v4, v5
	v_mad_i64_i32 v[4:5], s[10:11], v132, s10, v[126:127]
	v_cvt_pk_bf16_f32 v10, v14, v15
	v_cvt_pk_bf16_f32 v11, v16, v17
	v_cvt_pk_bf16_f32 v14, v22, v23
	v_cvt_pk_bf16_f32 v15, v24, v25
	v_cvt_pk_bf16_f32 v16, v26, v27
	v_cvt_pk_bf16_f32 v17, v28, v29
	ds_write2st64_b64 v228, v[6:7], v[8:9] offset0:27 offset1:28
	ds_write2st64_b64 v228, v[10:11], v[12:13] offset0:29 offset1:30
	ds_write2st64_b64 v228, v[14:15], v[16:17] offset0:31 offset1:32
	ds_write2st64_b64 v228, v[18:19], v[2:3] offset0:33 offset1:34
	global_store_dwordx2 v[4:5], v[6:7], off
	global_store_dwordx2 v[4:5], v[8:9], off offset:32
	global_store_dwordx2 v[4:5], v[10:11], off offset:64
	global_store_dwordx2 v[4:5], v[12:13], off offset:96
	global_store_dwordx2 v[4:5], v[14:15], off offset:128
	global_store_dwordx2 v[4:5], v[16:17], off offset:160
	global_store_dwordx2 v[4:5], v[18:19], off offset:192
	global_store_dwordx2 v[4:5], v[2:3], off offset:224
	s_cbranch_scc0 .LBB0_922

; template <bool SLC, bool NOMASK> ...
;     const int kq = lane >> 4;
;     const int pos0 = SLC ? (dcur & 0xfffff) : dcur;
;     const int lo = SLC ? ((((dcur >> 20) == qi) | ((dcur >> 20) == 4)) ? 0 : (1 << 30)) : lo_in;
;     load_frag8(nxt, KF, VF, SLC ? (dnext & 0xfffff) : dnext, lane);
;     f32x4 sa[2] = {(f32x4){0.f, 0.f, 0.f, 0.f}, (f32x4){0.f, 0.f, 0.f, 0.f}};
; #pragma unroll
;     for (int T = 0; T < 2; ++T)
; #pragma unroll
;         for (int s2 = 0; s2 < 4; ++s2) sa[T] = __builtin_amdgcn_mfma_f32_16x16x32_fp8_fp8(cur.k[T][s2], qf[s2], sa[T], 0, 0, 0);
;     float sc[8]; bool vd[8]; float mx = -1e30f;
;     const bool act = lo == 0 || !SLC;
;     if (NOMASK) {
; #pragma unroll
;         for (int j = 0; j < 8; ++j) { sc[j] = sa[j >> 2][j & 3]; vd[j] = act; }
;         mx = fmaxf(fmaxf(fmaxf(sc[0], sc[1]), fmaxf(sc[2], sc[3])), fmaxf(fmaxf(sc[4], sc[5]), fmaxf(sc[6], sc[7])));
;         mx = act ? mx : -1e30f;
;     } else {
; #pragma unroll
;         for (int T = 0; T < 2; ++T)
; #pragma unroll
;             for (int r = 0; r < 4; ++r) { const int p = pos0 + 16 * T + 4 * kq + r; const bool v = (p >= lo) & (p <= hi); const float x = sa[T][r];
;                 sc[4 * T + r] = x; vd[4 * T + r] = v; mx = v ? fmaxf(mx, x) : mx; }
;     }
;     if (__builtin_amdgcn_ballot_w64(mx > st.m + 4.f) != 0ull) {
;         mx = fmaxf(mx, __shfl_xor(mx, 16)); mx = fmaxf(mx, __shfl_xor(mx, 32));
;         const float mn = fmaxf(st.m, mx), alpha = __builtin_amdgcn_exp2f(st.m - mn); st.m = mn; st.l *= alpha;
; #pragma unroll
;         for (int j = 0; j < 8; ++j) st.o[j] = st.o[j] * alpha;
;     }
;     f32x4 pa, pb; float ps = 0.f;
;     const float mref = st.m - 4.f;
;     if (NOMASK) {
; #pragma unroll
;         for (int j = 0; j < 4; ++j) { pa[j] = __builtin_amdgcn_exp2f(sc[j] - mref); pb[j] = __builtin_amdgcn_exp2f(sc[4 + j] - mref); }
;         if (SLC) {
; #pragma unroll
;             for (int j = 0; j < 4; ++j) { pa[j] = act ? pa[j] : 0.f; pb[j] = act ? pb[j] : 0.f; }
;         }
; #pragma unroll
;         for (int j = 0; j < 4; ++j) ps += pa[j] + pb[j];
;     } else {
; #pragma unroll
;         for (int j = 0; j < 4; ++j) { pa[j] = vd[j] ? __builtin_amdgcn_exp2f(sc[j] - mref) : 0.f; pb[j] = vd[4 + j] ? __builtin_amdgcn_exp2f(sc[4 + j] - mref) : 0.f; ps += pa[j] + pb[j]; }
;     }
;     st.l += ps;
;     const u32x2 pw = pack8_fp8(pa, pb);
.LBB0_867:
	s_and_b32 s13, s12, 0xfffffbff
	s_cmp_eq_u32 s13, 4
	s_cselect_b64 s[10:11], -1, 0
	s_lshl_b32 s14, s66, 7
	s_and_b32 s50, s14, 0x7fff800
	v_lshl_add_u64 v[10:11], v[86:87], 0, s[50:51]
	s_and_b32 s50, s14, 0x7fff000
	global_load_dwordx2 v[190:191], v[10:11], off
	global_load_dwordx2 v[196:197], v[10:11], off offset:512
	global_load_dwordx2 v[198:199], v[10:11], off offset:1024
	global_load_dwordx2 v[194:195], v[10:11], off offset:1536
	global_load_dwordx2 v[200:201], v[10:11], off offset:2048
	global_load_dwordx2 v[192:193], v[10:11], off offset:2560
	global_load_dwordx2 v[188:189], v[10:11], off offset:3072
	global_load_dwordx2 v[186:187], v[10:11], off offset:3584
	v_lshl_add_u64 v[10:11], v[88:89], 0, s[50:51]
	global_load_dwordx2 v[170:171], v[10:11], off
	global_load_dwordx2 v[172:173], v[10:11], off offset:512
	global_load_dwordx2 v[174:175], v[10:11], off offset:1024
	global_load_dwordx2 v[176:177], v[10:11], off offset:1536
	global_load_dwordx2 v[182:183], v[10:11], off offset:2048
	global_load_dwordx2 v[184:185], v[10:11], off offset:2560
	global_load_dwordx2 v[180:181], v[10:11], off offset:3072
	global_load_dwordx2 v[178:179], v[10:11], off offset:3584
	s_waitcnt vmcnt(47)
	v_mfma_f32_16x16x32_fp8_fp8 v[2:5], v[150:151], v[78:79], 0
	v_cmp_eq_u32_e32 vcc, s13, v209
	s_or_b64 s[10:11], s[10:11], vcc
	v_mov_b64_e32 v[74:75], v[38:39]
	s_waitcnt vmcnt(43)
	v_mfma_f32_16x16x32_fp8_fp8 v[6:9], v[144:145], v[78:79], 0
	v_mov_b64_e32 v[70:71], v[42:43]
	v_mov_b64_e32 v[30:31], v[44:45]
	v_mov_b64_e32 v[26:27], v[48:49]
	v_mfma_f32_16x16x32_fp8_fp8 v[2:5], v[152:153], v[80:81], v[2:5]
	v_mov_b64_e32 v[22:23], v[52:53]
	v_mov_b64_e32 v[18:19], v[56:57]
	v_mov_b64_e32 v[14:15], v[60:61]
	s_waitcnt vmcnt(42)
	v_mfma_f32_16x16x32_fp8_fp8 v[6:9], v[142:143], v[80:81], v[6:9]
	v_mov_b64_e32 v[72:73], v[36:37]
	v_mov_b64_e32 v[68:69], v[40:41]
	v_mov_b64_e32 v[32:33], v[46:47]
	v_mfma_f32_16x16x32_fp8_fp8 v[2:5], v[148:149], v[82:83], v[2:5]
	v_mov_b64_e32 v[28:29], v[50:51]
	v_mov_b64_e32 v[24:25], v[54:55]
	v_mov_b64_e32 v[20:21], v[58:59]
	s_waitcnt vmcnt(41)
	v_mfma_f32_16x16x32_fp8_fp8 v[6:9], v[140:141], v[82:83], v[6:9]
	v_mov_b64_e32 v[16:17], v[62:63]
	v_mov_b32_e32 v133, v203
	v_mfma_f32_16x16x32_fp8_fp8 v[2:5], v[146:147], v[84:85], v[2:5]
	s_waitcnt vmcnt(40)
	v_mfma_f32_16x16x32_fp8_fp8 v[6:9], v[138:139], v[84:85], v[6:9]
	s_nop 5
	v_max_f32_e32 v0, v3, v3
	v_max_f32_e32 v10, v2, v2
	v_max_f32_e32 v0, v10, v0
	v_max_f32_e32 v10, v5, v5
	v_max_f32_e32 v11, v4, v4
	v_max_f32_e32 v10, v11, v10
	v_max_f32_e32 v11, v9, v9
	v_max_f32_e32 v12, v8, v8
	v_max_f32_e32 v11, v12, v11
	v_max3_f32 v11, v6, v7, v11
	v_max3_f32 v0, v0, v10, v11
	v_cndmask_b32_e64 v34, v223, v0, s[10:11]
	v_mov_b64_e32 v[10:11], v[64:65]
	v_cmp_gt_f32_e32 vcc, v34, v204
	v_mov_b32_e32 v0, v202
	v_mov_b64_e32 v[12:13], v[66:67]
	s_cbranch_vccz .LBB0_869
	ds_bpermute_b32 v0, v227, v34
	v_max_f32_e32 v10, v34, v34
	s_waitcnt lgkmcnt(0)
	v_max_f32_e32 v0, v0, v0
	v_max_f32_e32 v0, v10, v0
	ds_bpermute_b32 v10, v226, v0
	s_waitcnt lgkmcnt(0)
	v_max3_f32 v0, v202, v0, v10
	v_sub_f32_e32 v10, v202, v0
	v_exp_f32_e32 v34, v10
	s_nop 0
	v_mul_f32_e32 v133, v203, v34
	v_pk_mul_f32 v[12:13], v[66:67], v[34:35] op_sel_hi:[1,0]
	v_pk_mul_f32 v[10:11], v[64:65], v[34:35] op_sel_hi:[1,0]
	v_pk_mul_f32 v[16:17], v[62:63], v[34:35] op_sel_hi:[1,0]
	v_pk_mul_f32 v[14:15], v[60:61], v[34:35] op_sel_hi:[1,0]
	v_pk_mul_f32 v[20:21], v[58:59], v[34:35] op_sel_hi:[1,0]
	v_pk_mul_f32 v[18:19], v[56:57], v[34:35] op_sel_hi:[1,0]
	v_pk_mul_f32 v[24:25], v[54:55], v[34:35] op_sel_hi:[1,0]
	v_pk_mul_f32 v[22:23], v[52:53], v[34:35] op_sel_hi:[1,0]
	v_pk_mul_f32 v[28:29], v[50:51], v[34:35] op_sel_hi:[1,0]
	v_pk_mul_f32 v[26:27], v[48:49], v[34:35] op_sel_hi:[1,0]
	v_pk_mul_f32 v[32:33], v[46:47], v[34:35] op_sel_hi:[1,0]
	v_pk_mul_f32 v[30:31], v[44:45], v[34:35] op_sel_hi:[1,0]
	v_pk_mul_f32 v[70:71], v[42:43], v[34:35] op_sel_hi:[1,0]
	v_pk_mul_f32 v[68:69], v[40:41], v[34:35] op_sel_hi:[1,0]
	v_pk_mul_f32 v[74:75], v[38:39], v[34:35] op_sel_hi:[1,0]
	v_pk_mul_f32 v[72:73], v[36:37], v[34:35] op_sel_hi:[1,0]
.LBB0_869:
	v_add_f32_e32 v34, -4.0, v0
	v_sub_f32_e32 v2, v2, v34
	v_sub_f32_e32 v6, v6, v34
	v_sub_f32_e32 v3, v3, v34
	v_sub_f32_e32 v7, v7, v34
	v_exp_f32_e32 v2, v2
	v_exp_f32_e32 v6, v6
	v_exp_f32_e32 v3, v3
	v_exp_f32_e32 v7, v7
	v_sub_f32_e32 v4, v4, v34
	v_sub_f32_e32 v8, v8, v34
	v_sub_f32_e32 v5, v5, v34
	v_sub_f32_e32 v9, v9, v34
	v_exp_f32_e32 v4, v4
	v_exp_f32_e32 v8, v8
	v_exp_f32_e32 v5, v5
	v_exp_f32_e32 v9, v9
	v_cndmask_b32_e64 v34, 0, v2, s[10:11]
	v_cndmask_b32_e64 v6, 0, v6, s[10:11]
	v_cndmask_b32_e64 v35, 0, v3, s[10:11]
	v_cndmask_b32_e64 v7, 0, v7, s[10:11]
	v_mov_b32_e32 v2, v1
	v_mov_b32_e32 v3, v1
	v_cvt_pk_fp8_f32 v2, v34, v35
	v_cvt_pk_fp8_f32 v3, v6, v7
	v_cndmask_b32_e64 v4, 0, v4, s[10:11]
	v_cndmask_b32_e64 v205, 0, v8, s[10:11]
	v_cndmask_b32_e64 v5, 0, v5, s[10:11]
	v_cndmask_b32_e64 v229, 0, v9, s[10:11]
	v_add_f32_e32 v6, v34, v6
	v_cvt_pk_fp8_f32 v2, v4, v5 op_sel:[0,0,1]
	v_cvt_pk_fp8_f32 v3, v205, v229 op_sel:[0,0,1]
	v_add_f32_e32 v6, 0, v6
	v_add_f32_e32 v7, v35, v7
	v_add_f32_e32 v6, v7, v6
	v_add_f32_e32 v4, v4, v205
	v_add_f32_e32 v4, v4, v6
	v_add_f32_e32 v5, v5, v229
	v_add_f32_e32 v4, v5, v4
	s_waitcnt vmcnt(39)
	v_mfma_f32_16x16x32_fp8_fp8 v[8:11], v[90:91], v[2:3], v[10:13]
	v_add_f32_e32 v133, v133, v4
	s_waitcnt vmcnt(38)
	v_mfma_f32_16x16x32_fp8_fp8 v[12:15], v[92:93], v[2:3], v[14:17]
	s_waitcnt vmcnt(37)
	v_mfma_f32_16x16x32_fp8_fp8 v[16:19], v[94:95], v[2:3], v[18:21]
	s_waitcnt vmcnt(36)
	v_mfma_f32_16x16x32_fp8_fp8 v[20:23], v[96:97], v[2:3], v[22:25]
	s_waitcnt vmcnt(35)
	v_mfma_f32_16x16x32_fp8_fp8 v[24:27], v[102:103], v[2:3], v[26:29]
	s_waitcnt vmcnt(34)
	v_mfma_f32_16x16x32_fp8_fp8 v[32:35], v[104:105], v[2:3], v[30:33]
	s_waitcnt vmcnt(33)
	v_mfma_f32_16x16x32_fp8_fp8 v[28:31], v[100:101], v[2:3], v[68:71]
	s_waitcnt vmcnt(32)
	v_mfma_f32_16x16x32_fp8_fp8 v[4:7], v[98:99], v[2:3], v[72:75]
	s_branch .LBB0_863
; template <bool SLC, bool NOMASK> ...
;     const int kq = lane >> 4;
;     const int pos0 = SLC ? (dcur & 0xfffff) : dcur;
;     const int lo = SLC ? ((((dcur >> 20) == qi) | ((dcur >> 20) == 4)) ? 0 : (1 << 30)) : lo_in;
;     load_frag8(nxt, KF, VF, SLC ? (dnext & 0xfffff) : dnext, lane);
;     f32x4 sa[2] = {(f32x4){0.f, 0.f, 0.f, 0.f}, (f32x4){0.f, 0.f, 0.f, 0.f}};
; #pragma unroll
;     for (int T = 0; T < 2; ++T)
; #pragma unroll
;         for (int s2 = 0; s2 < 4; ++s2) sa[T] = __builtin_amdgcn_mfma_f32_16x16x32_fp8_fp8(cur.k[T][s2], qf[s2], sa[T], 0, 0, 0);
;     float sc[8]; bool vd[8]; float mx = -1e30f;
;     const bool act = lo == 0 || !SLC;
;     if (NOMASK) {
; #pragma unroll
;         for (int j = 0; j < 8; ++j) { sc[j] = sa[j >> 2][j & 3]; vd[j] = act; }
;         mx = fmaxf(fmaxf(fmaxf(sc[0], sc[1]), fmaxf(sc[2], sc[3])), fmaxf(fmaxf(sc[4], sc[5]), fmaxf(sc[6], sc[7])));
;         mx = act ? mx : -1e30f;
;     } else {
; #pragma unroll
;         for (int T = 0; T < 2; ++T)
; #pragma unroll
;             for (int r = 0; r < 4; ++r) { const int p = pos0 + 16 * T + 4 * kq + r; const bool v = (p >= lo) & (p <= hi); const float x = sa[T][r];
;                 sc[4 * T + r] = x; vd[4 * T + r] = v; mx = v ? fmaxf(mx, x) : mx; }
;     }
;     if (__builtin_amdgcn_ballot_w64(mx > st.m + 4.f) != 0ull) {
;         mx = fmaxf(mx, __shfl_xor(mx, 16)); mx = fmaxf(mx, __shfl_xor(mx, 32));
;         const float mn = fmaxf(st.m, mx), alpha = __builtin_amdgcn_exp2f(st.m - mn); st.m = mn; st.l *= alpha;
; #pragma unroll
;         for (int j = 0; j < 8; ++j) st.o[j] = st.o[j] * alpha;
;     }
;     f32x4 pa, pb; float ps = 0.f;
;     const float mref = st.m - 4.f;
;     if (NOMASK) {
; #pragma unroll
;         for (int j = 0; j < 4; ++j) { pa[j] = __builtin_amdgcn_exp2f(sc[j] - mref); pb[j] = __builtin_amdgcn_exp2f(sc[4 + j] - mref); }
;         if (SLC) {
; #pragma unroll
;             for (int j = 0; j < 4; ++j) { pa[j] = act ? pa[j] : 0.f; pb[j] = act ? pb[j] : 0.f; }
;         }
; #pragma unroll
;         for (int j = 0; j < 4; ++j) ps += pa[j] + pb[j];
;     } else {
; #pragma unroll
;         for (int j = 0; j < 4; ++j) { pa[j] = vd[j] ? __builtin_amdgcn_exp2f(sc[j] - mref) : 0.f; pb[j] = vd[4 + j] ? __builtin_amdgcn_exp2f(sc[4 + j] - mref) : 0.f; ps += pa[j] + pb[j]; }
;     }
;     st.l += ps;
;     const u32x2 pw = pack8_fp8(pa, pb);
.LBB0_870:
	s_cmp_eq_u32 s12, 4
	s_cselect_b64 s[10:11], -1, 0
	s_lshl_b32 s13, s66, 7
	s_and_b32 s50, s13, 0x7fff800
	v_lshl_add_u64 v[10:11], v[86:87], 0, s[50:51]
	s_and_b32 s50, s13, 0x7fff000
	global_load_dwordx2 v[190:191], v[10:11], off
	global_load_dwordx2 v[196:197], v[10:11], off offset:512
	global_load_dwordx2 v[198:199], v[10:11], off offset:1024
	global_load_dwordx2 v[194:195], v[10:11], off offset:1536
	global_load_dwordx2 v[200:201], v[10:11], off offset:2048
	global_load_dwordx2 v[192:193], v[10:11], off offset:2560
	global_load_dwordx2 v[188:189], v[10:11], off offset:3072
	global_load_dwordx2 v[186:187], v[10:11], off offset:3584
	v_lshl_add_u64 v[10:11], v[88:89], 0, s[50:51]
	global_load_dwordx2 v[170:171], v[10:11], off
	global_load_dwordx2 v[172:173], v[10:11], off offset:512
	global_load_dwordx2 v[174:175], v[10:11], off offset:1024
	global_load_dwordx2 v[176:177], v[10:11], off offset:1536
	global_load_dwordx2 v[182:183], v[10:11], off offset:2048
	global_load_dwordx2 v[184:185], v[10:11], off offset:2560
	global_load_dwordx2 v[180:181], v[10:11], off offset:3072
	global_load_dwordx2 v[178:179], v[10:11], off offset:3584
	s_waitcnt vmcnt(47)
	v_mfma_f32_16x16x32_fp8_fp8 v[2:5], v[150:151], v[78:79], 0
	s_and_b32 s13, s59, 0xfffff
	v_cmp_eq_u32_e32 vcc, s12, v209
	v_add_u32_e32 v0, s13, v211
	s_waitcnt vmcnt(46)
	v_mfma_f32_16x16x32_fp8_fp8 v[2:5], v[152:153], v[80:81], v[2:5]
	s_or_b64 s[18:19], s[10:11], vcc
	v_cmp_le_i32_e32 vcc, v0, v132
	s_and_b64 s[16:17], s[18:19], vcc
	s_waitcnt vmcnt(45)
	v_mfma_f32_16x16x32_fp8_fp8 v[2:5], v[148:149], v[82:83], v[2:5]
	v_cmp_lt_i32_e32 vcc, v0, v132
	s_and_b64 s[12:13], s[18:19], vcc
	s_waitcnt vmcnt(43)
	v_mfma_f32_16x16x32_fp8_fp8 v[6:9], v[144:145], v[78:79], 0
	v_mfma_f32_16x16x32_fp8_fp8 v[2:5], v[146:147], v[84:85], v[2:5]
	s_waitcnt vmcnt(42)
	v_mfma_f32_16x16x32_fp8_fp8 v[6:9], v[142:143], v[80:81], v[6:9]
	s_waitcnt vmcnt(41)
	v_mfma_f32_16x16x32_fp8_fp8 v[6:9], v[140:141], v[82:83], v[6:9]
	s_nop 3
	v_max_f32_e32 v10, v2, v2
	v_max_f32_e32 v10, 0xf149f2ca, v10
	v_cndmask_b32_e64 v10, v223, v10, s[16:17]
	v_max_f32_e32 v11, v3, v3
	v_max_f32_e32 v11, v10, v11
	v_cndmask_b32_e64 v10, v10, v11, s[12:13]
	v_add_u32_e32 v11, 2, v0
	v_cmp_le_i32_e32 vcc, v11, v132
	v_max_f32_e32 v11, v4, v4
	v_max_f32_e32 v11, v10, v11
	s_and_b64 s[14:15], s[18:19], vcc
	s_waitcnt vmcnt(40)
	v_mfma_f32_16x16x32_fp8_fp8 v[6:9], v[138:139], v[84:85], v[6:9]
	v_cndmask_b32_e64 v10, v10, v11, s[14:15]
	v_add_u32_e32 v11, 3, v0
	v_cmp_le_i32_e32 vcc, v11, v132
	v_max_f32_e32 v11, v5, v5
	v_max_f32_e32 v11, v10, v11
	s_and_b64 s[10:11], s[18:19], vcc
	v_cndmask_b32_e64 v10, v10, v11, s[10:11]
	v_add_u32_e32 v11, 16, v0
	v_cmp_le_i32_e32 vcc, v11, v132
	v_max_f32_e32 v11, v6, v6
	v_max_f32_e32 v11, v10, v11
	s_and_b64 s[24:25], s[18:19], vcc
	v_cndmask_b32_e64 v10, v10, v11, s[24:25]
	v_add_u32_e32 v11, 17, v0
	v_cmp_le_i32_e32 vcc, v11, v132
	v_max_f32_e32 v11, v10, v10
	v_max_f32_e32 v12, v7, v7
	v_max_f32_e32 v11, v11, v12
	s_and_b64 s[20:21], s[18:19], vcc
	v_cndmask_b32_e64 v10, v10, v11, s[20:21]
	v_add_u32_e32 v11, 18, v0
	v_cmp_le_i32_e32 vcc, v11, v132
	v_max_f32_e32 v11, v10, v10
	v_max_f32_e32 v12, v8, v8
	v_max_f32_e32 v11, v11, v12
	s_and_b64 s[22:23], s[18:19], vcc
	v_cndmask_b32_e64 v10, v10, v11, s[22:23]
	v_add_u32_e32 v0, 19, v0
	v_cmp_le_i32_e32 vcc, v0, v132
	v_max_f32_e32 v0, v10, v10
	v_max_f32_e32 v11, v9, v9
	v_max_f32_e32 v0, v0, v11
	s_and_b64 s[18:19], s[18:19], vcc
	v_cndmask_b32_e64 v0, v10, v0, s[18:19]
	v_cmp_gt_f32_e32 vcc, v0, v204
	s_cbranch_vccz .LBB0_872
	ds_bpermute_b32 v10, v227, v0
	v_max_f32_e32 v0, v0, v0
	s_waitcnt lgkmcnt(0)
	v_max_f32_e32 v10, v10, v10
	v_max_f32_e32 v0, v0, v10
	ds_bpermute_b32 v10, v226, v0
	s_waitcnt lgkmcnt(0)
	v_max3_f32 v10, v202, v0, v10
	v_sub_f32_e32 v0, v202, v10
	v_exp_f32_e32 v0, v0
	v_mov_b32_e32 v202, v10
	v_mul_f32_e32 v203, v203, v0
	v_pk_mul_f32 v[66:67], v[66:67], v[0:1] op_sel_hi:[1,0]
	v_pk_mul_f32 v[64:65], v[64:65], v[0:1] op_sel_hi:[1,0]
	v_pk_mul_f32 v[62:63], v[62:63], v[0:1] op_sel_hi:[1,0]
	v_pk_mul_f32 v[60:61], v[60:61], v[0:1] op_sel_hi:[1,0]
	v_pk_mul_f32 v[58:59], v[58:59], v[0:1] op_sel_hi:[1,0]
	v_pk_mul_f32 v[56:57], v[56:57], v[0:1] op_sel_hi:[1,0]
	v_pk_mul_f32 v[54:55], v[54:55], v[0:1] op_sel_hi:[1,0]
	v_pk_mul_f32 v[52:53], v[52:53], v[0:1] op_sel_hi:[1,0]
	v_pk_mul_f32 v[50:51], v[50:51], v[0:1] op_sel_hi:[1,0]
	v_pk_mul_f32 v[48:49], v[48:49], v[0:1] op_sel_hi:[1,0]
	v_pk_mul_f32 v[46:47], v[46:47], v[0:1] op_sel_hi:[1,0]
	v_pk_mul_f32 v[44:45], v[44:45], v[0:1] op_sel_hi:[1,0]
	v_pk_mul_f32 v[42:43], v[42:43], v[0:1] op_sel_hi:[1,0]
	v_pk_mul_f32 v[40:41], v[40:41], v[0:1] op_sel_hi:[1,0]
	v_pk_mul_f32 v[38:39], v[38:39], v[0:1] op_sel_hi:[1,0]
	v_pk_mul_f32 v[36:37], v[36:37], v[0:1] op_sel_hi:[1,0]
.LBB0_872:
	v_add_f32_e32 v0, -4.0, v202
	v_sub_f32_e32 v2, v2, v0
	v_exp_f32_e32 v2, v2
	v_sub_f32_e32 v6, v6, v0
	v_exp_f32_e32 v6, v6
	v_sub_f32_e32 v4, v4, v0
	v_cndmask_b32_e64 v28, 0, v2, s[16:17]
	v_sub_f32_e32 v2, v3, v0
	v_exp_f32_e32 v2, v2
	v_sub_f32_e32 v3, v7, v0
	v_exp_f32_e32 v3, v3
	v_sub_f32_e32 v7, v8, v0
	v_cndmask_b32_e64 v29, 0, v2, s[12:13]
	v_sub_f32_e32 v2, v5, v0
	v_sub_f32_e32 v0, v9, v0
	v_cndmask_b32_e64 v6, 0, v6, s[24:25]
	v_exp_f32_e32 v4, v4
	v_exp_f32_e32 v7, v7
	v_cndmask_b32_e64 v30, 0, v3, s[20:21]
	v_exp_f32_e32 v5, v2
	v_exp_f32_e32 v0, v0
	v_mov_b32_e32 v2, v1
	v_mov_b32_e32 v3, v1
	v_cvt_pk_fp8_f32 v2, v28, v29
	v_cvt_pk_fp8_f32 v3, v6, v30
	v_cndmask_b32_e64 v4, 0, v4, s[14:15]
	v_cndmask_b32_e64 v7, 0, v7, s[22:23]
	v_cndmask_b32_e64 v5, 0, v5, s[10:11]
	v_cndmask_b32_e64 v0, 0, v0, s[18:19]
	v_cvt_pk_fp8_f32 v2, v4, v5 op_sel:[0,0,1]
	v_cvt_pk_fp8_f32 v3, v7, v0 op_sel:[0,0,1]
	v_add_f32_e32 v6, v28, v6
	v_add_f32_e32 v6, 0, v6
	v_add_f32_e32 v28, v29, v30
	v_add_f32_e32 v6, v28, v6
	v_add_f32_e32 v4, v4, v7
	v_add_f32_e32 v4, v4, v6
	v_add_f32_e32 v0, v5, v0
	s_waitcnt vmcnt(39)
	v_mfma_f32_16x16x32_fp8_fp8 v[8:11], v[90:91], v[2:3], v[64:67]
	v_add_f32_e32 v0, v0, v4
	v_add_f32_e32 v133, v203, v0
	v_mov_b32_e32 v0, v202
	s_waitcnt vmcnt(38)
	v_mfma_f32_16x16x32_fp8_fp8 v[12:15], v[92:93], v[2:3], v[60:63]
	s_waitcnt vmcnt(37)
	v_mfma_f32_16x16x32_fp8_fp8 v[16:19], v[94:95], v[2:3], v[56:59]
	s_waitcnt vmcnt(36)
	v_mfma_f32_16x16x32_fp8_fp8 v[20:23], v[96:97], v[2:3], v[52:55]
	s_waitcnt vmcnt(35)
	v_mfma_f32_16x16x32_fp8_fp8 v[24:27], v[102:103], v[2:3], v[48:51]
	s_waitcnt vmcnt(34)
	v_mfma_f32_16x16x32_fp8_fp8 v[32:35], v[104:105], v[2:3], v[44:47]
	s_waitcnt vmcnt(33)
	v_mfma_f32_16x16x32_fp8_fp8 v[28:31], v[100:101], v[2:3], v[40:43]
	s_waitcnt vmcnt(32)
	v_mfma_f32_16x16x32_fp8_fp8 v[4:7], v[98:99], v[2:3], v[36:39]
	s_add_i32 s10, s58, -3
	s_cmp_ge_u32 s10, s56
	s_mov_b64 s[10:11], -1
	s_cbranch_scc0 .LBB0_864

; template <bool SLC, bool NOMASK> ...
;     const int kq = lane >> 4;
;     const int pos0 = SLC ? (dcur & 0xfffff) : dcur;
;     const int lo = SLC ? ((((dcur >> 20) == qi) | ((dcur >> 20) == 4)) ? 0 : (1 << 30)) : lo_in;
;     load_frag8(nxt, KF, VF, SLC ? (dnext & 0xfffff) : dnext, lane);
;     f32x4 sa[2] = {(f32x4){0.f, 0.f, 0.f, 0.f}, (f32x4){0.f, 0.f, 0.f, 0.f}};
; #pragma unroll
;     for (int T = 0; T < 2; ++T)
; #pragma unroll
;         for (int s2 = 0; s2 < 4; ++s2) sa[T] = __builtin_amdgcn_mfma_f32_16x16x32_fp8_fp8(cur.k[T][s2], qf[s2], sa[T], 0, 0, 0);
;     float sc[8]; bool vd[8]; float mx = -1e30f;
;     const bool act = lo == 0 || !SLC;
;     if (NOMASK) {
; #pragma unroll
;         for (int j = 0; j < 8; ++j) { sc[j] = sa[j >> 2][j & 3]; vd[j] = act; }
;         mx = fmaxf(fmaxf(fmaxf(sc[0], sc[1]), fmaxf(sc[2], sc[3])), fmaxf(fmaxf(sc[4], sc[5]), fmaxf(sc[6], sc[7])));
;         mx = act ? mx : -1e30f;
;     } else {
; #pragma unroll
;         for (int T = 0; T < 2; ++T)
; #pragma unroll
;             for (int r = 0; r < 4; ++r) { const int p = pos0 + 16 * T + 4 * kq + r; const bool v = (p >= lo) & (p <= hi); const float x = sa[T][r];
;                 sc[4 * T + r] = x; vd[4 * T + r] = v; mx = v ? fmaxf(mx, x) : mx; }
;     }
;     if (__builtin_amdgcn_ballot_w64(mx > st.m + 4.f) != 0ull) {
;         mx = fmaxf(mx, __shfl_xor(mx, 16)); mx = fmaxf(mx, __shfl_xor(mx, 32));
;         const float mn = fmaxf(st.m, mx), alpha = __builtin_amdgcn_exp2f(st.m - mn); st.m = mn; st.l *= alpha;
; #pragma unroll
;         for (int j = 0; j < 8; ++j) st.o[j] = st.o[j] * alpha;
;     }
;     f32x4 pa, pb; float ps = 0.f;
;     const float mref = st.m - 4.f;
;     if (NOMASK) {
; #pragma unroll
;         for (int j = 0; j < 4; ++j) { pa[j] = __builtin_amdgcn_exp2f(sc[j] - mref); pb[j] = __builtin_amdgcn_exp2f(sc[4 + j] - mref); }
;         if (SLC) {
; #pragma unroll
;             for (int j = 0; j < 4; ++j) { pa[j] = act ? pa[j] : 0.f; pb[j] = act ? pb[j] : 0.f; }
;         }
; #pragma unroll
;         for (int j = 0; j < 4; ++j) ps += pa[j] + pb[j];
;     } else {
; #pragma unroll
;         for (int j = 0; j < 4; ++j) { pa[j] = vd[j] ? __builtin_amdgcn_exp2f(sc[j] - mref) : 0.f; pb[j] = vd[4 + j] ? __builtin_amdgcn_exp2f(sc[4 + j] - mref) : 0.f; ps += pa[j] + pb[j]; }
;     }
;     st.l += ps;
;     const u32x2 pw = pack8_fp8(pa, pb);
.LBB0_874:
	s_and_b32 s13, s12, 0xfffffbff
	s_cmp_eq_u32 s13, 4
	s_cselect_b64 s[10:11], -1, 0
	s_lshl_b32 s14, s59, 7
	s_and_b32 s50, s14, 0x7fff800
	v_lshl_add_u64 v[44:45], v[86:87], 0, s[50:51]
	s_and_b32 s50, s14, 0x7fff000
	global_load_dwordx2 v[150:151], v[44:45], off
	global_load_dwordx2 v[152:153], v[44:45], off offset:512
	global_load_dwordx2 v[148:149], v[44:45], off offset:1024
	global_load_dwordx2 v[146:147], v[44:45], off offset:1536
	global_load_dwordx2 v[144:145], v[44:45], off offset:2048
	global_load_dwordx2 v[142:143], v[44:45], off offset:2560
	global_load_dwordx2 v[140:141], v[44:45], off offset:3072
	global_load_dwordx2 v[138:139], v[44:45], off offset:3584
	v_lshl_add_u64 v[44:45], v[88:89], 0, s[50:51]
	global_load_dwordx2 v[90:91], v[44:45], off
	global_load_dwordx2 v[92:93], v[44:45], off offset:512
	global_load_dwordx2 v[94:95], v[44:45], off offset:1024
	global_load_dwordx2 v[96:97], v[44:45], off offset:1536
	global_load_dwordx2 v[102:103], v[44:45], off offset:2048
	global_load_dwordx2 v[104:105], v[44:45], off offset:2560
	global_load_dwordx2 v[100:101], v[44:45], off offset:3072
	global_load_dwordx2 v[98:99], v[44:45], off offset:3584
	s_waitcnt vmcnt(47)
	v_mfma_f32_16x16x32_fp8_fp8 v[36:39], v[166:167], v[78:79], 0
	v_cmp_eq_u32_e32 vcc, s13, v209
	s_or_b64 s[10:11], s[10:11], vcc
	v_mov_b64_e32 v[74:75], v[6:7]
	s_waitcnt vmcnt(43)
	v_mfma_f32_16x16x32_fp8_fp8 v[40:43], v[160:161], v[78:79], 0
	v_mov_b64_e32 v[70:71], v[30:31]
	v_mov_b64_e32 v[66:67], v[34:35]
	v_mov_b64_e32 v[62:63], v[26:27]
	v_mfma_f32_16x16x32_fp8_fp8 v[36:39], v[168:169], v[80:81], v[36:39]
	v_mov_b64_e32 v[58:59], v[22:23]
	v_mov_b64_e32 v[54:55], v[18:19]
	v_mov_b64_e32 v[50:51], v[14:15]
	s_waitcnt vmcnt(42)
	v_mfma_f32_16x16x32_fp8_fp8 v[40:43], v[158:159], v[80:81], v[40:43]
	v_mov_b32_e32 v203, v0
	v_mov_b64_e32 v[72:73], v[4:5]
	v_mov_b64_e32 v[68:69], v[28:29]
	v_mfma_f32_16x16x32_fp8_fp8 v[36:39], v[164:165], v[82:83], v[36:39]
	v_mov_b64_e32 v[64:65], v[32:33]
	v_mov_b64_e32 v[60:61], v[24:25]
	v_mov_b64_e32 v[56:57], v[20:21]
	s_waitcnt vmcnt(41)
	v_mfma_f32_16x16x32_fp8_fp8 v[40:43], v[156:157], v[82:83], v[40:43]
	v_mov_b64_e32 v[52:53], v[16:17]
	v_mov_b64_e32 v[48:49], v[12:13]
	v_mfma_f32_16x16x32_fp8_fp8 v[36:39], v[162:163], v[84:85], v[36:39]
	s_waitcnt vmcnt(40)
	v_mfma_f32_16x16x32_fp8_fp8 v[40:43], v[154:155], v[84:85], v[40:43]
	s_nop 5
	v_max_f32_e32 v3, v37, v37
	v_max_f32_e32 v44, v36, v36
	v_max_f32_e32 v3, v44, v3
	v_max_f32_e32 v44, v39, v39
	v_max_f32_e32 v45, v38, v38
	v_max_f32_e32 v44, v45, v44
	v_max_f32_e32 v45, v43, v43
	v_max_f32_e32 v46, v42, v42
	v_max_f32_e32 v45, v46, v45
	v_max3_f32 v45, v40, v41, v45
	v_max3_f32 v3, v3, v44, v45
	v_cndmask_b32_e64 v202, v223, v3, s[10:11]
	v_mov_b64_e32 v[46:47], v[10:11]
	v_cmp_gt_f32_e32 vcc, v202, v2
	v_mov_b64_e32 v[44:45], v[8:9]
	v_mov_b32_e32 v3, v133
	s_cbranch_vccz .LBB0_876
	ds_bpermute_b32 v3, v227, v202
	v_max_f32_e32 v44, v202, v202
	s_waitcnt lgkmcnt(0)
	v_max_f32_e32 v3, v3, v3
	v_max_f32_e32 v3, v44, v3
	ds_bpermute_b32 v44, v226, v3
	s_waitcnt lgkmcnt(0)
	v_max3_f32 v203, v0, v3, v44
	v_sub_f32_e32 v3, v0, v203
	v_exp_f32_e32 v72, v3
	s_nop 0
	v_mul_f32_e32 v3, v133, v72
	v_pk_mul_f32 v[46:47], v[10:11], v[72:73] op_sel_hi:[1,0]
	v_pk_mul_f32 v[44:45], v[8:9], v[72:73] op_sel_hi:[1,0]
	v_pk_mul_f32 v[50:51], v[14:15], v[72:73] op_sel_hi:[1,0]
	v_pk_mul_f32 v[48:49], v[12:13], v[72:73] op_sel_hi:[1,0]
	v_pk_mul_f32 v[54:55], v[18:19], v[72:73] op_sel_hi:[1,0]
	v_pk_mul_f32 v[52:53], v[16:17], v[72:73] op_sel_hi:[1,0]
	v_pk_mul_f32 v[58:59], v[22:23], v[72:73] op_sel_hi:[1,0]
	v_pk_mul_f32 v[56:57], v[20:21], v[72:73] op_sel_hi:[1,0]
	v_pk_mul_f32 v[62:63], v[26:27], v[72:73] op_sel_hi:[1,0]
	v_pk_mul_f32 v[60:61], v[24:25], v[72:73] op_sel_hi:[1,0]
	v_pk_mul_f32 v[66:67], v[34:35], v[72:73] op_sel_hi:[1,0]
	v_pk_mul_f32 v[64:65], v[32:33], v[72:73] op_sel_hi:[1,0]
	v_pk_mul_f32 v[70:71], v[30:31], v[72:73] op_sel_hi:[1,0]
	v_pk_mul_f32 v[68:69], v[28:29], v[72:73] op_sel_hi:[1,0]
	v_pk_mul_f32 v[74:75], v[6:7], v[72:73] op_sel_hi:[1,0]
	v_pk_mul_f32 v[72:73], v[4:5], v[72:73] op_sel_hi:[1,0]
.LBB0_876:
	v_add_f32_e32 v202, -4.0, v203
	v_sub_f32_e32 v36, v36, v202
	v_sub_f32_e32 v40, v40, v202
	v_sub_f32_e32 v37, v37, v202
	v_sub_f32_e32 v41, v41, v202
	v_exp_f32_e32 v36, v36
	v_exp_f32_e32 v40, v40
	v_exp_f32_e32 v37, v37
	v_exp_f32_e32 v41, v41
	v_sub_f32_e32 v38, v38, v202
	v_sub_f32_e32 v42, v42, v202
	v_sub_f32_e32 v39, v39, v202
	v_sub_f32_e32 v43, v43, v202
	v_exp_f32_e32 v38, v38
	v_exp_f32_e32 v42, v42
	v_exp_f32_e32 v39, v39
	v_exp_f32_e32 v43, v43
	v_cndmask_b32_e64 v202, 0, v36, s[10:11]
	v_cndmask_b32_e64 v204, 0, v40, s[10:11]
	v_cndmask_b32_e64 v205, 0, v37, s[10:11]
	v_cndmask_b32_e64 v229, 0, v41, s[10:11]
	v_mov_b32_e32 v230, v1
	v_mov_b32_e32 v231, v1
	v_cvt_pk_fp8_f32 v230, v202, v205
	v_cvt_pk_fp8_f32 v231, v204, v229
	v_cndmask_b32_e64 v232, 0, v38, s[10:11]
	v_cndmask_b32_e64 v233, 0, v42, s[10:11]
	v_cndmask_b32_e64 v234, 0, v39, s[10:11]
	v_cndmask_b32_e64 v235, 0, v43, s[10:11]
	v_cvt_pk_fp8_f32 v230, v232, v234 op_sel:[0,0,1]
	v_cvt_pk_fp8_f32 v231, v233, v235 op_sel:[0,0,1]
	s_waitcnt vmcnt(38)
	s_nop 0
	v_mfma_f32_16x16x32_fp8_fp8 v[40:43], v[110:111], v[230:231], v[48:51]
	s_waitcnt vmcnt(36)
	v_mfma_f32_16x16x32_fp8_fp8 v[48:51], v[116:117], v[230:231], v[56:59]
	s_nop 2
	v_add_f32_e32 v56, v202, v204
	v_mfma_f32_16x16x32_fp8_fp8 v[36:39], v[106:107], v[230:231], v[44:47]
	v_mfma_f32_16x16x32_fp8_fp8 v[44:47], v[112:113], v[230:231], v[52:55]
	s_waitcnt vmcnt(35)
	v_mfma_f32_16x16x32_fp8_fp8 v[52:55], v[136:137], v[230:231], v[60:63]
	s_nop 2
	v_add_f32_e32 v60, 0, v56
	v_add_f32_e32 v61, v205, v229
	v_add_f32_e32 v60, v61, v60
	v_add_f32_e32 v61, v232, v233
	s_waitcnt vmcnt(34)
	v_mfma_f32_16x16x32_fp8_fp8 v[56:59], v[134:135], v[230:231], v[64:67]
	s_nop 2
	v_add_f32_e32 v64, v61, v60
	v_add_f32_e32 v65, v234, v235
	v_add_f32_e32 v64, v65, v64
	s_waitcnt vmcnt(33)
	v_mfma_f32_16x16x32_fp8_fp8 v[60:63], v[114:115], v[230:231], v[68:71]
	v_add_f32_e32 v204, v3, v64
	s_waitcnt vmcnt(32)
	v_mfma_f32_16x16x32_fp8_fp8 v[64:67], v[108:109], v[230:231], v[72:75]
	s_branch .LBB0_866
; template <bool SLC, bool NOMASK> ...
;     const int kq = lane >> 4;
;     const int pos0 = SLC ? (dcur & 0xfffff) : dcur;
;     const int lo = SLC ? ((((dcur >> 20) == qi) | ((dcur >> 20) == 4)) ? 0 : (1 << 30)) : lo_in;
;     load_frag8(nxt, KF, VF, SLC ? (dnext & 0xfffff) : dnext, lane);
;     f32x4 sa[2] = {(f32x4){0.f, 0.f, 0.f, 0.f}, (f32x4){0.f, 0.f, 0.f, 0.f}};
; #pragma unroll
;     for (int T = 0; T < 2; ++T)
; #pragma unroll
;         for (int s2 = 0; s2 < 4; ++s2) sa[T] = __builtin_amdgcn_mfma_f32_16x16x32_fp8_fp8(cur.k[T][s2], qf[s2], sa[T], 0, 0, 0);
;     float sc[8]; bool vd[8]; float mx = -1e30f;
;     const bool act = lo == 0 || !SLC;
;     if (NOMASK) {
; #pragma unroll
;         for (int j = 0; j < 8; ++j) { sc[j] = sa[j >> 2][j & 3]; vd[j] = act; }
;         mx = fmaxf(fmaxf(fmaxf(sc[0], sc[1]), fmaxf(sc[2], sc[3])), fmaxf(fmaxf(sc[4], sc[5]), fmaxf(sc[6], sc[7])));
;         mx = act ? mx : -1e30f;
;     } else {
; #pragma unroll
;         for (int T = 0; T < 2; ++T)
; #pragma unroll
;             for (int r = 0; r < 4; ++r) { const int p = pos0 + 16 * T + 4 * kq + r; const bool v = (p >= lo) & (p <= hi); const float x = sa[T][r];
;                 sc[4 * T + r] = x; vd[4 * T + r] = v; mx = v ? fmaxf(mx, x) : mx; }
;     }
;     if (__builtin_amdgcn_ballot_w64(mx > st.m + 4.f) != 0ull) {
.LBB0_877:
	s_cmp_eq_u32 s12, 4
	s_cselect_b64 s[10:11], -1, 0
	s_lshl_b32 s13, s59, 7
	s_and_b32 s50, s13, 0x7fff800
	v_lshl_add_u64 v[44:45], v[86:87], 0, s[50:51]
	s_and_b32 s50, s13, 0x7fff000
	global_load_dwordx2 v[150:151], v[44:45], off
	global_load_dwordx2 v[152:153], v[44:45], off offset:512
	global_load_dwordx2 v[148:149], v[44:45], off offset:1024
	global_load_dwordx2 v[146:147], v[44:45], off offset:1536
	global_load_dwordx2 v[144:145], v[44:45], off offset:2048
	global_load_dwordx2 v[142:143], v[44:45], off offset:2560
	global_load_dwordx2 v[140:141], v[44:45], off offset:3072
	global_load_dwordx2 v[138:139], v[44:45], off offset:3584
	v_lshl_add_u64 v[44:45], v[88:89], 0, s[50:51]
	global_load_dwordx2 v[90:91], v[44:45], off
	global_load_dwordx2 v[92:93], v[44:45], off offset:512
	global_load_dwordx2 v[94:95], v[44:45], off offset:1024
	global_load_dwordx2 v[96:97], v[44:45], off offset:1536
	global_load_dwordx2 v[102:103], v[44:45], off offset:2048
	global_load_dwordx2 v[104:105], v[44:45], off offset:2560
	global_load_dwordx2 v[100:101], v[44:45], off offset:3072
	global_load_dwordx2 v[98:99], v[44:45], off offset:3584
	s_waitcnt vmcnt(47)
	v_mfma_f32_16x16x32_fp8_fp8 v[36:39], v[166:167], v[78:79], 0
	s_and_b32 s13, s97, 0xfffff
	v_cmp_eq_u32_e32 vcc, s12, v209
	v_add_u32_e32 v3, s13, v211
	s_waitcnt vmcnt(46)
	v_mfma_f32_16x16x32_fp8_fp8 v[36:39], v[168:169], v[80:81], v[36:39]
	s_or_b64 s[18:19], s[10:11], vcc
	v_cmp_le_i32_e32 vcc, v3, v132
	s_and_b64 s[16:17], s[18:19], vcc
	s_waitcnt vmcnt(45)
	v_mfma_f32_16x16x32_fp8_fp8 v[36:39], v[164:165], v[82:83], v[36:39]
	v_cmp_lt_i32_e32 vcc, v3, v132
	s_and_b64 s[12:13], s[18:19], vcc
	s_waitcnt vmcnt(43)
	v_mfma_f32_16x16x32_fp8_fp8 v[40:43], v[160:161], v[78:79], 0
	v_mfma_f32_16x16x32_fp8_fp8 v[36:39], v[162:163], v[84:85], v[36:39]
	s_waitcnt vmcnt(42)
	v_mfma_f32_16x16x32_fp8_fp8 v[40:43], v[158:159], v[80:81], v[40:43]
	s_waitcnt vmcnt(41)
	v_mfma_f32_16x16x32_fp8_fp8 v[40:43], v[156:157], v[82:83], v[40:43]
	s_nop 3
	v_max_f32_e32 v44, v36, v36
	v_max_f32_e32 v44, 0xf149f2ca, v44
	v_cndmask_b32_e64 v44, v223, v44, s[16:17]
	v_max_f32_e32 v45, v37, v37
	v_max_f32_e32 v45, v44, v45
	v_cndmask_b32_e64 v44, v44, v45, s[12:13]
	v_add_u32_e32 v45, 2, v3
	v_cmp_le_i32_e32 vcc, v45, v132
	v_max_f32_e32 v45, v38, v38
	v_max_f32_e32 v45, v44, v45
	s_and_b64 s[14:15], s[18:19], vcc
	s_waitcnt vmcnt(40)
	v_mfma_f32_16x16x32_fp8_fp8 v[40:43], v[154:155], v[84:85], v[40:43]
	v_cndmask_b32_e64 v44, v44, v45, s[14:15]
	v_add_u32_e32 v45, 3, v3
	v_cmp_le_i32_e32 vcc, v45, v132
	v_max_f32_e32 v45, v39, v39
	v_max_f32_e32 v45, v44, v45
	s_and_b64 s[10:11], s[18:19], vcc
	v_cndmask_b32_e64 v44, v44, v45, s[10:11]
	v_add_u32_e32 v45, 16, v3
	v_cmp_le_i32_e32 vcc, v45, v132
	v_max_f32_e32 v45, v40, v40
	v_max_f32_e32 v45, v44, v45
	s_and_b64 s[24:25], s[18:19], vcc
	v_cndmask_b32_e64 v44, v44, v45, s[24:25]
	v_add_u32_e32 v45, 17, v3
	v_cmp_le_i32_e32 vcc, v45, v132
	v_max_f32_e32 v45, v44, v44
	v_max_f32_e32 v46, v41, v41
	v_max_f32_e32 v45, v45, v46
	s_and_b64 s[20:21], s[18:19], vcc
	v_cndmask_b32_e64 v44, v44, v45, s[20:21]
	v_add_u32_e32 v45, 18, v3
	v_cmp_le_i32_e32 vcc, v45, v132
	v_max_f32_e32 v45, v44, v44
	v_max_f32_e32 v46, v42, v42
	v_max_f32_e32 v45, v45, v46
	s_and_b64 s[22:23], s[18:19], vcc
	v_cndmask_b32_e64 v44, v44, v45, s[22:23]
	v_add_u32_e32 v3, 19, v3
	v_cmp_le_i32_e32 vcc, v3, v132
	v_max_f32_e32 v3, v44, v44
	v_max_f32_e32 v45, v43, v43
	v_max_f32_e32 v3, v3, v45
	s_and_b64 s[18:19], s[18:19], vcc
	v_cndmask_b32_e64 v3, v44, v3, s[18:19]
	v_cmp_gt_f32_e32 vcc, v3, v2
	s_cbranch_vccz .LBB0_879
	ds_bpermute_b32 v2, v227, v3
	v_max_f32_e32 v3, v3, v3
	s_waitcnt lgkmcnt(0)
	v_max_f32_e32 v2, v2, v2
	v_max_f32_e32 v2, v3, v2
	ds_bpermute_b32 v3, v226, v2
	s_waitcnt lgkmcnt(0)
	v_max3_f32 v2, v0, v2, v3
	v_sub_f32_e32 v0, v0, v2
	v_exp_f32_e32 v0, v0
	s_nop 0
	v_mul_f32_e32 v133, v133, v0
	v_pk_mul_f32 v[10:11], v[10:11], v[0:1] op_sel_hi:[1,0]
	v_pk_mul_f32 v[8:9], v[8:9], v[0:1] op_sel_hi:[1,0]
	v_pk_mul_f32 v[14:15], v[14:15], v[0:1] op_sel_hi:[1,0]
	v_pk_mul_f32 v[12:13], v[12:13], v[0:1] op_sel_hi:[1,0]
	v_pk_mul_f32 v[18:19], v[18:19], v[0:1] op_sel_hi:[1,0]
	v_pk_mul_f32 v[16:17], v[16:17], v[0:1] op_sel_hi:[1,0]
	v_pk_mul_f32 v[22:23], v[22:23], v[0:1] op_sel_hi:[1,0]
	v_pk_mul_f32 v[20:21], v[20:21], v[0:1] op_sel_hi:[1,0]
	v_pk_mul_f32 v[26:27], v[26:27], v[0:1] op_sel_hi:[1,0]
	v_pk_mul_f32 v[24:25], v[24:25], v[0:1] op_sel_hi:[1,0]
	v_pk_mul_f32 v[34:35], v[34:35], v[0:1] op_sel_hi:[1,0]
	v_pk_mul_f32 v[32:33], v[32:33], v[0:1] op_sel_hi:[1,0]
	v_pk_mul_f32 v[30:31], v[30:31], v[0:1] op_sel_hi:[1,0]
	v_pk_mul_f32 v[28:29], v[28:29], v[0:1] op_sel_hi:[1,0]
	v_pk_mul_f32 v[6:7], v[6:7], v[0:1] op_sel_hi:[1,0]
	v_pk_mul_f32 v[4:5], v[4:5], v[0:1] op_sel_hi:[1,0]
	v_mov_b32_e32 v0, v2
; #define F8_STEP(CUR, NXT2, DC, DN2) do { \
;         if ((DC) & (1 << 30)) step_frag8<SLC, true>(qf, CUR, NXT2, KF, VF, (DC) & NM, (DN2) & NM, lo_in, hi, qi, st, lane); \
;         else step_frag8<SLC, false>(qf, CUR, NXT2, KF, VF, (DC), (DN2) & NM, lo_in, hi, qi, st, lane); } while (0)
; template <bool SLC, bool NOMASK> ...
;     ...
;     } else {
; #pragma unroll
;         for (int j = 0; j < 4; ++j) { pa[j] = vd[j] ? __builtin_amdgcn_exp2f(sc[j] - mref) : 0.f; pb[j] = vd[4 + j] ? __builtin_amdgcn_exp2f(sc[4 + j] - mref) : 0.f; ps += pa[j] + pb[j]; }
;     }
;     st.l += ps;
;     const u32x2 pw = pack8_fp8(pa, pb);
;     const i64_t pf = __builtin_bit_cast(i64_t, pw);
; #pragma unroll
;     for (int db = 0; db < 8; ++db) st.o[db] = __builtin_amdgcn_mfma_f32_16x16x32_fp8_fp8(cur.v[db], pf, st.o[db], 0, 0, 0);
; template <bool SLC, class Desc>
; __device__ __forceinline__ void attn_run_frag8(const i64_t (&qf)[4], const unsigned char* __restrict__ KF, const unsigned char* __restrict__ VF, const Desc& desc, int n,
;                                                int lo_in, int hi, int qi, AState& st, int lane) {
;     ...
;     for (int i = 0; i < n; i += 3) {
;         const int d2 = desc(i + 2 < n ? i + 2 : n - 1);
;         F8_STEP(fa, fc, d0, d2);
;         if (i + 1 >= n) break;
;         const int d3 = desc(i + 3 < n ? i + 3 : n - 1);
;         F8_STEP(fb, fa, d1, d3);
;         if (i + 2 >= n) break;
;         const int d4 = desc(i + 4 < n ? i + 4 : n - 1);
;         F8_STEP(fc, fb, d2, d4);
; __device__ __forceinline__ void nsa_unit(int unit, const bf16_t* proj, const bf16_t* kc, const bf16_t* vc, const bf16_t* gn, const float* cs, const float* sn, ...
;     ...
;     { auto desc = [&](int i) { return __builtin_amdgcn_readfirstlane(list[i]); };
.LBB0_879:
	v_add_f32_e32 v2, -4.0, v0
	v_sub_f32_e32 v3, v36, v2
	v_exp_f32_e32 v3, v3
	v_sub_f32_e32 v36, v40, v2
	v_exp_f32_e32 v36, v36
	v_mov_b32_e32 v203, v0
	v_cndmask_b32_e64 v56, 0, v3, s[16:17]
	v_sub_f32_e32 v3, v37, v2
	v_cndmask_b32_e64 v57, 0, v36, s[24:25]
	v_exp_f32_e32 v3, v3
	v_sub_f32_e32 v36, v41, v2
	v_sub_f32_e32 v37, v38, v2
	v_exp_f32_e32 v36, v36
	v_exp_f32_e32 v37, v37
	v_sub_f32_e32 v38, v42, v2
	v_cndmask_b32_e64 v58, 0, v3, s[12:13]
	v_sub_f32_e32 v3, v39, v2
	v_sub_f32_e32 v2, v43, v2
	v_exp_f32_e32 v38, v38
	v_cndmask_b32_e64 v59, 0, v36, s[20:21]
	v_cndmask_b32_e64 v60, 0, v37, s[14:15]
	v_exp_f32_e32 v36, v3
	v_exp_f32_e32 v37, v2
	v_mov_b32_e32 v2, v1
	v_mov_b32_e32 v3, v1
	v_cvt_pk_fp8_f32 v2, v56, v58
	v_cvt_pk_fp8_f32 v3, v57, v59
	v_cndmask_b32_e64 v61, 0, v38, s[22:23]
	v_cndmask_b32_e64 v64, 0, v36, s[10:11]
	v_cndmask_b32_e64 v65, 0, v37, s[18:19]
	v_cvt_pk_fp8_f32 v2, v60, v64 op_sel:[0,0,1]
	v_cvt_pk_fp8_f32 v3, v61, v65 op_sel:[0,0,1]
	s_waitcnt vmcnt(39)
	s_nop 0
	v_mfma_f32_16x16x32_fp8_fp8 v[36:39], v[106:107], v[2:3], v[8:11]
	s_nop 2
	v_add_f32_e32 v8, v56, v57
	v_add_f32_e32 v8, 0, v8
	v_add_f32_e32 v9, v58, v59
	v_add_f32_e32 v8, v9, v8
	v_add_f32_e32 v9, v60, v61
	s_waitcnt vmcnt(38)
	v_mfma_f32_16x16x32_fp8_fp8 v[40:43], v[110:111], v[2:3], v[12:15]
	v_add_f32_e32 v8, v9, v8
	v_add_f32_e32 v9, v64, v65
	v_add_f32_e32 v8, v9, v8
	s_waitcnt vmcnt(37)
	v_mfma_f32_16x16x32_fp8_fp8 v[44:47], v[112:113], v[2:3], v[16:19]
	v_add_f32_e32 v204, v133, v8
	s_waitcnt vmcnt(36)
	v_mfma_f32_16x16x32_fp8_fp8 v[48:51], v[116:117], v[2:3], v[20:23]
	s_waitcnt vmcnt(35)
	v_mfma_f32_16x16x32_fp8_fp8 v[52:55], v[136:137], v[2:3], v[24:27]
	s_waitcnt vmcnt(34)
	v_mfma_f32_16x16x32_fp8_fp8 v[56:59], v[134:135], v[2:3], v[32:35]
	s_waitcnt vmcnt(33)
	v_mfma_f32_16x16x32_fp8_fp8 v[60:63], v[114:115], v[2:3], v[28:31]
	s_waitcnt vmcnt(32)
	v_mfma_f32_16x16x32_fp8_fp8 v[64:67], v[108:109], v[2:3], v[4:7]
	s_andn2_b64 vcc, exec, s[26:27]
	s_mov_b64 s[10:11], -1
	s_cbranch_vccnz .LBB0_859
.LBB0_880:
	s_cmp_lt_u32 s58, s56
	s_cselect_b32 s10, s58, s57
	s_lshl_b32 s10, s10, 2
	s_add_i32 s10, s3, s10
	v_mov_b32_e32 v0, s10
	ds_read_b32 v0, v0 offset:13632
	s_and_b32 s13, s66, 2.0
	s_ashr_i32 s12, s66, 20
	s_mov_b64 s[10:11], -1
	s_cmp_eq_u32 s13, 0
	s_waitcnt lgkmcnt(0)
	v_readfirstlane_b32 s97, v0
	v_add_f32_e32 v0, 4.0, v203
	s_cbranch_scc1 .LBB0_884
	s_and_b32 s13, s12, 0xfffffbff
	s_cmp_eq_u32 s13, 4
	s_cselect_b64 s[10:11], -1, 0
	s_lshl_b32 s14, s97, 7
	s_and_b32 s50, s14, 0x7fff800
	v_lshl_add_u64 v[10:11], v[86:87], 0, s[50:51]
	s_and_b32 s50, s14, 0x7fff000
	global_load_dwordx2 v[166:167], v[10:11], off
	global_load_dwordx2 v[168:169], v[10:11], off offset:512
	global_load_dwordx2 v[164:165], v[10:11], off offset:1024
	global_load_dwordx2 v[162:163], v[10:11], off offset:1536
	global_load_dwordx2 v[160:161], v[10:11], off offset:2048
	global_load_dwordx2 v[158:159], v[10:11], off offset:2560
	global_load_dwordx2 v[156:157], v[10:11], off offset:3072
	global_load_dwordx2 v[154:155], v[10:11], off offset:3584
	v_lshl_add_u64 v[10:11], v[88:89], 0, s[50:51]
	global_load_dwordx2 v[106:107], v[10:11], off
	global_load_dwordx2 v[110:111], v[10:11], off offset:512
	global_load_dwordx2 v[112:113], v[10:11], off offset:1024
	global_load_dwordx2 v[116:117], v[10:11], off offset:1536
	global_load_dwordx2 v[136:137], v[10:11], off offset:2048
	global_load_dwordx2 v[134:135], v[10:11], off offset:2560
	global_load_dwordx2 v[114:115], v[10:11], off offset:3072
	global_load_dwordx2 v[108:109], v[10:11], off offset:3584
	s_waitcnt vmcnt(47)
	v_mfma_f32_16x16x32_fp8_fp8 v[2:5], v[190:191], v[78:79], 0
	v_cmp_eq_u32_e32 vcc, s13, v209
	s_or_b64 s[10:11], s[10:11], vcc
	v_mov_b64_e32 v[74:75], v[66:67]
	s_waitcnt vmcnt(43)
	v_mfma_f32_16x16x32_fp8_fp8 v[6:9], v[200:201], v[78:79], 0
	v_mov_b64_e32 v[70:71], v[62:63]
	v_mov_b64_e32 v[30:31], v[56:57]
	v_mov_b64_e32 v[26:27], v[52:53]
	v_mfma_f32_16x16x32_fp8_fp8 v[2:5], v[196:197], v[80:81], v[2:5]
	v_mov_b64_e32 v[22:23], v[48:49]
	v_mov_b64_e32 v[18:19], v[44:45]
	v_mov_b64_e32 v[14:15], v[40:41]
	s_waitcnt vmcnt(42)
	v_mfma_f32_16x16x32_fp8_fp8 v[6:9], v[192:193], v[80:81], v[6:9]
	v_mov_b32_e32 v202, v203
	v_mov_b64_e32 v[72:73], v[64:65]
	v_mov_b64_e32 v[68:69], v[60:61]
	v_mfma_f32_16x16x32_fp8_fp8 v[2:5], v[198:199], v[82:83], v[2:5]
	v_mov_b64_e32 v[32:33], v[58:59]
	v_mov_b64_e32 v[28:29], v[54:55]
	v_mov_b64_e32 v[24:25], v[50:51]
	s_waitcnt vmcnt(41)
	v_mfma_f32_16x16x32_fp8_fp8 v[6:9], v[188:189], v[82:83], v[6:9]
	v_mov_b64_e32 v[20:21], v[46:47]
	v_mov_b64_e32 v[16:17], v[42:43]
	v_mov_b32_e32 v133, v204
	v_mfma_f32_16x16x32_fp8_fp8 v[2:5], v[194:195], v[84:85], v[2:5]
	s_waitcnt vmcnt(40)
	v_mfma_f32_16x16x32_fp8_fp8 v[6:9], v[186:187], v[84:85], v[6:9]
	s_nop 5
	v_max_f32_e32 v10, v3, v3
	v_max_f32_e32 v11, v2, v2
	v_max_f32_e32 v10, v11, v10
	v_max_f32_e32 v11, v5, v5
	v_max_f32_e32 v12, v4, v4
	v_max_f32_e32 v11, v12, v11
	v_max_f32_e32 v12, v9, v9
	v_max_f32_e32 v13, v8, v8
	v_max_f32_e32 v12, v13, v12
	v_max3_f32 v12, v6, v7, v12
	v_max3_f32 v10, v10, v11, v12
	v_cndmask_b32_e64 v34, v223, v10, s[10:11]
	v_mov_b64_e32 v[10:11], v[36:37]
	v_cmp_gt_f32_e32 vcc, v34, v0
	v_mov_b64_e32 v[12:13], v[38:39]
	s_cbranch_vccz .LBB0_883
	ds_bpermute_b32 v10, v227, v34
	v_max_f32_e32 v11, v34, v34
	s_waitcnt lgkmcnt(0)
	v_max_f32_e32 v10, v10, v10
	v_max_f32_e32 v10, v11, v10
	ds_bpermute_b32 v11, v226, v10
	s_waitcnt lgkmcnt(0)
	v_max3_f32 v202, v203, v10, v11
	v_sub_f32_e32 v10, v203, v202
	v_exp_f32_e32 v34, v10
	s_nop 0
	v_mul_f32_e32 v133, v204, v34
	v_pk_mul_f32 v[12:13], v[38:39], v[34:35] op_sel_hi:[1,0]
	v_pk_mul_f32 v[10:11], v[36:37], v[34:35] op_sel_hi:[1,0]
	v_pk_mul_f32 v[16:17], v[42:43], v[34:35] op_sel_hi:[1,0]
	v_pk_mul_f32 v[14:15], v[40:41], v[34:35] op_sel_hi:[1,0]
	v_pk_mul_f32 v[20:21], v[46:47], v[34:35] op_sel_hi:[1,0]
	v_pk_mul_f32 v[18:19], v[44:45], v[34:35] op_sel_hi:[1,0]
	v_pk_mul_f32 v[24:25], v[50:51], v[34:35] op_sel_hi:[1,0]
	v_pk_mul_f32 v[22:23], v[48:49], v[34:35] op_sel_hi:[1,0]
	v_pk_mul_f32 v[28:29], v[54:55], v[34:35] op_sel_hi:[1,0]
	v_pk_mul_f32 v[26:27], v[52:53], v[34:35] op_sel_hi:[1,0]
	v_pk_mul_f32 v[32:33], v[58:59], v[34:35] op_sel_hi:[1,0]
	v_pk_mul_f32 v[30:31], v[56:57], v[34:35] op_sel_hi:[1,0]
	v_pk_mul_f32 v[70:71], v[62:63], v[34:35] op_sel_hi:[1,0]
	v_pk_mul_f32 v[68:69], v[60:61], v[34:35] op_sel_hi:[1,0]
	v_pk_mul_f32 v[74:75], v[66:67], v[34:35] op_sel_hi:[1,0]
	v_pk_mul_f32 v[72:73], v[64:65], v[34:35] op_sel_hi:[1,0]
; template <bool SLC, bool NOMASK> ...
;     ...
;         for (int j = 0; j < 4; ++j) { pa[j] = __builtin_amdgcn_exp2f(sc[j] - mref); pb[j] = __builtin_amdgcn_exp2f(sc[4 + j] - mref); }
;         if (SLC) {
; #pragma unroll
;             for (int j = 0; j < 4; ++j) { pa[j] = act ? pa[j] : 0.f; pb[j] = act ? pb[j] : 0.f; }
;         }
; #pragma unroll
;         for (int j = 0; j < 4; ++j) ps += pa[j] + pb[j];
;     } else {
; #pragma unroll
;         for (int j = 0; j < 4; ++j) { pa[j] = vd[j] ? __builtin_amdgcn_exp2f(sc[j] - mref) : 0.f; pb[j] = vd[4 + j] ? __builtin_amdgcn_exp2f(sc[4 + j] - mref) : 0.f; ps += pa[j] + pb[j]; }
;     }
;     st.l += ps;
;     const u32x2 pw = pack8_fp8(pa, pb);
;     const i64_t pf = __builtin_bit_cast(i64_t, pw);
; #pragma unroll
;     for (int db = 0; db < 8; ++db) st.o[db] = __builtin_amdgcn_mfma_f32_16x16x32_fp8_fp8(cur.v[db], pf, st.o[db], 0, 0, 0);
.LBB0_883:
	v_add_f32_e32 v34, -4.0, v202
	v_sub_f32_e32 v2, v2, v34
	v_sub_f32_e32 v6, v6, v34
	v_sub_f32_e32 v3, v3, v34
	v_sub_f32_e32 v7, v7, v34
	v_exp_f32_e32 v2, v2
	v_exp_f32_e32 v6, v6
	v_exp_f32_e32 v3, v3
	v_exp_f32_e32 v7, v7
	v_sub_f32_e32 v4, v4, v34
	v_sub_f32_e32 v8, v8, v34
	v_sub_f32_e32 v5, v5, v34
	v_sub_f32_e32 v9, v9, v34
	v_exp_f32_e32 v4, v4
	v_exp_f32_e32 v8, v8
	v_exp_f32_e32 v5, v5
	v_exp_f32_e32 v9, v9
	v_cndmask_b32_e64 v34, 0, v2, s[10:11]
	v_cndmask_b32_e64 v6, 0, v6, s[10:11]
	v_cndmask_b32_e64 v35, 0, v3, s[10:11]
	v_cndmask_b32_e64 v7, 0, v7, s[10:11]
	v_mov_b32_e32 v2, v1
	v_mov_b32_e32 v3, v1
	v_cvt_pk_fp8_f32 v2, v34, v35
	v_cvt_pk_fp8_f32 v3, v6, v7
	v_cndmask_b32_e64 v4, 0, v4, s[10:11]
	v_cndmask_b32_e64 v205, 0, v8, s[10:11]
	v_cndmask_b32_e64 v5, 0, v5, s[10:11]
	v_cndmask_b32_e64 v229, 0, v9, s[10:11]
	v_add_f32_e32 v6, v34, v6
	v_cvt_pk_fp8_f32 v2, v4, v5 op_sel:[0,0,1]
	v_cvt_pk_fp8_f32 v3, v205, v229 op_sel:[0,0,1]
	v_add_f32_e32 v6, 0, v6
	v_add_f32_e32 v7, v35, v7
	v_add_f32_e32 v6, v7, v6
	v_add_f32_e32 v4, v4, v205
	v_add_f32_e32 v4, v4, v6
	v_add_f32_e32 v5, v5, v229
	v_add_f32_e32 v4, v5, v4
	s_waitcnt vmcnt(39)
	v_mfma_f32_16x16x32_fp8_fp8 v[8:11], v[170:171], v[2:3], v[10:13]
	v_add_f32_e32 v133, v133, v4
	s_mov_b64 s[10:11], 0
	s_waitcnt vmcnt(38)
	v_mfma_f32_16x16x32_fp8_fp8 v[12:15], v[172:173], v[2:3], v[14:17]
	s_waitcnt vmcnt(37)
	v_mfma_f32_16x16x32_fp8_fp8 v[16:19], v[174:175], v[2:3], v[18:21]
	s_waitcnt vmcnt(36)
	v_mfma_f32_16x16x32_fp8_fp8 v[20:23], v[176:177], v[2:3], v[22:25]
	s_waitcnt vmcnt(35)
	v_mfma_f32_16x16x32_fp8_fp8 v[24:27], v[182:183], v[2:3], v[26:29]
	s_waitcnt vmcnt(34)
	v_mfma_f32_16x16x32_fp8_fp8 v[32:35], v[184:185], v[2:3], v[30:33]
	s_waitcnt vmcnt(33)
	v_mfma_f32_16x16x32_fp8_fp8 v[28:31], v[180:181], v[2:3], v[68:71]
	s_waitcnt vmcnt(32)
	v_mfma_f32_16x16x32_fp8_fp8 v[4:7], v[178:179], v[2:3], v[72:75]
; template <bool SLC, bool NOMASK> ...
;     const int kq = lane >> 4;
;     const int pos0 = SLC ? (dcur & 0xfffff) : dcur;
;     const int lo = SLC ? ((((dcur >> 20) == qi) | ((dcur >> 20) == 4)) ? 0 : (1 << 30)) : lo_in;
;     load_frag8(nxt, KF, VF, SLC ? (dnext & 0xfffff) : dnext, lane);
;     f32x4 sa[2] = {(f32x4){0.f, 0.f, 0.f, 0.f}, (f32x4){0.f, 0.f, 0.f, 0.f}};
; #pragma unroll
;     for (int T = 0; T < 2; ++T)
; #pragma unroll
;         for (int s2 = 0; s2 < 4; ++s2) sa[T] = __builtin_amdgcn_mfma_f32_16x16x32_fp8_fp8(cur.k[T][s2], qf[s2], sa[T], 0, 0, 0);
;     float sc[8]; bool vd[8]; float mx = -1e30f;
;     const bool act = lo == 0 || !SLC;
;     if (NOMASK) {
; #pragma unroll
;         for (int j = 0; j < 8; ++j) { sc[j] = sa[j >> 2][j & 3]; vd[j] = act; }
;         mx = fmaxf(fmaxf(fmaxf(sc[0], sc[1]), fmaxf(sc[2], sc[3])), fmaxf(fmaxf(sc[4], sc[5]), fmaxf(sc[6], sc[7])));
;         mx = act ? mx : -1e30f;
;     } else {
; #pragma unroll
;         for (int T = 0; T < 2; ++T)
; #pragma unroll
;             for (int r = 0; r < 4; ++r) { const int p = pos0 + 16 * T + 4 * kq + r; const bool v = (p >= lo) & (p <= hi); const float x = sa[T][r];
;                 sc[4 * T + r] = x; vd[4 * T + r] = v; mx = v ? fmaxf(mx, x) : mx; }
;     }
;     if (__builtin_amdgcn_ballot_w64(mx > st.m + 4.f) != 0ull) {
;         mx = fmaxf(mx, __shfl_xor(mx, 16)); mx = fmaxf(mx, __shfl_xor(mx, 32));
;         const float mn = fmaxf(st.m, mx), alpha = __builtin_amdgcn_exp2f(st.m - mn); st.m = mn; st.l *= alpha;
; #pragma unroll
;         for (int j = 0; j < 8; ++j) st.o[j] = st.o[j] * alpha;
;     }
;     f32x4 pa, pb; float ps = 0.f;
;     const float mref = st.m - 4.f;
;     if (NOMASK) {
; #pragma unroll
;         for (int j = 0; j < 4; ++j) { pa[j] = __builtin_amdgcn_exp2f(sc[j] - mref); pb[j] = __builtin_amdgcn_exp2f(sc[4 + j] - mref); }
;         if (SLC) {
; #pragma unroll
;             for (int j = 0; j < 4; ++j) { pa[j] = act ? pa[j] : 0.f; pb[j] = act ? pb[j] : 0.f; }
;         }
; #pragma unroll
;         for (int j = 0; j < 4; ++j) ps += pa[j] + pb[j];
;     } else {
; #pragma unroll
;         for (int j = 0; j < 4; ++j) { pa[j] = vd[j] ? __builtin_amdgcn_exp2f(sc[j] - mref) : 0.f; pb[j] = vd[4 + j] ? __builtin_amdgcn_exp2f(sc[4 + j] - mref) : 0.f; ps += pa[j] + pb[j]; }
;     }
;     st.l += ps;
;     const u32x2 pw = pack8_fp8(pa, pb);
.LBB0_884:
	s_and_b64 vcc, exec, s[10:11]
	s_cbranch_vccz .LBB0_888
	s_cmp_eq_u32 s12, 4
	s_cselect_b64 s[10:11], -1, 0
	s_lshl_b32 s13, s97, 7
	s_and_b32 s50, s13, 0x7fff800
	v_lshl_add_u64 v[10:11], v[86:87], 0, s[50:51]
	s_and_b32 s50, s13, 0x7fff000
	global_load_dwordx2 v[166:167], v[10:11], off
	global_load_dwordx2 v[168:169], v[10:11], off offset:512
	global_load_dwordx2 v[164:165], v[10:11], off offset:1024
	global_load_dwordx2 v[162:163], v[10:11], off offset:1536
	global_load_dwordx2 v[160:161], v[10:11], off offset:2048
	global_load_dwordx2 v[158:159], v[10:11], off offset:2560
	global_load_dwordx2 v[156:157], v[10:11], off offset:3072
	global_load_dwordx2 v[154:155], v[10:11], off offset:3584
	v_lshl_add_u64 v[10:11], v[88:89], 0, s[50:51]
	global_load_dwordx2 v[106:107], v[10:11], off
	global_load_dwordx2 v[110:111], v[10:11], off offset:512
	global_load_dwordx2 v[112:113], v[10:11], off offset:1024
	global_load_dwordx2 v[116:117], v[10:11], off offset:1536
	global_load_dwordx2 v[136:137], v[10:11], off offset:2048
	global_load_dwordx2 v[134:135], v[10:11], off offset:2560
	global_load_dwordx2 v[114:115], v[10:11], off offset:3072
	global_load_dwordx2 v[108:109], v[10:11], off offset:3584
	s_waitcnt vmcnt(47)
	v_mfma_f32_16x16x32_fp8_fp8 v[2:5], v[190:191], v[78:79], 0
	s_and_b32 s13, s66, 0xfffff
	v_cmp_eq_u32_e32 vcc, s12, v209
	v_add_u32_e32 v10, s13, v211
	s_waitcnt vmcnt(46)
	v_mfma_f32_16x16x32_fp8_fp8 v[2:5], v[196:197], v[80:81], v[2:5]
	s_or_b64 s[18:19], s[10:11], vcc
	v_cmp_le_i32_e32 vcc, v10, v132
	s_and_b64 s[16:17], s[18:19], vcc
	s_waitcnt vmcnt(45)
	v_mfma_f32_16x16x32_fp8_fp8 v[2:5], v[198:199], v[82:83], v[2:5]
	v_cmp_lt_i32_e32 vcc, v10, v132
	s_and_b64 s[12:13], s[18:19], vcc
	s_waitcnt vmcnt(43)
	v_mfma_f32_16x16x32_fp8_fp8 v[6:9], v[200:201], v[78:79], 0
	v_mfma_f32_16x16x32_fp8_fp8 v[2:5], v[194:195], v[84:85], v[2:5]
	s_waitcnt vmcnt(42)
	v_mfma_f32_16x16x32_fp8_fp8 v[6:9], v[192:193], v[80:81], v[6:9]
	s_waitcnt vmcnt(41)
	v_mfma_f32_16x16x32_fp8_fp8 v[6:9], v[188:189], v[82:83], v[6:9]
	s_nop 3
	v_max_f32_e32 v11, v2, v2
	v_max_f32_e32 v11, 0xf149f2ca, v11
	v_cndmask_b32_e64 v11, v223, v11, s[16:17]
	v_max_f32_e32 v12, v3, v3
	v_max_f32_e32 v12, v11, v12
	v_cndmask_b32_e64 v11, v11, v12, s[12:13]
	v_add_u32_e32 v12, 2, v10
	v_cmp_le_i32_e32 vcc, v12, v132
	v_max_f32_e32 v12, v4, v4
	v_max_f32_e32 v12, v11, v12
	s_and_b64 s[14:15], s[18:19], vcc
	s_waitcnt vmcnt(40)
	v_mfma_f32_16x16x32_fp8_fp8 v[6:9], v[186:187], v[84:85], v[6:9]
	v_cndmask_b32_e64 v11, v11, v12, s[14:15]
	v_add_u32_e32 v12, 3, v10
	v_cmp_le_i32_e32 vcc, v12, v132
	v_max_f32_e32 v12, v5, v5
	v_max_f32_e32 v12, v11, v12
	s_and_b64 s[10:11], s[18:19], vcc
	v_cndmask_b32_e64 v11, v11, v12, s[10:11]
	v_add_u32_e32 v12, 16, v10
	v_cmp_le_i32_e32 vcc, v12, v132
	v_max_f32_e32 v12, v6, v6
	v_max_f32_e32 v12, v11, v12
	s_and_b64 s[24:25], s[18:19], vcc
	v_cndmask_b32_e64 v11, v11, v12, s[24:25]
	v_add_u32_e32 v12, 17, v10
	v_cmp_le_i32_e32 vcc, v12, v132
	v_max_f32_e32 v12, v11, v11
	v_max_f32_e32 v13, v7, v7
	v_max_f32_e32 v12, v12, v13
	s_and_b64 s[20:21], s[18:19], vcc
	v_cndmask_b32_e64 v11, v11, v12, s[20:21]
	v_add_u32_e32 v12, 18, v10
	v_cmp_le_i32_e32 vcc, v12, v132
	v_max_f32_e32 v12, v11, v11
	v_max_f32_e32 v13, v8, v8
	v_max_f32_e32 v12, v12, v13
	s_and_b64 s[22:23], s[18:19], vcc
	v_cndmask_b32_e64 v11, v11, v12, s[22:23]
	v_add_u32_e32 v10, 19, v10
	v_cmp_le_i32_e32 vcc, v10, v132
	v_max_f32_e32 v10, v11, v11
	v_max_f32_e32 v12, v9, v9
	v_max_f32_e32 v10, v10, v12
	s_and_b64 s[18:19], s[18:19], vcc
	v_cndmask_b32_e64 v10, v11, v10, s[18:19]
	v_cmp_gt_f32_e32 vcc, v10, v0
	s_cbranch_vccz .LBB0_887
	ds_bpermute_b32 v0, v227, v10
	v_max_f32_e32 v10, v10, v10
	s_waitcnt lgkmcnt(0)
	v_max_f32_e32 v0, v0, v0
	v_max_f32_e32 v0, v10, v0
	ds_bpermute_b32 v10, v226, v0
	s_waitcnt lgkmcnt(0)
	v_max3_f32 v10, v203, v0, v10
	v_sub_f32_e32 v0, v203, v10
	v_exp_f32_e32 v0, v0
	v_mov_b32_e32 v203, v10
	v_mul_f32_e32 v204, v204, v0
	v_pk_mul_f32 v[38:39], v[38:39], v[0:1] op_sel_hi:[1,0]
	v_pk_mul_f32 v[36:37], v[36:37], v[0:1] op_sel_hi:[1,0]
	v_pk_mul_f32 v[42:43], v[42:43], v[0:1] op_sel_hi:[1,0]
	v_pk_mul_f32 v[40:41], v[40:41], v[0:1] op_sel_hi:[1,0]
	v_pk_mul_f32 v[46:47], v[46:47], v[0:1] op_sel_hi:[1,0]
	v_pk_mul_f32 v[44:45], v[44:45], v[0:1] op_sel_hi:[1,0]
	v_pk_mul_f32 v[50:51], v[50:51], v[0:1] op_sel_hi:[1,0]
	v_pk_mul_f32 v[48:49], v[48:49], v[0:1] op_sel_hi:[1,0]
	v_pk_mul_f32 v[54:55], v[54:55], v[0:1] op_sel_hi:[1,0]
	v_pk_mul_f32 v[52:53], v[52:53], v[0:1] op_sel_hi:[1,0]
	v_pk_mul_f32 v[58:59], v[58:59], v[0:1] op_sel_hi:[1,0]
	v_pk_mul_f32 v[56:57], v[56:57], v[0:1] op_sel_hi:[1,0]
	v_pk_mul_f32 v[62:63], v[62:63], v[0:1] op_sel_hi:[1,0]
	v_pk_mul_f32 v[60:61], v[60:61], v[0:1] op_sel_hi:[1,0]
	v_pk_mul_f32 v[66:67], v[66:67], v[0:1] op_sel_hi:[1,0]
	v_pk_mul_f32 v[64:65], v[64:65], v[0:1] op_sel_hi:[1,0]
.LBB0_887:
	v_add_f32_e32 v0, -4.0, v203
	v_sub_f32_e32 v2, v2, v0
	v_exp_f32_e32 v2, v2
	v_sub_f32_e32 v6, v6, v0
	v_exp_f32_e32 v6, v6
	v_sub_f32_e32 v4, v4, v0
	v_cndmask_b32_e64 v28, 0, v2, s[16:17]
	v_sub_f32_e32 v2, v3, v0
	v_exp_f32_e32 v2, v2
	v_sub_f32_e32 v3, v7, v0
	v_exp_f32_e32 v3, v3
	v_sub_f32_e32 v7, v8, v0
	v_cndmask_b32_e64 v29, 0, v2, s[12:13]
	v_sub_f32_e32 v2, v5, v0
	v_sub_f32_e32 v0, v9, v0
	v_cndmask_b32_e64 v6, 0, v6, s[24:25]
	v_exp_f32_e32 v4, v4
	v_exp_f32_e32 v7, v7
	v_cndmask_b32_e64 v30, 0, v3, s[20:21]
	v_exp_f32_e32 v5, v2
	v_exp_f32_e32 v0, v0
	v_mov_b32_e32 v2, v1
	v_mov_b32_e32 v3, v1
	v_cvt_pk_fp8_f32 v2, v28, v29
	v_cvt_pk_fp8_f32 v3, v6, v30
	v_cndmask_b32_e64 v4, 0, v4, s[14:15]
	v_cndmask_b32_e64 v7, 0, v7, s[22:23]
	v_cndmask_b32_e64 v5, 0, v5, s[10:11]
	v_cndmask_b32_e64 v0, 0, v0, s[18:19]
	v_cvt_pk_fp8_f32 v2, v4, v5 op_sel:[0,0,1]
	v_cvt_pk_fp8_f32 v3, v7, v0 op_sel:[0,0,1]
	v_add_f32_e32 v6, v28, v6
	v_add_f32_e32 v6, 0, v6
	v_add_f32_e32 v28, v29, v30
	v_add_f32_e32 v6, v28, v6
	v_add_f32_e32 v4, v4, v7
	v_add_f32_e32 v4, v4, v6
	v_add_f32_e32 v0, v5, v0
	s_waitcnt vmcnt(39)
	v_mfma_f32_16x16x32_fp8_fp8 v[8:11], v[170:171], v[2:3], v[36:39]
	v_add_f32_e32 v0, v0, v4
	v_add_f32_e32 v133, v204, v0
	v_mov_b32_e32 v202, v203
	s_waitcnt vmcnt(38)
	v_mfma_f32_16x16x32_fp8_fp8 v[12:15], v[172:173], v[2:3], v[40:43]
	s_waitcnt vmcnt(37)
	v_mfma_f32_16x16x32_fp8_fp8 v[16:19], v[174:175], v[2:3], v[44:47]
	s_waitcnt vmcnt(36)
	v_mfma_f32_16x16x32_fp8_fp8 v[20:23], v[176:177], v[2:3], v[48:51]
	s_waitcnt vmcnt(35)
	v_mfma_f32_16x16x32_fp8_fp8 v[24:27], v[182:183], v[2:3], v[52:55]
	s_waitcnt vmcnt(34)
	v_mfma_f32_16x16x32_fp8_fp8 v[32:35], v[184:185], v[2:3], v[56:59]
	s_waitcnt vmcnt(33)
	v_mfma_f32_16x16x32_fp8_fp8 v[28:31], v[180:181], v[2:3], v[60:63]
	s_waitcnt vmcnt(32)
	v_mfma_f32_16x16x32_fp8_fp8 v[4:7], v[178:179], v[2:3], v[64:67]

; __device__ __forceinline__ unsigned cvt_pk_bf16(float lo, float hi) { f32x2 v = {lo, hi}; bf16x2_t b = __builtin_convertvector(v, bf16x2_t); return __builtin_bit_cast(unsigned, b); }
; __device__ __forceinline__ float bf2f(unsigned short b) { return __uint_as_float(((unsigned)b) << 16); }
; __device__ __forceinline__ float bflo(unsigned w) { return __uint_as_float(w << 16); }
; __device__ __forceinline__ float bfhi(unsigned w) { return __uint_as_float(w & 0xffff0000u); }
; __device__ __forceinline__ float quad_total(float v) { v += __shfl_xor(v, 16); v += __shfl_xor(v, 32); return v; }
; __device__ __forceinline__ void nsa_unit(int unit, const bf16_t* proj, const bf16_t* kc, const bf16_t* vc, const bf16_t* gn, const float* cs, const float* sn, ...
;     ...
;     { const float g1 = bf2f(gn[(size_t)tc * 32 + head * 3 + 1]); const float lt = quad_total(st.l), inv = (lt > 0.f ? 1.f / lt : 0.f) * g1;
; #pragma unroll
;         for (int i = 0; i < 8; ++i) { const f32x4 o = st.o[i] * inv; u32x2 w = outl[64 * i]; w.x = cvt_pk_bf16(bflo(w.x) + o[0], bfhi(w.x) + o[1]); w.y = cvt_pk_bf16(bflo(w.y) + o[2], bfhi(w.y) + o[3]); outl[64 * i] = w; } }
;     astate_init(st);
;     { const int lo = tc - 511 < 0 ? 0 : tc - 511; const int first = t0 < 511 ? 0 : (t0 - 511) >> 5, last = (t0 + 3) >> 5;
.LBB0_890:
	s_waitcnt vmcnt(16)
	global_load_ushort v0, v[76:77], off offset:2
	ds_bpermute_b32 v2, v227, v133
	ds_read2st64_b64 v[36:39], v228 offset0:27 offset1:28
	ds_read2st64_b64 v[40:43], v228 offset0:29 offset1:30
	ds_read2st64_b64 v[44:47], v228 offset0:31 offset1:32
	ds_read2st64_b64 v[48:51], v228 offset0:33 offset1:34
	s_mov_b32 s58, 0
	s_waitcnt lgkmcnt(3)
	v_and_b32_e32 v3, 0xffff0000, v36
	v_lshlrev_b32_e32 v52, 16, v38
	v_add_f32_e32 v64, v133, v2
	ds_bpermute_b32 v65, v226, v64
	v_lshlrev_b32_e32 v2, 16, v36
	v_lshlrev_b32_e32 v36, 16, v37
	v_and_b32_e32 v37, 0xffff0000, v37
	v_and_b32_e32 v53, 0xffff0000, v38
	s_waitcnt lgkmcnt(0)
	v_add_f32_e32 v64, v64, v65
	v_div_scale_f32 v65, s[10:11], v64, v64, 1.0
	v_rcp_f32_e32 v66, v65
	v_div_scale_f32 v67, vcc, 1.0, v64, 1.0
	v_lshlrev_b32_e32 v38, 16, v39
	v_fma_f32 v68, -v65, v66, 1.0
	v_fmac_f32_e32 v66, v68, v66
	v_mul_f32_e32 v68, v67, v66
	v_fma_f32 v69, -v65, v68, v67
	v_fmac_f32_e32 v68, v69, v66
	v_fma_f32 v65, -v65, v68, v67
	v_div_fmas_f32 v65, v65, v66, v68
	v_div_fixup_f32 v65, v65, v64, 1.0
	v_cmp_lt_f32_e32 vcc, 0, v64
	v_and_b32_e32 v39, 0xffff0000, v39
	v_lshlrev_b32_e32 v54, 16, v40
	v_cndmask_b32_e32 v64, 0, v65, vcc
	v_and_b32_e32 v55, 0xffff0000, v40
	v_lshlrev_b32_e32 v40, 16, v41
	v_and_b32_e32 v41, 0xffff0000, v41
	v_lshlrev_b32_e32 v56, 16, v42
	v_and_b32_e32 v57, 0xffff0000, v42
	v_lshlrev_b32_e32 v42, 16, v43
	v_and_b32_e32 v43, 0xffff0000, v43
	v_lshlrev_b32_e32 v58, 16, v44
	v_and_b32_e32 v59, 0xffff0000, v44
	v_lshlrev_b32_e32 v44, 16, v45
	v_and_b32_e32 v45, 0xffff0000, v45
	v_lshlrev_b32_e32 v60, 16, v46
	v_and_b32_e32 v61, 0xffff0000, v46
	v_lshlrev_b32_e32 v46, 16, v47
	v_and_b32_e32 v47, 0xffff0000, v47
	v_lshlrev_b32_e32 v62, 16, v48
	v_and_b32_e32 v63, 0xffff0000, v48
	v_lshlrev_b32_e32 v48, 16, v49
	v_and_b32_e32 v49, 0xffff0000, v49
	s_add_i32 s10, s96, 0xfffffe01
	s_lshr_b32 s10, s10, 5
	s_cmpk_gt_i32 s96, 0x1fe
	s_cselect_b32 s26, s10, 0
	s_ashr_i32 s15, s72, 4
	s_sub_i32 s27, s15, s26
	s_mov_b64 s[12:13], s[52:53]
	s_cmp_lt_i32 s27, 0
	s_waitcnt vmcnt(0)
	v_lshlrev_b32_e32 v0, 16, v0
	v_mul_f32_e32 v0, v64, v0
	v_pk_fma_f32 v[2:3], v[8:9], v[0:1], v[2:3] op_sel_hi:[1,0,1]
	v_pk_fma_f32 v[8:9], v[10:11], v[0:1], v[36:37] op_sel_hi:[1,0,1]
	v_pk_fma_f32 v[10:11], v[12:13], v[0:1], v[52:53] op_sel_hi:[1,0,1]
	v_pk_fma_f32 v[12:13], v[14:15], v[0:1], v[38:39] op_sel_hi:[1,0,1]
	v_pk_fma_f32 v[14:15], v[16:17], v[0:1], v[54:55] op_sel_hi:[1,0,1]
	v_pk_fma_f32 v[16:17], v[18:19], v[0:1], v[40:41] op_sel_hi:[1,0,1]
	v_pk_fma_f32 v[18:19], v[20:21], v[0:1], v[56:57] op_sel_hi:[1,0,1]
	v_pk_fma_f32 v[20:21], v[22:23], v[0:1], v[42:43] op_sel_hi:[1,0,1]
	v_pk_fma_f32 v[22:23], v[24:25], v[0:1], v[58:59] op_sel_hi:[1,0,1]
	v_pk_fma_f32 v[24:25], v[26:27], v[0:1], v[44:45] op_sel_hi:[1,0,1]
	v_pk_fma_f32 v[26:27], v[32:33], v[0:1], v[60:61] op_sel_hi:[1,0,1]
	v_pk_fma_f32 v[32:33], v[34:35], v[0:1], v[46:47] op_sel_hi:[1,0,1]
	v_cvt_pk_bf16_f32 v2, v2, v3
	v_cvt_pk_bf16_f32 v3, v8, v9
	v_cvt_pk_bf16_f32 v8, v10, v11
	v_cvt_pk_bf16_f32 v9, v12, v13
	v_cvt_pk_bf16_f32 v10, v14, v15
	v_cvt_pk_bf16_f32 v11, v16, v17
	v_cvt_pk_bf16_f32 v12, v18, v19
	v_cvt_pk_bf16_f32 v13, v20, v21
	v_cvt_pk_bf16_f32 v14, v22, v23
	v_cvt_pk_bf16_f32 v15, v24, v25
	v_cvt_pk_bf16_f32 v16, v26, v27
	v_cvt_pk_bf16_f32 v17, v32, v33
	ds_write2st64_b64 v228, v[2:3], v[8:9] offset0:27 offset1:28
	ds_write2st64_b64 v228, v[10:11], v[12:13] offset0:29 offset1:30
	ds_write2st64_b64 v228, v[14:15], v[16:17] offset0:31 offset1:32
	v_pk_fma_f32 v[2:3], v[30:31], v[0:1], v[48:49] op_sel_hi:[1,0,1]
	v_pk_fma_f32 v[28:29], v[28:29], v[0:1], v[62:63] op_sel_hi:[1,0,1]
	v_cvt_pk_bf16_f32 v19, v2, v3
	v_lshlrev_b32_e32 v2, 16, v50
	v_and_b32_e32 v3, 0xffff0000, v50
	v_pk_fma_f32 v[2:3], v[4:5], v[0:1], v[2:3] op_sel_hi:[1,0,1]
	v_lshlrev_b32_e32 v4, 16, v51
	v_and_b32_e32 v5, 0xffff0000, v51
	v_pk_fma_f32 v[4:5], v[6:7], v[0:1], v[4:5] op_sel_hi:[1,0,1]
	v_cvt_pk_bf16_f32 v18, v28, v29
	v_cvt_pk_bf16_f32 v2, v2, v3
	v_cvt_pk_bf16_f32 v3, v4, v5
	ds_write2st64_b64 v228, v[18:19], v[2:3] offset0:33 offset1:34
	s_cbranch_scc1 .LBB0_825
; template <bool SLC, class Desc>
; __device__ __forceinline__ void attn_run_frag8(const i64_t (&qf)[4], const unsigned char* __restrict__ KF, const unsigned char* __restrict__ VF, const Desc& desc, int n,
;                                                int lo_in, int hi, int qi, AState& st, int lane) {
;     ...
;     Frag8 fa, fb, fc;
;     constexpr int NM = ~(1 << 30);
;     int d0 = desc(0), d1 = desc(n > 1 ? 1 : 0);
;     load_frag8(fa, KF, VF, SLC ? (d0 & 0xfffff) : (d0 & NM), lane);
;     load_frag8(fb, KF, VF, SLC ? (d1 & 0xfffff) : (d1 & NM), lane);
; __device__ __forceinline__ void nsa_unit(int unit, const bf16_t* proj, const bf16_t* kc, const bf16_t* vc, const bf16_t* gn, const float* cs, const float* sn, ...
;     ...
;     { const int lo = tc - 511 < 0 ? 0 : tc - 511; const int first = t0 < 511 ? 0 : (t0 - 511) >> 5, last = (t0 + 3) >> 5;
;       auto desc = [&](int i) { const int p0 = 32 * (first + i); return p0 | ((p0 >= t0 + 3 - 511 && p0 + 31 <= t0) ? (1 << 30) : 0); };
;       unsigned long long goff = (unsigned long long)g * S * 128; asm volatile("" : "+s"(goff));
;       attn_run_frag8<false>(q8, (const unsigned char*)kslf + ((size_t)16 << 20) + goff, (const unsigned char*)kslf + ((size_t)24 << 20) + goff, desc, last - first + 1, lo, tc, 0, st, lane); }
	s_add_u32 s10, s81, s12
	s_addc_u32 s11, s82, s13
	s_add_u32 s12, s83, s12
	s_addc_u32 s13, s84, s13
	s_lshl_b32 s20, s26, 5
	s_add_i32 s56, s96, 0xfffffe04
	s_cmp_lt_i32 s20, s56
	s_cselect_b64 s[16:17], -1, 0
	s_or_b32 s14, s20, 31
	s_cmp_gt_i32 s14, s96
	s_cselect_b64 s[18:19], -1, 0
	s_or_b64 s[16:17], s[16:17], s[18:19]
	s_and_b64 s[16:17], s[16:17], exec
	s_cselect_b32 s14, 0, 2.0
	s_or_b32 s14, s14, s20
	s_cmp_lg_u32 s15, s26
	s_cselect_b64 s[16:17], -1, 0
	v_cndmask_b32_e64 v0, 0, 1, s[16:17]
	v_lshl_add_u64 v[86:87], s[12:13], 0, v[118:119]
	v_readfirstlane_b32 s15, v0
	s_add_i32 s15, s26, s15
	s_lshl_b32 s21, s15, 5
	s_cmp_lt_i32 s21, s56
	s_cselect_b64 s[16:17], -1, 0
	s_or_b32 s18, s21, 31
	s_cmp_gt_i32 s18, s96
	s_cselect_b64 s[18:19], -1, 0
	s_or_b64 s[16:17], s[16:17], s[18:19]
	s_and_b64 s[16:17], s[16:17], exec
	s_cselect_b32 s16, 0, 2.0
	s_or_b32 s66, s16, s21
	s_and_b32 s16, s20, 0x3fffffe0
	s_lshr_b32 s50, s16, 4
	s_lshl_b64 s[16:17], s[50:51], 11
	s_add_u32 s16, s12, s16
	s_addc_u32 s17, s13, s17
	s_and_b32 s50, s26, 0x1ffffff
	v_lshl_add_u64 v[2:3], s[16:17], 0, v[118:119]
	s_lshl_b64 s[16:17], s[50:51], 12
	s_add_u32 s16, s10, s16
	s_addc_u32 s17, s11, s17
	global_load_dwordx2 v[150:151], v[2:3], off
	global_load_dwordx2 v[152:153], v[2:3], off offset:512
	global_load_dwordx2 v[148:149], v[2:3], off offset:1024
	global_load_dwordx2 v[146:147], v[2:3], off offset:1536
	global_load_dwordx2 v[144:145], v[2:3], off offset:2048
	global_load_dwordx2 v[142:143], v[2:3], off offset:2560
	global_load_dwordx2 v[140:141], v[2:3], off offset:3072
	global_load_dwordx2 v[138:139], v[2:3], off offset:3584
	v_lshl_add_u64 v[2:3], s[16:17], 0, v[118:119]
	s_and_b32 s16, s21, 0x3fffffe0
	s_lshr_b32 s50, s16, 4
	s_lshl_b64 s[16:17], s[50:51], 11
	s_add_u32 s16, s12, s16
	s_addc_u32 s17, s13, s17
	s_and_b32 s50, s15, 0x1ffffff
	global_load_dwordx2 v[90:91], v[2:3], off
	global_load_dwordx2 v[92:93], v[2:3], off offset:512
	global_load_dwordx2 v[94:95], v[2:3], off offset:1024
	global_load_dwordx2 v[96:97], v[2:3], off offset:1536
	global_load_dwordx2 v[104:105], v[2:3], off offset:2048
	global_load_dwordx2 v[100:101], v[2:3], off offset:2560
	global_load_dwordx2 v[102:103], v[2:3], off offset:3072
	global_load_dwordx2 v[98:99], v[2:3], off offset:3584
	v_lshl_add_u64 v[2:3], s[16:17], 0, v[118:119]
	s_lshl_b64 s[16:17], s[50:51], 12
	s_add_u32 s16, s10, s16
	s_addc_u32 s17, s11, s17
	global_load_dwordx2 v[166:167], v[2:3], off
	global_load_dwordx2 v[168:169], v[2:3], off offset:512
	global_load_dwordx2 v[164:165], v[2:3], off offset:1024
	global_load_dwordx2 v[162:163], v[2:3], off offset:1536
	global_load_dwordx2 v[160:161], v[2:3], off offset:2048
	global_load_dwordx2 v[158:159], v[2:3], off offset:2560
	global_load_dwordx2 v[156:157], v[2:3], off offset:3072
	global_load_dwordx2 v[154:155], v[2:3], off offset:3584
	v_lshl_add_u64 v[2:3], s[16:17], 0, v[118:119]
	global_load_dwordx2 v[106:107], v[2:3], off
	global_load_dwordx2 v[110:111], v[2:3], off offset:512
	global_load_dwordx2 v[112:113], v[2:3], off offset:1024
	global_load_dwordx2 v[116:117], v[2:3], off offset:1536
	global_load_dwordx2 v[136:137], v[2:3], off offset:2048
	global_load_dwordx2 v[134:135], v[2:3], off offset:2560
	global_load_dwordx2 v[114:115], v[2:3], off offset:3072
	global_load_dwordx2 v[108:109], v[2:3], off offset:3584
	v_max_i32_e32 v0, 0x1ff, v132
	v_mov_b32_e32 v2, v1
	v_mov_b32_e32 v3, v1
	v_add_u32_e32 v35, 0xfffffe01, v0
	v_mov_b32_e32 v0, v1
	v_mov_b64_e32 v[38:39], v[2:3]
	v_mov_b64_e32 v[42:43], v[2:3]
	v_mov_b64_e32 v[46:47], v[2:3]
	v_mov_b64_e32 v[50:51], v[2:3]
	v_mov_b64_e32 v[54:55], v[2:3]
	v_mov_b64_e32 v[58:59], v[2:3]
	v_mov_b64_e32 v[62:63], v[2:3]
	v_mov_b64_e32 v[66:67], v[2:3]
	v_lshl_add_u64 v[88:89], s[10:11], 0, v[118:119]
	v_mov_b32_e32 v133, 0xf149f2ca
	v_mov_b32_e32 v230, 0
	v_mov_b64_e32 v[36:37], v[0:1]
	v_mov_b64_e32 v[40:41], v[0:1]
	v_mov_b64_e32 v[44:45], v[0:1]
	v_mov_b64_e32 v[48:49], v[0:1]
	v_mov_b64_e32 v[52:53], v[0:1]
	v_mov_b64_e32 v[56:57], v[0:1]
	v_mov_b64_e32 v[60:61], v[0:1]
	v_mov_b64_e32 v[64:65], v[0:1]
	s_branch .LBB0_894

; template <bool SLC, bool NOMASK> ...
;     const int kq = lane >> 4;
;     const int pos0 = SLC ? (dcur & 0xfffff) : dcur;
;     const int lo = SLC ? ((((dcur >> 20) == qi) | ((dcur >> 20) == 4)) ? 0 : (1 << 30)) : lo_in;
;     load_frag8(nxt, KF, VF, SLC ? (dnext & 0xfffff) : dnext, lane);
;     f32x4 sa[2] = {(f32x4){0.f, 0.f, 0.f, 0.f}, (f32x4){0.f, 0.f, 0.f, 0.f}};
; #pragma unroll
;     for (int T = 0; T < 2; ++T)
; #pragma unroll
;         for (int s2 = 0; s2 < 4; ++s2) sa[T] = __builtin_amdgcn_mfma_f32_16x16x32_fp8_fp8(cur.k[T][s2], qf[s2], sa[T], 0, 0, 0);
;     float sc[8]; bool vd[8]; float mx = -1e30f;
;     const bool act = lo == 0 || !SLC;
;     if (NOMASK) {
; #pragma unroll
;         for (int j = 0; j < 8; ++j) { sc[j] = sa[j >> 2][j & 3]; vd[j] = act; }
;         mx = fmaxf(fmaxf(fmaxf(sc[0], sc[1]), fmaxf(sc[2], sc[3])), fmaxf(fmaxf(sc[4], sc[5]), fmaxf(sc[6], sc[7])));
;         mx = act ? mx : -1e30f;
;     } else {
; #pragma unroll
;         for (int T = 0; T < 2; ++T)
; #pragma unroll
;             for (int r = 0; r < 4; ++r) { const int p = pos0 + 16 * T + 4 * kq + r; const bool v = (p >= lo) & (p <= hi); const float x = sa[T][r];
;                 sc[4 * T + r] = x; vd[4 * T + r] = v; mx = v ? fmaxf(mx, x) : mx; }
;     }
;     if (__builtin_amdgcn_ballot_w64(mx > st.m + 4.f) != 0ull) {
;         mx = fmaxf(mx, __shfl_xor(mx, 16)); mx = fmaxf(mx, __shfl_xor(mx, 32));
;         const float mn = fmaxf(st.m, mx), alpha = __builtin_amdgcn_exp2f(st.m - mn); st.m = mn; st.l *= alpha;
; #pragma unroll
;         for (int j = 0; j < 8; ++j) st.o[j] = st.o[j] * alpha;
;     }
;     f32x4 pa, pb; float ps = 0.f;
;     const float mref = st.m - 4.f;
;     if (NOMASK) {
; #pragma unroll
;         for (int j = 0; j < 4; ++j) { pa[j] = __builtin_amdgcn_exp2f(sc[j] - mref); pb[j] = __builtin_amdgcn_exp2f(sc[4 + j] - mref); }
;         if (SLC) {
; #pragma unroll
;             for (int j = 0; j < 4; ++j) { pa[j] = act ? pa[j] : 0.f; pb[j] = act ? pb[j] : 0.f; }
;         }
; #pragma unroll
;         for (int j = 0; j < 4; ++j) ps += pa[j] + pb[j];
;     } else {
; #pragma unroll
;         for (int j = 0; j < 4; ++j) { pa[j] = vd[j] ? __builtin_amdgcn_exp2f(sc[j] - mref) : 0.f; pb[j] = vd[4 + j] ? __builtin_amdgcn_exp2f(sc[4 + j] - mref) : 0.f; ps += pa[j] + pb[j]; }
;     }
;     st.l += ps;
;     const u32x2 pw = pack8_fp8(pa, pb);
.LBB0_900:
	global_load_dwordx2 v[194:195], v[204:205], off
	global_load_dwordx2 v[200:201], v[204:205], off offset:512
	global_load_dwordx2 v[198:199], v[204:205], off offset:1024
	global_load_dwordx2 v[192:193], v[204:205], off offset:1536
	global_load_dwordx2 v[196:197], v[204:205], off offset:2048
	global_load_dwordx2 v[190:191], v[204:205], off offset:2560
	global_load_dwordx2 v[188:189], v[204:205], off offset:3072
	global_load_dwordx2 v[186:187], v[204:205], off offset:3584
	global_load_dwordx2 v[170:171], v[202:203], off
	global_load_dwordx2 v[172:173], v[202:203], off offset:512
	global_load_dwordx2 v[174:175], v[202:203], off offset:1024
	global_load_dwordx2 v[176:177], v[202:203], off offset:1536
	global_load_dwordx2 v[184:185], v[202:203], off offset:2048
	global_load_dwordx2 v[180:181], v[202:203], off offset:2560
	global_load_dwordx2 v[182:183], v[202:203], off offset:3072
	global_load_dwordx2 v[178:179], v[202:203], off offset:3584
	s_waitcnt vmcnt(47)
	v_mfma_f32_16x16x32_fp8_fp8 v[2:5], v[150:151], v[78:79], 0
	v_mov_b64_e32 v[74:75], v[38:39]
	v_mov_b64_e32 v[70:71], v[42:43]
	v_mov_b64_e32 v[30:31], v[44:45]
	s_waitcnt vmcnt(43)
	v_mfma_f32_16x16x32_fp8_fp8 v[6:9], v[144:145], v[78:79], 0
	v_mov_b64_e32 v[26:27], v[48:49]
	v_mov_b64_e32 v[22:23], v[52:53]
	v_mov_b64_e32 v[18:19], v[56:57]
	v_mfma_f32_16x16x32_fp8_fp8 v[2:5], v[152:153], v[80:81], v[2:5]
	v_mov_b64_e32 v[14:15], v[60:61]
	v_mov_b32_e32 v229, v133
	v_mov_b64_e32 v[72:73], v[36:37]
	s_waitcnt vmcnt(42)
	v_mfma_f32_16x16x32_fp8_fp8 v[6:9], v[142:143], v[80:81], v[6:9]
	v_mov_b64_e32 v[68:69], v[40:41]
	v_mov_b64_e32 v[32:33], v[46:47]
	v_mov_b64_e32 v[28:29], v[50:51]
	v_mfma_f32_16x16x32_fp8_fp8 v[2:5], v[148:149], v[82:83], v[2:5]
	v_mov_b64_e32 v[24:25], v[54:55]
	v_mov_b64_e32 v[20:21], v[58:59]
	v_mov_b64_e32 v[16:17], v[62:63]
	s_waitcnt vmcnt(41)
	v_mfma_f32_16x16x32_fp8_fp8 v[6:9], v[140:141], v[82:83], v[6:9]
	v_mov_b32_e32 v34, v230
	v_mfma_f32_16x16x32_fp8_fp8 v[2:5], v[146:147], v[84:85], v[2:5]
	s_waitcnt vmcnt(40)
	v_mfma_f32_16x16x32_fp8_fp8 v[6:9], v[138:139], v[84:85], v[6:9]
	s_nop 5
	v_max_f32_e32 v0, v3, v3
	v_max_f32_e32 v10, v2, v2
	v_max_f32_e32 v0, v10, v0
	v_max_f32_e32 v10, v5, v5
	v_max_f32_e32 v11, v4, v4
	v_max_f32_e32 v10, v11, v10
	v_max_f32_e32 v11, v9, v9
	v_max_f32_e32 v12, v8, v8
	v_max_f32_e32 v11, v12, v11
	v_max3_f32 v11, v6, v7, v11
	v_max3_f32 v0, v0, v10, v11
	v_mov_b64_e32 v[10:11], v[64:65]
	v_cmp_gt_f32_e32 vcc, v0, v231
	v_mov_b64_e32 v[12:13], v[66:67]
	s_cbranch_vccz .LBB0_902
	ds_bpermute_b32 v10, v227, v0
	v_max_f32_e32 v0, v0, v0
	s_waitcnt lgkmcnt(0)
	v_max_f32_e32 v10, v10, v10
	v_max_f32_e32 v0, v0, v10
	ds_bpermute_b32 v10, v226, v0
	s_waitcnt lgkmcnt(0)
	v_max3_f32 v229, v133, v0, v10
	v_sub_f32_e32 v0, v133, v229
	v_exp_f32_e32 v0, v0
	s_nop 0
	v_mul_f32_e32 v34, v230, v0
	v_pk_mul_f32 v[12:13], v[66:67], v[0:1] op_sel_hi:[1,0]
	v_pk_mul_f32 v[10:11], v[64:65], v[0:1] op_sel_hi:[1,0]
	v_pk_mul_f32 v[16:17], v[62:63], v[0:1] op_sel_hi:[1,0]
	v_pk_mul_f32 v[14:15], v[60:61], v[0:1] op_sel_hi:[1,0]
	v_pk_mul_f32 v[20:21], v[58:59], v[0:1] op_sel_hi:[1,0]
	v_pk_mul_f32 v[18:19], v[56:57], v[0:1] op_sel_hi:[1,0]
	v_pk_mul_f32 v[24:25], v[54:55], v[0:1] op_sel_hi:[1,0]
	v_pk_mul_f32 v[22:23], v[52:53], v[0:1] op_sel_hi:[1,0]
	v_pk_mul_f32 v[28:29], v[50:51], v[0:1] op_sel_hi:[1,0]
	v_pk_mul_f32 v[26:27], v[48:49], v[0:1] op_sel_hi:[1,0]
	v_pk_mul_f32 v[32:33], v[46:47], v[0:1] op_sel_hi:[1,0]
	v_pk_mul_f32 v[30:31], v[44:45], v[0:1] op_sel_hi:[1,0]
	v_pk_mul_f32 v[70:71], v[42:43], v[0:1] op_sel_hi:[1,0]
	v_pk_mul_f32 v[68:69], v[40:41], v[0:1] op_sel_hi:[1,0]
	v_pk_mul_f32 v[74:75], v[38:39], v[0:1] op_sel_hi:[1,0]
	v_pk_mul_f32 v[72:73], v[36:37], v[0:1] op_sel_hi:[1,0]
.LBB0_902:
	v_add_f32_e32 v232, -4.0, v229
	v_sub_f32_e32 v0, v2, v232
	v_exp_f32_e32 v233, v0
	v_sub_f32_e32 v0, v6, v232
	v_exp_f32_e32 v236, v0
	v_sub_f32_e32 v0, v3, v232
	v_exp_f32_e32 v2, v0
	v_sub_f32_e32 v0, v7, v232
	v_exp_f32_e32 v0, v0
	v_sub_f32_e32 v3, v4, v232
	v_exp_f32_e32 v237, v3
	v_sub_f32_e32 v3, v8, v232
	v_exp_f32_e32 v238, v3
	v_sub_f32_e32 v3, v5, v232
	v_exp_f32_e32 v4, v3
	v_sub_f32_e32 v3, v9, v232
	v_mov_b32_e32 v234, v1
	v_mov_b32_e32 v235, v1
	v_exp_f32_e32 v232, v3
	v_cvt_pk_fp8_f32 v234, v233, v2
	v_cvt_pk_fp8_f32 v235, v236, v0
	v_add_f32_e32 v3, v233, v236
	v_pk_add_f32 v[2:3], v[2:3], v[0:1]
	v_cvt_pk_fp8_f32 v234, v237, v4 op_sel:[0,0,1]
	v_cvt_pk_fp8_f32 v235, v238, v232 op_sel:[0,0,1]
	v_pk_add_f32 v[2:3], v[2:3], v[2:3] op_sel_hi:[0,1]
	v_add_f32_e32 v5, v237, v238
	v_mov_b32_e32 v233, v3
	v_pk_add_f32 v[2:3], v[4:5], v[232:233]
	s_waitcnt vmcnt(39)
	v_mfma_f32_16x16x32_fp8_fp8 v[6:9], v[90:91], v[234:235], v[10:13]
	v_add_f32_e32 v0, v2, v3
	v_add_f32_e32 v34, v0, v34
	s_waitcnt vmcnt(38)
	v_mfma_f32_16x16x32_fp8_fp8 v[10:13], v[92:93], v[234:235], v[14:17]
	s_waitcnt vmcnt(37)
	v_mfma_f32_16x16x32_fp8_fp8 v[14:17], v[94:95], v[234:235], v[18:21]
	s_waitcnt vmcnt(36)
	v_mfma_f32_16x16x32_fp8_fp8 v[18:21], v[96:97], v[234:235], v[22:25]
	s_waitcnt vmcnt(35)
	v_mfma_f32_16x16x32_fp8_fp8 v[22:25], v[104:105], v[234:235], v[26:29]
	s_waitcnt vmcnt(34)
	v_mfma_f32_16x16x32_fp8_fp8 v[26:29], v[100:101], v[234:235], v[30:33]
	s_waitcnt vmcnt(33)
	v_mfma_f32_16x16x32_fp8_fp8 v[30:33], v[102:103], v[234:235], v[68:71]
	s_waitcnt vmcnt(32)
	v_mfma_f32_16x16x32_fp8_fp8 v[2:5], v[98:99], v[234:235], v[72:75]
	s_branch .LBB0_896
; template <bool SLC, bool NOMASK> ...
;     const int kq = lane >> 4;
;     const int pos0 = SLC ? (dcur & 0xfffff) : dcur;
;     const int lo = SLC ? ((((dcur >> 20) == qi) | ((dcur >> 20) == 4)) ? 0 : (1 << 30)) : lo_in;
;     load_frag8(nxt, KF, VF, SLC ? (dnext & 0xfffff) : dnext, lane);
;     f32x4 sa[2] = {(f32x4){0.f, 0.f, 0.f, 0.f}, (f32x4){0.f, 0.f, 0.f, 0.f}};
; #pragma unroll
;     for (int T = 0; T < 2; ++T)
; #pragma unroll
;         for (int s2 = 0; s2 < 4; ++s2) sa[T] = __builtin_amdgcn_mfma_f32_16x16x32_fp8_fp8(cur.k[T][s2], qf[s2], sa[T], 0, 0, 0);
;     float sc[8]; bool vd[8]; float mx = -1e30f;
;     const bool act = lo == 0 || !SLC;
;     if (NOMASK) {
; #pragma unroll
;         for (int j = 0; j < 8; ++j) { sc[j] = sa[j >> 2][j & 3]; vd[j] = act; }
;         mx = fmaxf(fmaxf(fmaxf(sc[0], sc[1]), fmaxf(sc[2], sc[3])), fmaxf(fmaxf(sc[4], sc[5]), fmaxf(sc[6], sc[7])));
;         mx = act ? mx : -1e30f;
;     } else {
; #pragma unroll
;         for (int T = 0; T < 2; ++T)
; #pragma unroll
;             for (int r = 0; r < 4; ++r) { const int p = pos0 + 16 * T + 4 * kq + r; const bool v = (p >= lo) & (p <= hi); const float x = sa[T][r];
;                 sc[4 * T + r] = x; vd[4 * T + r] = v; mx = v ? fmaxf(mx, x) : mx; }
;     }
;     if (__builtin_amdgcn_ballot_w64(mx > st.m + 4.f) != 0ull) {
;         mx = fmaxf(mx, __shfl_xor(mx, 16)); mx = fmaxf(mx, __shfl_xor(mx, 32));
;         const float mn = fmaxf(st.m, mx), alpha = __builtin_amdgcn_exp2f(st.m - mn); st.m = mn; st.l *= alpha;
; #pragma unroll
;         for (int j = 0; j < 8; ++j) st.o[j] = st.o[j] * alpha;
;     }
;     f32x4 pa, pb; float ps = 0.f;
;     const float mref = st.m - 4.f;
;     if (NOMASK) {
; #pragma unroll
;         for (int j = 0; j < 4; ++j) { pa[j] = __builtin_amdgcn_exp2f(sc[j] - mref); pb[j] = __builtin_amdgcn_exp2f(sc[4 + j] - mref); }
;         if (SLC) {
; #pragma unroll
;             for (int j = 0; j < 4; ++j) { pa[j] = act ? pa[j] : 0.f; pb[j] = act ? pb[j] : 0.f; }
;         }
; #pragma unroll
;         for (int j = 0; j < 4; ++j) ps += pa[j] + pb[j];
;     } else {
; #pragma unroll
;         for (int j = 0; j < 4; ++j) { pa[j] = vd[j] ? __builtin_amdgcn_exp2f(sc[j] - mref) : 0.f; pb[j] = vd[4 + j] ? __builtin_amdgcn_exp2f(sc[4 + j] - mref) : 0.f; ps += pa[j] + pb[j]; }
;     }
;     st.l += ps;
;     const u32x2 pw = pack8_fp8(pa, pb);
.LBB0_903:
	global_load_dwordx2 v[194:195], v[204:205], off
	global_load_dwordx2 v[200:201], v[204:205], off offset:512
	global_load_dwordx2 v[198:199], v[204:205], off offset:1024
	global_load_dwordx2 v[192:193], v[204:205], off offset:1536
	global_load_dwordx2 v[196:197], v[204:205], off offset:2048
	global_load_dwordx2 v[190:191], v[204:205], off offset:2560
	global_load_dwordx2 v[188:189], v[204:205], off offset:3072
	global_load_dwordx2 v[186:187], v[204:205], off offset:3584
	global_load_dwordx2 v[170:171], v[202:203], off
	global_load_dwordx2 v[172:173], v[202:203], off offset:512
	global_load_dwordx2 v[174:175], v[202:203], off offset:1024
	global_load_dwordx2 v[176:177], v[202:203], off offset:1536
	global_load_dwordx2 v[184:185], v[202:203], off offset:2048
	global_load_dwordx2 v[180:181], v[202:203], off offset:2560
	global_load_dwordx2 v[182:183], v[202:203], off offset:3072
	global_load_dwordx2 v[178:179], v[202:203], off offset:3584
	s_waitcnt vmcnt(47)
	v_mfma_f32_16x16x32_fp8_fp8 v[2:5], v[150:151], v[78:79], 0
	v_add_u32_e32 v0, s14, v211
	v_cmp_ge_i32_e32 vcc, v0, v35
	v_cmp_le_i32_e64 s[10:11], v0, v132
	s_waitcnt vmcnt(46)
	v_mfma_f32_16x16x32_fp8_fp8 v[2:5], v[152:153], v[80:81], v[2:5]
	s_and_b64 s[16:17], vcc, s[10:11]
	v_add_u32_e32 v11, 1, v0
	v_cmp_ge_i32_e32 vcc, v11, v35
	s_waitcnt vmcnt(45)
	v_mfma_f32_16x16x32_fp8_fp8 v[2:5], v[148:149], v[82:83], v[2:5]
	v_cmp_lt_i32_e64 s[10:11], v0, v132
	s_and_b64 s[12:13], s[10:11], vcc
	s_waitcnt vmcnt(43)
	v_mfma_f32_16x16x32_fp8_fp8 v[6:9], v[144:145], v[78:79], 0
	v_mfma_f32_16x16x32_fp8_fp8 v[2:5], v[146:147], v[84:85], v[2:5]
	s_waitcnt vmcnt(42)
	v_mfma_f32_16x16x32_fp8_fp8 v[6:9], v[142:143], v[80:81], v[6:9]
	s_waitcnt vmcnt(41)
	v_mfma_f32_16x16x32_fp8_fp8 v[6:9], v[140:141], v[82:83], v[6:9]
	s_nop 3
	v_max_f32_e32 v10, v2, v2
	v_max_f32_e32 v10, 0xf149f2ca, v10
	v_cndmask_b32_e64 v10, v223, v10, s[16:17]
	v_max_f32_e32 v11, v3, v3
	v_max_f32_e32 v11, v10, v11
	v_cndmask_b32_e64 v10, v10, v11, s[12:13]
	v_add_u32_e32 v11, 2, v0
	v_cmp_ge_i32_e32 vcc, v11, v35
	v_cmp_le_i32_e64 s[10:11], v11, v132
	v_max_f32_e32 v11, v4, v4
	v_max_f32_e32 v11, v10, v11
	s_and_b64 s[14:15], vcc, s[10:11]
	s_waitcnt vmcnt(40)
	v_mfma_f32_16x16x32_fp8_fp8 v[6:9], v[138:139], v[84:85], v[6:9]
	v_cndmask_b32_e64 v10, v10, v11, s[14:15]
	v_add_u32_e32 v11, 3, v0
	v_cmp_ge_i32_e32 vcc, v11, v35
	v_cmp_le_i32_e64 s[10:11], v11, v132
	v_max_f32_e32 v11, v5, v5
	v_max_f32_e32 v11, v10, v11
	s_and_b64 s[10:11], vcc, s[10:11]
	v_cndmask_b32_e64 v10, v10, v11, s[10:11]
	v_add_u32_e32 v11, 16, v0
	v_cmp_ge_i32_e32 vcc, v11, v35
	v_cmp_le_i32_e64 s[18:19], v11, v132
	v_max_f32_e32 v11, v6, v6
	v_max_f32_e32 v11, v10, v11
	s_and_b64 s[24:25], vcc, s[18:19]
	v_cndmask_b32_e64 v10, v10, v11, s[24:25]
	v_add_u32_e32 v11, 17, v0
	v_cmp_ge_i32_e32 vcc, v11, v35
	v_cmp_le_i32_e64 s[18:19], v11, v132
	v_max_f32_e32 v11, v10, v10
	v_max_f32_e32 v12, v7, v7
	v_max_f32_e32 v11, v11, v12
	s_and_b64 s[20:21], vcc, s[18:19]
	v_cndmask_b32_e64 v10, v10, v11, s[20:21]
	v_add_u32_e32 v11, 18, v0
	v_cmp_ge_i32_e32 vcc, v11, v35
	v_cmp_le_i32_e64 s[18:19], v11, v132
	v_max_f32_e32 v11, v10, v10
	v_max_f32_e32 v12, v8, v8
	v_max_f32_e32 v11, v11, v12
	s_and_b64 s[22:23], vcc, s[18:19]
	v_cndmask_b32_e64 v10, v10, v11, s[22:23]
	v_add_u32_e32 v0, 19, v0
	v_cmp_ge_i32_e32 vcc, v0, v35
	v_cmp_le_i32_e64 s[18:19], v0, v132
	v_max_f32_e32 v0, v10, v10
	v_max_f32_e32 v11, v9, v9
	v_max_f32_e32 v0, v0, v11
	s_and_b64 s[18:19], vcc, s[18:19]
	v_cndmask_b32_e64 v0, v10, v0, s[18:19]
	v_cmp_gt_f32_e32 vcc, v0, v231
	s_cbranch_vccz .LBB0_905
	ds_bpermute_b32 v10, v227, v0
	v_max_f32_e32 v0, v0, v0
	s_waitcnt lgkmcnt(0)
	v_max_f32_e32 v10, v10, v10
	v_max_f32_e32 v0, v0, v10
	ds_bpermute_b32 v10, v226, v0
	s_waitcnt lgkmcnt(0)
	v_max3_f32 v10, v133, v0, v10
	v_sub_f32_e32 v0, v133, v10
	v_exp_f32_e32 v0, v0
	v_mov_b32_e32 v133, v10
	v_mul_f32_e32 v230, v230, v0
	v_pk_mul_f32 v[66:67], v[66:67], v[0:1] op_sel_hi:[1,0]
	v_pk_mul_f32 v[64:65], v[64:65], v[0:1] op_sel_hi:[1,0]
	v_pk_mul_f32 v[62:63], v[62:63], v[0:1] op_sel_hi:[1,0]
	v_pk_mul_f32 v[60:61], v[60:61], v[0:1] op_sel_hi:[1,0]
	v_pk_mul_f32 v[58:59], v[58:59], v[0:1] op_sel_hi:[1,0]
	v_pk_mul_f32 v[56:57], v[56:57], v[0:1] op_sel_hi:[1,0]
	v_pk_mul_f32 v[54:55], v[54:55], v[0:1] op_sel_hi:[1,0]
	v_pk_mul_f32 v[52:53], v[52:53], v[0:1] op_sel_hi:[1,0]
	v_pk_mul_f32 v[50:51], v[50:51], v[0:1] op_sel_hi:[1,0]
	v_pk_mul_f32 v[48:49], v[48:49], v[0:1] op_sel_hi:[1,0]
	v_pk_mul_f32 v[46:47], v[46:47], v[0:1] op_sel_hi:[1,0]
	v_pk_mul_f32 v[44:45], v[44:45], v[0:1] op_sel_hi:[1,0]
	v_pk_mul_f32 v[42:43], v[42:43], v[0:1] op_sel_hi:[1,0]
	v_pk_mul_f32 v[40:41], v[40:41], v[0:1] op_sel_hi:[1,0]
	v_pk_mul_f32 v[38:39], v[38:39], v[0:1] op_sel_hi:[1,0]
	v_pk_mul_f32 v[36:37], v[36:37], v[0:1] op_sel_hi:[1,0]
.LBB0_905:
	v_add_f32_e32 v0, -4.0, v133
	v_sub_f32_e32 v2, v2, v0
	v_exp_f32_e32 v2, v2
	v_sub_f32_e32 v6, v6, v0
	v_exp_f32_e32 v6, v6
	v_sub_f32_e32 v4, v4, v0
	v_cndmask_b32_e64 v26, 0, v2, s[16:17]
	v_sub_f32_e32 v2, v3, v0
	v_exp_f32_e32 v2, v2
	v_sub_f32_e32 v3, v7, v0
	v_exp_f32_e32 v3, v3
	v_cndmask_b32_e64 v27, 0, v6, s[24:25]
	v_sub_f32_e32 v6, v8, v0
	v_cndmask_b32_e64 v28, 0, v2, s[12:13]
	v_sub_f32_e32 v2, v5, v0
	v_sub_f32_e32 v0, v9, v0
	v_exp_f32_e32 v4, v4
	v_exp_f32_e32 v6, v6
	v_cndmask_b32_e64 v29, 0, v3, s[20:21]
	v_exp_f32_e32 v5, v2
	v_exp_f32_e32 v0, v0
	v_mov_b32_e32 v2, v1
	v_mov_b32_e32 v3, v1
	v_cvt_pk_fp8_f32 v2, v26, v28
	v_cvt_pk_fp8_f32 v3, v27, v29
	v_cndmask_b32_e64 v4, 0, v4, s[14:15]
	v_cndmask_b32_e64 v30, 0, v6, s[22:23]
	v_cndmask_b32_e64 v5, 0, v5, s[10:11]
	v_cndmask_b32_e64 v0, 0, v0, s[18:19]
	v_cvt_pk_fp8_f32 v2, v4, v5 op_sel:[0,0,1]
	v_cvt_pk_fp8_f32 v3, v30, v0 op_sel:[0,0,1]
	v_add_f32_e32 v26, v26, v27
	v_add_f32_e32 v31, 0, v26
	v_add_f32_e32 v32, v28, v29
	v_add_f32_e32 v31, v32, v31
	v_add_f32_e32 v4, v4, v30
	v_add_f32_e32 v4, v4, v31
	v_add_f32_e32 v0, v5, v0
	s_waitcnt vmcnt(39)
	v_mfma_f32_16x16x32_fp8_fp8 v[6:9], v[90:91], v[2:3], v[64:67]
	v_add_f32_e32 v0, v0, v4
	v_add_f32_e32 v34, v230, v0
	v_mov_b32_e32 v229, v133
	s_waitcnt vmcnt(38)
	v_mfma_f32_16x16x32_fp8_fp8 v[10:13], v[92:93], v[2:3], v[60:63]
	s_waitcnt vmcnt(37)
	v_mfma_f32_16x16x32_fp8_fp8 v[14:17], v[94:95], v[2:3], v[56:59]
	s_waitcnt vmcnt(36)
	v_mfma_f32_16x16x32_fp8_fp8 v[18:21], v[96:97], v[2:3], v[52:55]
	s_waitcnt vmcnt(35)
	v_mfma_f32_16x16x32_fp8_fp8 v[22:25], v[104:105], v[2:3], v[48:51]
	s_waitcnt vmcnt(34)
	v_mfma_f32_16x16x32_fp8_fp8 v[26:29], v[100:101], v[2:3], v[44:47]
	s_waitcnt vmcnt(33)
	v_mfma_f32_16x16x32_fp8_fp8 v[30:33], v[102:103], v[2:3], v[40:43]
	s_waitcnt vmcnt(32)
	v_mfma_f32_16x16x32_fp8_fp8 v[2:5], v[98:99], v[2:3], v[36:39]
	s_cmp_ge_i32 s58, s27
	s_mov_b64 s[10:11], -1
	s_cbranch_scc0 .LBB0_897

; template <bool SLC, bool NOMASK> ...
;     const int kq = lane >> 4;
;     const int pos0 = SLC ? (dcur & 0xfffff) : dcur;
;     const int lo = SLC ? ((((dcur >> 20) == qi) | ((dcur >> 20) == 4)) ? 0 : (1 << 30)) : lo_in;
;     load_frag8(nxt, KF, VF, SLC ? (dnext & 0xfffff) : dnext, lane);
;     f32x4 sa[2] = {(f32x4){0.f, 0.f, 0.f, 0.f}, (f32x4){0.f, 0.f, 0.f, 0.f}};
; #pragma unroll
;     for (int T = 0; T < 2; ++T)
; #pragma unroll
;         for (int s2 = 0; s2 < 4; ++s2) sa[T] = __builtin_amdgcn_mfma_f32_16x16x32_fp8_fp8(cur.k[T][s2], qf[s2], sa[T], 0, 0, 0);
;     float sc[8]; bool vd[8]; float mx = -1e30f;
;     const bool act = lo == 0 || !SLC;
;     if (NOMASK) {
; #pragma unroll
;         for (int j = 0; j < 8; ++j) { sc[j] = sa[j >> 2][j & 3]; vd[j] = act; }
;         mx = fmaxf(fmaxf(fmaxf(sc[0], sc[1]), fmaxf(sc[2], sc[3])), fmaxf(fmaxf(sc[4], sc[5]), fmaxf(sc[6], sc[7])));
;         mx = act ? mx : -1e30f;
;     } else {
; #pragma unroll
;         for (int T = 0; T < 2; ++T)
; #pragma unroll
;             for (int r = 0; r < 4; ++r) { const int p = pos0 + 16 * T + 4 * kq + r; const bool v = (p >= lo) & (p <= hi); const float x = sa[T][r];
;                 sc[4 * T + r] = x; vd[4 * T + r] = v; mx = v ? fmaxf(mx, x) : mx; }
;     }
;     if (__builtin_amdgcn_ballot_w64(mx > st.m + 4.f) != 0ull) {
;         mx = fmaxf(mx, __shfl_xor(mx, 16)); mx = fmaxf(mx, __shfl_xor(mx, 32));
;         const float mn = fmaxf(st.m, mx), alpha = __builtin_amdgcn_exp2f(st.m - mn); st.m = mn; st.l *= alpha;
; #pragma unroll
;         for (int j = 0; j < 8; ++j) st.o[j] = st.o[j] * alpha;
;     }
;     f32x4 pa, pb; float ps = 0.f;
;     const float mref = st.m - 4.f;
;     if (NOMASK) {
; #pragma unroll
;         for (int j = 0; j < 4; ++j) { pa[j] = __builtin_amdgcn_exp2f(sc[j] - mref); pb[j] = __builtin_amdgcn_exp2f(sc[4 + j] - mref); }
;         if (SLC) {
; #pragma unroll
;             for (int j = 0; j < 4; ++j) { pa[j] = act ? pa[j] : 0.f; pb[j] = act ? pb[j] : 0.f; }
;         }
; #pragma unroll
;         for (int j = 0; j < 4; ++j) ps += pa[j] + pb[j];
;     } else {
; #pragma unroll
;         for (int j = 0; j < 4; ++j) { pa[j] = vd[j] ? __builtin_amdgcn_exp2f(sc[j] - mref) : 0.f; pb[j] = vd[4 + j] ? __builtin_amdgcn_exp2f(sc[4 + j] - mref) : 0.f; ps += pa[j] + pb[j]; }
;     }
;     st.l += ps;
;     const u32x2 pw = pack8_fp8(pa, pb);
.LBB0_907:
	global_load_dwordx2 v[150:151], v[204:205], off
	global_load_dwordx2 v[152:153], v[204:205], off offset:512
	global_load_dwordx2 v[148:149], v[204:205], off offset:1024
	global_load_dwordx2 v[146:147], v[204:205], off offset:1536
	global_load_dwordx2 v[144:145], v[204:205], off offset:2048
	global_load_dwordx2 v[142:143], v[204:205], off offset:2560
	global_load_dwordx2 v[140:141], v[204:205], off offset:3072
	global_load_dwordx2 v[138:139], v[204:205], off offset:3584
	global_load_dwordx2 v[90:91], v[202:203], off
	global_load_dwordx2 v[92:93], v[202:203], off offset:512
	global_load_dwordx2 v[94:95], v[202:203], off offset:1024
	global_load_dwordx2 v[96:97], v[202:203], off offset:1536
	global_load_dwordx2 v[104:105], v[202:203], off offset:2048
	global_load_dwordx2 v[100:101], v[202:203], off offset:2560
	global_load_dwordx2 v[102:103], v[202:203], off offset:3072
	global_load_dwordx2 v[98:99], v[202:203], off offset:3584
	s_waitcnt vmcnt(47)
	v_mfma_f32_16x16x32_fp8_fp8 v[36:39], v[166:167], v[78:79], 0
	v_mov_b64_e32 v[74:75], v[4:5]
	v_mov_b64_e32 v[70:71], v[32:33]
	v_mov_b64_e32 v[66:67], v[28:29]
	s_waitcnt vmcnt(43)
	v_mfma_f32_16x16x32_fp8_fp8 v[40:43], v[160:161], v[78:79], 0
	v_mov_b64_e32 v[62:63], v[24:25]
	v_mov_b64_e32 v[58:59], v[20:21]
	v_mov_b64_e32 v[54:55], v[16:17]
	v_mfma_f32_16x16x32_fp8_fp8 v[36:39], v[168:169], v[80:81], v[36:39]
	v_mov_b64_e32 v[50:51], v[12:13]
	v_mov_b32_e32 v230, v229
	v_mov_b64_e32 v[72:73], v[2:3]
	s_waitcnt vmcnt(42)
	v_mfma_f32_16x16x32_fp8_fp8 v[40:43], v[158:159], v[80:81], v[40:43]
	v_mov_b64_e32 v[68:69], v[30:31]
	v_mov_b64_e32 v[64:65], v[26:27]
	v_mov_b64_e32 v[60:61], v[22:23]
	v_mfma_f32_16x16x32_fp8_fp8 v[36:39], v[164:165], v[82:83], v[36:39]
	v_mov_b64_e32 v[56:57], v[18:19]
	v_mov_b64_e32 v[52:53], v[14:15]
	v_mov_b64_e32 v[48:49], v[10:11]
	s_waitcnt vmcnt(41)
	v_mfma_f32_16x16x32_fp8_fp8 v[40:43], v[156:157], v[82:83], v[40:43]
	v_mov_b32_e32 v231, v34
	v_mfma_f32_16x16x32_fp8_fp8 v[36:39], v[162:163], v[84:85], v[36:39]
	s_waitcnt vmcnt(40)
	v_mfma_f32_16x16x32_fp8_fp8 v[40:43], v[154:155], v[84:85], v[40:43]
	s_nop 5
	v_max_f32_e32 v0, v37, v37
	v_max_f32_e32 v44, v36, v36
	v_max_f32_e32 v0, v44, v0
	v_max_f32_e32 v44, v39, v39
	v_max_f32_e32 v45, v38, v38
	v_max_f32_e32 v44, v45, v44
	v_max_f32_e32 v45, v43, v43
	v_max_f32_e32 v46, v42, v42
	v_max_f32_e32 v45, v46, v45
	v_max3_f32 v45, v40, v41, v45
	v_max3_f32 v0, v0, v44, v45
	v_mov_b64_e32 v[46:47], v[8:9]
	v_cmp_gt_f32_e32 vcc, v0, v133
	v_mov_b64_e32 v[44:45], v[6:7]
	s_cbranch_vccz .LBB0_909
	ds_bpermute_b32 v44, v227, v0
	v_max_f32_e32 v0, v0, v0
	s_waitcnt lgkmcnt(0)
	v_max_f32_e32 v44, v44, v44
	v_max_f32_e32 v0, v0, v44
	ds_bpermute_b32 v44, v226, v0
	s_waitcnt lgkmcnt(0)
	v_max3_f32 v230, v229, v0, v44
	v_sub_f32_e32 v0, v229, v230
	v_exp_f32_e32 v0, v0
	s_nop 0
	v_mul_f32_e32 v231, v34, v0
	v_pk_mul_f32 v[46:47], v[8:9], v[0:1] op_sel_hi:[1,0]
	v_pk_mul_f32 v[44:45], v[6:7], v[0:1] op_sel_hi:[1,0]
	v_pk_mul_f32 v[50:51], v[12:13], v[0:1] op_sel_hi:[1,0]
	v_pk_mul_f32 v[48:49], v[10:11], v[0:1] op_sel_hi:[1,0]
	v_pk_mul_f32 v[54:55], v[16:17], v[0:1] op_sel_hi:[1,0]
	v_pk_mul_f32 v[52:53], v[14:15], v[0:1] op_sel_hi:[1,0]
	v_pk_mul_f32 v[58:59], v[20:21], v[0:1] op_sel_hi:[1,0]
	v_pk_mul_f32 v[56:57], v[18:19], v[0:1] op_sel_hi:[1,0]
	v_pk_mul_f32 v[62:63], v[24:25], v[0:1] op_sel_hi:[1,0]
	v_pk_mul_f32 v[60:61], v[22:23], v[0:1] op_sel_hi:[1,0]
	v_pk_mul_f32 v[66:67], v[28:29], v[0:1] op_sel_hi:[1,0]
	v_pk_mul_f32 v[64:65], v[26:27], v[0:1] op_sel_hi:[1,0]
	v_pk_mul_f32 v[70:71], v[32:33], v[0:1] op_sel_hi:[1,0]
	v_pk_mul_f32 v[68:69], v[30:31], v[0:1] op_sel_hi:[1,0]
	v_pk_mul_f32 v[74:75], v[4:5], v[0:1] op_sel_hi:[1,0]
	v_pk_mul_f32 v[72:73], v[2:3], v[0:1] op_sel_hi:[1,0]
.LBB0_909:
	v_add_f32_e32 v233, -4.0, v230
	v_sub_f32_e32 v0, v36, v233
	v_exp_f32_e32 v235, v0
	v_sub_f32_e32 v0, v40, v233
	v_exp_f32_e32 v237, v0
	v_sub_f32_e32 v0, v37, v233
	v_exp_f32_e32 v232, v0
	v_sub_f32_e32 v0, v41, v233
	v_exp_f32_e32 v0, v0
	v_sub_f32_e32 v36, v38, v233
	v_exp_f32_e32 v240, v36
	v_sub_f32_e32 v36, v42, v233
	v_exp_f32_e32 v241, v36
	v_sub_f32_e32 v36, v39, v233
	v_exp_f32_e32 v234, v36
	v_sub_f32_e32 v36, v43, v233
	v_mov_b32_e32 v238, v1
	v_mov_b32_e32 v239, v1
	v_exp_f32_e32 v236, v36
	v_cvt_pk_fp8_f32 v238, v235, v232
	v_cvt_pk_fp8_f32 v239, v237, v0
	v_add_f32_e32 v233, v235, v237
	v_add_f32_e32 v235, v240, v241
	v_cvt_pk_fp8_f32 v238, v240, v234 op_sel:[0,0,1]
	v_cvt_pk_fp8_f32 v239, v241, v236 op_sel:[0,0,1]
	s_waitcnt vmcnt(39)
	s_nop 0
	v_mfma_f32_16x16x32_fp8_fp8 v[36:39], v[106:107], v[238:239], v[44:47]
	s_waitcnt vmcnt(37)
	v_mfma_f32_16x16x32_fp8_fp8 v[44:47], v[112:113], v[238:239], v[52:55]
	s_waitcnt vmcnt(35)
	v_mfma_f32_16x16x32_fp8_fp8 v[52:55], v[136:137], v[238:239], v[60:63]
	s_nop 2
	v_add_f32_e64 v60, v232, v0
	v_add_f32_e64 v61, v233, v1
	v_mfma_f32_16x16x32_fp8_fp8 v[40:43], v[110:111], v[238:239], v[48:51]
	v_pk_add_f32 v[60:61], v[60:61], v[60:61] op_sel_hi:[0,1]
	v_mov_b32_e32 v237, v61
	v_mfma_f32_16x16x32_fp8_fp8 v[48:51], v[116:117], v[238:239], v[56:59]
	s_waitcnt vmcnt(34)
	v_mfma_f32_16x16x32_fp8_fp8 v[56:59], v[134:135], v[238:239], v[64:67]
	s_nop 2
	v_add_f32_e64 v64, v234, v236
	v_add_f32_e64 v65, v235, v237
	s_waitcnt vmcnt(33)
	v_mfma_f32_16x16x32_fp8_fp8 v[60:63], v[114:115], v[238:239], v[68:71]
	v_add_f32_e32 v0, v64, v65
	v_add_f32_e32 v231, v0, v231
	s_waitcnt vmcnt(32)
	v_mfma_f32_16x16x32_fp8_fp8 v[64:67], v[108:109], v[238:239], v[72:75]
	s_branch .LBB0_899
; template <bool SLC, bool NOMASK> ...
;     const int kq = lane >> 4;
;     const int pos0 = SLC ? (dcur & 0xfffff) : dcur;
;     const int lo = SLC ? ((((dcur >> 20) == qi) | ((dcur >> 20) == 4)) ? 0 : (1 << 30)) : lo_in;
;     load_frag8(nxt, KF, VF, SLC ? (dnext & 0xfffff) : dnext, lane);
;     f32x4 sa[2] = {(f32x4){0.f, 0.f, 0.f, 0.f}, (f32x4){0.f, 0.f, 0.f, 0.f}};
; #pragma unroll
;     for (int T = 0; T < 2; ++T)
; #pragma unroll
;         for (int s2 = 0; s2 < 4; ++s2) sa[T] = __builtin_amdgcn_mfma_f32_16x16x32_fp8_fp8(cur.k[T][s2], qf[s2], sa[T], 0, 0, 0);
;     float sc[8]; bool vd[8]; float mx = -1e30f;
;     const bool act = lo == 0 || !SLC;
;     if (NOMASK) {
; #pragma unroll
;         for (int j = 0; j < 8; ++j) { sc[j] = sa[j >> 2][j & 3]; vd[j] = act; }
;         mx = fmaxf(fmaxf(fmaxf(sc[0], sc[1]), fmaxf(sc[2], sc[3])), fmaxf(fmaxf(sc[4], sc[5]), fmaxf(sc[6], sc[7])));
;         mx = act ? mx : -1e30f;
;     } else {
; #pragma unroll
;         for (int T = 0; T < 2; ++T)
; #pragma unroll
;             for (int r = 0; r < 4; ++r) { const int p = pos0 + 16 * T + 4 * kq + r; const bool v = (p >= lo) & (p <= hi); const float x = sa[T][r];
;                 sc[4 * T + r] = x; vd[4 * T + r] = v; mx = v ? fmaxf(mx, x) : mx; }
;     }
;     if (__builtin_amdgcn_ballot_w64(mx > st.m + 4.f) != 0ull) {
;         mx = fmaxf(mx, __shfl_xor(mx, 16)); mx = fmaxf(mx, __shfl_xor(mx, 32));
;         const float mn = fmaxf(st.m, mx), alpha = __builtin_amdgcn_exp2f(st.m - mn); st.m = mn; st.l *= alpha;
; #pragma unroll
;         for (int j = 0; j < 8; ++j) st.o[j] = st.o[j] * alpha;
;     }
.LBB0_910:
	global_load_dwordx2 v[150:151], v[204:205], off
	global_load_dwordx2 v[152:153], v[204:205], off offset:512
	global_load_dwordx2 v[148:149], v[204:205], off offset:1024
	global_load_dwordx2 v[146:147], v[204:205], off offset:1536
	global_load_dwordx2 v[144:145], v[204:205], off offset:2048
	global_load_dwordx2 v[142:143], v[204:205], off offset:2560
	global_load_dwordx2 v[140:141], v[204:205], off offset:3072
	global_load_dwordx2 v[138:139], v[204:205], off offset:3584
	global_load_dwordx2 v[90:91], v[202:203], off
	global_load_dwordx2 v[92:93], v[202:203], off offset:512
	global_load_dwordx2 v[94:95], v[202:203], off offset:1024
	global_load_dwordx2 v[96:97], v[202:203], off offset:1536
	global_load_dwordx2 v[104:105], v[202:203], off offset:2048
	global_load_dwordx2 v[100:101], v[202:203], off offset:2560
	global_load_dwordx2 v[102:103], v[202:203], off offset:3072
	global_load_dwordx2 v[98:99], v[202:203], off offset:3584
	s_waitcnt vmcnt(47)
	v_mfma_f32_16x16x32_fp8_fp8 v[36:39], v[166:167], v[78:79], 0
	v_add_u32_e32 v0, s66, v211
	v_cmp_ge_i32_e32 vcc, v0, v35
	v_cmp_le_i32_e64 s[10:11], v0, v132
	s_waitcnt vmcnt(46)
	v_mfma_f32_16x16x32_fp8_fp8 v[36:39], v[168:169], v[80:81], v[36:39]
	s_and_b64 s[16:17], vcc, s[10:11]
	v_add_u32_e32 v45, 1, v0
	v_cmp_ge_i32_e32 vcc, v45, v35
	s_waitcnt vmcnt(45)
	v_mfma_f32_16x16x32_fp8_fp8 v[36:39], v[164:165], v[82:83], v[36:39]
	v_cmp_lt_i32_e64 s[10:11], v0, v132
	s_and_b64 s[12:13], s[10:11], vcc
	s_waitcnt vmcnt(43)
	v_mfma_f32_16x16x32_fp8_fp8 v[40:43], v[160:161], v[78:79], 0
	v_mfma_f32_16x16x32_fp8_fp8 v[36:39], v[162:163], v[84:85], v[36:39]
	s_waitcnt vmcnt(42)
	v_mfma_f32_16x16x32_fp8_fp8 v[40:43], v[158:159], v[80:81], v[40:43]
	s_waitcnt vmcnt(41)
	v_mfma_f32_16x16x32_fp8_fp8 v[40:43], v[156:157], v[82:83], v[40:43]
	s_nop 3
	v_max_f32_e32 v44, v36, v36
	v_max_f32_e32 v44, 0xf149f2ca, v44
	v_cndmask_b32_e64 v44, v223, v44, s[16:17]
	v_max_f32_e32 v45, v37, v37
	v_max_f32_e32 v45, v44, v45
	v_cndmask_b32_e64 v44, v44, v45, s[12:13]
	v_add_u32_e32 v45, 2, v0
	v_cmp_ge_i32_e32 vcc, v45, v35
	v_cmp_le_i32_e64 s[10:11], v45, v132
	v_max_f32_e32 v45, v38, v38
	v_max_f32_e32 v45, v44, v45
	s_and_b64 s[14:15], vcc, s[10:11]
	s_waitcnt vmcnt(40)
	v_mfma_f32_16x16x32_fp8_fp8 v[40:43], v[154:155], v[84:85], v[40:43]
	v_cndmask_b32_e64 v44, v44, v45, s[14:15]
	v_add_u32_e32 v45, 3, v0
	v_cmp_ge_i32_e32 vcc, v45, v35
	v_cmp_le_i32_e64 s[10:11], v45, v132
	v_max_f32_e32 v45, v39, v39
	v_max_f32_e32 v45, v44, v45
	s_and_b64 s[10:11], vcc, s[10:11]
	v_cndmask_b32_e64 v44, v44, v45, s[10:11]
	v_add_u32_e32 v45, 16, v0
	v_cmp_ge_i32_e32 vcc, v45, v35
	v_cmp_le_i32_e64 s[18:19], v45, v132
	v_max_f32_e32 v45, v40, v40
	v_max_f32_e32 v45, v44, v45
	s_and_b64 s[24:25], vcc, s[18:19]
	v_cndmask_b32_e64 v44, v44, v45, s[24:25]
	v_add_u32_e32 v45, 17, v0
	v_cmp_ge_i32_e32 vcc, v45, v35
	v_cmp_le_i32_e64 s[18:19], v45, v132
	v_max_f32_e32 v45, v44, v44
	v_max_f32_e32 v46, v41, v41
	v_max_f32_e32 v45, v45, v46
	s_and_b64 s[20:21], vcc, s[18:19]
	v_cndmask_b32_e64 v44, v44, v45, s[20:21]
	v_add_u32_e32 v45, 18, v0
	v_cmp_ge_i32_e32 vcc, v45, v35
	v_cmp_le_i32_e64 s[18:19], v45, v132
	v_max_f32_e32 v45, v44, v44
	v_max_f32_e32 v46, v42, v42
	v_max_f32_e32 v45, v45, v46
	s_and_b64 s[22:23], vcc, s[18:19]
	v_cndmask_b32_e64 v44, v44, v45, s[22:23]
	v_add_u32_e32 v0, 19, v0
	v_cmp_ge_i32_e32 vcc, v0, v35
	v_cmp_le_i32_e64 s[18:19], v0, v132
	v_max_f32_e32 v0, v44, v44
	v_max_f32_e32 v45, v43, v43
	v_max_f32_e32 v0, v0, v45
	s_and_b64 s[18:19], vcc, s[18:19]
	v_cndmask_b32_e64 v0, v44, v0, s[18:19]
	v_cmp_gt_f32_e32 vcc, v0, v133
	s_cbranch_vccz .LBB0_912
	ds_bpermute_b32 v44, v227, v0
	v_max_f32_e32 v0, v0, v0
	s_waitcnt lgkmcnt(0)
	v_max_f32_e32 v44, v44, v44
	v_max_f32_e32 v0, v0, v44
	ds_bpermute_b32 v44, v226, v0
	s_waitcnt lgkmcnt(0)
	v_max3_f32 v44, v229, v0, v44
	v_sub_f32_e32 v0, v229, v44
	v_exp_f32_e32 v0, v0
	v_mov_b32_e32 v229, v44
	v_mul_f32_e32 v34, v34, v0
	v_pk_mul_f32 v[8:9], v[8:9], v[0:1] op_sel_hi:[1,0]
	v_pk_mul_f32 v[6:7], v[6:7], v[0:1] op_sel_hi:[1,0]
	v_pk_mul_f32 v[12:13], v[12:13], v[0:1] op_sel_hi:[1,0]
	v_pk_mul_f32 v[10:11], v[10:11], v[0:1] op_sel_hi:[1,0]
	v_pk_mul_f32 v[16:17], v[16:17], v[0:1] op_sel_hi:[1,0]
	v_pk_mul_f32 v[14:15], v[14:15], v[0:1] op_sel_hi:[1,0]
	v_pk_mul_f32 v[20:21], v[20:21], v[0:1] op_sel_hi:[1,0]
	v_pk_mul_f32 v[18:19], v[18:19], v[0:1] op_sel_hi:[1,0]
	v_pk_mul_f32 v[24:25], v[24:25], v[0:1] op_sel_hi:[1,0]
	v_pk_mul_f32 v[22:23], v[22:23], v[0:1] op_sel_hi:[1,0]
	v_pk_mul_f32 v[28:29], v[28:29], v[0:1] op_sel_hi:[1,0]
	v_pk_mul_f32 v[26:27], v[26:27], v[0:1] op_sel_hi:[1,0]
	v_pk_mul_f32 v[32:33], v[32:33], v[0:1] op_sel_hi:[1,0]
	v_pk_mul_f32 v[30:31], v[30:31], v[0:1] op_sel_hi:[1,0]
	v_pk_mul_f32 v[4:5], v[4:5], v[0:1] op_sel_hi:[1,0]
	v_pk_mul_f32 v[2:3], v[2:3], v[0:1] op_sel_hi:[1,0]
; #define F8_STEP(CUR, NXT2, DC, DN2) do { \
;         if ((DC) & (1 << 30)) step_frag8<SLC, true>(qf, CUR, NXT2, KF, VF, (DC) & NM, (DN2) & NM, lo_in, hi, qi, st, lane); \
;         else step_frag8<SLC, false>(qf, CUR, NXT2, KF, VF, (DC), (DN2) & NM, lo_in, hi, qi, st, lane); } while (0)
; template <bool SLC, bool NOMASK> ...
;     ...
;     f32x4 pa, pb; float ps = 0.f;
;     const float mref = st.m - 4.f;
;     if (NOMASK) {
; #pragma unroll
;         for (int j = 0; j < 4; ++j) { pa[j] = __builtin_amdgcn_exp2f(sc[j] - mref); pb[j] = __builtin_amdgcn_exp2f(sc[4 + j] - mref); }
;         if (SLC) {
; #pragma unroll
;             for (int j = 0; j < 4; ++j) { pa[j] = act ? pa[j] : 0.f; pb[j] = act ? pb[j] : 0.f; }
;         }
; #pragma unroll
;         for (int j = 0; j < 4; ++j) ps += pa[j] + pb[j];
;     } else {
; #pragma unroll
;         for (int j = 0; j < 4; ++j) { pa[j] = vd[j] ? __builtin_amdgcn_exp2f(sc[j] - mref) : 0.f; pb[j] = vd[4 + j] ? __builtin_amdgcn_exp2f(sc[4 + j] - mref) : 0.f; ps += pa[j] + pb[j]; }
;     }
;     st.l += ps;
;     const u32x2 pw = pack8_fp8(pa, pb);
;     const i64_t pf = __builtin_bit_cast(i64_t, pw);
; #pragma unroll
;     for (int db = 0; db < 8; ++db) st.o[db] = __builtin_amdgcn_mfma_f32_16x16x32_fp8_fp8(cur.v[db], pf, st.o[db], 0, 0, 0);
; template <bool SLC, class Desc>
; __device__ __forceinline__ void attn_run_frag8(const i64_t (&qf)[4], const unsigned char* __restrict__ KF, const unsigned char* __restrict__ VF, const Desc& desc, int n,
;                                                int lo_in, int hi, int qi, AState& st, int lane) {
;     ...
; #pragma unroll 1
;     for (int i = 0; i < n; i += 3) {
;         const int d2 = desc(i + 2 < n ? i + 2 : n - 1);
;         F8_STEP(fa, fc, d0, d2);
;         if (i + 1 >= n) break;
;         const int d3 = desc(i + 3 < n ? i + 3 : n - 1);
;         F8_STEP(fb, fa, d1, d3);
;         if (i + 2 >= n) break;
;         const int d4 = desc(i + 4 < n ? i + 4 : n - 1);
;         F8_STEP(fc, fb, d2, d4);
;         d0 = d3; d1 = d4;
.LBB0_912:
	v_add_f32_e32 v0, -4.0, v229
	v_sub_f32_e32 v36, v36, v0
	v_exp_f32_e32 v36, v36
	v_sub_f32_e32 v40, v40, v0
	v_exp_f32_e32 v40, v40
	v_sub_f32_e32 v38, v38, v0
	v_cndmask_b32_e64 v56, 0, v36, s[16:17]
	v_sub_f32_e32 v36, v37, v0
	v_exp_f32_e32 v36, v36
	v_sub_f32_e32 v37, v41, v0
	v_exp_f32_e32 v37, v37
	v_cndmask_b32_e64 v57, 0, v40, s[24:25]
	v_sub_f32_e32 v40, v42, v0
	v_cndmask_b32_e64 v58, 0, v36, s[12:13]
	v_sub_f32_e32 v36, v39, v0
	v_sub_f32_e32 v0, v43, v0
	v_exp_f32_e32 v38, v38
	v_exp_f32_e32 v40, v40
	v_cndmask_b32_e64 v59, 0, v37, s[20:21]
	v_exp_f32_e32 v36, v36
	v_exp_f32_e32 v0, v0
	v_mov_b32_e32 v64, v1
	v_mov_b32_e32 v65, v1
	v_cvt_pk_fp8_f32 v64, v56, v58
	v_cvt_pk_fp8_f32 v65, v57, v59
	v_cndmask_b32_e64 v60, 0, v38, s[14:15]
	v_cndmask_b32_e64 v61, 0, v40, s[22:23]
	v_cndmask_b32_e64 v66, 0, v36, s[10:11]
	v_cndmask_b32_e64 v0, 0, v0, s[18:19]
	v_cvt_pk_fp8_f32 v64, v60, v66 op_sel:[0,0,1]
	v_cvt_pk_fp8_f32 v65, v61, v0 op_sel:[0,0,1]
	v_add_f32_e32 v0, v66, v0
	v_mov_b32_e32 v230, v229
	s_waitcnt vmcnt(39)
	v_mfma_f32_16x16x32_fp8_fp8 v[36:39], v[106:107], v[64:65], v[6:9]
	s_nop 2
	v_add_f32_e32 v6, v56, v57
	v_add_f32_e32 v6, 0, v6
	v_add_f32_e32 v7, v58, v59
	s_waitcnt vmcnt(38)
	v_mfma_f32_16x16x32_fp8_fp8 v[40:43], v[110:111], v[64:65], v[10:13]
	v_add_f32_e32 v6, v7, v6
	v_add_f32_e32 v7, v60, v61
	v_add_f32_e32 v6, v7, v6
	s_waitcnt vmcnt(37)
	v_mfma_f32_16x16x32_fp8_fp8 v[44:47], v[112:113], v[64:65], v[14:17]
	v_add_f32_e32 v0, v0, v6
	v_add_f32_e32 v231, v34, v0
	s_waitcnt vmcnt(36)
	v_mfma_f32_16x16x32_fp8_fp8 v[48:51], v[116:117], v[64:65], v[18:21]
	s_waitcnt vmcnt(35)
	v_mfma_f32_16x16x32_fp8_fp8 v[52:55], v[136:137], v[64:65], v[22:25]
	s_waitcnt vmcnt(34)
	v_mfma_f32_16x16x32_fp8_fp8 v[56:59], v[134:135], v[64:65], v[26:29]
	s_waitcnt vmcnt(33)
	v_mfma_f32_16x16x32_fp8_fp8 v[60:63], v[114:115], v[64:65], v[30:33]
	s_waitcnt vmcnt(32)
	v_mfma_f32_16x16x32_fp8_fp8 v[64:67], v[108:109], v[64:65], v[2:5]
	s_cmp_gt_i32 s57, s27
	s_mov_b64 s[10:11], -1
	s_cbranch_scc1 .LBB0_892
.LBB0_913:
	s_cmp_lt_i32 s59, s56
	s_cselect_b64 s[10:11], -1, 0
	s_or_b32 s12, s59, 31
	s_cmp_gt_i32 s12, s96
	s_cselect_b64 s[12:13], -1, 0
	s_or_b64 s[10:11], s[10:11], s[12:13]
	s_and_b64 s[10:11], s[10:11], exec
	s_cselect_b32 s10, 0, 2.0
	s_add_i32 s58, s58, 4
	s_or_b32 s14, s10, s59
	s_min_i32 s10, s58, s27
	s_add_i32 s12, s10, s26
	s_lshl_b32 s43, s12, 5
	s_and_b32 s10, s43, 0x3fffffe0
	s_lshr_b32 s50, s10, 4
	s_lshl_b64 s[10:11], s[50:51], 11
	s_and_b32 s50, s12, 0x1ffffff
	s_lshl_b64 s[12:13], s[50:51], 12
	s_cmp_lt_u32 s14, 2.0
	v_lshl_add_u64 v[204:205], v[86:87], 0, s[10:11]
	v_lshl_add_u64 v[202:203], v[88:89], 0, s[12:13]
	s_mov_b64 s[10:11], -1
	v_add_f32_e32 v229, 4.0, v230
	s_cbranch_scc1 .LBB0_917
	global_load_dwordx2 v[166:167], v[204:205], off
	global_load_dwordx2 v[168:169], v[204:205], off offset:512
	global_load_dwordx2 v[164:165], v[204:205], off offset:1024
	global_load_dwordx2 v[162:163], v[204:205], off offset:1536
	global_load_dwordx2 v[160:161], v[204:205], off offset:2048
	global_load_dwordx2 v[158:159], v[204:205], off offset:2560
	global_load_dwordx2 v[156:157], v[204:205], off offset:3072
	global_load_dwordx2 v[154:155], v[204:205], off offset:3584
	global_load_dwordx2 v[106:107], v[202:203], off
	global_load_dwordx2 v[110:111], v[202:203], off offset:512
	global_load_dwordx2 v[112:113], v[202:203], off offset:1024
	global_load_dwordx2 v[116:117], v[202:203], off offset:1536
	global_load_dwordx2 v[136:137], v[202:203], off offset:2048
	global_load_dwordx2 v[134:135], v[202:203], off offset:2560
	global_load_dwordx2 v[114:115], v[202:203], off offset:3072
	global_load_dwordx2 v[108:109], v[202:203], off offset:3584
	s_waitcnt vmcnt(47)
	v_mfma_f32_16x16x32_fp8_fp8 v[2:5], v[194:195], v[78:79], 0
	v_mov_b64_e32 v[74:75], v[66:67]
	v_mov_b64_e32 v[70:71], v[62:63]
	v_mov_b64_e32 v[30:31], v[56:57]
	s_waitcnt vmcnt(43)
	v_mfma_f32_16x16x32_fp8_fp8 v[6:9], v[196:197], v[78:79], 0
	v_mov_b64_e32 v[26:27], v[52:53]
	v_mov_b64_e32 v[22:23], v[48:49]
	v_mov_b64_e32 v[18:19], v[44:45]
	v_mfma_f32_16x16x32_fp8_fp8 v[2:5], v[200:201], v[80:81], v[2:5]
	v_mov_b64_e32 v[14:15], v[40:41]
	v_mov_b32_e32 v133, v230
	v_mov_b64_e32 v[72:73], v[64:65]
	s_waitcnt vmcnt(42)
	v_mfma_f32_16x16x32_fp8_fp8 v[6:9], v[190:191], v[80:81], v[6:9]
	v_mov_b64_e32 v[68:69], v[60:61]
	v_mov_b64_e32 v[32:33], v[58:59]
	v_mov_b64_e32 v[28:29], v[54:55]
	v_mfma_f32_16x16x32_fp8_fp8 v[2:5], v[198:199], v[82:83], v[2:5]
	v_mov_b64_e32 v[24:25], v[50:51]
	v_mov_b64_e32 v[20:21], v[46:47]
	v_mov_b64_e32 v[16:17], v[42:43]
	s_waitcnt vmcnt(41)
	v_mfma_f32_16x16x32_fp8_fp8 v[6:9], v[188:189], v[82:83], v[6:9]
	v_mov_b32_e32 v34, v231
	v_mfma_f32_16x16x32_fp8_fp8 v[2:5], v[192:193], v[84:85], v[2:5]
	s_waitcnt vmcnt(40)
	v_mfma_f32_16x16x32_fp8_fp8 v[6:9], v[186:187], v[84:85], v[6:9]
	s_nop 5
	v_max_f32_e32 v0, v3, v3
	v_max_f32_e32 v10, v2, v2
	v_max_f32_e32 v0, v10, v0
	v_max_f32_e32 v10, v5, v5
	v_max_f32_e32 v11, v4, v4
	v_max_f32_e32 v10, v11, v10
	v_max_f32_e32 v11, v9, v9
	v_max_f32_e32 v12, v8, v8
	v_max_f32_e32 v11, v12, v11
	v_max3_f32 v11, v6, v7, v11
	v_max3_f32 v0, v0, v10, v11
	v_mov_b64_e32 v[10:11], v[36:37]
	v_cmp_gt_f32_e32 vcc, v0, v229
	v_mov_b64_e32 v[12:13], v[38:39]
	s_cbranch_vccz .LBB0_916
	ds_bpermute_b32 v10, v227, v0
	v_max_f32_e32 v0, v0, v0
	s_waitcnt lgkmcnt(0)
	v_max_f32_e32 v10, v10, v10
	v_max_f32_e32 v0, v0, v10
	ds_bpermute_b32 v10, v226, v0
	s_waitcnt lgkmcnt(0)
	v_max3_f32 v133, v230, v0, v10
	v_sub_f32_e32 v0, v230, v133
	v_exp_f32_e32 v0, v0
	s_nop 0
	v_mul_f32_e32 v34, v231, v0
	v_pk_mul_f32 v[12:13], v[38:39], v[0:1] op_sel_hi:[1,0]
	v_pk_mul_f32 v[10:11], v[36:37], v[0:1] op_sel_hi:[1,0]
	v_pk_mul_f32 v[16:17], v[42:43], v[0:1] op_sel_hi:[1,0]
	v_pk_mul_f32 v[14:15], v[40:41], v[0:1] op_sel_hi:[1,0]
	v_pk_mul_f32 v[20:21], v[46:47], v[0:1] op_sel_hi:[1,0]
	v_pk_mul_f32 v[18:19], v[44:45], v[0:1] op_sel_hi:[1,0]
	v_pk_mul_f32 v[24:25], v[50:51], v[0:1] op_sel_hi:[1,0]
	v_pk_mul_f32 v[22:23], v[48:49], v[0:1] op_sel_hi:[1,0]
	v_pk_mul_f32 v[28:29], v[54:55], v[0:1] op_sel_hi:[1,0]
	v_pk_mul_f32 v[26:27], v[52:53], v[0:1] op_sel_hi:[1,0]
	v_pk_mul_f32 v[32:33], v[58:59], v[0:1] op_sel_hi:[1,0]
	v_pk_mul_f32 v[30:31], v[56:57], v[0:1] op_sel_hi:[1,0]
	v_pk_mul_f32 v[70:71], v[62:63], v[0:1] op_sel_hi:[1,0]
	v_pk_mul_f32 v[68:69], v[60:61], v[0:1] op_sel_hi:[1,0]
	v_pk_mul_f32 v[74:75], v[66:67], v[0:1] op_sel_hi:[1,0]
	v_pk_mul_f32 v[72:73], v[64:65], v[0:1] op_sel_hi:[1,0]
; template <bool SLC, bool NOMASK> ...
;     const int kq = lane >> 4;
;     const int pos0 = SLC ? (dcur & 0xfffff) : dcur;
;     const int lo = SLC ? ((((dcur >> 20) == qi) | ((dcur >> 20) == 4)) ? 0 : (1 << 30)) : lo_in;
;     load_frag8(nxt, KF, VF, SLC ? (dnext & 0xfffff) : dnext, lane);
;     f32x4 sa[2] = {(f32x4){0.f, 0.f, 0.f, 0.f}, (f32x4){0.f, 0.f, 0.f, 0.f}};
; #pragma unroll
;     for (int T = 0; T < 2; ++T)
; #pragma unroll
;         for (int s2 = 0; s2 < 4; ++s2) sa[T] = __builtin_amdgcn_mfma_f32_16x16x32_fp8_fp8(cur.k[T][s2], qf[s2], sa[T], 0, 0, 0);
;     float sc[8]; bool vd[8]; float mx = -1e30f;
;     const bool act = lo == 0 || !SLC;
;     if (NOMASK) {
; #pragma unroll
;         for (int j = 0; j < 8; ++j) { sc[j] = sa[j >> 2][j & 3]; vd[j] = act; }
;         mx = fmaxf(fmaxf(fmaxf(sc[0], sc[1]), fmaxf(sc[2], sc[3])), fmaxf(fmaxf(sc[4], sc[5]), fmaxf(sc[6], sc[7])));
;         mx = act ? mx : -1e30f;
;     } else {
; #pragma unroll
;         for (int T = 0; T < 2; ++T)
; #pragma unroll
;             for (int r = 0; r < 4; ++r) { const int p = pos0 + 16 * T + 4 * kq + r; const bool v = (p >= lo) & (p <= hi); const float x = sa[T][r];
;                 sc[4 * T + r] = x; vd[4 * T + r] = v; mx = v ? fmaxf(mx, x) : mx; }
;     }
;     if (__builtin_amdgcn_ballot_w64(mx > st.m + 4.f) != 0ull) {
;         mx = fmaxf(mx, __shfl_xor(mx, 16)); mx = fmaxf(mx, __shfl_xor(mx, 32));
;         const float mn = fmaxf(st.m, mx), alpha = __builtin_amdgcn_exp2f(st.m - mn); st.m = mn; st.l *= alpha;
; #pragma unroll
;         for (int j = 0; j < 8; ++j) st.o[j] = st.o[j] * alpha;
;     }
;     f32x4 pa, pb; float ps = 0.f;
;     const float mref = st.m - 4.f;
;     if (NOMASK) {
; #pragma unroll
;         for (int j = 0; j < 4; ++j) { pa[j] = __builtin_amdgcn_exp2f(sc[j] - mref); pb[j] = __builtin_amdgcn_exp2f(sc[4 + j] - mref); }
;         if (SLC) {
; #pragma unroll
;             for (int j = 0; j < 4; ++j) { pa[j] = act ? pa[j] : 0.f; pb[j] = act ? pb[j] : 0.f; }
;         }
; #pragma unroll
;         for (int j = 0; j < 4; ++j) ps += pa[j] + pb[j];
;     } else {
; #pragma unroll
;         for (int j = 0; j < 4; ++j) { pa[j] = vd[j] ? __builtin_amdgcn_exp2f(sc[j] - mref) : 0.f; pb[j] = vd[4 + j] ? __builtin_amdgcn_exp2f(sc[4 + j] - mref) : 0.f; ps += pa[j] + pb[j]; }
;     }
;     st.l += ps;
;     const u32x2 pw = pack8_fp8(pa, pb);
.LBB0_916:
	v_add_f32_e32 v232, -4.0, v133
	v_sub_f32_e32 v0, v2, v232
	v_exp_f32_e32 v233, v0
	v_sub_f32_e32 v0, v6, v232
	v_exp_f32_e32 v236, v0
	v_sub_f32_e32 v0, v3, v232
	v_exp_f32_e32 v2, v0
	v_sub_f32_e32 v0, v7, v232
	v_exp_f32_e32 v0, v0
	v_sub_f32_e32 v3, v4, v232
	v_exp_f32_e32 v237, v3
	v_sub_f32_e32 v3, v8, v232
	v_exp_f32_e32 v238, v3
	v_sub_f32_e32 v3, v5, v232
	v_exp_f32_e32 v4, v3
	v_sub_f32_e32 v3, v9, v232
	v_mov_b32_e32 v234, v1
	v_mov_b32_e32 v235, v1
	v_exp_f32_e32 v232, v3
	v_cvt_pk_fp8_f32 v234, v233, v2
	v_cvt_pk_fp8_f32 v235, v236, v0
	v_add_f32_e32 v3, v233, v236
	v_pk_add_f32 v[2:3], v[2:3], v[0:1]
	v_cvt_pk_fp8_f32 v234, v237, v4 op_sel:[0,0,1]
	v_cvt_pk_fp8_f32 v235, v238, v232 op_sel:[0,0,1]
	v_pk_add_f32 v[2:3], v[2:3], v[2:3] op_sel_hi:[0,1]
	v_add_f32_e32 v5, v237, v238
	v_mov_b32_e32 v233, v3
	v_pk_add_f32 v[2:3], v[4:5], v[232:233]
	s_waitcnt vmcnt(39)
	v_mfma_f32_16x16x32_fp8_fp8 v[6:9], v[170:171], v[234:235], v[10:13]
	v_add_f32_e32 v0, v2, v3
	v_add_f32_e32 v34, v0, v34
	s_mov_b64 s[10:11], 0
	s_waitcnt vmcnt(38)
	v_mfma_f32_16x16x32_fp8_fp8 v[10:13], v[172:173], v[234:235], v[14:17]
	s_waitcnt vmcnt(37)
	v_mfma_f32_16x16x32_fp8_fp8 v[14:17], v[174:175], v[234:235], v[18:21]
	s_waitcnt vmcnt(36)
	v_mfma_f32_16x16x32_fp8_fp8 v[18:21], v[176:177], v[234:235], v[22:25]
	s_waitcnt vmcnt(35)
	v_mfma_f32_16x16x32_fp8_fp8 v[22:25], v[184:185], v[234:235], v[26:29]
	s_waitcnt vmcnt(34)
	v_mfma_f32_16x16x32_fp8_fp8 v[26:29], v[180:181], v[234:235], v[30:33]
	s_waitcnt vmcnt(33)
	v_mfma_f32_16x16x32_fp8_fp8 v[30:33], v[182:183], v[234:235], v[68:71]
	s_waitcnt vmcnt(32)
	v_mfma_f32_16x16x32_fp8_fp8 v[2:5], v[178:179], v[234:235], v[72:75]
.LBB0_917:
	s_and_b64 vcc, exec, s[10:11]
	s_cbranch_vccz .LBB0_921
	global_load_dwordx2 v[166:167], v[204:205], off
	global_load_dwordx2 v[168:169], v[204:205], off offset:512
	global_load_dwordx2 v[164:165], v[204:205], off offset:1024
	global_load_dwordx2 v[162:163], v[204:205], off offset:1536
	global_load_dwordx2 v[160:161], v[204:205], off offset:2048
	global_load_dwordx2 v[158:159], v[204:205], off offset:2560
	global_load_dwordx2 v[156:157], v[204:205], off offset:3072
	global_load_dwordx2 v[154:155], v[204:205], off offset:3584
	global_load_dwordx2 v[106:107], v[202:203], off
	global_load_dwordx2 v[110:111], v[202:203], off offset:512
	global_load_dwordx2 v[112:113], v[202:203], off offset:1024
	global_load_dwordx2 v[116:117], v[202:203], off offset:1536
	global_load_dwordx2 v[136:137], v[202:203], off offset:2048
	global_load_dwordx2 v[134:135], v[202:203], off offset:2560
	global_load_dwordx2 v[114:115], v[202:203], off offset:3072
	global_load_dwordx2 v[108:109], v[202:203], off offset:3584
	s_waitcnt vmcnt(47)
	v_mfma_f32_16x16x32_fp8_fp8 v[2:5], v[194:195], v[78:79], 0
	v_or_b32_e32 v0, s59, v211
	v_cmp_ge_i32_e32 vcc, v0, v35
	v_cmp_le_i32_e64 s[10:11], v0, v132
	s_waitcnt vmcnt(46)
	v_mfma_f32_16x16x32_fp8_fp8 v[2:5], v[200:201], v[80:81], v[2:5]
	s_and_b64 s[16:17], vcc, s[10:11]
	v_or_b32_e32 v11, 1, v0
	v_cmp_ge_i32_e32 vcc, v11, v35
	s_waitcnt vmcnt(45)
	v_mfma_f32_16x16x32_fp8_fp8 v[2:5], v[198:199], v[82:83], v[2:5]
	v_cmp_lt_i32_e64 s[10:11], v0, v132
	s_and_b64 s[12:13], s[10:11], vcc
	s_waitcnt vmcnt(43)
	v_mfma_f32_16x16x32_fp8_fp8 v[6:9], v[196:197], v[78:79], 0
	v_mfma_f32_16x16x32_fp8_fp8 v[2:5], v[192:193], v[84:85], v[2:5]
	s_waitcnt vmcnt(42)
	v_mfma_f32_16x16x32_fp8_fp8 v[6:9], v[190:191], v[80:81], v[6:9]
	s_waitcnt vmcnt(41)
	v_mfma_f32_16x16x32_fp8_fp8 v[6:9], v[188:189], v[82:83], v[6:9]
	s_nop 3
	v_max_f32_e32 v10, v2, v2
	v_max_f32_e32 v10, 0xf149f2ca, v10
	v_cndmask_b32_e64 v10, v223, v10, s[16:17]
	v_max_f32_e32 v11, v3, v3
	v_max_f32_e32 v11, v10, v11
	v_cndmask_b32_e64 v10, v10, v11, s[12:13]
	v_or_b32_e32 v11, 2, v0
	v_cmp_ge_i32_e32 vcc, v11, v35
	v_cmp_le_i32_e64 s[10:11], v11, v132
	v_max_f32_e32 v11, v4, v4
	v_max_f32_e32 v11, v10, v11
	s_and_b64 s[14:15], vcc, s[10:11]
	s_waitcnt vmcnt(40)
	v_mfma_f32_16x16x32_fp8_fp8 v[6:9], v[186:187], v[84:85], v[6:9]
	v_cndmask_b32_e64 v10, v10, v11, s[14:15]
	v_or_b32_e32 v11, 3, v0
	v_cmp_ge_i32_e32 vcc, v11, v35
	v_cmp_le_i32_e64 s[10:11], v11, v132
	v_max_f32_e32 v11, v5, v5
	v_max_f32_e32 v11, v10, v11
	s_and_b64 s[10:11], vcc, s[10:11]
	v_cndmask_b32_e64 v10, v10, v11, s[10:11]
	v_or_b32_e32 v11, 16, v0
	v_cmp_ge_i32_e32 vcc, v11, v35
	v_cmp_le_i32_e64 s[18:19], v11, v132
	v_max_f32_e32 v11, v6, v6
	v_max_f32_e32 v11, v10, v11
	s_and_b64 s[24:25], vcc, s[18:19]
	v_cndmask_b32_e64 v10, v10, v11, s[24:25]
	v_or_b32_e32 v11, 17, v0
	v_cmp_ge_i32_e32 vcc, v11, v35
	v_cmp_le_i32_e64 s[18:19], v11, v132
	v_max_f32_e32 v11, v10, v10
	v_max_f32_e32 v12, v7, v7
	v_max_f32_e32 v11, v11, v12
	s_and_b64 s[20:21], vcc, s[18:19]
	v_cndmask_b32_e64 v10, v10, v11, s[20:21]
	v_or_b32_e32 v11, 18, v0
	v_cmp_ge_i32_e32 vcc, v11, v35
	v_cmp_le_i32_e64 s[18:19], v11, v132
	v_max_f32_e32 v11, v10, v10
	v_max_f32_e32 v12, v8, v8
	v_max_f32_e32 v11, v11, v12
	s_and_b64 s[22:23], vcc, s[18:19]
	v_cndmask_b32_e64 v10, v10, v11, s[22:23]
	v_or_b32_e32 v0, 19, v0
	v_cmp_ge_i32_e32 vcc, v0, v35
	v_cmp_le_i32_e64 s[18:19], v0, v132
	v_max_f32_e32 v0, v10, v10
	v_max_f32_e32 v11, v9, v9
	v_max_f32_e32 v0, v0, v11
	s_and_b64 s[18:19], vcc, s[18:19]
	v_cndmask_b32_e64 v0, v10, v0, s[18:19]
	v_cmp_gt_f32_e32 vcc, v0, v229
	s_cbranch_vccz .LBB0_920
	ds_bpermute_b32 v10, v227, v0
	v_max_f32_e32 v0, v0, v0
	s_waitcnt lgkmcnt(0)
	v_max_f32_e32 v10, v10, v10
	v_max_f32_e32 v0, v0, v10
	ds_bpermute_b32 v10, v226, v0
	s_waitcnt lgkmcnt(0)
	v_max3_f32 v10, v230, v0, v10
	v_sub_f32_e32 v0, v230, v10
	v_exp_f32_e32 v0, v0
	v_mov_b32_e32 v230, v10
	v_mul_f32_e32 v231, v231, v0
	v_pk_mul_f32 v[38:39], v[38:39], v[0:1] op_sel_hi:[1,0]
	v_pk_mul_f32 v[36:37], v[36:37], v[0:1] op_sel_hi:[1,0]
	v_pk_mul_f32 v[42:43], v[42:43], v[0:1] op_sel_hi:[1,0]
	v_pk_mul_f32 v[40:41], v[40:41], v[0:1] op_sel_hi:[1,0]
	v_pk_mul_f32 v[46:47], v[46:47], v[0:1] op_sel_hi:[1,0]
	v_pk_mul_f32 v[44:45], v[44:45], v[0:1] op_sel_hi:[1,0]
	v_pk_mul_f32 v[50:51], v[50:51], v[0:1] op_sel_hi:[1,0]
	v_pk_mul_f32 v[48:49], v[48:49], v[0:1] op_sel_hi:[1,0]
	v_pk_mul_f32 v[54:55], v[54:55], v[0:1] op_sel_hi:[1,0]
	v_pk_mul_f32 v[52:53], v[52:53], v[0:1] op_sel_hi:[1,0]
	v_pk_mul_f32 v[58:59], v[58:59], v[0:1] op_sel_hi:[1,0]
	v_pk_mul_f32 v[56:57], v[56:57], v[0:1] op_sel_hi:[1,0]
	v_pk_mul_f32 v[62:63], v[62:63], v[0:1] op_sel_hi:[1,0]
	v_pk_mul_f32 v[60:61], v[60:61], v[0:1] op_sel_hi:[1,0]
	v_pk_mul_f32 v[66:67], v[66:67], v[0:1] op_sel_hi:[1,0]
	v_pk_mul_f32 v[64:65], v[64:65], v[0:1] op_sel_hi:[1,0]
; template <bool SLC, bool NOMASK> ...
;     ...
;     f32x4 pa, pb; float ps = 0.f;
;     const float mref = st.m - 4.f;
;     if (NOMASK) {
; #pragma unroll
;         for (int j = 0; j < 4; ++j) { pa[j] = __builtin_amdgcn_exp2f(sc[j] - mref); pb[j] = __builtin_amdgcn_exp2f(sc[4 + j] - mref); }
;         if (SLC) {
; #pragma unroll
;             for (int j = 0; j < 4; ++j) { pa[j] = act ? pa[j] : 0.f; pb[j] = act ? pb[j] : 0.f; }
;         }
; #pragma unroll
;         for (int j = 0; j < 4; ++j) ps += pa[j] + pb[j];
;     } else {
; #pragma unroll
;         for (int j = 0; j < 4; ++j) { pa[j] = vd[j] ? __builtin_amdgcn_exp2f(sc[j] - mref) : 0.f; pb[j] = vd[4 + j] ? __builtin_amdgcn_exp2f(sc[4 + j] - mref) : 0.f; ps += pa[j] + pb[j]; }
;     }
;     st.l += ps;
;     const u32x2 pw = pack8_fp8(pa, pb);
;     const i64_t pf = __builtin_bit_cast(i64_t, pw);
; #pragma unroll
;     for (int db = 0; db < 8; ++db) st.o[db] = __builtin_amdgcn_mfma_f32_16x16x32_fp8_fp8(cur.v[db], pf, st.o[db], 0, 0, 0);
.LBB0_920:
	v_add_f32_e32 v0, -4.0, v230
	v_sub_f32_e32 v2, v2, v0
	v_exp_f32_e32 v2, v2
	v_sub_f32_e32 v6, v6, v0
	v_exp_f32_e32 v6, v6
	v_sub_f32_e32 v4, v4, v0
	v_cndmask_b32_e64 v26, 0, v2, s[16:17]
	v_sub_f32_e32 v2, v3, v0
	v_exp_f32_e32 v2, v2
	v_sub_f32_e32 v3, v7, v0
	v_exp_f32_e32 v3, v3
	v_cndmask_b32_e64 v27, 0, v6, s[24:25]
	v_sub_f32_e32 v6, v8, v0
	v_cndmask_b32_e64 v28, 0, v2, s[12:13]
	v_sub_f32_e32 v2, v5, v0
	v_sub_f32_e32 v0, v9, v0
	v_exp_f32_e32 v4, v4
	v_exp_f32_e32 v6, v6
	v_cndmask_b32_e64 v29, 0, v3, s[20:21]
	v_exp_f32_e32 v5, v2
	v_exp_f32_e32 v0, v0
	v_mov_b32_e32 v2, v1
	v_mov_b32_e32 v3, v1
	v_cvt_pk_fp8_f32 v2, v26, v28
	v_cvt_pk_fp8_f32 v3, v27, v29
	v_cndmask_b32_e64 v4, 0, v4, s[14:15]
	v_cndmask_b32_e64 v30, 0, v6, s[22:23]
	v_cndmask_b32_e64 v5, 0, v5, s[10:11]
	v_cndmask_b32_e64 v0, 0, v0, s[18:19]
	v_cvt_pk_fp8_f32 v2, v4, v5 op_sel:[0,0,1]
	v_cvt_pk_fp8_f32 v3, v30, v0 op_sel:[0,0,1]
	v_add_f32_e32 v26, v26, v27
	v_add_f32_e32 v31, 0, v26
	v_add_f32_e32 v32, v28, v29
	v_add_f32_e32 v31, v32, v31
	v_add_f32_e32 v4, v4, v30
	v_add_f32_e32 v4, v4, v31
	v_add_f32_e32 v0, v5, v0
	s_waitcnt vmcnt(39)
	v_mfma_f32_16x16x32_fp8_fp8 v[6:9], v[170:171], v[2:3], v[36:39]
	v_add_f32_e32 v0, v0, v4
	v_add_f32_e32 v34, v231, v0
	v_mov_b32_e32 v133, v230
	s_waitcnt vmcnt(38)
	v_mfma_f32_16x16x32_fp8_fp8 v[10:13], v[172:173], v[2:3], v[40:43]
	s_waitcnt vmcnt(37)
	v_mfma_f32_16x16x32_fp8_fp8 v[14:17], v[174:175], v[2:3], v[44:47]
	s_waitcnt vmcnt(36)
	v_mfma_f32_16x16x32_fp8_fp8 v[18:21], v[176:177], v[2:3], v[48:51]
	s_waitcnt vmcnt(35)
	v_mfma_f32_16x16x32_fp8_fp8 v[22:25], v[184:185], v[2:3], v[52:55]
	s_waitcnt vmcnt(34)
	v_mfma_f32_16x16x32_fp8_fp8 v[26:29], v[180:181], v[2:3], v[56:59]
	s_waitcnt vmcnt(33)
	v_mfma_f32_16x16x32_fp8_fp8 v[30:33], v[182:183], v[2:3], v[60:63]
	s_waitcnt vmcnt(32)
	v_mfma_f32_16x16x32_fp8_fp8 v[2:5], v[178:179], v[2:3], v[64:67]

; __device__ __forceinline__ unsigned cvt_pk_bf16(float lo, float hi) { f32x2 v = {lo, hi}; bf16x2_t b = __builtin_convertvector(v, bf16x2_t); return __builtin_bit_cast(unsigned, b); }
; __device__ __forceinline__ float bf2f(unsigned short b) { return __uint_as_float(((unsigned)b) << 16); }
; __device__ __forceinline__ float bflo(unsigned w) { return __uint_as_float(w << 16); }
; __device__ __forceinline__ float bfhi(unsigned w) { return __uint_as_float(w & 0xffff0000u); }
; __device__ __forceinline__ float quad_total(float v) { v += __shfl_xor(v, 16); v += __shfl_xor(v, 32); return v; }
; __device__ __forceinline__ void nsa_unit(int unit, const bf16_t* proj, const bf16_t* kc, const bf16_t* vc, const bf16_t* gn, const float* cs, const float* sn, ...
;     ...
;     { const float g2 = bf2f(gn[(size_t)tc * 32 + head * 3 + 2]); const float lt = quad_total(st.l), inv = (lt > 0.f ? 1.f / lt : 0.f) * g2;
; #pragma unroll
;         for (int i = 0; i < 8; ++i) { const f32x4 o = st.o[i] * inv; u32x2 w = outl[64 * i]; w.x = cvt_pk_bf16(bflo(w.x) + o[0], bfhi(w.x) + o[1]); w.y = cvt_pk_bf16(bflo(w.y) + o[2], bfhi(w.y) + o[3]); outl[64 * i] = w; } }
;     bf16_t* op = nsaout + (size_t)tc * NOLD + head * 128 + 4 * kq;
; #pragma unroll
;     for (int db = 0; db < 8; ++db) *(u32x2*)(op + 16 * db) = outl[64 * db];
.LBB0_926:
	s_waitcnt vmcnt(16)
	global_load_ushort v0, v[76:77], off offset:4
	ds_bpermute_b32 v35, v225, v34
	ds_read2st64_b64 v[36:39], v226 offset0:27 offset1:28
	ds_read2st64_b64 v[40:43], v226 offset0:29 offset1:30
	ds_read2st64_b64 v[44:47], v226 offset0:31 offset1:32
	ds_read2st64_b64 v[48:51], v226 offset0:33 offset1:34
	s_waitcnt lgkmcnt(3)
	v_lshlrev_b32_e32 v52, 16, v38
	v_and_b32_e32 v53, 0xffff0000, v38
	v_add_f32_e32 v64, v34, v35
	ds_bpermute_b32 v65, v224, v64
	v_lshlrev_b32_e32 v34, 16, v36
	v_and_b32_e32 v35, 0xffff0000, v36
	v_lshlrev_b32_e32 v36, 16, v37
	v_and_b32_e32 v37, 0xffff0000, v37
	s_waitcnt lgkmcnt(0)
	v_add_f32_e32 v64, v64, v65
	v_div_scale_f32 v65, s[10:11], v64, v64, 1.0
	v_rcp_f32_e32 v66, v65
	v_div_scale_f32 v67, vcc, 1.0, v64, 1.0
	v_lshlrev_b32_e32 v38, 16, v39
	v_fma_f32 v68, -v65, v66, 1.0
	v_fmac_f32_e32 v66, v68, v66
	v_mul_f32_e32 v68, v67, v66
	v_fma_f32 v69, -v65, v68, v67
	v_fmac_f32_e32 v68, v69, v66
	v_fma_f32 v65, -v65, v68, v67
	v_div_fmas_f32 v65, v65, v66, v68
	v_div_fixup_f32 v65, v65, v64, 1.0
	v_cmp_lt_f32_e32 vcc, 0, v64
	v_and_b32_e32 v39, 0xffff0000, v39
	v_lshlrev_b32_e32 v56, 16, v42
	v_cndmask_b32_e32 v64, 0, v65, vcc
	v_and_b32_e32 v57, 0xffff0000, v42
	v_lshlrev_b32_e32 v42, 16, v43
	v_and_b32_e32 v43, 0xffff0000, v43
	v_lshlrev_b32_e32 v62, 16, v48
	v_and_b32_e32 v63, 0xffff0000, v48
	v_lshlrev_b32_e32 v48, 16, v49
	v_and_b32_e32 v49, 0xffff0000, v49
	v_lshlrev_b32_e32 v54, 16, v40
	v_and_b32_e32 v55, 0xffff0000, v40
	v_lshlrev_b32_e32 v40, 16, v41
	v_and_b32_e32 v41, 0xffff0000, v41
	v_lshlrev_b32_e32 v58, 16, v44
	v_and_b32_e32 v59, 0xffff0000, v44
	v_lshlrev_b32_e32 v44, 16, v45
	v_and_b32_e32 v45, 0xffff0000, v45
	v_lshlrev_b32_e32 v60, 16, v46
	v_and_b32_e32 v61, 0xffff0000, v46
	v_lshlrev_b32_e32 v46, 16, v47
	v_and_b32_e32 v47, 0xffff0000, v47
	s_waitcnt vmcnt(0)
	v_lshlrev_b32_e32 v0, 16, v0
	v_mul_f32_e32 v0, v64, v0
	v_pk_fma_f32 v[6:7], v[6:7], v[0:1], v[34:35] op_sel_hi:[1,0,1]
	v_pk_fma_f32 v[8:9], v[8:9], v[0:1], v[36:37] op_sel_hi:[1,0,1]
	v_pk_fma_f32 v[12:13], v[12:13], v[0:1], v[38:39] op_sel_hi:[1,0,1]
	v_pk_fma_f32 v[20:21], v[20:21], v[0:1], v[42:43] op_sel_hi:[1,0,1]
	v_cvt_pk_bf16_f32 v6, v6, v7
	v_cvt_pk_bf16_f32 v7, v8, v9
	v_cvt_pk_bf16_f32 v9, v12, v13
	v_cvt_pk_bf16_f32 v13, v20, v21
	v_lshlrev_b32_e32 v20, 16, v50
	v_and_b32_e32 v21, 0xffff0000, v50
	v_pk_fma_f32 v[2:3], v[2:3], v[0:1], v[20:21] op_sel_hi:[1,0,1]
	v_lshlrev_b32_e32 v20, 16, v51
	v_and_b32_e32 v21, 0xffff0000, v51
	v_pk_fma_f32 v[10:11], v[10:11], v[0:1], v[52:53] op_sel_hi:[1,0,1]
	v_pk_fma_f32 v[18:19], v[18:19], v[0:1], v[56:57] op_sel_hi:[1,0,1]
	v_pk_fma_f32 v[30:31], v[30:31], v[0:1], v[62:63] op_sel_hi:[1,0,1]
	v_pk_fma_f32 v[32:33], v[32:33], v[0:1], v[48:49] op_sel_hi:[1,0,1]
	v_pk_fma_f32 v[4:5], v[4:5], v[0:1], v[20:21] op_sel_hi:[1,0,1]
	v_pk_fma_f32 v[14:15], v[14:15], v[0:1], v[54:55] op_sel_hi:[1,0,1]
	v_pk_fma_f32 v[16:17], v[16:17], v[0:1], v[40:41] op_sel_hi:[1,0,1]
	v_pk_fma_f32 v[22:23], v[22:23], v[0:1], v[58:59] op_sel_hi:[1,0,1]
	v_pk_fma_f32 v[24:25], v[24:25], v[0:1], v[44:45] op_sel_hi:[1,0,1]
	v_pk_fma_f32 v[26:27], v[26:27], v[0:1], v[60:61] op_sel_hi:[1,0,1]
	v_pk_fma_f32 v[28:29], v[28:29], v[0:1], v[46:47] op_sel_hi:[1,0,1]
	v_cvt_pk_bf16_f32 v8, v10, v11
	v_cvt_pk_bf16_f32 v12, v18, v19
	v_cvt_pk_bf16_f32 v18, v30, v31
	v_cvt_pk_bf16_f32 v19, v32, v33
	v_cvt_pk_bf16_f32 v2, v2, v3
	v_cvt_pk_bf16_f32 v3, v4, v5
	v_mad_i64_i32 v[4:5], s[10:11], v132, s88, v[126:127]
	v_cvt_pk_bf16_f32 v10, v14, v15
	v_cvt_pk_bf16_f32 v11, v16, v17
	v_cvt_pk_bf16_f32 v14, v22, v23
	v_cvt_pk_bf16_f32 v15, v24, v25
	v_cvt_pk_bf16_f32 v16, v26, v27
	v_cvt_pk_bf16_f32 v17, v28, v29
	ds_write2st64_b64 v226, v[6:7], v[8:9] offset0:27 offset1:28
	ds_write2st64_b64 v226, v[10:11], v[12:13] offset0:29 offset1:30
	ds_write2st64_b64 v226, v[14:15], v[16:17] offset0:31 offset1:32
	ds_write2st64_b64 v226, v[18:19], v[2:3] offset0:33 offset1:34
	global_store_dwordx2 v[4:5], v[6:7], off
	global_store_dwordx2 v[4:5], v[8:9], off offset:32
	global_store_dwordx2 v[4:5], v[10:11], off offset:64
	global_store_dwordx2 v[4:5], v[12:13], off offset:96
	global_store_dwordx2 v[4:5], v[14:15], off offset:128
	global_store_dwordx2 v[4:5], v[16:17], off offset:160
	global_store_dwordx2 v[4:5], v[18:19], off offset:192
	global_store_dwordx2 v[4:5], v[2:3], off offset:224

; template <bool SLC, bool NOMASK> ...
;     const int kq = lane >> 4;
;     const int pos0 = SLC ? (dcur & 0xfffff) : dcur;
;     const int lo = SLC ? ((((dcur >> 20) == qi) | ((dcur >> 20) == 4)) ? 0 : (1 << 30)) : lo_in;
;     load_frag8(nxt, KF, VF, SLC ? (dnext & 0xfffff) : dnext, lane);
;     f32x4 sa[2] = {(f32x4){0.f, 0.f, 0.f, 0.f}, (f32x4){0.f, 0.f, 0.f, 0.f}};
; #pragma unroll
;     for (int T = 0; T < 2; ++T)
; #pragma unroll
;         for (int s2 = 0; s2 < 4; ++s2) sa[T] = __builtin_amdgcn_mfma_f32_16x16x32_fp8_fp8(cur.k[T][s2], qf[s2], sa[T], 0, 0, 0);
;     float sc[8]; bool vd[8]; float mx = -1e30f;
;     const bool act = lo == 0 || !SLC;
;     if (NOMASK) {
; #pragma unroll
;         for (int j = 0; j < 8; ++j) { sc[j] = sa[j >> 2][j & 3]; vd[j] = act; }
;         mx = fmaxf(fmaxf(fmaxf(sc[0], sc[1]), fmaxf(sc[2], sc[3])), fmaxf(fmaxf(sc[4], sc[5]), fmaxf(sc[6], sc[7])));
;         mx = act ? mx : -1e30f;
;     } else {
; #pragma unroll
;         for (int T = 0; T < 2; ++T)
; #pragma unroll
;             for (int r = 0; r < 4; ++r) { const int p = pos0 + 16 * T + 4 * kq + r; const bool v = (p >= lo) & (p <= hi); const float x = sa[T][r];
;                 sc[4 * T + r] = x; vd[4 * T + r] = v; mx = v ? fmaxf(mx, x) : mx; }
;     }
;     if (__builtin_amdgcn_ballot_w64(mx > st.m + 4.f) != 0ull) {
;         mx = fmaxf(mx, __shfl_xor(mx, 16)); mx = fmaxf(mx, __shfl_xor(mx, 32));
;         const float mn = fmaxf(st.m, mx), alpha = __builtin_amdgcn_exp2f(st.m - mn); st.m = mn; st.l *= alpha;
; #pragma unroll
;         for (int j = 0; j < 8; ++j) st.o[j] = st.o[j] * alpha;
;     }
;     f32x4 pa, pb; float ps = 0.f;
;     const float mref = st.m - 4.f;
;     if (NOMASK) {
; #pragma unroll
;         for (int j = 0; j < 4; ++j) { pa[j] = __builtin_amdgcn_exp2f(sc[j] - mref); pb[j] = __builtin_amdgcn_exp2f(sc[4 + j] - mref); }
;         if (SLC) {
; #pragma unroll
;             for (int j = 0; j < 4; ++j) { pa[j] = act ? pa[j] : 0.f; pb[j] = act ? pb[j] : 0.f; }
;         }
; #pragma unroll
;         for (int j = 0; j < 4; ++j) ps += pa[j] + pb[j];
;     } else {
; #pragma unroll
;         for (int j = 0; j < 4; ++j) { pa[j] = vd[j] ? __builtin_amdgcn_exp2f(sc[j] - mref) : 0.f; pb[j] = vd[4 + j] ? __builtin_amdgcn_exp2f(sc[4 + j] - mref) : 0.f; ps += pa[j] + pb[j]; }
;     }
;     st.l += ps;
;     const u32x2 pw = pack8_fp8(pa, pb);
.LBB0_969:
	s_and_b32 s13, s12, 0xfffffbff
	s_cmp_eq_u32 s13, 4
	s_cselect_b64 s[10:11], -1, 0
	s_lshl_b32 s14, s66, 7
	s_and_b32 s50, s14, 0x7fff800
	v_lshl_add_u64 v[10:11], v[86:87], 0, s[50:51]
	s_and_b32 s50, s14, 0x7fff000
	global_load_dwordx2 v[192:193], v[10:11], off
	global_load_dwordx2 v[200:201], v[10:11], off offset:512
	global_load_dwordx2 v[198:199], v[10:11], off offset:1024
	global_load_dwordx2 v[194:195], v[10:11], off offset:1536
	global_load_dwordx2 v[196:197], v[10:11], off offset:2048
	global_load_dwordx2 v[190:191], v[10:11], off offset:2560
	global_load_dwordx2 v[188:189], v[10:11], off offset:3072
	global_load_dwordx2 v[186:187], v[10:11], off offset:3584
	v_lshl_add_u64 v[10:11], v[88:89], 0, s[50:51]
	global_load_dwordx2 v[170:171], v[10:11], off
	global_load_dwordx2 v[172:173], v[10:11], off offset:512
	global_load_dwordx2 v[174:175], v[10:11], off offset:1024
	global_load_dwordx2 v[176:177], v[10:11], off offset:1536
	global_load_dwordx2 v[184:185], v[10:11], off offset:2048
	global_load_dwordx2 v[182:183], v[10:11], off offset:2560
	global_load_dwordx2 v[180:181], v[10:11], off offset:3072
	global_load_dwordx2 v[178:179], v[10:11], off offset:3584
	s_waitcnt vmcnt(47)
	v_mfma_f32_16x16x32_fp8_fp8 v[2:5], v[144:145], v[78:79], 0
	v_cmp_eq_u32_e32 vcc, s13, v209
	s_or_b64 s[10:11], s[10:11], vcc
	v_mov_b64_e32 v[74:75], v[38:39]
	s_waitcnt vmcnt(43)
	v_mfma_f32_16x16x32_fp8_fp8 v[6:9], v[148:149], v[78:79], 0
	v_mov_b64_e32 v[70:71], v[42:43]
	v_mov_b64_e32 v[30:31], v[44:45]
	v_mov_b64_e32 v[26:27], v[48:49]
	v_mfma_f32_16x16x32_fp8_fp8 v[2:5], v[152:153], v[80:81], v[2:5]
	v_mov_b64_e32 v[22:23], v[52:53]
	v_mov_b64_e32 v[18:19], v[56:57]
	v_mov_b64_e32 v[14:15], v[60:61]
	s_waitcnt vmcnt(42)
	v_mfma_f32_16x16x32_fp8_fp8 v[6:9], v[142:143], v[80:81], v[6:9]
	v_mov_b64_e32 v[72:73], v[36:37]
	v_mov_b64_e32 v[68:69], v[40:41]
	v_mov_b64_e32 v[32:33], v[46:47]
	v_mfma_f32_16x16x32_fp8_fp8 v[2:5], v[150:151], v[82:83], v[2:5]
	v_mov_b64_e32 v[28:29], v[50:51]
	v_mov_b64_e32 v[24:25], v[54:55]
	v_mov_b64_e32 v[20:21], v[58:59]
	s_waitcnt vmcnt(41)
	v_mfma_f32_16x16x32_fp8_fp8 v[6:9], v[140:141], v[82:83], v[6:9]
	v_mov_b64_e32 v[16:17], v[62:63]
	v_mov_b32_e32 v133, v203
	v_mfma_f32_16x16x32_fp8_fp8 v[2:5], v[146:147], v[84:85], v[2:5]
	s_waitcnt vmcnt(40)
	v_mfma_f32_16x16x32_fp8_fp8 v[6:9], v[138:139], v[84:85], v[6:9]
	s_nop 5
	v_max_f32_e32 v0, v3, v3
	v_max_f32_e32 v10, v2, v2
	v_max_f32_e32 v0, v10, v0
	v_max_f32_e32 v10, v5, v5
	v_max_f32_e32 v11, v4, v4
	v_max_f32_e32 v10, v11, v10
	v_max_f32_e32 v11, v9, v9
	v_max_f32_e32 v12, v8, v8
	v_max_f32_e32 v11, v12, v11
	v_max3_f32 v11, v6, v7, v11
	v_max3_f32 v0, v0, v10, v11
	v_cndmask_b32_e64 v34, v220, v0, s[10:11]
	v_mov_b64_e32 v[10:11], v[64:65]
	v_cmp_gt_f32_e32 vcc, v34, v204
	v_mov_b32_e32 v0, v202
	v_mov_b64_e32 v[12:13], v[66:67]
	s_cbranch_vccz .LBB0_971
	ds_bpermute_b32 v0, v225, v34
	v_max_f32_e32 v10, v34, v34
	s_waitcnt lgkmcnt(0)
	v_max_f32_e32 v0, v0, v0
	v_max_f32_e32 v0, v10, v0
	ds_bpermute_b32 v10, v224, v0
	s_waitcnt lgkmcnt(0)
	v_max3_f32 v0, v202, v0, v10
	v_sub_f32_e32 v10, v202, v0
	v_exp_f32_e32 v34, v10
	s_nop 0
	v_mul_f32_e32 v133, v203, v34
	v_pk_mul_f32 v[12:13], v[66:67], v[34:35] op_sel_hi:[1,0]
	v_pk_mul_f32 v[10:11], v[64:65], v[34:35] op_sel_hi:[1,0]
	v_pk_mul_f32 v[16:17], v[62:63], v[34:35] op_sel_hi:[1,0]
	v_pk_mul_f32 v[14:15], v[60:61], v[34:35] op_sel_hi:[1,0]
	v_pk_mul_f32 v[20:21], v[58:59], v[34:35] op_sel_hi:[1,0]
	v_pk_mul_f32 v[18:19], v[56:57], v[34:35] op_sel_hi:[1,0]
	v_pk_mul_f32 v[24:25], v[54:55], v[34:35] op_sel_hi:[1,0]
	v_pk_mul_f32 v[22:23], v[52:53], v[34:35] op_sel_hi:[1,0]
	v_pk_mul_f32 v[28:29], v[50:51], v[34:35] op_sel_hi:[1,0]
	v_pk_mul_f32 v[26:27], v[48:49], v[34:35] op_sel_hi:[1,0]
	v_pk_mul_f32 v[32:33], v[46:47], v[34:35] op_sel_hi:[1,0]
	v_pk_mul_f32 v[30:31], v[44:45], v[34:35] op_sel_hi:[1,0]
	v_pk_mul_f32 v[70:71], v[42:43], v[34:35] op_sel_hi:[1,0]
	v_pk_mul_f32 v[68:69], v[40:41], v[34:35] op_sel_hi:[1,0]
	v_pk_mul_f32 v[74:75], v[38:39], v[34:35] op_sel_hi:[1,0]
	v_pk_mul_f32 v[72:73], v[36:37], v[34:35] op_sel_hi:[1,0]
.LBB0_971:
	v_add_f32_e32 v34, -4.0, v0
	v_sub_f32_e32 v2, v2, v34
	v_sub_f32_e32 v6, v6, v34
	v_sub_f32_e32 v3, v3, v34
	v_sub_f32_e32 v7, v7, v34
	v_exp_f32_e32 v2, v2
	v_exp_f32_e32 v6, v6
	v_exp_f32_e32 v3, v3
	v_exp_f32_e32 v7, v7
	v_sub_f32_e32 v4, v4, v34
	v_sub_f32_e32 v8, v8, v34
	v_sub_f32_e32 v5, v5, v34
	v_sub_f32_e32 v9, v9, v34
	v_exp_f32_e32 v4, v4
	v_exp_f32_e32 v8, v8
	v_exp_f32_e32 v5, v5
	v_exp_f32_e32 v9, v9
	v_cndmask_b32_e64 v34, 0, v2, s[10:11]
	v_cndmask_b32_e64 v6, 0, v6, s[10:11]
	v_cndmask_b32_e64 v35, 0, v3, s[10:11]
	v_cndmask_b32_e64 v7, 0, v7, s[10:11]
	v_mov_b32_e32 v2, v1
	v_mov_b32_e32 v3, v1
	v_cvt_pk_fp8_f32 v2, v34, v35
	v_cvt_pk_fp8_f32 v3, v6, v7
	v_cndmask_b32_e64 v4, 0, v4, s[10:11]
	v_cndmask_b32_e64 v205, 0, v8, s[10:11]
	v_cndmask_b32_e64 v5, 0, v5, s[10:11]
	v_cndmask_b32_e64 v227, 0, v9, s[10:11]
	v_add_f32_e32 v6, v34, v6
	v_cvt_pk_fp8_f32 v2, v4, v5 op_sel:[0,0,1]
	v_cvt_pk_fp8_f32 v3, v205, v227 op_sel:[0,0,1]
	v_add_f32_e32 v6, 0, v6
	v_add_f32_e32 v7, v35, v7
	v_add_f32_e32 v6, v7, v6
	v_add_f32_e32 v4, v4, v205
	v_add_f32_e32 v4, v4, v6
	v_add_f32_e32 v5, v5, v227
	v_add_f32_e32 v4, v5, v4
	s_waitcnt vmcnt(39)
	v_mfma_f32_16x16x32_fp8_fp8 v[8:11], v[90:91], v[2:3], v[10:13]
	v_add_f32_e32 v133, v133, v4
	s_waitcnt vmcnt(38)
	v_mfma_f32_16x16x32_fp8_fp8 v[12:15], v[92:93], v[2:3], v[14:17]
	s_waitcnt vmcnt(37)
	v_mfma_f32_16x16x32_fp8_fp8 v[16:19], v[94:95], v[2:3], v[18:21]
	s_waitcnt vmcnt(36)
	v_mfma_f32_16x16x32_fp8_fp8 v[20:23], v[96:97], v[2:3], v[22:25]
	s_waitcnt vmcnt(35)
	v_mfma_f32_16x16x32_fp8_fp8 v[24:27], v[104:105], v[2:3], v[26:29]
	s_waitcnt vmcnt(34)
	v_mfma_f32_16x16x32_fp8_fp8 v[32:35], v[102:103], v[2:3], v[30:33]
	s_waitcnt vmcnt(33)
	v_mfma_f32_16x16x32_fp8_fp8 v[28:31], v[100:101], v[2:3], v[68:71]
	s_waitcnt vmcnt(32)
	v_mfma_f32_16x16x32_fp8_fp8 v[4:7], v[98:99], v[2:3], v[72:75]
	s_branch .LBB0_965
; template <bool SLC, bool NOMASK> ...
;     const int kq = lane >> 4;
;     const int pos0 = SLC ? (dcur & 0xfffff) : dcur;
;     const int lo = SLC ? ((((dcur >> 20) == qi) | ((dcur >> 20) == 4)) ? 0 : (1 << 30)) : lo_in;
;     load_frag8(nxt, KF, VF, SLC ? (dnext & 0xfffff) : dnext, lane);
;     f32x4 sa[2] = {(f32x4){0.f, 0.f, 0.f, 0.f}, (f32x4){0.f, 0.f, 0.f, 0.f}};
; #pragma unroll
;     for (int T = 0; T < 2; ++T)
; #pragma unroll
;         for (int s2 = 0; s2 < 4; ++s2) sa[T] = __builtin_amdgcn_mfma_f32_16x16x32_fp8_fp8(cur.k[T][s2], qf[s2], sa[T], 0, 0, 0);
;     float sc[8]; bool vd[8]; float mx = -1e30f;
;     const bool act = lo == 0 || !SLC;
;     if (NOMASK) {
; #pragma unroll
;         for (int j = 0; j < 8; ++j) { sc[j] = sa[j >> 2][j & 3]; vd[j] = act; }
;         mx = fmaxf(fmaxf(fmaxf(sc[0], sc[1]), fmaxf(sc[2], sc[3])), fmaxf(fmaxf(sc[4], sc[5]), fmaxf(sc[6], sc[7])));
;         mx = act ? mx : -1e30f;
;     } else {
; #pragma unroll
;         for (int T = 0; T < 2; ++T)
; #pragma unroll
;             for (int r = 0; r < 4; ++r) { const int p = pos0 + 16 * T + 4 * kq + r; const bool v = (p >= lo) & (p <= hi); const float x = sa[T][r];
;                 sc[4 * T + r] = x; vd[4 * T + r] = v; mx = v ? fmaxf(mx, x) : mx; }
;     }
;     if (__builtin_amdgcn_ballot_w64(mx > st.m + 4.f) != 0ull) {
;         mx = fmaxf(mx, __shfl_xor(mx, 16)); mx = fmaxf(mx, __shfl_xor(mx, 32));
;         const float mn = fmaxf(st.m, mx), alpha = __builtin_amdgcn_exp2f(st.m - mn); st.m = mn; st.l *= alpha;
; #pragma unroll
;         for (int j = 0; j < 8; ++j) st.o[j] = st.o[j] * alpha;
;     }
;     f32x4 pa, pb; float ps = 0.f;
;     const float mref = st.m - 4.f;
;     if (NOMASK) {
; #pragma unroll
;         for (int j = 0; j < 4; ++j) { pa[j] = __builtin_amdgcn_exp2f(sc[j] - mref); pb[j] = __builtin_amdgcn_exp2f(sc[4 + j] - mref); }
;         if (SLC) {
; #pragma unroll
;             for (int j = 0; j < 4; ++j) { pa[j] = act ? pa[j] : 0.f; pb[j] = act ? pb[j] : 0.f; }
;         }
; #pragma unroll
;         for (int j = 0; j < 4; ++j) ps += pa[j] + pb[j];
;     } else {
; #pragma unroll
;         for (int j = 0; j < 4; ++j) { pa[j] = vd[j] ? __builtin_amdgcn_exp2f(sc[j] - mref) : 0.f; pb[j] = vd[4 + j] ? __builtin_amdgcn_exp2f(sc[4 + j] - mref) : 0.f; ps += pa[j] + pb[j]; }
;     }
;     st.l += ps;
;     const u32x2 pw = pack8_fp8(pa, pb);
.LBB0_972:
	s_cmp_eq_u32 s12, 4
	s_cselect_b64 s[10:11], -1, 0
	s_lshl_b32 s13, s66, 7
	s_and_b32 s50, s13, 0x7fff800
	v_lshl_add_u64 v[10:11], v[86:87], 0, s[50:51]
	s_and_b32 s50, s13, 0x7fff000
	global_load_dwordx2 v[192:193], v[10:11], off
	global_load_dwordx2 v[200:201], v[10:11], off offset:512
	global_load_dwordx2 v[198:199], v[10:11], off offset:1024
	global_load_dwordx2 v[194:195], v[10:11], off offset:1536
	global_load_dwordx2 v[196:197], v[10:11], off offset:2048
	global_load_dwordx2 v[190:191], v[10:11], off offset:2560
	global_load_dwordx2 v[188:189], v[10:11], off offset:3072
	global_load_dwordx2 v[186:187], v[10:11], off offset:3584
	v_lshl_add_u64 v[10:11], v[88:89], 0, s[50:51]
	global_load_dwordx2 v[170:171], v[10:11], off
	global_load_dwordx2 v[172:173], v[10:11], off offset:512
	global_load_dwordx2 v[174:175], v[10:11], off offset:1024
	global_load_dwordx2 v[176:177], v[10:11], off offset:1536
	global_load_dwordx2 v[184:185], v[10:11], off offset:2048
	global_load_dwordx2 v[182:183], v[10:11], off offset:2560
	global_load_dwordx2 v[180:181], v[10:11], off offset:3072
	global_load_dwordx2 v[178:179], v[10:11], off offset:3584
	s_waitcnt vmcnt(47)
	v_mfma_f32_16x16x32_fp8_fp8 v[2:5], v[144:145], v[78:79], 0
	s_and_b32 s13, s57, 0xfffff
	v_cmp_eq_u32_e32 vcc, s12, v209
	v_add_u32_e32 v0, s13, v210
	s_waitcnt vmcnt(46)
	v_mfma_f32_16x16x32_fp8_fp8 v[2:5], v[152:153], v[80:81], v[2:5]
	s_or_b64 s[18:19], s[10:11], vcc
	v_cmp_le_i32_e32 vcc, v0, v132
	s_and_b64 s[16:17], s[18:19], vcc
	s_waitcnt vmcnt(45)
	v_mfma_f32_16x16x32_fp8_fp8 v[2:5], v[150:151], v[82:83], v[2:5]
	v_cmp_lt_i32_e32 vcc, v0, v132
	s_and_b64 s[12:13], s[18:19], vcc
	s_waitcnt vmcnt(43)
	v_mfma_f32_16x16x32_fp8_fp8 v[6:9], v[148:149], v[78:79], 0
	v_mfma_f32_16x16x32_fp8_fp8 v[2:5], v[146:147], v[84:85], v[2:5]
	s_waitcnt vmcnt(42)
	v_mfma_f32_16x16x32_fp8_fp8 v[6:9], v[142:143], v[80:81], v[6:9]
	s_waitcnt vmcnt(41)
	v_mfma_f32_16x16x32_fp8_fp8 v[6:9], v[140:141], v[82:83], v[6:9]
	s_nop 3
	v_max_f32_e32 v10, v2, v2
	v_max_f32_e32 v10, 0xf149f2ca, v10
	v_cndmask_b32_e64 v10, v220, v10, s[16:17]
	v_max_f32_e32 v11, v3, v3
	v_max_f32_e32 v11, v10, v11
	v_cndmask_b32_e64 v10, v10, v11, s[12:13]
	v_add_u32_e32 v11, 2, v0
	v_cmp_le_i32_e32 vcc, v11, v132
	v_max_f32_e32 v11, v4, v4
	v_max_f32_e32 v11, v10, v11
	s_and_b64 s[14:15], s[18:19], vcc
	s_waitcnt vmcnt(40)
	v_mfma_f32_16x16x32_fp8_fp8 v[6:9], v[138:139], v[84:85], v[6:9]
	v_cndmask_b32_e64 v10, v10, v11, s[14:15]
	v_add_u32_e32 v11, 3, v0
	v_cmp_le_i32_e32 vcc, v11, v132
	v_max_f32_e32 v11, v5, v5
	v_max_f32_e32 v11, v10, v11
	s_and_b64 s[10:11], s[18:19], vcc
	v_cndmask_b32_e64 v10, v10, v11, s[10:11]
	v_add_u32_e32 v11, 16, v0
	v_cmp_le_i32_e32 vcc, v11, v132
	v_max_f32_e32 v11, v6, v6
	v_max_f32_e32 v11, v10, v11
	s_and_b64 s[24:25], s[18:19], vcc
	v_cndmask_b32_e64 v10, v10, v11, s[24:25]
	v_add_u32_e32 v11, 17, v0
	v_cmp_le_i32_e32 vcc, v11, v132
	v_max_f32_e32 v11, v10, v10
	v_max_f32_e32 v12, v7, v7
	v_max_f32_e32 v11, v11, v12
	s_and_b64 s[20:21], s[18:19], vcc
	v_cndmask_b32_e64 v10, v10, v11, s[20:21]
	v_add_u32_e32 v11, 18, v0
	v_cmp_le_i32_e32 vcc, v11, v132
	v_max_f32_e32 v11, v10, v10
	v_max_f32_e32 v12, v8, v8
	v_max_f32_e32 v11, v11, v12
	s_and_b64 s[22:23], s[18:19], vcc
	v_cndmask_b32_e64 v10, v10, v11, s[22:23]
	v_add_u32_e32 v0, 19, v0
	v_cmp_le_i32_e32 vcc, v0, v132
	v_max_f32_e32 v0, v10, v10
	v_max_f32_e32 v11, v9, v9
	v_max_f32_e32 v0, v0, v11
	s_and_b64 s[18:19], s[18:19], vcc
	v_cndmask_b32_e64 v0, v10, v0, s[18:19]
	v_cmp_gt_f32_e32 vcc, v0, v204
	s_cbranch_vccz .LBB0_974
	ds_bpermute_b32 v10, v225, v0
	v_max_f32_e32 v0, v0, v0
	s_waitcnt lgkmcnt(0)
	v_max_f32_e32 v10, v10, v10
	v_max_f32_e32 v0, v0, v10
	ds_bpermute_b32 v10, v224, v0
	s_waitcnt lgkmcnt(0)
	v_max3_f32 v10, v202, v0, v10
	v_sub_f32_e32 v0, v202, v10
	v_exp_f32_e32 v0, v0
	v_mov_b32_e32 v202, v10
	v_mul_f32_e32 v203, v203, v0
	v_pk_mul_f32 v[66:67], v[66:67], v[0:1] op_sel_hi:[1,0]
	v_pk_mul_f32 v[64:65], v[64:65], v[0:1] op_sel_hi:[1,0]
	v_pk_mul_f32 v[62:63], v[62:63], v[0:1] op_sel_hi:[1,0]
	v_pk_mul_f32 v[60:61], v[60:61], v[0:1] op_sel_hi:[1,0]
	v_pk_mul_f32 v[58:59], v[58:59], v[0:1] op_sel_hi:[1,0]
	v_pk_mul_f32 v[56:57], v[56:57], v[0:1] op_sel_hi:[1,0]
	v_pk_mul_f32 v[54:55], v[54:55], v[0:1] op_sel_hi:[1,0]
	v_pk_mul_f32 v[52:53], v[52:53], v[0:1] op_sel_hi:[1,0]
	v_pk_mul_f32 v[50:51], v[50:51], v[0:1] op_sel_hi:[1,0]
	v_pk_mul_f32 v[48:49], v[48:49], v[0:1] op_sel_hi:[1,0]
	v_pk_mul_f32 v[46:47], v[46:47], v[0:1] op_sel_hi:[1,0]
	v_pk_mul_f32 v[44:45], v[44:45], v[0:1] op_sel_hi:[1,0]
	v_pk_mul_f32 v[42:43], v[42:43], v[0:1] op_sel_hi:[1,0]
	v_pk_mul_f32 v[40:41], v[40:41], v[0:1] op_sel_hi:[1,0]
	v_pk_mul_f32 v[38:39], v[38:39], v[0:1] op_sel_hi:[1,0]
	v_pk_mul_f32 v[36:37], v[36:37], v[0:1] op_sel_hi:[1,0]
.LBB0_974:
	v_add_f32_e32 v0, -4.0, v202
	v_sub_f32_e32 v2, v2, v0
	v_exp_f32_e32 v2, v2
	v_sub_f32_e32 v6, v6, v0
	v_exp_f32_e32 v6, v6
	v_sub_f32_e32 v4, v4, v0
	v_cndmask_b32_e64 v28, 0, v2, s[16:17]
	v_sub_f32_e32 v2, v3, v0
	v_exp_f32_e32 v2, v2
	v_sub_f32_e32 v3, v7, v0
	v_exp_f32_e32 v3, v3
	v_sub_f32_e32 v7, v8, v0
	v_cndmask_b32_e64 v29, 0, v2, s[12:13]
	v_sub_f32_e32 v2, v5, v0
	v_sub_f32_e32 v0, v9, v0
	v_cndmask_b32_e64 v6, 0, v6, s[24:25]
	v_exp_f32_e32 v4, v4
	v_exp_f32_e32 v7, v7
	v_cndmask_b32_e64 v30, 0, v3, s[20:21]
	v_exp_f32_e32 v5, v2
	v_exp_f32_e32 v0, v0
	v_mov_b32_e32 v2, v1
	v_mov_b32_e32 v3, v1
	v_cvt_pk_fp8_f32 v2, v28, v29
	v_cvt_pk_fp8_f32 v3, v6, v30
	v_cndmask_b32_e64 v4, 0, v4, s[14:15]
	v_cndmask_b32_e64 v7, 0, v7, s[22:23]
	v_cndmask_b32_e64 v5, 0, v5, s[10:11]
	v_cndmask_b32_e64 v0, 0, v0, s[18:19]
	v_cvt_pk_fp8_f32 v2, v4, v5 op_sel:[0,0,1]
	v_cvt_pk_fp8_f32 v3, v7, v0 op_sel:[0,0,1]
	v_add_f32_e32 v6, v28, v6
	v_add_f32_e32 v6, 0, v6
	v_add_f32_e32 v28, v29, v30
	v_add_f32_e32 v6, v28, v6
	v_add_f32_e32 v4, v4, v7
	v_add_f32_e32 v4, v4, v6
	v_add_f32_e32 v0, v5, v0
	s_waitcnt vmcnt(39)
	v_mfma_f32_16x16x32_fp8_fp8 v[8:11], v[90:91], v[2:3], v[64:67]
	v_add_f32_e32 v0, v0, v4
	v_add_f32_e32 v133, v203, v0
	v_mov_b32_e32 v0, v202
	s_waitcnt vmcnt(38)
	v_mfma_f32_16x16x32_fp8_fp8 v[12:15], v[92:93], v[2:3], v[60:63]
	s_waitcnt vmcnt(37)
	v_mfma_f32_16x16x32_fp8_fp8 v[16:19], v[94:95], v[2:3], v[56:59]
	s_waitcnt vmcnt(36)
	v_mfma_f32_16x16x32_fp8_fp8 v[20:23], v[96:97], v[2:3], v[52:55]
	s_waitcnt vmcnt(35)
	v_mfma_f32_16x16x32_fp8_fp8 v[24:27], v[104:105], v[2:3], v[48:51]
	s_waitcnt vmcnt(34)
	v_mfma_f32_16x16x32_fp8_fp8 v[32:35], v[102:103], v[2:3], v[44:47]
	s_waitcnt vmcnt(33)
	v_mfma_f32_16x16x32_fp8_fp8 v[28:31], v[100:101], v[2:3], v[40:43]
	s_waitcnt vmcnt(32)
	v_mfma_f32_16x16x32_fp8_fp8 v[4:7], v[98:99], v[2:3], v[36:39]
	s_add_i32 s10, s56, -3
	s_cmp_ge_u32 s10, s54
	s_mov_b64 s[10:11], -1
	s_cbranch_scc0 .LBB0_966

; template <bool SLC, bool NOMASK> ...
;     const int kq = lane >> 4;
;     const int pos0 = SLC ? (dcur & 0xfffff) : dcur;
;     const int lo = SLC ? ((((dcur >> 20) == qi) | ((dcur >> 20) == 4)) ? 0 : (1 << 30)) : lo_in;
;     load_frag8(nxt, KF, VF, SLC ? (dnext & 0xfffff) : dnext, lane);
;     f32x4 sa[2] = {(f32x4){0.f, 0.f, 0.f, 0.f}, (f32x4){0.f, 0.f, 0.f, 0.f}};
; #pragma unroll
;     for (int T = 0; T < 2; ++T)
; #pragma unroll
;         for (int s2 = 0; s2 < 4; ++s2) sa[T] = __builtin_amdgcn_mfma_f32_16x16x32_fp8_fp8(cur.k[T][s2], qf[s2], sa[T], 0, 0, 0);
;     float sc[8]; bool vd[8]; float mx = -1e30f;
;     const bool act = lo == 0 || !SLC;
;     if (NOMASK) {
; #pragma unroll
;         for (int j = 0; j < 8; ++j) { sc[j] = sa[j >> 2][j & 3]; vd[j] = act; }
;         mx = fmaxf(fmaxf(fmaxf(sc[0], sc[1]), fmaxf(sc[2], sc[3])), fmaxf(fmaxf(sc[4], sc[5]), fmaxf(sc[6], sc[7])));
;         mx = act ? mx : -1e30f;
;     } else {
; #pragma unroll
;         for (int T = 0; T < 2; ++T)
; #pragma unroll
;             for (int r = 0; r < 4; ++r) { const int p = pos0 + 16 * T + 4 * kq + r; const bool v = (p >= lo) & (p <= hi); const float x = sa[T][r];
;                 sc[4 * T + r] = x; vd[4 * T + r] = v; mx = v ? fmaxf(mx, x) : mx; }
;     }
;     if (__builtin_amdgcn_ballot_w64(mx > st.m + 4.f) != 0ull) {
;         mx = fmaxf(mx, __shfl_xor(mx, 16)); mx = fmaxf(mx, __shfl_xor(mx, 32));
;         const float mn = fmaxf(st.m, mx), alpha = __builtin_amdgcn_exp2f(st.m - mn); st.m = mn; st.l *= alpha;
; #pragma unroll
;         for (int j = 0; j < 8; ++j) st.o[j] = st.o[j] * alpha;
;     }
;     f32x4 pa, pb; float ps = 0.f;
;     const float mref = st.m - 4.f;
;     if (NOMASK) {
; #pragma unroll
;         for (int j = 0; j < 4; ++j) { pa[j] = __builtin_amdgcn_exp2f(sc[j] - mref); pb[j] = __builtin_amdgcn_exp2f(sc[4 + j] - mref); }
;         if (SLC) {
; #pragma unroll
;             for (int j = 0; j < 4; ++j) { pa[j] = act ? pa[j] : 0.f; pb[j] = act ? pb[j] : 0.f; }
;         }
; #pragma unroll
;         for (int j = 0; j < 4; ++j) ps += pa[j] + pb[j];
;     } else {
; #pragma unroll
;         for (int j = 0; j < 4; ++j) { pa[j] = vd[j] ? __builtin_amdgcn_exp2f(sc[j] - mref) : 0.f; pb[j] = vd[4 + j] ? __builtin_amdgcn_exp2f(sc[4 + j] - mref) : 0.f; ps += pa[j] + pb[j]; }
;     }
;     st.l += ps;
;     const u32x2 pw = pack8_fp8(pa, pb);
.LBB0_976:
	s_and_b32 s13, s12, 0xfffffbff
	s_cmp_eq_u32 s13, 4
	s_cselect_b64 s[10:11], -1, 0
	s_lshl_b32 s14, s57, 7
	s_and_b32 s50, s14, 0x7fff800
	v_lshl_add_u64 v[44:45], v[86:87], 0, s[50:51]
	s_and_b32 s50, s14, 0x7fff000
	global_load_dwordx2 v[144:145], v[44:45], off
	global_load_dwordx2 v[152:153], v[44:45], off offset:512
	global_load_dwordx2 v[150:151], v[44:45], off offset:1024
	global_load_dwordx2 v[146:147], v[44:45], off offset:1536
	global_load_dwordx2 v[148:149], v[44:45], off offset:2048
	global_load_dwordx2 v[142:143], v[44:45], off offset:2560
	global_load_dwordx2 v[140:141], v[44:45], off offset:3072
	global_load_dwordx2 v[138:139], v[44:45], off offset:3584
	v_lshl_add_u64 v[44:45], v[88:89], 0, s[50:51]
	global_load_dwordx2 v[90:91], v[44:45], off
	global_load_dwordx2 v[92:93], v[44:45], off offset:512
	global_load_dwordx2 v[94:95], v[44:45], off offset:1024
	global_load_dwordx2 v[96:97], v[44:45], off offset:1536
	global_load_dwordx2 v[104:105], v[44:45], off offset:2048
	global_load_dwordx2 v[102:103], v[44:45], off offset:2560
	global_load_dwordx2 v[100:101], v[44:45], off offset:3072
	global_load_dwordx2 v[98:99], v[44:45], off offset:3584
	s_waitcnt vmcnt(47)
	v_mfma_f32_16x16x32_fp8_fp8 v[36:39], v[166:167], v[78:79], 0
	v_cmp_eq_u32_e32 vcc, s13, v209
	s_or_b64 s[10:11], s[10:11], vcc
	v_mov_b64_e32 v[74:75], v[6:7]
	s_waitcnt vmcnt(43)
	v_mfma_f32_16x16x32_fp8_fp8 v[40:43], v[160:161], v[78:79], 0
	v_mov_b64_e32 v[70:71], v[30:31]
	v_mov_b64_e32 v[66:67], v[34:35]
	v_mov_b64_e32 v[62:63], v[26:27]
	v_mfma_f32_16x16x32_fp8_fp8 v[36:39], v[168:169], v[80:81], v[36:39]
	v_mov_b64_e32 v[58:59], v[22:23]
	v_mov_b64_e32 v[54:55], v[18:19]
	v_mov_b64_e32 v[50:51], v[14:15]
	s_waitcnt vmcnt(42)
	v_mfma_f32_16x16x32_fp8_fp8 v[40:43], v[158:159], v[80:81], v[40:43]
	v_mov_b32_e32 v203, v0
	v_mov_b64_e32 v[72:73], v[4:5]
	v_mov_b64_e32 v[68:69], v[28:29]
	v_mfma_f32_16x16x32_fp8_fp8 v[36:39], v[164:165], v[82:83], v[36:39]
	v_mov_b64_e32 v[64:65], v[32:33]
	v_mov_b64_e32 v[60:61], v[24:25]
	v_mov_b64_e32 v[56:57], v[20:21]
	s_waitcnt vmcnt(41)
	v_mfma_f32_16x16x32_fp8_fp8 v[40:43], v[156:157], v[82:83], v[40:43]
	v_mov_b64_e32 v[52:53], v[16:17]
	v_mov_b64_e32 v[48:49], v[12:13]
	v_mfma_f32_16x16x32_fp8_fp8 v[36:39], v[162:163], v[84:85], v[36:39]
	s_waitcnt vmcnt(40)
	v_mfma_f32_16x16x32_fp8_fp8 v[40:43], v[154:155], v[84:85], v[40:43]
	s_nop 5
	v_max_f32_e32 v3, v37, v37
	v_max_f32_e32 v44, v36, v36
	v_max_f32_e32 v3, v44, v3
	v_max_f32_e32 v44, v39, v39
	v_max_f32_e32 v45, v38, v38
	v_max_f32_e32 v44, v45, v44
	v_max_f32_e32 v45, v43, v43
	v_max_f32_e32 v46, v42, v42
	v_max_f32_e32 v45, v46, v45
	v_max3_f32 v45, v40, v41, v45
	v_max3_f32 v3, v3, v44, v45
	v_cndmask_b32_e64 v202, v220, v3, s[10:11]
	v_mov_b64_e32 v[46:47], v[10:11]
	v_cmp_gt_f32_e32 vcc, v202, v2
	v_mov_b64_e32 v[44:45], v[8:9]
	v_mov_b32_e32 v3, v133
	s_cbranch_vccz .LBB0_978
	ds_bpermute_b32 v3, v225, v202
	v_max_f32_e32 v44, v202, v202
	s_waitcnt lgkmcnt(0)
	v_max_f32_e32 v3, v3, v3
	v_max_f32_e32 v3, v44, v3
	ds_bpermute_b32 v44, v224, v3
	s_waitcnt lgkmcnt(0)
	v_max3_f32 v203, v0, v3, v44
	v_sub_f32_e32 v3, v0, v203
	v_exp_f32_e32 v72, v3
	s_nop 0
	v_mul_f32_e32 v3, v133, v72
	v_pk_mul_f32 v[46:47], v[10:11], v[72:73] op_sel_hi:[1,0]
	v_pk_mul_f32 v[44:45], v[8:9], v[72:73] op_sel_hi:[1,0]
	v_pk_mul_f32 v[50:51], v[14:15], v[72:73] op_sel_hi:[1,0]
	v_pk_mul_f32 v[48:49], v[12:13], v[72:73] op_sel_hi:[1,0]
	v_pk_mul_f32 v[54:55], v[18:19], v[72:73] op_sel_hi:[1,0]
	v_pk_mul_f32 v[52:53], v[16:17], v[72:73] op_sel_hi:[1,0]
	v_pk_mul_f32 v[58:59], v[22:23], v[72:73] op_sel_hi:[1,0]
	v_pk_mul_f32 v[56:57], v[20:21], v[72:73] op_sel_hi:[1,0]
	v_pk_mul_f32 v[62:63], v[26:27], v[72:73] op_sel_hi:[1,0]
	v_pk_mul_f32 v[60:61], v[24:25], v[72:73] op_sel_hi:[1,0]
	v_pk_mul_f32 v[66:67], v[34:35], v[72:73] op_sel_hi:[1,0]
	v_pk_mul_f32 v[64:65], v[32:33], v[72:73] op_sel_hi:[1,0]
	v_pk_mul_f32 v[70:71], v[30:31], v[72:73] op_sel_hi:[1,0]
	v_pk_mul_f32 v[68:69], v[28:29], v[72:73] op_sel_hi:[1,0]
	v_pk_mul_f32 v[74:75], v[6:7], v[72:73] op_sel_hi:[1,0]
	v_pk_mul_f32 v[72:73], v[4:5], v[72:73] op_sel_hi:[1,0]
.LBB0_978:
	v_add_f32_e32 v202, -4.0, v203
	v_sub_f32_e32 v36, v36, v202
	v_sub_f32_e32 v40, v40, v202
	v_sub_f32_e32 v37, v37, v202
	v_sub_f32_e32 v41, v41, v202
	v_exp_f32_e32 v36, v36
	v_exp_f32_e32 v40, v40
	v_exp_f32_e32 v37, v37
	v_exp_f32_e32 v41, v41
	v_sub_f32_e32 v38, v38, v202
	v_sub_f32_e32 v42, v42, v202
	v_sub_f32_e32 v39, v39, v202
	v_sub_f32_e32 v43, v43, v202
	v_exp_f32_e32 v38, v38
	v_exp_f32_e32 v42, v42
	v_exp_f32_e32 v39, v39
	v_exp_f32_e32 v43, v43
	v_cndmask_b32_e64 v202, 0, v36, s[10:11]
	v_cndmask_b32_e64 v204, 0, v40, s[10:11]
	v_cndmask_b32_e64 v205, 0, v37, s[10:11]
	v_cndmask_b32_e64 v227, 0, v41, s[10:11]
	v_mov_b32_e32 v228, v1
	v_mov_b32_e32 v229, v1
	v_cvt_pk_fp8_f32 v228, v202, v205
	v_cvt_pk_fp8_f32 v229, v204, v227
	v_cndmask_b32_e64 v230, 0, v38, s[10:11]
	v_cndmask_b32_e64 v231, 0, v42, s[10:11]
	v_cndmask_b32_e64 v232, 0, v39, s[10:11]
	v_cndmask_b32_e64 v233, 0, v43, s[10:11]
	v_cvt_pk_fp8_f32 v228, v230, v232 op_sel:[0,0,1]
	v_cvt_pk_fp8_f32 v229, v231, v233 op_sel:[0,0,1]
	s_waitcnt vmcnt(38)
	s_nop 0
	v_mfma_f32_16x16x32_fp8_fp8 v[40:43], v[110:111], v[228:229], v[48:51]
	s_waitcnt vmcnt(36)
	v_mfma_f32_16x16x32_fp8_fp8 v[48:51], v[116:117], v[228:229], v[56:59]
	s_nop 2
	v_add_f32_e32 v56, v202, v204
	v_mfma_f32_16x16x32_fp8_fp8 v[36:39], v[106:107], v[228:229], v[44:47]
	v_mfma_f32_16x16x32_fp8_fp8 v[44:47], v[112:113], v[228:229], v[52:55]
	s_waitcnt vmcnt(35)
	v_mfma_f32_16x16x32_fp8_fp8 v[52:55], v[136:137], v[228:229], v[60:63]
	s_nop 2
	v_add_f32_e32 v60, 0, v56
	v_add_f32_e32 v61, v205, v227
	v_add_f32_e32 v60, v61, v60
	v_add_f32_e32 v61, v230, v231
	s_waitcnt vmcnt(34)
	v_mfma_f32_16x16x32_fp8_fp8 v[56:59], v[134:135], v[228:229], v[64:67]
	s_nop 2
	v_add_f32_e32 v64, v61, v60
	v_add_f32_e32 v65, v232, v233
	v_add_f32_e32 v64, v65, v64
	s_waitcnt vmcnt(33)
	v_mfma_f32_16x16x32_fp8_fp8 v[60:63], v[114:115], v[228:229], v[68:71]
	v_add_f32_e32 v204, v3, v64
	s_waitcnt vmcnt(32)
	v_mfma_f32_16x16x32_fp8_fp8 v[64:67], v[108:109], v[228:229], v[72:75]
	s_branch .LBB0_968
; template <bool SLC, bool NOMASK> ...
;     const int kq = lane >> 4;
;     const int pos0 = SLC ? (dcur & 0xfffff) : dcur;
;     const int lo = SLC ? ((((dcur >> 20) == qi) | ((dcur >> 20) == 4)) ? 0 : (1 << 30)) : lo_in;
;     load_frag8(nxt, KF, VF, SLC ? (dnext & 0xfffff) : dnext, lane);
;     f32x4 sa[2] = {(f32x4){0.f, 0.f, 0.f, 0.f}, (f32x4){0.f, 0.f, 0.f, 0.f}};
; #pragma unroll
;     for (int T = 0; T < 2; ++T)
; #pragma unroll
;         for (int s2 = 0; s2 < 4; ++s2) sa[T] = __builtin_amdgcn_mfma_f32_16x16x32_fp8_fp8(cur.k[T][s2], qf[s2], sa[T], 0, 0, 0);
;     float sc[8]; bool vd[8]; float mx = -1e30f;
;     const bool act = lo == 0 || !SLC;
;     if (NOMASK) {
; #pragma unroll
;         for (int j = 0; j < 8; ++j) { sc[j] = sa[j >> 2][j & 3]; vd[j] = act; }
;         mx = fmaxf(fmaxf(fmaxf(sc[0], sc[1]), fmaxf(sc[2], sc[3])), fmaxf(fmaxf(sc[4], sc[5]), fmaxf(sc[6], sc[7])));
;         mx = act ? mx : -1e30f;
;     } else {
; #pragma unroll
;         for (int T = 0; T < 2; ++T)
; #pragma unroll
;             for (int r = 0; r < 4; ++r) { const int p = pos0 + 16 * T + 4 * kq + r; const bool v = (p >= lo) & (p <= hi); const float x = sa[T][r];
;                 sc[4 * T + r] = x; vd[4 * T + r] = v; mx = v ? fmaxf(mx, x) : mx; }
;     }
;     if (__builtin_amdgcn_ballot_w64(mx > st.m + 4.f) != 0ull) {
;         mx = fmaxf(mx, __shfl_xor(mx, 16)); mx = fmaxf(mx, __shfl_xor(mx, 32));
;         const float mn = fmaxf(st.m, mx), alpha = __builtin_amdgcn_exp2f(st.m - mn); st.m = mn; st.l *= alpha;
; #pragma unroll
;         for (int j = 0; j < 8; ++j) st.o[j] = st.o[j] * alpha;
;     }
.LBB0_979:
	s_cmp_eq_u32 s12, 4
	s_cselect_b64 s[10:11], -1, 0
	s_lshl_b32 s13, s57, 7
	s_and_b32 s50, s13, 0x7fff800
	v_lshl_add_u64 v[44:45], v[86:87], 0, s[50:51]
	s_and_b32 s50, s13, 0x7fff000
	global_load_dwordx2 v[144:145], v[44:45], off
	global_load_dwordx2 v[152:153], v[44:45], off offset:512
	global_load_dwordx2 v[150:151], v[44:45], off offset:1024
	global_load_dwordx2 v[146:147], v[44:45], off offset:1536
	global_load_dwordx2 v[148:149], v[44:45], off offset:2048
	global_load_dwordx2 v[142:143], v[44:45], off offset:2560
	global_load_dwordx2 v[140:141], v[44:45], off offset:3072
	global_load_dwordx2 v[138:139], v[44:45], off offset:3584
	v_lshl_add_u64 v[44:45], v[88:89], 0, s[50:51]
	global_load_dwordx2 v[90:91], v[44:45], off
	global_load_dwordx2 v[92:93], v[44:45], off offset:512
	global_load_dwordx2 v[94:95], v[44:45], off offset:1024
	global_load_dwordx2 v[96:97], v[44:45], off offset:1536
	global_load_dwordx2 v[104:105], v[44:45], off offset:2048
	global_load_dwordx2 v[102:103], v[44:45], off offset:2560
	global_load_dwordx2 v[100:101], v[44:45], off offset:3072
	global_load_dwordx2 v[98:99], v[44:45], off offset:3584
	s_waitcnt vmcnt(47)
	v_mfma_f32_16x16x32_fp8_fp8 v[36:39], v[166:167], v[78:79], 0
	s_and_b32 s13, s92, 0xfffff
	v_cmp_eq_u32_e32 vcc, s12, v209
	v_add_u32_e32 v3, s13, v210
	s_waitcnt vmcnt(46)
	v_mfma_f32_16x16x32_fp8_fp8 v[36:39], v[168:169], v[80:81], v[36:39]
	s_or_b64 s[18:19], s[10:11], vcc
	v_cmp_le_i32_e32 vcc, v3, v132
	s_and_b64 s[16:17], s[18:19], vcc
	s_waitcnt vmcnt(45)
	v_mfma_f32_16x16x32_fp8_fp8 v[36:39], v[164:165], v[82:83], v[36:39]
	v_cmp_lt_i32_e32 vcc, v3, v132
	s_and_b64 s[12:13], s[18:19], vcc
	s_waitcnt vmcnt(43)
	v_mfma_f32_16x16x32_fp8_fp8 v[40:43], v[160:161], v[78:79], 0
	v_mfma_f32_16x16x32_fp8_fp8 v[36:39], v[162:163], v[84:85], v[36:39]
	s_waitcnt vmcnt(42)
	v_mfma_f32_16x16x32_fp8_fp8 v[40:43], v[158:159], v[80:81], v[40:43]
	s_waitcnt vmcnt(41)
	v_mfma_f32_16x16x32_fp8_fp8 v[40:43], v[156:157], v[82:83], v[40:43]
	s_nop 3
	v_max_f32_e32 v44, v36, v36
	v_max_f32_e32 v44, 0xf149f2ca, v44
	v_cndmask_b32_e64 v44, v220, v44, s[16:17]
	v_max_f32_e32 v45, v37, v37
	v_max_f32_e32 v45, v44, v45
	v_cndmask_b32_e64 v44, v44, v45, s[12:13]
	v_add_u32_e32 v45, 2, v3
	v_cmp_le_i32_e32 vcc, v45, v132
	v_max_f32_e32 v45, v38, v38
	v_max_f32_e32 v45, v44, v45
	s_and_b64 s[14:15], s[18:19], vcc
	s_waitcnt vmcnt(40)
	v_mfma_f32_16x16x32_fp8_fp8 v[40:43], v[154:155], v[84:85], v[40:43]
	v_cndmask_b32_e64 v44, v44, v45, s[14:15]
	v_add_u32_e32 v45, 3, v3
	v_cmp_le_i32_e32 vcc, v45, v132
	v_max_f32_e32 v45, v39, v39
	v_max_f32_e32 v45, v44, v45
	s_and_b64 s[10:11], s[18:19], vcc
	v_cndmask_b32_e64 v44, v44, v45, s[10:11]
	v_add_u32_e32 v45, 16, v3
	v_cmp_le_i32_e32 vcc, v45, v132
	v_max_f32_e32 v45, v40, v40
	v_max_f32_e32 v45, v44, v45
	s_and_b64 s[24:25], s[18:19], vcc
	v_cndmask_b32_e64 v44, v44, v45, s[24:25]
	v_add_u32_e32 v45, 17, v3
	v_cmp_le_i32_e32 vcc, v45, v132
	v_max_f32_e32 v45, v44, v44
	v_max_f32_e32 v46, v41, v41
	v_max_f32_e32 v45, v45, v46
	s_and_b64 s[20:21], s[18:19], vcc
	v_cndmask_b32_e64 v44, v44, v45, s[20:21]
	v_add_u32_e32 v45, 18, v3
	v_cmp_le_i32_e32 vcc, v45, v132
	v_max_f32_e32 v45, v44, v44
	v_max_f32_e32 v46, v42, v42
	v_max_f32_e32 v45, v45, v46
	s_and_b64 s[22:23], s[18:19], vcc
	v_cndmask_b32_e64 v44, v44, v45, s[22:23]
	v_add_u32_e32 v3, 19, v3
	v_cmp_le_i32_e32 vcc, v3, v132
	v_max_f32_e32 v3, v44, v44
	v_max_f32_e32 v45, v43, v43
	v_max_f32_e32 v3, v3, v45
	s_and_b64 s[18:19], s[18:19], vcc
	v_cndmask_b32_e64 v3, v44, v3, s[18:19]
	v_cmp_gt_f32_e32 vcc, v3, v2
	s_cbranch_vccz .LBB0_981
	ds_bpermute_b32 v2, v225, v3
	v_max_f32_e32 v3, v3, v3
	s_waitcnt lgkmcnt(0)
	v_max_f32_e32 v2, v2, v2
	v_max_f32_e32 v2, v3, v2
	ds_bpermute_b32 v3, v224, v2
	s_waitcnt lgkmcnt(0)
	v_max3_f32 v2, v0, v2, v3
	v_sub_f32_e32 v0, v0, v2
	v_exp_f32_e32 v0, v0
	s_nop 0
	v_mul_f32_e32 v133, v133, v0
	v_pk_mul_f32 v[10:11], v[10:11], v[0:1] op_sel_hi:[1,0]
	v_pk_mul_f32 v[8:9], v[8:9], v[0:1] op_sel_hi:[1,0]
	v_pk_mul_f32 v[14:15], v[14:15], v[0:1] op_sel_hi:[1,0]
	v_pk_mul_f32 v[12:13], v[12:13], v[0:1] op_sel_hi:[1,0]
	v_pk_mul_f32 v[18:19], v[18:19], v[0:1] op_sel_hi:[1,0]
	v_pk_mul_f32 v[16:17], v[16:17], v[0:1] op_sel_hi:[1,0]
	v_pk_mul_f32 v[22:23], v[22:23], v[0:1] op_sel_hi:[1,0]
	v_pk_mul_f32 v[20:21], v[20:21], v[0:1] op_sel_hi:[1,0]
	v_pk_mul_f32 v[26:27], v[26:27], v[0:1] op_sel_hi:[1,0]
	v_pk_mul_f32 v[24:25], v[24:25], v[0:1] op_sel_hi:[1,0]
	v_pk_mul_f32 v[34:35], v[34:35], v[0:1] op_sel_hi:[1,0]
	v_pk_mul_f32 v[32:33], v[32:33], v[0:1] op_sel_hi:[1,0]
	v_pk_mul_f32 v[30:31], v[30:31], v[0:1] op_sel_hi:[1,0]
	v_pk_mul_f32 v[28:29], v[28:29], v[0:1] op_sel_hi:[1,0]
	v_pk_mul_f32 v[6:7], v[6:7], v[0:1] op_sel_hi:[1,0]
	v_pk_mul_f32 v[4:5], v[4:5], v[0:1] op_sel_hi:[1,0]
	v_mov_b32_e32 v0, v2

; template <bool SLC, bool NOMASK> ...
;     const int kq = lane >> 4;
;     const int pos0 = SLC ? (dcur & 0xfffff) : dcur;
;     const int lo = SLC ? ((((dcur >> 20) == qi) | ((dcur >> 20) == 4)) ? 0 : (1 << 30)) : lo_in;
;     load_frag8(nxt, KF, VF, SLC ? (dnext & 0xfffff) : dnext, lane);
;     f32x4 sa[2] = {(f32x4){0.f, 0.f, 0.f, 0.f}, (f32x4){0.f, 0.f, 0.f, 0.f}};
; #pragma unroll
;     for (int T = 0; T < 2; ++T)
; #pragma unroll
;         for (int s2 = 0; s2 < 4; ++s2) sa[T] = __builtin_amdgcn_mfma_f32_16x16x32_fp8_fp8(cur.k[T][s2], qf[s2], sa[T], 0, 0, 0);
;     float sc[8]; bool vd[8]; float mx = -1e30f;
;     const bool act = lo == 0 || !SLC;
;     if (NOMASK) {
; #pragma unroll
;         for (int j = 0; j < 8; ++j) { sc[j] = sa[j >> 2][j & 3]; vd[j] = act; }
;         mx = fmaxf(fmaxf(fmaxf(sc[0], sc[1]), fmaxf(sc[2], sc[3])), fmaxf(fmaxf(sc[4], sc[5]), fmaxf(sc[6], sc[7])));
;         mx = act ? mx : -1e30f;
;     } else {
; #pragma unroll
;         for (int T = 0; T < 2; ++T)
; #pragma unroll
;             for (int r = 0; r < 4; ++r) { const int p = pos0 + 16 * T + 4 * kq + r; const bool v = (p >= lo) & (p <= hi); const float x = sa[T][r];
;                 sc[4 * T + r] = x; vd[4 * T + r] = v; mx = v ? fmaxf(mx, x) : mx; }
;     }
;     if (__builtin_amdgcn_ballot_w64(mx > st.m + 4.f) != 0ull) {
;         mx = fmaxf(mx, __shfl_xor(mx, 16)); mx = fmaxf(mx, __shfl_xor(mx, 32));
;         const float mn = fmaxf(st.m, mx), alpha = __builtin_amdgcn_exp2f(st.m - mn); st.m = mn; st.l *= alpha;
; #pragma unroll
;         for (int j = 0; j < 8; ++j) st.o[j] = st.o[j] * alpha;
;     }
;     f32x4 pa, pb; float ps = 0.f;
;     const float mref = st.m - 4.f;
;     if (NOMASK) {
; #pragma unroll
;         for (int j = 0; j < 4; ++j) { pa[j] = __builtin_amdgcn_exp2f(sc[j] - mref); pb[j] = __builtin_amdgcn_exp2f(sc[4 + j] - mref); }
;         if (SLC) {
; #pragma unroll
;             for (int j = 0; j < 4; ++j) { pa[j] = act ? pa[j] : 0.f; pb[j] = act ? pb[j] : 0.f; }
;         }
; #pragma unroll
;         for (int j = 0; j < 4; ++j) ps += pa[j] + pb[j];
;     } else {
; #pragma unroll
;         for (int j = 0; j < 4; ++j) { pa[j] = vd[j] ? __builtin_amdgcn_exp2f(sc[j] - mref) : 0.f; pb[j] = vd[4 + j] ? __builtin_amdgcn_exp2f(sc[4 + j] - mref) : 0.f; ps += pa[j] + pb[j]; }
;     }
;     st.l += ps;
;     const u32x2 pw = pack8_fp8(pa, pb);
.LBB0_982:
	s_cmp_lt_u32 s56, s54
	s_cselect_b32 s10, s56, s55
	s_lshl_b32 s10, s10, 2
	s_add_i32 s10, s3, s10
	v_mov_b32_e32 v0, s10
	ds_read_b32 v0, v0 offset:13632
	s_and_b32 s13, s66, 2.0
	s_ashr_i32 s12, s66, 20
	s_mov_b64 s[10:11], -1
	s_cmp_eq_u32 s13, 0
	s_waitcnt lgkmcnt(0)
	v_readfirstlane_b32 s92, v0
	v_add_f32_e32 v0, 4.0, v203
	s_cbranch_scc1 .LBB0_986
	s_and_b32 s13, s12, 0xfffffbff
	s_cmp_eq_u32 s13, 4
	s_cselect_b64 s[10:11], -1, 0
	s_lshl_b32 s14, s92, 7
	s_and_b32 s50, s14, 0x7fff800
	v_lshl_add_u64 v[10:11], v[86:87], 0, s[50:51]
	s_and_b32 s50, s14, 0x7fff000
	global_load_dwordx2 v[166:167], v[10:11], off
	global_load_dwordx2 v[168:169], v[10:11], off offset:512
	global_load_dwordx2 v[164:165], v[10:11], off offset:1024
	global_load_dwordx2 v[162:163], v[10:11], off offset:1536
	global_load_dwordx2 v[160:161], v[10:11], off offset:2048
	global_load_dwordx2 v[158:159], v[10:11], off offset:2560
	global_load_dwordx2 v[156:157], v[10:11], off offset:3072
	global_load_dwordx2 v[154:155], v[10:11], off offset:3584
	v_lshl_add_u64 v[10:11], v[88:89], 0, s[50:51]
	global_load_dwordx2 v[106:107], v[10:11], off
	global_load_dwordx2 v[110:111], v[10:11], off offset:512
	global_load_dwordx2 v[112:113], v[10:11], off offset:1024
	global_load_dwordx2 v[116:117], v[10:11], off offset:1536
	global_load_dwordx2 v[136:137], v[10:11], off offset:2048
	global_load_dwordx2 v[134:135], v[10:11], off offset:2560
	global_load_dwordx2 v[114:115], v[10:11], off offset:3072
	global_load_dwordx2 v[108:109], v[10:11], off offset:3584
	s_waitcnt vmcnt(47)
	v_mfma_f32_16x16x32_fp8_fp8 v[2:5], v[192:193], v[78:79], 0
	v_cmp_eq_u32_e32 vcc, s13, v209
	s_or_b64 s[10:11], s[10:11], vcc
	v_mov_b64_e32 v[74:75], v[66:67]
	s_waitcnt vmcnt(43)
	v_mfma_f32_16x16x32_fp8_fp8 v[6:9], v[196:197], v[78:79], 0
	v_mov_b64_e32 v[70:71], v[62:63]
	v_mov_b64_e32 v[30:31], v[56:57]
	v_mov_b64_e32 v[26:27], v[52:53]
	v_mfma_f32_16x16x32_fp8_fp8 v[2:5], v[200:201], v[80:81], v[2:5]
	v_mov_b64_e32 v[22:23], v[48:49]
	v_mov_b64_e32 v[18:19], v[44:45]
	v_mov_b64_e32 v[14:15], v[40:41]
	s_waitcnt vmcnt(42)
	v_mfma_f32_16x16x32_fp8_fp8 v[6:9], v[190:191], v[80:81], v[6:9]
	v_mov_b32_e32 v202, v203
	v_mov_b64_e32 v[72:73], v[64:65]
	v_mov_b64_e32 v[68:69], v[60:61]
	v_mfma_f32_16x16x32_fp8_fp8 v[2:5], v[198:199], v[82:83], v[2:5]
	v_mov_b64_e32 v[32:33], v[58:59]
	v_mov_b64_e32 v[28:29], v[54:55]
	v_mov_b64_e32 v[24:25], v[50:51]
	s_waitcnt vmcnt(41)
	v_mfma_f32_16x16x32_fp8_fp8 v[6:9], v[188:189], v[82:83], v[6:9]
	v_mov_b64_e32 v[20:21], v[46:47]
	v_mov_b64_e32 v[16:17], v[42:43]
	v_mov_b32_e32 v133, v204
	v_mfma_f32_16x16x32_fp8_fp8 v[2:5], v[194:195], v[84:85], v[2:5]
	s_waitcnt vmcnt(40)
	v_mfma_f32_16x16x32_fp8_fp8 v[6:9], v[186:187], v[84:85], v[6:9]
	s_nop 5
	v_max_f32_e32 v10, v3, v3
	v_max_f32_e32 v11, v2, v2
	v_max_f32_e32 v10, v11, v10
	v_max_f32_e32 v11, v5, v5
	v_max_f32_e32 v12, v4, v4
	v_max_f32_e32 v11, v12, v11
	v_max_f32_e32 v12, v9, v9
	v_max_f32_e32 v13, v8, v8
	v_max_f32_e32 v12, v13, v12
	v_max3_f32 v12, v6, v7, v12
	v_max3_f32 v10, v10, v11, v12
	v_cndmask_b32_e64 v34, v220, v10, s[10:11]
	v_mov_b64_e32 v[10:11], v[36:37]
	v_cmp_gt_f32_e32 vcc, v34, v0
	v_mov_b64_e32 v[12:13], v[38:39]
	s_cbranch_vccz .LBB0_985
	ds_bpermute_b32 v10, v225, v34
	v_max_f32_e32 v11, v34, v34
	s_waitcnt lgkmcnt(0)
	v_max_f32_e32 v10, v10, v10
	v_max_f32_e32 v10, v11, v10
	ds_bpermute_b32 v11, v224, v10
	s_waitcnt lgkmcnt(0)
	v_max3_f32 v202, v203, v10, v11
	v_sub_f32_e32 v10, v203, v202
	v_exp_f32_e32 v34, v10
	s_nop 0
	v_mul_f32_e32 v133, v204, v34
	v_pk_mul_f32 v[12:13], v[38:39], v[34:35] op_sel_hi:[1,0]
	v_pk_mul_f32 v[10:11], v[36:37], v[34:35] op_sel_hi:[1,0]
	v_pk_mul_f32 v[16:17], v[42:43], v[34:35] op_sel_hi:[1,0]
	v_pk_mul_f32 v[14:15], v[40:41], v[34:35] op_sel_hi:[1,0]
	v_pk_mul_f32 v[20:21], v[46:47], v[34:35] op_sel_hi:[1,0]
	v_pk_mul_f32 v[18:19], v[44:45], v[34:35] op_sel_hi:[1,0]
	v_pk_mul_f32 v[24:25], v[50:51], v[34:35] op_sel_hi:[1,0]
	v_pk_mul_f32 v[22:23], v[48:49], v[34:35] op_sel_hi:[1,0]
	v_pk_mul_f32 v[28:29], v[54:55], v[34:35] op_sel_hi:[1,0]
	v_pk_mul_f32 v[26:27], v[52:53], v[34:35] op_sel_hi:[1,0]
	v_pk_mul_f32 v[32:33], v[58:59], v[34:35] op_sel_hi:[1,0]
	v_pk_mul_f32 v[30:31], v[56:57], v[34:35] op_sel_hi:[1,0]
	v_pk_mul_f32 v[70:71], v[62:63], v[34:35] op_sel_hi:[1,0]
	v_pk_mul_f32 v[68:69], v[60:61], v[34:35] op_sel_hi:[1,0]
	v_pk_mul_f32 v[74:75], v[66:67], v[34:35] op_sel_hi:[1,0]
	v_pk_mul_f32 v[72:73], v[64:65], v[34:35] op_sel_hi:[1,0]
.LBB0_985:
	v_add_f32_e32 v34, -4.0, v202
	v_sub_f32_e32 v2, v2, v34
	v_sub_f32_e32 v6, v6, v34
	v_sub_f32_e32 v3, v3, v34
	v_sub_f32_e32 v7, v7, v34
	v_exp_f32_e32 v2, v2
	v_exp_f32_e32 v6, v6
	v_exp_f32_e32 v3, v3
	v_exp_f32_e32 v7, v7
	v_sub_f32_e32 v4, v4, v34
	v_sub_f32_e32 v8, v8, v34
	v_sub_f32_e32 v5, v5, v34
	v_sub_f32_e32 v9, v9, v34
	v_exp_f32_e32 v4, v4
	v_exp_f32_e32 v8, v8
	v_exp_f32_e32 v5, v5
	v_exp_f32_e32 v9, v9
	v_cndmask_b32_e64 v34, 0, v2, s[10:11]
	v_cndmask_b32_e64 v6, 0, v6, s[10:11]
	v_cndmask_b32_e64 v35, 0, v3, s[10:11]
	v_cndmask_b32_e64 v7, 0, v7, s[10:11]
	v_mov_b32_e32 v2, v1
	v_mov_b32_e32 v3, v1
	v_cvt_pk_fp8_f32 v2, v34, v35
	v_cvt_pk_fp8_f32 v3, v6, v7
	v_cndmask_b32_e64 v4, 0, v4, s[10:11]
	v_cndmask_b32_e64 v205, 0, v8, s[10:11]
	v_cndmask_b32_e64 v5, 0, v5, s[10:11]
	v_cndmask_b32_e64 v227, 0, v9, s[10:11]
	v_add_f32_e32 v6, v34, v6
	v_cvt_pk_fp8_f32 v2, v4, v5 op_sel:[0,0,1]
	v_cvt_pk_fp8_f32 v3, v205, v227 op_sel:[0,0,1]
	v_add_f32_e32 v6, 0, v6
	v_add_f32_e32 v7, v35, v7
	v_add_f32_e32 v6, v7, v6
	v_add_f32_e32 v4, v4, v205
	v_add_f32_e32 v4, v4, v6
	v_add_f32_e32 v5, v5, v227
	v_add_f32_e32 v4, v5, v4
	s_waitcnt vmcnt(39)
	v_mfma_f32_16x16x32_fp8_fp8 v[8:11], v[170:171], v[2:3], v[10:13]
	v_add_f32_e32 v133, v133, v4
	s_mov_b64 s[10:11], 0
	s_waitcnt vmcnt(38)
	v_mfma_f32_16x16x32_fp8_fp8 v[12:15], v[172:173], v[2:3], v[14:17]
	s_waitcnt vmcnt(37)
	v_mfma_f32_16x16x32_fp8_fp8 v[16:19], v[174:175], v[2:3], v[18:21]
	s_waitcnt vmcnt(36)
	v_mfma_f32_16x16x32_fp8_fp8 v[20:23], v[176:177], v[2:3], v[22:25]
	s_waitcnt vmcnt(35)
	v_mfma_f32_16x16x32_fp8_fp8 v[24:27], v[184:185], v[2:3], v[26:29]
	s_waitcnt vmcnt(34)
	v_mfma_f32_16x16x32_fp8_fp8 v[32:35], v[182:183], v[2:3], v[30:33]
	s_waitcnt vmcnt(33)
	v_mfma_f32_16x16x32_fp8_fp8 v[28:31], v[180:181], v[2:3], v[68:71]
	s_waitcnt vmcnt(32)
	v_mfma_f32_16x16x32_fp8_fp8 v[4:7], v[178:179], v[2:3], v[72:75]
; template <bool SLC, bool NOMASK> ...
;     const int kq = lane >> 4;
;     const int pos0 = SLC ? (dcur & 0xfffff) : dcur;
;     const int lo = SLC ? ((((dcur >> 20) == qi) | ((dcur >> 20) == 4)) ? 0 : (1 << 30)) : lo_in;
;     load_frag8(nxt, KF, VF, SLC ? (dnext & 0xfffff) : dnext, lane);
;     f32x4 sa[2] = {(f32x4){0.f, 0.f, 0.f, 0.f}, (f32x4){0.f, 0.f, 0.f, 0.f}};
; #pragma unroll
;     for (int T = 0; T < 2; ++T)
; #pragma unroll
;         for (int s2 = 0; s2 < 4; ++s2) sa[T] = __builtin_amdgcn_mfma_f32_16x16x32_fp8_fp8(cur.k[T][s2], qf[s2], sa[T], 0, 0, 0);
;     float sc[8]; bool vd[8]; float mx = -1e30f;
;     const bool act = lo == 0 || !SLC;
;     if (NOMASK) {
; #pragma unroll
;         for (int j = 0; j < 8; ++j) { sc[j] = sa[j >> 2][j & 3]; vd[j] = act; }
;         mx = fmaxf(fmaxf(fmaxf(sc[0], sc[1]), fmaxf(sc[2], sc[3])), fmaxf(fmaxf(sc[4], sc[5]), fmaxf(sc[6], sc[7])));
;         mx = act ? mx : -1e30f;
;     } else {
; #pragma unroll
;         for (int T = 0; T < 2; ++T)
; #pragma unroll
;             for (int r = 0; r < 4; ++r) { const int p = pos0 + 16 * T + 4 * kq + r; const bool v = (p >= lo) & (p <= hi); const float x = sa[T][r];
;                 sc[4 * T + r] = x; vd[4 * T + r] = v; mx = v ? fmaxf(mx, x) : mx; }
;     }
;     if (__builtin_amdgcn_ballot_w64(mx > st.m + 4.f) != 0ull) {
;         mx = fmaxf(mx, __shfl_xor(mx, 16)); mx = fmaxf(mx, __shfl_xor(mx, 32));
;         const float mn = fmaxf(st.m, mx), alpha = __builtin_amdgcn_exp2f(st.m - mn); st.m = mn; st.l *= alpha;
; #pragma unroll
;         for (int j = 0; j < 8; ++j) st.o[j] = st.o[j] * alpha;
;     }
;     f32x4 pa, pb; float ps = 0.f;
;     const float mref = st.m - 4.f;
;     if (NOMASK) {
; #pragma unroll
;         for (int j = 0; j < 4; ++j) { pa[j] = __builtin_amdgcn_exp2f(sc[j] - mref); pb[j] = __builtin_amdgcn_exp2f(sc[4 + j] - mref); }
;         if (SLC) {
; #pragma unroll
;             for (int j = 0; j < 4; ++j) { pa[j] = act ? pa[j] : 0.f; pb[j] = act ? pb[j] : 0.f; }
;         }
; #pragma unroll
;         for (int j = 0; j < 4; ++j) ps += pa[j] + pb[j];
;     } else {
; #pragma unroll
;         for (int j = 0; j < 4; ++j) { pa[j] = vd[j] ? __builtin_amdgcn_exp2f(sc[j] - mref) : 0.f; pb[j] = vd[4 + j] ? __builtin_amdgcn_exp2f(sc[4 + j] - mref) : 0.f; ps += pa[j] + pb[j]; }
;     }
;     st.l += ps;
;     const u32x2 pw = pack8_fp8(pa, pb);
.LBB0_986:
	s_and_b64 vcc, exec, s[10:11]
	s_cbranch_vccz .LBB0_990
	s_cmp_eq_u32 s12, 4
	s_cselect_b64 s[10:11], -1, 0
	s_lshl_b32 s13, s92, 7
	s_and_b32 s50, s13, 0x7fff800
	v_lshl_add_u64 v[10:11], v[86:87], 0, s[50:51]
	s_and_b32 s50, s13, 0x7fff000
	global_load_dwordx2 v[166:167], v[10:11], off
	global_load_dwordx2 v[168:169], v[10:11], off offset:512
	global_load_dwordx2 v[164:165], v[10:11], off offset:1024
	global_load_dwordx2 v[162:163], v[10:11], off offset:1536
	global_load_dwordx2 v[160:161], v[10:11], off offset:2048
	global_load_dwordx2 v[158:159], v[10:11], off offset:2560
	global_load_dwordx2 v[156:157], v[10:11], off offset:3072
	global_load_dwordx2 v[154:155], v[10:11], off offset:3584
	v_lshl_add_u64 v[10:11], v[88:89], 0, s[50:51]
	global_load_dwordx2 v[106:107], v[10:11], off
	global_load_dwordx2 v[110:111], v[10:11], off offset:512
	global_load_dwordx2 v[112:113], v[10:11], off offset:1024
	global_load_dwordx2 v[116:117], v[10:11], off offset:1536
	global_load_dwordx2 v[136:137], v[10:11], off offset:2048
	global_load_dwordx2 v[134:135], v[10:11], off offset:2560
	global_load_dwordx2 v[114:115], v[10:11], off offset:3072
	global_load_dwordx2 v[108:109], v[10:11], off offset:3584
	s_waitcnt vmcnt(47)
	v_mfma_f32_16x16x32_fp8_fp8 v[2:5], v[192:193], v[78:79], 0
	s_and_b32 s13, s66, 0xfffff
	v_cmp_eq_u32_e32 vcc, s12, v209
	v_add_u32_e32 v10, s13, v210
	s_waitcnt vmcnt(46)
	v_mfma_f32_16x16x32_fp8_fp8 v[2:5], v[200:201], v[80:81], v[2:5]
	s_or_b64 s[18:19], s[10:11], vcc
	v_cmp_le_i32_e32 vcc, v10, v132
	s_and_b64 s[16:17], s[18:19], vcc
	s_waitcnt vmcnt(45)
	v_mfma_f32_16x16x32_fp8_fp8 v[2:5], v[198:199], v[82:83], v[2:5]
	v_cmp_lt_i32_e32 vcc, v10, v132
	s_and_b64 s[12:13], s[18:19], vcc
	s_waitcnt vmcnt(43)
	v_mfma_f32_16x16x32_fp8_fp8 v[6:9], v[196:197], v[78:79], 0
	v_mfma_f32_16x16x32_fp8_fp8 v[2:5], v[194:195], v[84:85], v[2:5]
	s_waitcnt vmcnt(42)
	v_mfma_f32_16x16x32_fp8_fp8 v[6:9], v[190:191], v[80:81], v[6:9]
	s_waitcnt vmcnt(41)
	v_mfma_f32_16x16x32_fp8_fp8 v[6:9], v[188:189], v[82:83], v[6:9]
	s_nop 3
	v_max_f32_e32 v11, v2, v2
	v_max_f32_e32 v11, 0xf149f2ca, v11
	v_cndmask_b32_e64 v11, v220, v11, s[16:17]
	v_max_f32_e32 v12, v3, v3
	v_max_f32_e32 v12, v11, v12
	v_cndmask_b32_e64 v11, v11, v12, s[12:13]
	v_add_u32_e32 v12, 2, v10
	v_cmp_le_i32_e32 vcc, v12, v132
	v_max_f32_e32 v12, v4, v4
	v_max_f32_e32 v12, v11, v12
	s_and_b64 s[14:15], s[18:19], vcc
	s_waitcnt vmcnt(40)
	v_mfma_f32_16x16x32_fp8_fp8 v[6:9], v[186:187], v[84:85], v[6:9]
	v_cndmask_b32_e64 v11, v11, v12, s[14:15]
	v_add_u32_e32 v12, 3, v10
	v_cmp_le_i32_e32 vcc, v12, v132
	v_max_f32_e32 v12, v5, v5
	v_max_f32_e32 v12, v11, v12
	s_and_b64 s[10:11], s[18:19], vcc
	v_cndmask_b32_e64 v11, v11, v12, s[10:11]
	v_add_u32_e32 v12, 16, v10
	v_cmp_le_i32_e32 vcc, v12, v132
	v_max_f32_e32 v12, v6, v6
	v_max_f32_e32 v12, v11, v12
	s_and_b64 s[24:25], s[18:19], vcc
	v_cndmask_b32_e64 v11, v11, v12, s[24:25]
	v_add_u32_e32 v12, 17, v10
	v_cmp_le_i32_e32 vcc, v12, v132
	v_max_f32_e32 v12, v11, v11
	v_max_f32_e32 v13, v7, v7
	v_max_f32_e32 v12, v12, v13
	s_and_b64 s[20:21], s[18:19], vcc
	v_cndmask_b32_e64 v11, v11, v12, s[20:21]
	v_add_u32_e32 v12, 18, v10
	v_cmp_le_i32_e32 vcc, v12, v132
	v_max_f32_e32 v12, v11, v11
	v_max_f32_e32 v13, v8, v8
	v_max_f32_e32 v12, v12, v13
	s_and_b64 s[22:23], s[18:19], vcc
	v_cndmask_b32_e64 v11, v11, v12, s[22:23]
	v_add_u32_e32 v10, 19, v10
	v_cmp_le_i32_e32 vcc, v10, v132
	v_max_f32_e32 v10, v11, v11
	v_max_f32_e32 v12, v9, v9
	v_max_f32_e32 v10, v10, v12
	s_and_b64 s[18:19], s[18:19], vcc
	v_cndmask_b32_e64 v10, v11, v10, s[18:19]
	v_cmp_gt_f32_e32 vcc, v10, v0
	s_cbranch_vccz .LBB0_989
	ds_bpermute_b32 v0, v225, v10
	v_max_f32_e32 v10, v10, v10
	s_waitcnt lgkmcnt(0)
	v_max_f32_e32 v0, v0, v0
	v_max_f32_e32 v0, v10, v0
	ds_bpermute_b32 v10, v224, v0
	s_waitcnt lgkmcnt(0)
	v_max3_f32 v10, v203, v0, v10
	v_sub_f32_e32 v0, v203, v10
	v_exp_f32_e32 v0, v0
	v_mov_b32_e32 v203, v10
	v_mul_f32_e32 v204, v204, v0
	v_pk_mul_f32 v[38:39], v[38:39], v[0:1] op_sel_hi:[1,0]
	v_pk_mul_f32 v[36:37], v[36:37], v[0:1] op_sel_hi:[1,0]
	v_pk_mul_f32 v[42:43], v[42:43], v[0:1] op_sel_hi:[1,0]
	v_pk_mul_f32 v[40:41], v[40:41], v[0:1] op_sel_hi:[1,0]
	v_pk_mul_f32 v[46:47], v[46:47], v[0:1] op_sel_hi:[1,0]
	v_pk_mul_f32 v[44:45], v[44:45], v[0:1] op_sel_hi:[1,0]
	v_pk_mul_f32 v[50:51], v[50:51], v[0:1] op_sel_hi:[1,0]
	v_pk_mul_f32 v[48:49], v[48:49], v[0:1] op_sel_hi:[1,0]
	v_pk_mul_f32 v[54:55], v[54:55], v[0:1] op_sel_hi:[1,0]
	v_pk_mul_f32 v[52:53], v[52:53], v[0:1] op_sel_hi:[1,0]
	v_pk_mul_f32 v[58:59], v[58:59], v[0:1] op_sel_hi:[1,0]
	v_pk_mul_f32 v[56:57], v[56:57], v[0:1] op_sel_hi:[1,0]
	v_pk_mul_f32 v[62:63], v[62:63], v[0:1] op_sel_hi:[1,0]
	v_pk_mul_f32 v[60:61], v[60:61], v[0:1] op_sel_hi:[1,0]
	v_pk_mul_f32 v[66:67], v[66:67], v[0:1] op_sel_hi:[1,0]
	v_pk_mul_f32 v[64:65], v[64:65], v[0:1] op_sel_hi:[1,0]
.LBB0_989:
	v_add_f32_e32 v0, -4.0, v203
	v_sub_f32_e32 v2, v2, v0
	v_exp_f32_e32 v2, v2
	v_sub_f32_e32 v6, v6, v0
	v_exp_f32_e32 v6, v6
	v_sub_f32_e32 v4, v4, v0
	v_cndmask_b32_e64 v28, 0, v2, s[16:17]
	v_sub_f32_e32 v2, v3, v0
	v_exp_f32_e32 v2, v2
	v_sub_f32_e32 v3, v7, v0
	v_exp_f32_e32 v3, v3
	v_sub_f32_e32 v7, v8, v0
	v_cndmask_b32_e64 v29, 0, v2, s[12:13]
	v_sub_f32_e32 v2, v5, v0
	v_sub_f32_e32 v0, v9, v0
	v_cndmask_b32_e64 v6, 0, v6, s[24:25]
	v_exp_f32_e32 v4, v4
	v_exp_f32_e32 v7, v7
	v_cndmask_b32_e64 v30, 0, v3, s[20:21]
	v_exp_f32_e32 v5, v2
	v_exp_f32_e32 v0, v0
	v_mov_b32_e32 v2, v1
	v_mov_b32_e32 v3, v1
	v_cvt_pk_fp8_f32 v2, v28, v29
	v_cvt_pk_fp8_f32 v3, v6, v30
	v_cndmask_b32_e64 v4, 0, v4, s[14:15]
	v_cndmask_b32_e64 v7, 0, v7, s[22:23]
	v_cndmask_b32_e64 v5, 0, v5, s[10:11]
	v_cndmask_b32_e64 v0, 0, v0, s[18:19]
	v_cvt_pk_fp8_f32 v2, v4, v5 op_sel:[0,0,1]
	v_cvt_pk_fp8_f32 v3, v7, v0 op_sel:[0,0,1]
	v_add_f32_e32 v6, v28, v6
	v_add_f32_e32 v6, 0, v6
	v_add_f32_e32 v28, v29, v30
	v_add_f32_e32 v6, v28, v6
	v_add_f32_e32 v4, v4, v7
	v_add_f32_e32 v4, v4, v6
	v_add_f32_e32 v0, v5, v0
	s_waitcnt vmcnt(39)
	v_mfma_f32_16x16x32_fp8_fp8 v[8:11], v[170:171], v[2:3], v[36:39]
	v_add_f32_e32 v0, v0, v4
	v_add_f32_e32 v133, v204, v0
	v_mov_b32_e32 v202, v203
	s_waitcnt vmcnt(38)
	v_mfma_f32_16x16x32_fp8_fp8 v[12:15], v[172:173], v[2:3], v[40:43]
	s_waitcnt vmcnt(37)
	v_mfma_f32_16x16x32_fp8_fp8 v[16:19], v[174:175], v[2:3], v[44:47]
	s_waitcnt vmcnt(36)
	v_mfma_f32_16x16x32_fp8_fp8 v[20:23], v[176:177], v[2:3], v[48:51]
	s_waitcnt vmcnt(35)
	v_mfma_f32_16x16x32_fp8_fp8 v[24:27], v[184:185], v[2:3], v[52:55]
	s_waitcnt vmcnt(34)
	v_mfma_f32_16x16x32_fp8_fp8 v[32:35], v[182:183], v[2:3], v[56:59]
	s_waitcnt vmcnt(33)
	v_mfma_f32_16x16x32_fp8_fp8 v[28:31], v[180:181], v[2:3], v[60:63]
	s_waitcnt vmcnt(32)
	v_mfma_f32_16x16x32_fp8_fp8 v[4:7], v[178:179], v[2:3], v[64:67]

; __device__ __forceinline__ unsigned cvt_pk_bf16(float lo, float hi) { f32x2 v = {lo, hi}; bf16x2_t b = __builtin_convertvector(v, bf16x2_t); return __builtin_bit_cast(unsigned, b); }
; __device__ __forceinline__ float bf2f(unsigned short b) { return __uint_as_float(((unsigned)b) << 16); }
; __device__ __forceinline__ float bflo(unsigned w) { return __uint_as_float(w << 16); }
; __device__ __forceinline__ float bfhi(unsigned w) { return __uint_as_float(w & 0xffff0000u); }
; __device__ __forceinline__ float quad_total(float v) { v += __shfl_xor(v, 16); v += __shfl_xor(v, 32); return v; }
; __device__ __forceinline__ void nsa_unit(int unit, const bf16_t* proj, const bf16_t* kc, const bf16_t* vc, const bf16_t* gn, const float* cs, const float* sn, ...
;     ...
;     { const float g1 = bf2f(gn[(size_t)tc * 32 + head * 3 + 1]); const float lt = quad_total(st.l), inv = (lt > 0.f ? 1.f / lt : 0.f) * g1;
; #pragma unroll
;         for (int i = 0; i < 8; ++i) { const f32x4 o = st.o[i] * inv; u32x2 w = outl[64 * i]; w.x = cvt_pk_bf16(bflo(w.x) + o[0], bfhi(w.x) + o[1]); w.y = cvt_pk_bf16(bflo(w.y) + o[2], bfhi(w.y) + o[3]); outl[64 * i] = w; } }
;     astate_init(st);
;     { const int lo = tc - 511 < 0 ? 0 : tc - 511; const int first = t0 < 511 ? 0 : (t0 - 511) >> 5, last = (t0 + 3) >> 5;
.LBB0_992:
	s_waitcnt vmcnt(16)
	global_load_ushort v0, v[76:77], off offset:2
	ds_bpermute_b32 v2, v225, v133
	ds_read2st64_b64 v[36:39], v226 offset0:27 offset1:28
	ds_read2st64_b64 v[40:43], v226 offset0:29 offset1:30
	ds_read2st64_b64 v[44:47], v226 offset0:31 offset1:32
	ds_read2st64_b64 v[48:51], v226 offset0:33 offset1:34
	s_mov_b32 s56, 0
	s_waitcnt lgkmcnt(3)
	v_and_b32_e32 v3, 0xffff0000, v36
	v_lshlrev_b32_e32 v52, 16, v38
	v_add_f32_e32 v64, v133, v2
	ds_bpermute_b32 v65, v224, v64
	v_lshlrev_b32_e32 v2, 16, v36
	v_lshlrev_b32_e32 v36, 16, v37
	v_and_b32_e32 v37, 0xffff0000, v37
	v_and_b32_e32 v53, 0xffff0000, v38
	s_waitcnt lgkmcnt(0)
	v_add_f32_e32 v64, v64, v65
	v_div_scale_f32 v65, s[10:11], v64, v64, 1.0
	v_rcp_f32_e32 v66, v65
	v_div_scale_f32 v67, vcc, 1.0, v64, 1.0
	v_lshlrev_b32_e32 v38, 16, v39
	v_fma_f32 v68, -v65, v66, 1.0
	v_fmac_f32_e32 v66, v68, v66
	v_mul_f32_e32 v68, v67, v66
	v_fma_f32 v69, -v65, v68, v67
	v_fmac_f32_e32 v68, v69, v66
	v_fma_f32 v65, -v65, v68, v67
	v_div_fmas_f32 v65, v65, v66, v68
	v_div_fixup_f32 v65, v65, v64, 1.0
	v_cmp_lt_f32_e32 vcc, 0, v64
	v_and_b32_e32 v39, 0xffff0000, v39
	v_lshlrev_b32_e32 v54, 16, v40
	v_cndmask_b32_e32 v64, 0, v65, vcc
	v_and_b32_e32 v55, 0xffff0000, v40
	v_lshlrev_b32_e32 v40, 16, v41
	v_and_b32_e32 v41, 0xffff0000, v41
	v_lshlrev_b32_e32 v56, 16, v42
	v_and_b32_e32 v57, 0xffff0000, v42
	v_lshlrev_b32_e32 v42, 16, v43
	v_and_b32_e32 v43, 0xffff0000, v43
	v_lshlrev_b32_e32 v58, 16, v44
	v_and_b32_e32 v59, 0xffff0000, v44
	v_lshlrev_b32_e32 v44, 16, v45
	v_and_b32_e32 v45, 0xffff0000, v45
	v_lshlrev_b32_e32 v60, 16, v46
	v_and_b32_e32 v61, 0xffff0000, v46
	v_lshlrev_b32_e32 v46, 16, v47
	v_and_b32_e32 v47, 0xffff0000, v47
	v_lshlrev_b32_e32 v62, 16, v48
	v_and_b32_e32 v63, 0xffff0000, v48
	v_lshlrev_b32_e32 v48, 16, v49
	v_and_b32_e32 v49, 0xffff0000, v49
	s_add_i32 s10, s90, 0xfffffe01
	s_lshr_b32 s10, s10, 5
	s_cmpk_gt_i32 s90, 0x1fe
	s_cselect_b32 s26, s10, 0
	s_ashr_i32 s15, s91, 3
	s_sub_i32 s27, s15, s26
	s_mov_b64 s[12:13], s[52:53]
	s_cmp_lt_i32 s27, 0
	s_waitcnt vmcnt(0)
	v_lshlrev_b32_e32 v0, 16, v0
	v_mul_f32_e32 v0, v64, v0
	v_pk_fma_f32 v[2:3], v[8:9], v[0:1], v[2:3] op_sel_hi:[1,0,1]
	v_pk_fma_f32 v[8:9], v[10:11], v[0:1], v[36:37] op_sel_hi:[1,0,1]
	v_pk_fma_f32 v[10:11], v[12:13], v[0:1], v[52:53] op_sel_hi:[1,0,1]
	v_pk_fma_f32 v[12:13], v[14:15], v[0:1], v[38:39] op_sel_hi:[1,0,1]
	v_pk_fma_f32 v[14:15], v[16:17], v[0:1], v[54:55] op_sel_hi:[1,0,1]
	v_pk_fma_f32 v[16:17], v[18:19], v[0:1], v[40:41] op_sel_hi:[1,0,1]
	v_pk_fma_f32 v[18:19], v[20:21], v[0:1], v[56:57] op_sel_hi:[1,0,1]
	v_pk_fma_f32 v[20:21], v[22:23], v[0:1], v[42:43] op_sel_hi:[1,0,1]
	v_pk_fma_f32 v[22:23], v[24:25], v[0:1], v[58:59] op_sel_hi:[1,0,1]
	v_pk_fma_f32 v[24:25], v[26:27], v[0:1], v[44:45] op_sel_hi:[1,0,1]
	v_pk_fma_f32 v[26:27], v[32:33], v[0:1], v[60:61] op_sel_hi:[1,0,1]
	v_pk_fma_f32 v[32:33], v[34:35], v[0:1], v[46:47] op_sel_hi:[1,0,1]
	v_cvt_pk_bf16_f32 v2, v2, v3
	v_cvt_pk_bf16_f32 v3, v8, v9
	v_cvt_pk_bf16_f32 v8, v10, v11
	v_cvt_pk_bf16_f32 v9, v12, v13
	v_cvt_pk_bf16_f32 v10, v14, v15
	v_cvt_pk_bf16_f32 v11, v16, v17
	v_cvt_pk_bf16_f32 v12, v18, v19
	v_cvt_pk_bf16_f32 v13, v20, v21
	v_cvt_pk_bf16_f32 v14, v22, v23
	v_cvt_pk_bf16_f32 v15, v24, v25
	v_cvt_pk_bf16_f32 v16, v26, v27
	v_cvt_pk_bf16_f32 v17, v32, v33
	ds_write2st64_b64 v226, v[2:3], v[8:9] offset0:27 offset1:28
	ds_write2st64_b64 v226, v[10:11], v[12:13] offset0:29 offset1:30
	ds_write2st64_b64 v226, v[14:15], v[16:17] offset0:31 offset1:32
	v_pk_fma_f32 v[2:3], v[30:31], v[0:1], v[48:49] op_sel_hi:[1,0,1]
	v_pk_fma_f32 v[28:29], v[28:29], v[0:1], v[62:63] op_sel_hi:[1,0,1]
	v_cvt_pk_bf16_f32 v19, v2, v3
	v_lshlrev_b32_e32 v2, 16, v50
	v_and_b32_e32 v3, 0xffff0000, v50
	v_pk_fma_f32 v[2:3], v[4:5], v[0:1], v[2:3] op_sel_hi:[1,0,1]
	v_lshlrev_b32_e32 v4, 16, v51
	v_and_b32_e32 v5, 0xffff0000, v51
	v_pk_fma_f32 v[4:5], v[6:7], v[0:1], v[4:5] op_sel_hi:[1,0,1]
	v_cvt_pk_bf16_f32 v18, v28, v29
	v_cvt_pk_bf16_f32 v2, v2, v3
	v_cvt_pk_bf16_f32 v3, v4, v5
	ds_write2st64_b64 v226, v[18:19], v[2:3] offset0:33 offset1:34
	s_cbranch_scc1 .LBB0_925
; template <bool SLC, class Desc>
; __device__ __forceinline__ void attn_run_frag8(const i64_t (&qf)[4], const unsigned char* __restrict__ KF, const unsigned char* __restrict__ VF, const Desc& desc, int n,
;                                                int lo_in, int hi, int qi, AState& st, int lane) {
;     ...
;     Frag8 fa, fb, fc;
;     constexpr int NM = ~(1 << 30);
;     int d0 = desc(0), d1 = desc(n > 1 ? 1 : 0);
;     load_frag8(fa, KF, VF, SLC ? (d0 & 0xfffff) : (d0 & NM), lane);
;     load_frag8(fb, KF, VF, SLC ? (d1 & 0xfffff) : (d1 & NM), lane);
; __device__ __forceinline__ void nsa_unit(int unit, const bf16_t* proj, const bf16_t* kc, const bf16_t* vc, const bf16_t* gn, const float* cs, const float* sn, ...
;     ...
;     { const int lo = tc - 511 < 0 ? 0 : tc - 511; const int first = t0 < 511 ? 0 : (t0 - 511) >> 5, last = (t0 + 3) >> 5;
;       auto desc = [&](int i) { const int p0 = 32 * (first + i); return p0 | ((p0 >= t0 + 3 - 511 && p0 + 31 <= t0) ? (1 << 30) : 0); };
;       unsigned long long goff = (unsigned long long)g * S * 128; asm volatile("" : "+s"(goff));
;       attn_run_frag8<false>(q8, (const unsigned char*)kslf + ((size_t)16 << 20) + goff, (const unsigned char*)kslf + ((size_t)24 << 20) + goff, desc, last - first + 1, lo, tc, 0, st, lane); }
	s_add_u32 s10, s71, s12
	s_addc_u32 s11, s72, s13
	s_add_u32 s12, s73, s12
	s_addc_u32 s13, s74, s13
	s_lshl_b32 s20, s26, 5
	s_add_i32 s54, s90, 0xfffffe04
	s_cmp_lt_i32 s20, s54
	s_cselect_b64 s[16:17], -1, 0
	s_or_b32 s14, s20, 31
	s_cmp_gt_i32 s14, s90
	s_cselect_b64 s[18:19], -1, 0
	s_or_b64 s[16:17], s[16:17], s[18:19]
	s_and_b64 s[16:17], s[16:17], exec
	s_cselect_b32 s14, 0, 2.0
	s_or_b32 s14, s14, s20
	s_cmp_lg_u32 s15, s26
	s_cselect_b64 s[16:17], -1, 0
	v_cndmask_b32_e64 v0, 0, 1, s[16:17]
	v_lshl_add_u64 v[86:87], s[12:13], 0, v[120:121]
	v_readfirstlane_b32 s15, v0
	s_add_i32 s15, s26, s15
	s_lshl_b32 s21, s15, 5
	s_cmp_lt_i32 s21, s54
	s_cselect_b64 s[16:17], -1, 0
	s_or_b32 s18, s21, 31
	s_cmp_gt_i32 s18, s90
	s_cselect_b64 s[18:19], -1, 0
	s_or_b64 s[16:17], s[16:17], s[18:19]
	s_and_b64 s[16:17], s[16:17], exec
	s_cselect_b32 s16, 0, 2.0
	s_or_b32 s66, s16, s21
	s_and_b32 s16, s20, 0x3fffffe0
	s_lshr_b32 s50, s16, 4
	s_lshl_b64 s[16:17], s[50:51], 11
	s_add_u32 s16, s12, s16
	s_addc_u32 s17, s13, s17
	s_and_b32 s50, s26, 0x1ffffff
	v_lshl_add_u64 v[2:3], s[16:17], 0, v[120:121]
	s_lshl_b64 s[16:17], s[50:51], 12
	s_add_u32 s16, s10, s16
	s_addc_u32 s17, s11, s17
	global_load_dwordx2 v[148:149], v[2:3], off
	global_load_dwordx2 v[152:153], v[2:3], off offset:512
	global_load_dwordx2 v[150:151], v[2:3], off offset:1024
	global_load_dwordx2 v[144:145], v[2:3], off offset:1536
	global_load_dwordx2 v[146:147], v[2:3], off offset:2048
	global_load_dwordx2 v[142:143], v[2:3], off offset:2560
	global_load_dwordx2 v[140:141], v[2:3], off offset:3072
	global_load_dwordx2 v[138:139], v[2:3], off offset:3584
	v_lshl_add_u64 v[2:3], s[16:17], 0, v[120:121]
	s_and_b32 s16, s21, 0x3fffffe0
	s_lshr_b32 s50, s16, 4
	s_lshl_b64 s[16:17], s[50:51], 11
	s_add_u32 s16, s12, s16
	s_addc_u32 s17, s13, s17
	s_and_b32 s50, s15, 0x1ffffff
	global_load_dwordx2 v[90:91], v[2:3], off
	global_load_dwordx2 v[92:93], v[2:3], off offset:512
	global_load_dwordx2 v[94:95], v[2:3], off offset:1024
	global_load_dwordx2 v[96:97], v[2:3], off offset:1536
	global_load_dwordx2 v[104:105], v[2:3], off offset:2048
	global_load_dwordx2 v[102:103], v[2:3], off offset:2560
	global_load_dwordx2 v[100:101], v[2:3], off offset:3072
	global_load_dwordx2 v[98:99], v[2:3], off offset:3584
	v_lshl_add_u64 v[2:3], s[16:17], 0, v[120:121]
	s_lshl_b64 s[16:17], s[50:51], 12
	s_add_u32 s16, s10, s16
	s_addc_u32 s17, s11, s17
	global_load_dwordx2 v[166:167], v[2:3], off
	global_load_dwordx2 v[168:169], v[2:3], off offset:512
	global_load_dwordx2 v[164:165], v[2:3], off offset:1024
	global_load_dwordx2 v[162:163], v[2:3], off offset:1536
	global_load_dwordx2 v[160:161], v[2:3], off offset:2048
	global_load_dwordx2 v[158:159], v[2:3], off offset:2560
	global_load_dwordx2 v[156:157], v[2:3], off offset:3072
	global_load_dwordx2 v[154:155], v[2:3], off offset:3584
	v_lshl_add_u64 v[2:3], s[16:17], 0, v[120:121]
	global_load_dwordx2 v[106:107], v[2:3], off
	global_load_dwordx2 v[110:111], v[2:3], off offset:512
	global_load_dwordx2 v[112:113], v[2:3], off offset:1024
	global_load_dwordx2 v[116:117], v[2:3], off offset:1536
	global_load_dwordx2 v[136:137], v[2:3], off offset:2048
	global_load_dwordx2 v[134:135], v[2:3], off offset:2560
	global_load_dwordx2 v[114:115], v[2:3], off offset:3072
	global_load_dwordx2 v[108:109], v[2:3], off offset:3584
	v_max_i32_e32 v0, 0x1ff, v132
	v_mov_b32_e32 v2, v1
	v_mov_b32_e32 v3, v1
	v_add_u32_e32 v35, 0xfffffe01, v0
	v_mov_b32_e32 v0, v1
	v_mov_b64_e32 v[38:39], v[2:3]
	v_mov_b64_e32 v[42:43], v[2:3]
	v_mov_b64_e32 v[46:47], v[2:3]
	v_mov_b64_e32 v[50:51], v[2:3]
	v_mov_b64_e32 v[54:55], v[2:3]
	v_mov_b64_e32 v[58:59], v[2:3]
	v_mov_b64_e32 v[62:63], v[2:3]
	v_mov_b64_e32 v[66:67], v[2:3]
	v_lshl_add_u64 v[88:89], s[10:11], 0, v[120:121]
	v_mov_b32_e32 v133, 0xf149f2ca
	v_mov_b32_e32 v227, 0
	v_mov_b64_e32 v[36:37], v[0:1]
	v_mov_b64_e32 v[40:41], v[0:1]
	v_mov_b64_e32 v[44:45], v[0:1]
	v_mov_b64_e32 v[48:49], v[0:1]
	v_mov_b64_e32 v[52:53], v[0:1]
	v_mov_b64_e32 v[56:57], v[0:1]
	v_mov_b64_e32 v[60:61], v[0:1]
	v_mov_b64_e32 v[64:65], v[0:1]
	s_branch .LBB0_996

; template <bool SLC, bool NOMASK> ...
;     const int kq = lane >> 4;
;     const int pos0 = SLC ? (dcur & 0xfffff) : dcur;
;     const int lo = SLC ? ((((dcur >> 20) == qi) | ((dcur >> 20) == 4)) ? 0 : (1 << 30)) : lo_in;
;     load_frag8(nxt, KF, VF, SLC ? (dnext & 0xfffff) : dnext, lane);
;     f32x4 sa[2] = {(f32x4){0.f, 0.f, 0.f, 0.f}, (f32x4){0.f, 0.f, 0.f, 0.f}};
; #pragma unroll
;     for (int T = 0; T < 2; ++T)
; #pragma unroll
;         for (int s2 = 0; s2 < 4; ++s2) sa[T] = __builtin_amdgcn_mfma_f32_16x16x32_fp8_fp8(cur.k[T][s2], qf[s2], sa[T], 0, 0, 0);
;     float sc[8]; bool vd[8]; float mx = -1e30f;
;     const bool act = lo == 0 || !SLC;
;     if (NOMASK) {
; #pragma unroll
;         for (int j = 0; j < 8; ++j) { sc[j] = sa[j >> 2][j & 3]; vd[j] = act; }
;         mx = fmaxf(fmaxf(fmaxf(sc[0], sc[1]), fmaxf(sc[2], sc[3])), fmaxf(fmaxf(sc[4], sc[5]), fmaxf(sc[6], sc[7])));
;         mx = act ? mx : -1e30f;
;     } else {
; #pragma unroll
;         for (int T = 0; T < 2; ++T)
; #pragma unroll
;             for (int r = 0; r < 4; ++r) { const int p = pos0 + 16 * T + 4 * kq + r; const bool v = (p >= lo) & (p <= hi); const float x = sa[T][r];
;                 sc[4 * T + r] = x; vd[4 * T + r] = v; mx = v ? fmaxf(mx, x) : mx; }
;     }
;     if (__builtin_amdgcn_ballot_w64(mx > st.m + 4.f) != 0ull) {
;         mx = fmaxf(mx, __shfl_xor(mx, 16)); mx = fmaxf(mx, __shfl_xor(mx, 32));
;         const float mn = fmaxf(st.m, mx), alpha = __builtin_amdgcn_exp2f(st.m - mn); st.m = mn; st.l *= alpha;
; #pragma unroll
;         for (int j = 0; j < 8; ++j) st.o[j] = st.o[j] * alpha;
;     }
;     f32x4 pa, pb; float ps = 0.f;
;     const float mref = st.m - 4.f;
;     if (NOMASK) {
; #pragma unroll
;         for (int j = 0; j < 4; ++j) { pa[j] = __builtin_amdgcn_exp2f(sc[j] - mref); pb[j] = __builtin_amdgcn_exp2f(sc[4 + j] - mref); }
;         if (SLC) {
; #pragma unroll
;             for (int j = 0; j < 4; ++j) { pa[j] = act ? pa[j] : 0.f; pb[j] = act ? pb[j] : 0.f; }
;         }
; #pragma unroll
;         for (int j = 0; j < 4; ++j) ps += pa[j] + pb[j];
;     } else {
; #pragma unroll
;         for (int j = 0; j < 4; ++j) { pa[j] = vd[j] ? __builtin_amdgcn_exp2f(sc[j] - mref) : 0.f; pb[j] = vd[4 + j] ? __builtin_amdgcn_exp2f(sc[4 + j] - mref) : 0.f; ps += pa[j] + pb[j]; }
;     }
;     st.l += ps;
;     const u32x2 pw = pack8_fp8(pa, pb);
.LBB0_1002:
	global_load_dwordx2 v[196:197], v[204:205], off
	global_load_dwordx2 v[200:201], v[204:205], off offset:512
	global_load_dwordx2 v[198:199], v[204:205], off offset:1024
	global_load_dwordx2 v[192:193], v[204:205], off offset:1536
	global_load_dwordx2 v[194:195], v[204:205], off offset:2048
	global_load_dwordx2 v[190:191], v[204:205], off offset:2560
	global_load_dwordx2 v[188:189], v[204:205], off offset:3072
	global_load_dwordx2 v[186:187], v[204:205], off offset:3584
	global_load_dwordx2 v[170:171], v[202:203], off
	global_load_dwordx2 v[172:173], v[202:203], off offset:512
	global_load_dwordx2 v[174:175], v[202:203], off offset:1024
	global_load_dwordx2 v[176:177], v[202:203], off offset:1536
	global_load_dwordx2 v[184:185], v[202:203], off offset:2048
	global_load_dwordx2 v[182:183], v[202:203], off offset:2560
	global_load_dwordx2 v[180:181], v[202:203], off offset:3072
	global_load_dwordx2 v[178:179], v[202:203], off offset:3584
	s_waitcnt vmcnt(47)
	v_mfma_f32_16x16x32_fp8_fp8 v[2:5], v[148:149], v[78:79], 0
	v_mov_b64_e32 v[74:75], v[38:39]
	v_mov_b64_e32 v[70:71], v[42:43]
	v_mov_b64_e32 v[30:31], v[44:45]
	s_waitcnt vmcnt(43)
	v_mfma_f32_16x16x32_fp8_fp8 v[6:9], v[146:147], v[78:79], 0
	v_mov_b64_e32 v[26:27], v[48:49]
	v_mov_b64_e32 v[22:23], v[52:53]
	v_mov_b64_e32 v[18:19], v[56:57]
	v_mfma_f32_16x16x32_fp8_fp8 v[2:5], v[152:153], v[80:81], v[2:5]
	v_mov_b64_e32 v[14:15], v[60:61]
	v_mov_b32_e32 v228, v133
	v_mov_b64_e32 v[72:73], v[36:37]
	s_waitcnt vmcnt(42)
	v_mfma_f32_16x16x32_fp8_fp8 v[6:9], v[142:143], v[80:81], v[6:9]
	v_mov_b64_e32 v[68:69], v[40:41]
	v_mov_b64_e32 v[32:33], v[46:47]
	v_mov_b64_e32 v[28:29], v[50:51]
	v_mfma_f32_16x16x32_fp8_fp8 v[2:5], v[150:151], v[82:83], v[2:5]
	v_mov_b64_e32 v[24:25], v[54:55]
	v_mov_b64_e32 v[20:21], v[58:59]
	v_mov_b64_e32 v[16:17], v[62:63]
	s_waitcnt vmcnt(41)
	v_mfma_f32_16x16x32_fp8_fp8 v[6:9], v[140:141], v[82:83], v[6:9]
	v_mov_b32_e32 v34, v227
	v_mfma_f32_16x16x32_fp8_fp8 v[2:5], v[144:145], v[84:85], v[2:5]
	s_waitcnt vmcnt(40)
	v_mfma_f32_16x16x32_fp8_fp8 v[6:9], v[138:139], v[84:85], v[6:9]
	s_nop 5
	v_max_f32_e32 v0, v3, v3
	v_max_f32_e32 v10, v2, v2
	v_max_f32_e32 v0, v10, v0
	v_max_f32_e32 v10, v5, v5
	v_max_f32_e32 v11, v4, v4
	v_max_f32_e32 v10, v11, v10
	v_max_f32_e32 v11, v9, v9
	v_max_f32_e32 v12, v8, v8
	v_max_f32_e32 v11, v12, v11
	v_max3_f32 v11, v6, v7, v11
	v_max3_f32 v0, v0, v10, v11
	v_add_f32_e32 v10, 4.0, v133
	v_cmp_gt_f32_e32 vcc, v0, v10
	v_mov_b64_e32 v[10:11], v[64:65]
	v_mov_b64_e32 v[12:13], v[66:67]
	s_cbranch_vccz .LBB0_1004
	ds_bpermute_b32 v10, v225, v0
	v_max_f32_e32 v0, v0, v0
	s_waitcnt lgkmcnt(0)
	v_max_f32_e32 v10, v10, v10
	v_max_f32_e32 v0, v0, v10
	ds_bpermute_b32 v10, v224, v0
	s_waitcnt lgkmcnt(0)
	v_max3_f32 v228, v133, v0, v10
	v_sub_f32_e32 v0, v133, v228
	v_exp_f32_e32 v0, v0
	s_nop 0
	v_mul_f32_e32 v34, v227, v0
	v_pk_mul_f32 v[12:13], v[66:67], v[0:1] op_sel_hi:[1,0]
	v_pk_mul_f32 v[10:11], v[64:65], v[0:1] op_sel_hi:[1,0]
	v_pk_mul_f32 v[16:17], v[62:63], v[0:1] op_sel_hi:[1,0]
	v_pk_mul_f32 v[14:15], v[60:61], v[0:1] op_sel_hi:[1,0]
	v_pk_mul_f32 v[20:21], v[58:59], v[0:1] op_sel_hi:[1,0]
	v_pk_mul_f32 v[18:19], v[56:57], v[0:1] op_sel_hi:[1,0]
	v_pk_mul_f32 v[24:25], v[54:55], v[0:1] op_sel_hi:[1,0]
	v_pk_mul_f32 v[22:23], v[52:53], v[0:1] op_sel_hi:[1,0]
	v_pk_mul_f32 v[28:29], v[50:51], v[0:1] op_sel_hi:[1,0]
	v_pk_mul_f32 v[26:27], v[48:49], v[0:1] op_sel_hi:[1,0]
	v_pk_mul_f32 v[32:33], v[46:47], v[0:1] op_sel_hi:[1,0]
	v_pk_mul_f32 v[30:31], v[44:45], v[0:1] op_sel_hi:[1,0]
	v_pk_mul_f32 v[70:71], v[42:43], v[0:1] op_sel_hi:[1,0]
	v_pk_mul_f32 v[68:69], v[40:41], v[0:1] op_sel_hi:[1,0]
	v_pk_mul_f32 v[74:75], v[38:39], v[0:1] op_sel_hi:[1,0]
	v_pk_mul_f32 v[72:73], v[36:37], v[0:1] op_sel_hi:[1,0]
.LBB0_1004:
	v_add_f32_e32 v229, -4.0, v228
	v_sub_f32_e32 v0, v2, v229
	v_exp_f32_e32 v231, v0
	v_sub_f32_e32 v0, v6, v229
	v_exp_f32_e32 v234, v0
	v_sub_f32_e32 v0, v3, v229
	v_exp_f32_e32 v2, v0
	v_sub_f32_e32 v0, v7, v229
	v_exp_f32_e32 v0, v0
	v_sub_f32_e32 v3, v4, v229
	v_exp_f32_e32 v235, v3
	v_sub_f32_e32 v3, v8, v229
	v_exp_f32_e32 v236, v3
	v_sub_f32_e32 v3, v5, v229
	v_exp_f32_e32 v4, v3
	v_sub_f32_e32 v3, v9, v229
	v_mov_b32_e32 v232, v1
	v_mov_b32_e32 v233, v1
	v_exp_f32_e32 v230, v3
	v_cvt_pk_fp8_f32 v232, v231, v2
	v_cvt_pk_fp8_f32 v233, v234, v0
	v_add_f32_e32 v3, v231, v234
	v_pk_add_f32 v[2:3], v[2:3], v[0:1]
	v_cvt_pk_fp8_f32 v232, v235, v4 op_sel:[0,0,1]
	v_cvt_pk_fp8_f32 v233, v236, v230 op_sel:[0,0,1]
	v_pk_add_f32 v[2:3], v[2:3], v[2:3] op_sel_hi:[0,1]
	v_add_f32_e32 v5, v235, v236
	v_mov_b32_e32 v231, v3
	v_pk_add_f32 v[2:3], v[4:5], v[230:231]
	s_waitcnt vmcnt(39)
	v_mfma_f32_16x16x32_fp8_fp8 v[6:9], v[90:91], v[232:233], v[10:13]
	v_add_f32_e32 v0, v2, v3
	v_add_f32_e32 v34, v0, v34
	s_waitcnt vmcnt(38)
	v_mfma_f32_16x16x32_fp8_fp8 v[10:13], v[92:93], v[232:233], v[14:17]
	s_waitcnt vmcnt(37)
	v_mfma_f32_16x16x32_fp8_fp8 v[14:17], v[94:95], v[232:233], v[18:21]
	s_waitcnt vmcnt(36)
	v_mfma_f32_16x16x32_fp8_fp8 v[18:21], v[96:97], v[232:233], v[22:25]
	s_waitcnt vmcnt(35)
	v_mfma_f32_16x16x32_fp8_fp8 v[22:25], v[104:105], v[232:233], v[26:29]
	s_waitcnt vmcnt(34)
	v_mfma_f32_16x16x32_fp8_fp8 v[26:29], v[102:103], v[232:233], v[30:33]
	s_waitcnt vmcnt(33)
	v_mfma_f32_16x16x32_fp8_fp8 v[30:33], v[100:101], v[232:233], v[68:71]
	s_waitcnt vmcnt(32)
	v_mfma_f32_16x16x32_fp8_fp8 v[2:5], v[98:99], v[232:233], v[72:75]
	s_branch .LBB0_998
; template <bool SLC, bool NOMASK> ...
;     const int kq = lane >> 4;
;     const int pos0 = SLC ? (dcur & 0xfffff) : dcur;
;     const int lo = SLC ? ((((dcur >> 20) == qi) | ((dcur >> 20) == 4)) ? 0 : (1 << 30)) : lo_in;
;     load_frag8(nxt, KF, VF, SLC ? (dnext & 0xfffff) : dnext, lane);
;     f32x4 sa[2] = {(f32x4){0.f, 0.f, 0.f, 0.f}, (f32x4){0.f, 0.f, 0.f, 0.f}};
; #pragma unroll
;     for (int T = 0; T < 2; ++T)
; #pragma unroll
;         for (int s2 = 0; s2 < 4; ++s2) sa[T] = __builtin_amdgcn_mfma_f32_16x16x32_fp8_fp8(cur.k[T][s2], qf[s2], sa[T], 0, 0, 0);
;     float sc[8]; bool vd[8]; float mx = -1e30f;
;     const bool act = lo == 0 || !SLC;
;     if (NOMASK) {
; #pragma unroll
;         for (int j = 0; j < 8; ++j) { sc[j] = sa[j >> 2][j & 3]; vd[j] = act; }
;         mx = fmaxf(fmaxf(fmaxf(sc[0], sc[1]), fmaxf(sc[2], sc[3])), fmaxf(fmaxf(sc[4], sc[5]), fmaxf(sc[6], sc[7])));
;         mx = act ? mx : -1e30f;
;     } else {
; #pragma unroll
;         for (int T = 0; T < 2; ++T)
; #pragma unroll
;             for (int r = 0; r < 4; ++r) { const int p = pos0 + 16 * T + 4 * kq + r; const bool v = (p >= lo) & (p <= hi); const float x = sa[T][r];
;                 sc[4 * T + r] = x; vd[4 * T + r] = v; mx = v ? fmaxf(mx, x) : mx; }
;     }
;     if (__builtin_amdgcn_ballot_w64(mx > st.m + 4.f) != 0ull) {
;         mx = fmaxf(mx, __shfl_xor(mx, 16)); mx = fmaxf(mx, __shfl_xor(mx, 32));
;         const float mn = fmaxf(st.m, mx), alpha = __builtin_amdgcn_exp2f(st.m - mn); st.m = mn; st.l *= alpha;
; #pragma unroll
;         for (int j = 0; j < 8; ++j) st.o[j] = st.o[j] * alpha;
;     }
;     f32x4 pa, pb; float ps = 0.f;
;     const float mref = st.m - 4.f;
;     if (NOMASK) {
; #pragma unroll
;         for (int j = 0; j < 4; ++j) { pa[j] = __builtin_amdgcn_exp2f(sc[j] - mref); pb[j] = __builtin_amdgcn_exp2f(sc[4 + j] - mref); }
;         if (SLC) {
; #pragma unroll
;             for (int j = 0; j < 4; ++j) { pa[j] = act ? pa[j] : 0.f; pb[j] = act ? pb[j] : 0.f; }
;         }
; #pragma unroll
;         for (int j = 0; j < 4; ++j) ps += pa[j] + pb[j];
;     } else {
; #pragma unroll
;         for (int j = 0; j < 4; ++j) { pa[j] = vd[j] ? __builtin_amdgcn_exp2f(sc[j] - mref) : 0.f; pb[j] = vd[4 + j] ? __builtin_amdgcn_exp2f(sc[4 + j] - mref) : 0.f; ps += pa[j] + pb[j]; }
;     }
;     st.l += ps;
;     const u32x2 pw = pack8_fp8(pa, pb);
.LBB0_1005:
	global_load_dwordx2 v[196:197], v[204:205], off
	global_load_dwordx2 v[200:201], v[204:205], off offset:512
	global_load_dwordx2 v[198:199], v[204:205], off offset:1024
	global_load_dwordx2 v[192:193], v[204:205], off offset:1536
	global_load_dwordx2 v[194:195], v[204:205], off offset:2048
	global_load_dwordx2 v[190:191], v[204:205], off offset:2560
	global_load_dwordx2 v[188:189], v[204:205], off offset:3072
	global_load_dwordx2 v[186:187], v[204:205], off offset:3584
	global_load_dwordx2 v[170:171], v[202:203], off
	global_load_dwordx2 v[172:173], v[202:203], off offset:512
	global_load_dwordx2 v[174:175], v[202:203], off offset:1024
	global_load_dwordx2 v[176:177], v[202:203], off offset:1536
	global_load_dwordx2 v[184:185], v[202:203], off offset:2048
	global_load_dwordx2 v[182:183], v[202:203], off offset:2560
	global_load_dwordx2 v[180:181], v[202:203], off offset:3072
	global_load_dwordx2 v[178:179], v[202:203], off offset:3584
	s_waitcnt vmcnt(47)
	v_mfma_f32_16x16x32_fp8_fp8 v[2:5], v[148:149], v[78:79], 0
	v_add_u32_e32 v0, s14, v210
	v_cmp_ge_i32_e32 vcc, v0, v35
	v_cmp_le_i32_e64 s[10:11], v0, v132
	s_waitcnt vmcnt(46)
	v_mfma_f32_16x16x32_fp8_fp8 v[2:5], v[152:153], v[80:81], v[2:5]
	s_and_b64 s[16:17], vcc, s[10:11]
	v_add_u32_e32 v11, 1, v0
	v_cmp_ge_i32_e32 vcc, v11, v35
	s_waitcnt vmcnt(45)
	v_mfma_f32_16x16x32_fp8_fp8 v[2:5], v[150:151], v[82:83], v[2:5]
	v_cmp_lt_i32_e64 s[10:11], v0, v132
	s_and_b64 s[12:13], s[10:11], vcc
	s_waitcnt vmcnt(43)
	v_mfma_f32_16x16x32_fp8_fp8 v[6:9], v[146:147], v[78:79], 0
	v_mfma_f32_16x16x32_fp8_fp8 v[2:5], v[144:145], v[84:85], v[2:5]
	s_waitcnt vmcnt(42)
	v_mfma_f32_16x16x32_fp8_fp8 v[6:9], v[142:143], v[80:81], v[6:9]
	s_waitcnt vmcnt(41)
	v_mfma_f32_16x16x32_fp8_fp8 v[6:9], v[140:141], v[82:83], v[6:9]
	s_nop 3
	v_max_f32_e32 v10, v2, v2
	v_max_f32_e32 v10, 0xf149f2ca, v10
	v_cndmask_b32_e64 v10, v220, v10, s[16:17]
	v_max_f32_e32 v11, v3, v3
	v_max_f32_e32 v11, v10, v11
	v_cndmask_b32_e64 v10, v10, v11, s[12:13]
	v_add_u32_e32 v11, 2, v0
	v_cmp_ge_i32_e32 vcc, v11, v35
	v_cmp_le_i32_e64 s[10:11], v11, v132
	v_max_f32_e32 v11, v4, v4
	v_max_f32_e32 v11, v10, v11
	s_and_b64 s[14:15], vcc, s[10:11]
	s_waitcnt vmcnt(40)
	v_mfma_f32_16x16x32_fp8_fp8 v[6:9], v[138:139], v[84:85], v[6:9]
	v_cndmask_b32_e64 v10, v10, v11, s[14:15]
	v_add_u32_e32 v11, 3, v0
	v_cmp_ge_i32_e32 vcc, v11, v35
	v_cmp_le_i32_e64 s[10:11], v11, v132
	v_max_f32_e32 v11, v5, v5
	v_max_f32_e32 v11, v10, v11
	s_and_b64 s[10:11], vcc, s[10:11]
	v_cndmask_b32_e64 v10, v10, v11, s[10:11]
	v_add_u32_e32 v11, 16, v0
	v_cmp_ge_i32_e32 vcc, v11, v35
	v_cmp_le_i32_e64 s[18:19], v11, v132
	v_max_f32_e32 v11, v6, v6
	v_max_f32_e32 v11, v10, v11
	s_and_b64 s[24:25], vcc, s[18:19]
	v_cndmask_b32_e64 v10, v10, v11, s[24:25]
	v_add_u32_e32 v11, 17, v0
	v_cmp_ge_i32_e32 vcc, v11, v35
	v_cmp_le_i32_e64 s[18:19], v11, v132
	v_max_f32_e32 v11, v10, v10
	v_max_f32_e32 v12, v7, v7
	v_max_f32_e32 v11, v11, v12
	s_and_b64 s[20:21], vcc, s[18:19]
	v_cndmask_b32_e64 v10, v10, v11, s[20:21]
	v_add_u32_e32 v11, 18, v0
	v_cmp_ge_i32_e32 vcc, v11, v35
	v_cmp_le_i32_e64 s[18:19], v11, v132
	v_max_f32_e32 v11, v10, v10
	v_max_f32_e32 v12, v8, v8
	v_max_f32_e32 v11, v11, v12
	s_and_b64 s[22:23], vcc, s[18:19]
	v_cndmask_b32_e64 v10, v10, v11, s[22:23]
	v_add_u32_e32 v0, 19, v0
	v_cmp_ge_i32_e32 vcc, v0, v35
	v_cmp_le_i32_e64 s[18:19], v0, v132
	v_max_f32_e32 v0, v10, v10
	v_max_f32_e32 v11, v9, v9
	v_max_f32_e32 v0, v0, v11
	s_and_b64 s[18:19], vcc, s[18:19]
	v_cndmask_b32_e64 v0, v10, v0, s[18:19]
	v_add_f32_e32 v10, 4.0, v133
	v_cmp_gt_f32_e32 vcc, v0, v10
	s_cbranch_vccz .LBB0_1007
	ds_bpermute_b32 v10, v225, v0
	v_max_f32_e32 v0, v0, v0
	s_waitcnt lgkmcnt(0)
	v_max_f32_e32 v10, v10, v10
	v_max_f32_e32 v0, v0, v10
	ds_bpermute_b32 v10, v224, v0
	s_waitcnt lgkmcnt(0)
	v_max3_f32 v10, v133, v0, v10
	v_sub_f32_e32 v0, v133, v10
	v_exp_f32_e32 v0, v0
	v_mov_b32_e32 v133, v10
	v_mul_f32_e32 v227, v227, v0
	v_pk_mul_f32 v[66:67], v[66:67], v[0:1] op_sel_hi:[1,0]
	v_pk_mul_f32 v[64:65], v[64:65], v[0:1] op_sel_hi:[1,0]
	v_pk_mul_f32 v[62:63], v[62:63], v[0:1] op_sel_hi:[1,0]
	v_pk_mul_f32 v[60:61], v[60:61], v[0:1] op_sel_hi:[1,0]
	v_pk_mul_f32 v[58:59], v[58:59], v[0:1] op_sel_hi:[1,0]
	v_pk_mul_f32 v[56:57], v[56:57], v[0:1] op_sel_hi:[1,0]
	v_pk_mul_f32 v[54:55], v[54:55], v[0:1] op_sel_hi:[1,0]
	v_pk_mul_f32 v[52:53], v[52:53], v[0:1] op_sel_hi:[1,0]
	v_pk_mul_f32 v[50:51], v[50:51], v[0:1] op_sel_hi:[1,0]
	v_pk_mul_f32 v[48:49], v[48:49], v[0:1] op_sel_hi:[1,0]
	v_pk_mul_f32 v[46:47], v[46:47], v[0:1] op_sel_hi:[1,0]
	v_pk_mul_f32 v[44:45], v[44:45], v[0:1] op_sel_hi:[1,0]
	v_pk_mul_f32 v[42:43], v[42:43], v[0:1] op_sel_hi:[1,0]
	v_pk_mul_f32 v[40:41], v[40:41], v[0:1] op_sel_hi:[1,0]
	v_pk_mul_f32 v[38:39], v[38:39], v[0:1] op_sel_hi:[1,0]
	v_pk_mul_f32 v[36:37], v[36:37], v[0:1] op_sel_hi:[1,0]
.LBB0_1007:
	v_add_f32_e32 v0, -4.0, v133
	v_sub_f32_e32 v2, v2, v0
	v_exp_f32_e32 v2, v2
	v_sub_f32_e32 v6, v6, v0
	v_exp_f32_e32 v6, v6
	v_sub_f32_e32 v4, v4, v0
	v_cndmask_b32_e64 v26, 0, v2, s[16:17]
	v_sub_f32_e32 v2, v3, v0
	v_exp_f32_e32 v2, v2
	v_sub_f32_e32 v3, v7, v0
	v_exp_f32_e32 v3, v3
	v_cndmask_b32_e64 v27, 0, v6, s[24:25]
	v_sub_f32_e32 v6, v8, v0
	v_cndmask_b32_e64 v28, 0, v2, s[12:13]
	v_sub_f32_e32 v2, v5, v0
	v_sub_f32_e32 v0, v9, v0
	v_exp_f32_e32 v4, v4
	v_exp_f32_e32 v6, v6
	v_cndmask_b32_e64 v29, 0, v3, s[20:21]
	v_exp_f32_e32 v5, v2
	v_exp_f32_e32 v0, v0
	v_mov_b32_e32 v2, v1
	v_mov_b32_e32 v3, v1
	v_cvt_pk_fp8_f32 v2, v26, v28
	v_cvt_pk_fp8_f32 v3, v27, v29
	v_cndmask_b32_e64 v4, 0, v4, s[14:15]
	v_cndmask_b32_e64 v30, 0, v6, s[22:23]
	v_cndmask_b32_e64 v5, 0, v5, s[10:11]
	v_cndmask_b32_e64 v0, 0, v0, s[18:19]
	v_cvt_pk_fp8_f32 v2, v4, v5 op_sel:[0,0,1]
	v_cvt_pk_fp8_f32 v3, v30, v0 op_sel:[0,0,1]
	v_add_f32_e32 v26, v26, v27
	v_add_f32_e32 v31, 0, v26
	v_add_f32_e32 v32, v28, v29
	v_add_f32_e32 v31, v32, v31
	v_add_f32_e32 v4, v4, v30
	v_add_f32_e32 v4, v4, v31
	v_add_f32_e32 v0, v5, v0
	s_waitcnt vmcnt(39)
	v_mfma_f32_16x16x32_fp8_fp8 v[6:9], v[90:91], v[2:3], v[64:67]
	v_add_f32_e32 v0, v0, v4
	v_add_f32_e32 v34, v227, v0
	v_mov_b32_e32 v228, v133
	s_waitcnt vmcnt(38)
	v_mfma_f32_16x16x32_fp8_fp8 v[10:13], v[92:93], v[2:3], v[60:63]
	s_waitcnt vmcnt(37)
	v_mfma_f32_16x16x32_fp8_fp8 v[14:17], v[94:95], v[2:3], v[56:59]
	s_waitcnt vmcnt(36)
	v_mfma_f32_16x16x32_fp8_fp8 v[18:21], v[96:97], v[2:3], v[52:55]
	s_waitcnt vmcnt(35)
	v_mfma_f32_16x16x32_fp8_fp8 v[22:25], v[104:105], v[2:3], v[48:51]
	s_waitcnt vmcnt(34)
	v_mfma_f32_16x16x32_fp8_fp8 v[26:29], v[102:103], v[2:3], v[44:47]
	s_waitcnt vmcnt(33)
	v_mfma_f32_16x16x32_fp8_fp8 v[30:33], v[100:101], v[2:3], v[40:43]
	s_waitcnt vmcnt(32)
	v_mfma_f32_16x16x32_fp8_fp8 v[2:5], v[98:99], v[2:3], v[36:39]
	s_cmp_ge_i32 s56, s27
	s_mov_b64 s[10:11], -1
	s_cbranch_scc0 .LBB0_999

; template <bool SLC, bool NOMASK> ...
;     ...
;     load_frag8(nxt, KF, VF, SLC ? (dnext & 0xfffff) : dnext, lane);
;     f32x4 sa[2] = {(f32x4){0.f, 0.f, 0.f, 0.f}, (f32x4){0.f, 0.f, 0.f, 0.f}};
; #pragma unroll
;     for (int T = 0; T < 2; ++T)
; #pragma unroll
;         for (int s2 = 0; s2 < 4; ++s2) sa[T] = __builtin_amdgcn_mfma_f32_16x16x32_fp8_fp8(cur.k[T][s2], qf[s2], sa[T], 0, 0, 0);
;     float sc[8]; bool vd[8]; float mx = -1e30f;
;     const bool act = lo == 0 || !SLC;
;     if (NOMASK) {
; #pragma unroll
;         for (int j = 0; j < 8; ++j) { sc[j] = sa[j >> 2][j & 3]; vd[j] = act; }
;         mx = fmaxf(fmaxf(fmaxf(sc[0], sc[1]), fmaxf(sc[2], sc[3])), fmaxf(fmaxf(sc[4], sc[5]), fmaxf(sc[6], sc[7])));
;         mx = act ? mx : -1e30f;
;     } else {
; #pragma unroll
;         for (int T = 0; T < 2; ++T)
; #pragma unroll
;             for (int r = 0; r < 4; ++r) { const int p = pos0 + 16 * T + 4 * kq + r; const bool v = (p >= lo) & (p <= hi); const float x = sa[T][r];
;                 sc[4 * T + r] = x; vd[4 * T + r] = v; mx = v ? fmaxf(mx, x) : mx; }
;     }
;     if (__builtin_amdgcn_ballot_w64(mx > st.m + 4.f) != 0ull) {
;         mx = fmaxf(mx, __shfl_xor(mx, 16)); mx = fmaxf(mx, __shfl_xor(mx, 32));
;         const float mn = fmaxf(st.m, mx), alpha = __builtin_amdgcn_exp2f(st.m - mn); st.m = mn; st.l *= alpha;
; #pragma unroll
;         for (int j = 0; j < 8; ++j) st.o[j] = st.o[j] * alpha;
;     }
;     f32x4 pa, pb; float ps = 0.f;
;     const float mref = st.m - 4.f;
;     if (NOMASK) {
; #pragma unroll
;         for (int j = 0; j < 4; ++j) { pa[j] = __builtin_amdgcn_exp2f(sc[j] - mref); pb[j] = __builtin_amdgcn_exp2f(sc[4 + j] - mref); }
;         if (SLC) {
; #pragma unroll
;             for (int j = 0; j < 4; ++j) { pa[j] = act ? pa[j] : 0.f; pb[j] = act ? pb[j] : 0.f; }
;         }
; #pragma unroll
;         for (int j = 0; j < 4; ++j) ps += pa[j] + pb[j];
;     } else {
; #pragma unroll
;         for (int j = 0; j < 4; ++j) { pa[j] = vd[j] ? __builtin_amdgcn_exp2f(sc[j] - mref) : 0.f; pb[j] = vd[4 + j] ? __builtin_amdgcn_exp2f(sc[4 + j] - mref) : 0.f; ps += pa[j] + pb[j]; }
;     }
;     st.l += ps;
;     const u32x2 pw = pack8_fp8(pa, pb);
;     const i64_t pf = __builtin_bit_cast(i64_t, pw);
; #pragma unroll
;     for (int db = 0; db < 8; ++db) st.o[db] = __builtin_amdgcn_mfma_f32_16x16x32_fp8_fp8(cur.v[db], pf, st.o[db], 0, 0, 0);
.LBB0_1009:
	global_load_dwordx2 v[148:149], v[204:205], off
	global_load_dwordx2 v[152:153], v[204:205], off offset:512
	global_load_dwordx2 v[150:151], v[204:205], off offset:1024
	global_load_dwordx2 v[144:145], v[204:205], off offset:1536
	global_load_dwordx2 v[146:147], v[204:205], off offset:2048
	global_load_dwordx2 v[142:143], v[204:205], off offset:2560
	global_load_dwordx2 v[140:141], v[204:205], off offset:3072
	global_load_dwordx2 v[138:139], v[204:205], off offset:3584
	global_load_dwordx2 v[90:91], v[202:203], off
	global_load_dwordx2 v[92:93], v[202:203], off offset:512
	global_load_dwordx2 v[94:95], v[202:203], off offset:1024
	global_load_dwordx2 v[96:97], v[202:203], off offset:1536
	global_load_dwordx2 v[104:105], v[202:203], off offset:2048
	global_load_dwordx2 v[102:103], v[202:203], off offset:2560
	global_load_dwordx2 v[100:101], v[202:203], off offset:3072
	global_load_dwordx2 v[98:99], v[202:203], off offset:3584
	s_waitcnt vmcnt(47)
	v_mfma_f32_16x16x32_fp8_fp8 v[36:39], v[166:167], v[78:79], 0
	v_mov_b64_e32 v[74:75], v[4:5]
	v_mov_b64_e32 v[70:71], v[32:33]
	v_mov_b64_e32 v[66:67], v[28:29]
	s_waitcnt vmcnt(43)
	v_mfma_f32_16x16x32_fp8_fp8 v[40:43], v[160:161], v[78:79], 0
	v_mov_b64_e32 v[62:63], v[24:25]
	v_mov_b64_e32 v[58:59], v[20:21]
	v_mov_b64_e32 v[54:55], v[16:17]
	v_mfma_f32_16x16x32_fp8_fp8 v[36:39], v[168:169], v[80:81], v[36:39]
	v_mov_b64_e32 v[50:51], v[12:13]
	v_mov_b32_e32 v227, v228
	v_mov_b64_e32 v[72:73], v[2:3]
	s_waitcnt vmcnt(42)
	v_mfma_f32_16x16x32_fp8_fp8 v[40:43], v[158:159], v[80:81], v[40:43]
	v_mov_b64_e32 v[68:69], v[30:31]
	v_mov_b64_e32 v[64:65], v[26:27]
	v_mov_b64_e32 v[60:61], v[22:23]
	v_mfma_f32_16x16x32_fp8_fp8 v[36:39], v[164:165], v[82:83], v[36:39]
	v_mov_b64_e32 v[56:57], v[18:19]
	v_mov_b64_e32 v[52:53], v[14:15]
	v_mov_b64_e32 v[48:49], v[10:11]
	s_waitcnt vmcnt(41)
	v_mfma_f32_16x16x32_fp8_fp8 v[40:43], v[156:157], v[82:83], v[40:43]
	v_mov_b32_e32 v229, v34
	v_mfma_f32_16x16x32_fp8_fp8 v[36:39], v[162:163], v[84:85], v[36:39]
	s_waitcnt vmcnt(40)
	v_mfma_f32_16x16x32_fp8_fp8 v[40:43], v[154:155], v[84:85], v[40:43]
	s_nop 5
	v_max_f32_e32 v0, v37, v37
	v_max_f32_e32 v44, v36, v36
	v_max_f32_e32 v0, v44, v0
	v_max_f32_e32 v44, v39, v39
	v_max_f32_e32 v45, v38, v38
	v_max_f32_e32 v44, v45, v44
	v_max_f32_e32 v45, v43, v43
	v_max_f32_e32 v46, v42, v42
	v_max_f32_e32 v45, v46, v45
	v_max3_f32 v45, v40, v41, v45
	v_max3_f32 v0, v0, v44, v45
	v_mov_b64_e32 v[46:47], v[8:9]
	v_cmp_gt_f32_e32 vcc, v0, v133
	v_mov_b64_e32 v[44:45], v[6:7]
	s_cbranch_vccz .LBB0_1011
	ds_bpermute_b32 v44, v225, v0
	v_max_f32_e32 v0, v0, v0
	s_waitcnt lgkmcnt(0)
	v_max_f32_e32 v44, v44, v44
	v_max_f32_e32 v0, v0, v44
	ds_bpermute_b32 v44, v224, v0
	s_waitcnt lgkmcnt(0)
	v_max3_f32 v227, v228, v0, v44
	v_sub_f32_e32 v0, v228, v227
	v_exp_f32_e32 v0, v0
	s_nop 0
	v_mul_f32_e32 v229, v34, v0
	v_pk_mul_f32 v[46:47], v[8:9], v[0:1] op_sel_hi:[1,0]
	v_pk_mul_f32 v[44:45], v[6:7], v[0:1] op_sel_hi:[1,0]
	v_pk_mul_f32 v[50:51], v[12:13], v[0:1] op_sel_hi:[1,0]
	v_pk_mul_f32 v[48:49], v[10:11], v[0:1] op_sel_hi:[1,0]
	v_pk_mul_f32 v[54:55], v[16:17], v[0:1] op_sel_hi:[1,0]
	v_pk_mul_f32 v[52:53], v[14:15], v[0:1] op_sel_hi:[1,0]
	v_pk_mul_f32 v[58:59], v[20:21], v[0:1] op_sel_hi:[1,0]
	v_pk_mul_f32 v[56:57], v[18:19], v[0:1] op_sel_hi:[1,0]
	v_pk_mul_f32 v[62:63], v[24:25], v[0:1] op_sel_hi:[1,0]
	v_pk_mul_f32 v[60:61], v[22:23], v[0:1] op_sel_hi:[1,0]
	v_pk_mul_f32 v[66:67], v[28:29], v[0:1] op_sel_hi:[1,0]
	v_pk_mul_f32 v[64:65], v[26:27], v[0:1] op_sel_hi:[1,0]
	v_pk_mul_f32 v[70:71], v[32:33], v[0:1] op_sel_hi:[1,0]
	v_pk_mul_f32 v[68:69], v[30:31], v[0:1] op_sel_hi:[1,0]
	v_pk_mul_f32 v[74:75], v[4:5], v[0:1] op_sel_hi:[1,0]
	v_pk_mul_f32 v[72:73], v[2:3], v[0:1] op_sel_hi:[1,0]
.LBB0_1011:
	v_add_f32_e32 v231, -4.0, v227
	v_sub_f32_e32 v0, v36, v231
	v_exp_f32_e32 v233, v0
	v_sub_f32_e32 v0, v40, v231
	v_exp_f32_e32 v235, v0
	v_sub_f32_e32 v0, v37, v231
	v_exp_f32_e32 v230, v0
	v_sub_f32_e32 v0, v41, v231
	v_exp_f32_e32 v0, v0
	v_sub_f32_e32 v36, v38, v231
	v_exp_f32_e32 v238, v36
	v_sub_f32_e32 v36, v42, v231
	v_exp_f32_e32 v239, v36
	v_sub_f32_e32 v36, v39, v231
	v_exp_f32_e32 v232, v36
	v_sub_f32_e32 v36, v43, v231
	v_mov_b32_e32 v236, v1
	v_mov_b32_e32 v237, v1
	v_exp_f32_e32 v234, v36
	v_cvt_pk_fp8_f32 v236, v233, v230
	v_cvt_pk_fp8_f32 v237, v235, v0
	v_add_f32_e32 v231, v233, v235
	v_add_f32_e32 v233, v238, v239
	v_cvt_pk_fp8_f32 v236, v238, v232 op_sel:[0,0,1]
	v_cvt_pk_fp8_f32 v237, v239, v234 op_sel:[0,0,1]
	s_waitcnt vmcnt(39)
	s_nop 0
	v_mfma_f32_16x16x32_fp8_fp8 v[36:39], v[106:107], v[236:237], v[44:47]
	s_waitcnt vmcnt(37)
	v_mfma_f32_16x16x32_fp8_fp8 v[44:47], v[112:113], v[236:237], v[52:55]
	s_waitcnt vmcnt(35)
	v_mfma_f32_16x16x32_fp8_fp8 v[52:55], v[136:137], v[236:237], v[60:63]
	s_nop 2
	v_add_f32_e64 v60, v230, v0
	v_add_f32_e64 v61, v231, v1
	v_mfma_f32_16x16x32_fp8_fp8 v[40:43], v[110:111], v[236:237], v[48:51]
	v_pk_add_f32 v[60:61], v[60:61], v[60:61] op_sel_hi:[0,1]
	v_mov_b32_e32 v235, v61
	v_mfma_f32_16x16x32_fp8_fp8 v[48:51], v[116:117], v[236:237], v[56:59]
	s_waitcnt vmcnt(34)
	v_mfma_f32_16x16x32_fp8_fp8 v[56:59], v[134:135], v[236:237], v[64:67]
	s_nop 2
	v_add_f32_e64 v64, v232, v234
	v_add_f32_e64 v65, v233, v235
	s_waitcnt vmcnt(33)
	v_mfma_f32_16x16x32_fp8_fp8 v[60:63], v[114:115], v[236:237], v[68:71]
	v_add_f32_e32 v0, v64, v65
	v_add_f32_e32 v229, v0, v229
	s_waitcnt vmcnt(32)
	v_mfma_f32_16x16x32_fp8_fp8 v[64:67], v[108:109], v[236:237], v[72:75]
	s_branch .LBB0_1001
; template <bool SLC, bool NOMASK> ...
;     ...
;     load_frag8(nxt, KF, VF, SLC ? (dnext & 0xfffff) : dnext, lane);
;     f32x4 sa[2] = {(f32x4){0.f, 0.f, 0.f, 0.f}, (f32x4){0.f, 0.f, 0.f, 0.f}};
; #pragma unroll
;     for (int T = 0; T < 2; ++T)
; #pragma unroll
;         for (int s2 = 0; s2 < 4; ++s2) sa[T] = __builtin_amdgcn_mfma_f32_16x16x32_fp8_fp8(cur.k[T][s2], qf[s2], sa[T], 0, 0, 0);
;     float sc[8]; bool vd[8]; float mx = -1e30f;
;     const bool act = lo == 0 || !SLC;
;     if (NOMASK) {
; #pragma unroll
;         for (int j = 0; j < 8; ++j) { sc[j] = sa[j >> 2][j & 3]; vd[j] = act; }
;         mx = fmaxf(fmaxf(fmaxf(sc[0], sc[1]), fmaxf(sc[2], sc[3])), fmaxf(fmaxf(sc[4], sc[5]), fmaxf(sc[6], sc[7])));
;         mx = act ? mx : -1e30f;
;     } else {
; #pragma unroll
;         for (int T = 0; T < 2; ++T)
; #pragma unroll
;             for (int r = 0; r < 4; ++r) { const int p = pos0 + 16 * T + 4 * kq + r; const bool v = (p >= lo) & (p <= hi); const float x = sa[T][r];
;                 sc[4 * T + r] = x; vd[4 * T + r] = v; mx = v ? fmaxf(mx, x) : mx; }
;     }
;     if (__builtin_amdgcn_ballot_w64(mx > st.m + 4.f) != 0ull) {
;         mx = fmaxf(mx, __shfl_xor(mx, 16)); mx = fmaxf(mx, __shfl_xor(mx, 32));
;         const float mn = fmaxf(st.m, mx), alpha = __builtin_amdgcn_exp2f(st.m - mn); st.m = mn; st.l *= alpha;
; #pragma unroll
;         for (int j = 0; j < 8; ++j) st.o[j] = st.o[j] * alpha;
;     }
.LBB0_1012:
	global_load_dwordx2 v[148:149], v[204:205], off
	global_load_dwordx2 v[152:153], v[204:205], off offset:512
	global_load_dwordx2 v[150:151], v[204:205], off offset:1024
	global_load_dwordx2 v[144:145], v[204:205], off offset:1536
	global_load_dwordx2 v[146:147], v[204:205], off offset:2048
	global_load_dwordx2 v[142:143], v[204:205], off offset:2560
	global_load_dwordx2 v[140:141], v[204:205], off offset:3072
	global_load_dwordx2 v[138:139], v[204:205], off offset:3584
	global_load_dwordx2 v[90:91], v[202:203], off
	global_load_dwordx2 v[92:93], v[202:203], off offset:512
	global_load_dwordx2 v[94:95], v[202:203], off offset:1024
	global_load_dwordx2 v[96:97], v[202:203], off offset:1536
	global_load_dwordx2 v[104:105], v[202:203], off offset:2048
	global_load_dwordx2 v[102:103], v[202:203], off offset:2560
	global_load_dwordx2 v[100:101], v[202:203], off offset:3072
	global_load_dwordx2 v[98:99], v[202:203], off offset:3584
	s_waitcnt vmcnt(47)
	v_mfma_f32_16x16x32_fp8_fp8 v[36:39], v[166:167], v[78:79], 0
	v_add_u32_e32 v0, s66, v210
	v_cmp_ge_i32_e32 vcc, v0, v35
	v_cmp_le_i32_e64 s[10:11], v0, v132
	s_waitcnt vmcnt(46)
	v_mfma_f32_16x16x32_fp8_fp8 v[36:39], v[168:169], v[80:81], v[36:39]
	s_and_b64 s[16:17], vcc, s[10:11]
	v_add_u32_e32 v45, 1, v0
	v_cmp_ge_i32_e32 vcc, v45, v35
	s_waitcnt vmcnt(45)
	v_mfma_f32_16x16x32_fp8_fp8 v[36:39], v[164:165], v[82:83], v[36:39]
	v_cmp_lt_i32_e64 s[10:11], v0, v132
	s_and_b64 s[12:13], s[10:11], vcc
	s_waitcnt vmcnt(43)
	v_mfma_f32_16x16x32_fp8_fp8 v[40:43], v[160:161], v[78:79], 0
	v_mfma_f32_16x16x32_fp8_fp8 v[36:39], v[162:163], v[84:85], v[36:39]
	s_waitcnt vmcnt(42)
	v_mfma_f32_16x16x32_fp8_fp8 v[40:43], v[158:159], v[80:81], v[40:43]
	s_waitcnt vmcnt(41)
	v_mfma_f32_16x16x32_fp8_fp8 v[40:43], v[156:157], v[82:83], v[40:43]
	s_nop 3
	v_max_f32_e32 v44, v36, v36
	v_max_f32_e32 v44, 0xf149f2ca, v44
	v_cndmask_b32_e64 v44, v220, v44, s[16:17]
	v_max_f32_e32 v45, v37, v37
	v_max_f32_e32 v45, v44, v45
	v_cndmask_b32_e64 v44, v44, v45, s[12:13]
	v_add_u32_e32 v45, 2, v0
	v_cmp_ge_i32_e32 vcc, v45, v35
	v_cmp_le_i32_e64 s[10:11], v45, v132
	v_max_f32_e32 v45, v38, v38
	v_max_f32_e32 v45, v44, v45
	s_and_b64 s[14:15], vcc, s[10:11]
	s_waitcnt vmcnt(40)
	v_mfma_f32_16x16x32_fp8_fp8 v[40:43], v[154:155], v[84:85], v[40:43]
	v_cndmask_b32_e64 v44, v44, v45, s[14:15]
	v_add_u32_e32 v45, 3, v0
	v_cmp_ge_i32_e32 vcc, v45, v35
	v_cmp_le_i32_e64 s[10:11], v45, v132
	v_max_f32_e32 v45, v39, v39
	v_max_f32_e32 v45, v44, v45
	s_and_b64 s[10:11], vcc, s[10:11]
	v_cndmask_b32_e64 v44, v44, v45, s[10:11]
	v_add_u32_e32 v45, 16, v0
	v_cmp_ge_i32_e32 vcc, v45, v35
	v_cmp_le_i32_e64 s[18:19], v45, v132
	v_max_f32_e32 v45, v40, v40
	v_max_f32_e32 v45, v44, v45
	s_and_b64 s[24:25], vcc, s[18:19]
	v_cndmask_b32_e64 v44, v44, v45, s[24:25]
	v_add_u32_e32 v45, 17, v0
	v_cmp_ge_i32_e32 vcc, v45, v35
	v_cmp_le_i32_e64 s[18:19], v45, v132
	v_max_f32_e32 v45, v44, v44
	v_max_f32_e32 v46, v41, v41
	v_max_f32_e32 v45, v45, v46
	s_and_b64 s[20:21], vcc, s[18:19]
	v_cndmask_b32_e64 v44, v44, v45, s[20:21]
	v_add_u32_e32 v45, 18, v0
	v_cmp_ge_i32_e32 vcc, v45, v35
	v_cmp_le_i32_e64 s[18:19], v45, v132
	v_max_f32_e32 v45, v44, v44
	v_max_f32_e32 v46, v42, v42
	v_max_f32_e32 v45, v45, v46
	s_and_b64 s[22:23], vcc, s[18:19]
	v_cndmask_b32_e64 v44, v44, v45, s[22:23]
	v_add_u32_e32 v0, 19, v0
	v_cmp_ge_i32_e32 vcc, v0, v35
	v_cmp_le_i32_e64 s[18:19], v0, v132
	v_max_f32_e32 v0, v44, v44
	v_max_f32_e32 v45, v43, v43
	v_max_f32_e32 v0, v0, v45
	s_and_b64 s[18:19], vcc, s[18:19]
	v_cndmask_b32_e64 v0, v44, v0, s[18:19]
	v_cmp_gt_f32_e32 vcc, v0, v133
	s_cbranch_vccz .LBB0_1014
	ds_bpermute_b32 v44, v225, v0
	v_max_f32_e32 v0, v0, v0
	s_waitcnt lgkmcnt(0)
	v_max_f32_e32 v44, v44, v44
	v_max_f32_e32 v0, v0, v44
	ds_bpermute_b32 v44, v224, v0
	s_waitcnt lgkmcnt(0)
	v_max3_f32 v44, v228, v0, v44
	v_sub_f32_e32 v0, v228, v44
	v_exp_f32_e32 v0, v0
	v_mov_b32_e32 v228, v44
	v_mul_f32_e32 v34, v34, v0
	v_pk_mul_f32 v[8:9], v[8:9], v[0:1] op_sel_hi:[1,0]
	v_pk_mul_f32 v[6:7], v[6:7], v[0:1] op_sel_hi:[1,0]
	v_pk_mul_f32 v[12:13], v[12:13], v[0:1] op_sel_hi:[1,0]
	v_pk_mul_f32 v[10:11], v[10:11], v[0:1] op_sel_hi:[1,0]
	v_pk_mul_f32 v[16:17], v[16:17], v[0:1] op_sel_hi:[1,0]
	v_pk_mul_f32 v[14:15], v[14:15], v[0:1] op_sel_hi:[1,0]
	v_pk_mul_f32 v[20:21], v[20:21], v[0:1] op_sel_hi:[1,0]
	v_pk_mul_f32 v[18:19], v[18:19], v[0:1] op_sel_hi:[1,0]
	v_pk_mul_f32 v[24:25], v[24:25], v[0:1] op_sel_hi:[1,0]
	v_pk_mul_f32 v[22:23], v[22:23], v[0:1] op_sel_hi:[1,0]
	v_pk_mul_f32 v[28:29], v[28:29], v[0:1] op_sel_hi:[1,0]
	v_pk_mul_f32 v[26:27], v[26:27], v[0:1] op_sel_hi:[1,0]
	v_pk_mul_f32 v[32:33], v[32:33], v[0:1] op_sel_hi:[1,0]
	v_pk_mul_f32 v[30:31], v[30:31], v[0:1] op_sel_hi:[1,0]
	v_pk_mul_f32 v[4:5], v[4:5], v[0:1] op_sel_hi:[1,0]
	v_pk_mul_f32 v[2:3], v[2:3], v[0:1] op_sel_hi:[1,0]
; #define F8_STEP(CUR, NXT2, DC, DN2) do { \
;         if ((DC) & (1 << 30)) step_frag8<SLC, true>(qf, CUR, NXT2, KF, VF, (DC) & NM, (DN2) & NM, lo_in, hi, qi, st, lane); \
;         else step_frag8<SLC, false>(qf, CUR, NXT2, KF, VF, (DC), (DN2) & NM, lo_in, hi, qi, st, lane); } while (0)
; template <bool SLC, bool NOMASK> ...
;     ...
;     f32x4 pa, pb; float ps = 0.f;
;     const float mref = st.m - 4.f;
;     if (NOMASK) {
; #pragma unroll
;         for (int j = 0; j < 4; ++j) { pa[j] = __builtin_amdgcn_exp2f(sc[j] - mref); pb[j] = __builtin_amdgcn_exp2f(sc[4 + j] - mref); }
;         if (SLC) {
; #pragma unroll
;             for (int j = 0; j < 4; ++j) { pa[j] = act ? pa[j] : 0.f; pb[j] = act ? pb[j] : 0.f; }
;         }
; #pragma unroll
;         for (int j = 0; j < 4; ++j) ps += pa[j] + pb[j];
;     } else {
; #pragma unroll
;         for (int j = 0; j < 4; ++j) { pa[j] = vd[j] ? __builtin_amdgcn_exp2f(sc[j] - mref) : 0.f; pb[j] = vd[4 + j] ? __builtin_amdgcn_exp2f(sc[4 + j] - mref) : 0.f; ps += pa[j] + pb[j]; }
;     }
;     st.l += ps;
;     const u32x2 pw = pack8_fp8(pa, pb);
;     const i64_t pf = __builtin_bit_cast(i64_t, pw);
; #pragma unroll
;     for (int db = 0; db < 8; ++db) st.o[db] = __builtin_amdgcn_mfma_f32_16x16x32_fp8_fp8(cur.v[db], pf, st.o[db], 0, 0, 0);
; template <bool SLC, class Desc>
; __device__ __forceinline__ void attn_run_frag8(const i64_t (&qf)[4], const unsigned char* __restrict__ KF, const unsigned char* __restrict__ VF, const Desc& desc, int n,
;                                                int lo_in, int hi, int qi, AState& st, int lane) {
;     ...
;     for (int i = 0; i < n; i += 3) {
;         const int d2 = desc(i + 2 < n ? i + 2 : n - 1);
;         F8_STEP(fa, fc, d0, d2);
;         if (i + 1 >= n) break;
;         const int d3 = desc(i + 3 < n ? i + 3 : n - 1);
;         F8_STEP(fb, fa, d1, d3);
;         if (i + 2 >= n) break;
;         const int d4 = desc(i + 4 < n ? i + 4 : n - 1);
;         F8_STEP(fc, fb, d2, d4);
.LBB0_1014:
	v_add_f32_e32 v0, -4.0, v228
	v_sub_f32_e32 v36, v36, v0
	v_exp_f32_e32 v36, v36
	v_sub_f32_e32 v40, v40, v0
	v_exp_f32_e32 v40, v40
	v_sub_f32_e32 v38, v38, v0
	v_cndmask_b32_e64 v56, 0, v36, s[16:17]
	v_sub_f32_e32 v36, v37, v0
	v_exp_f32_e32 v36, v36
	v_sub_f32_e32 v37, v41, v0
	v_exp_f32_e32 v37, v37
	v_cndmask_b32_e64 v57, 0, v40, s[24:25]
	v_sub_f32_e32 v40, v42, v0
	v_cndmask_b32_e64 v58, 0, v36, s[12:13]
	v_sub_f32_e32 v36, v39, v0
	v_sub_f32_e32 v0, v43, v0
	v_exp_f32_e32 v38, v38
	v_exp_f32_e32 v40, v40
	v_cndmask_b32_e64 v59, 0, v37, s[20:21]
	v_exp_f32_e32 v36, v36
	v_exp_f32_e32 v0, v0
	v_mov_b32_e32 v64, v1
	v_mov_b32_e32 v65, v1
	v_cvt_pk_fp8_f32 v64, v56, v58
	v_cvt_pk_fp8_f32 v65, v57, v59
	v_cndmask_b32_e64 v60, 0, v38, s[14:15]
	v_cndmask_b32_e64 v61, 0, v40, s[22:23]
	v_cndmask_b32_e64 v66, 0, v36, s[10:11]
	v_cndmask_b32_e64 v0, 0, v0, s[18:19]
	v_cvt_pk_fp8_f32 v64, v60, v66 op_sel:[0,0,1]
	v_cvt_pk_fp8_f32 v65, v61, v0 op_sel:[0,0,1]
	v_add_f32_e32 v0, v66, v0
	v_mov_b32_e32 v227, v228
	s_waitcnt vmcnt(39)
	v_mfma_f32_16x16x32_fp8_fp8 v[36:39], v[106:107], v[64:65], v[6:9]
	s_nop 2
	v_add_f32_e32 v6, v56, v57
	v_add_f32_e32 v6, 0, v6
	v_add_f32_e32 v7, v58, v59
	s_waitcnt vmcnt(38)
	v_mfma_f32_16x16x32_fp8_fp8 v[40:43], v[110:111], v[64:65], v[10:13]
	v_add_f32_e32 v6, v7, v6
	v_add_f32_e32 v7, v60, v61
	v_add_f32_e32 v6, v7, v6
	s_waitcnt vmcnt(37)
	v_mfma_f32_16x16x32_fp8_fp8 v[44:47], v[112:113], v[64:65], v[14:17]
	v_add_f32_e32 v0, v0, v6
	v_add_f32_e32 v229, v34, v0
	s_waitcnt vmcnt(36)
	v_mfma_f32_16x16x32_fp8_fp8 v[48:51], v[116:117], v[64:65], v[18:21]
	s_waitcnt vmcnt(35)
	v_mfma_f32_16x16x32_fp8_fp8 v[52:55], v[136:137], v[64:65], v[22:25]
	s_waitcnt vmcnt(34)
	v_mfma_f32_16x16x32_fp8_fp8 v[56:59], v[134:135], v[64:65], v[26:29]
	s_waitcnt vmcnt(33)
	v_mfma_f32_16x16x32_fp8_fp8 v[60:63], v[114:115], v[64:65], v[30:33]
	s_waitcnt vmcnt(32)
	v_mfma_f32_16x16x32_fp8_fp8 v[64:67], v[108:109], v[64:65], v[2:5]
	s_cmp_gt_i32 s55, s27
	s_mov_b64 s[10:11], -1
	s_cbranch_scc1 .LBB0_994
.LBB0_1015:
	s_cmp_lt_i32 s57, s54
	s_cselect_b64 s[10:11], -1, 0
	s_or_b32 s12, s57, 31
	s_cmp_gt_i32 s12, s90
	s_cselect_b64 s[12:13], -1, 0
	s_or_b64 s[10:11], s[10:11], s[12:13]
	s_and_b64 s[10:11], s[10:11], exec
	s_cselect_b32 s10, 0, 2.0
	s_add_i32 s56, s56, 4
	s_or_b32 s14, s10, s57
	s_min_i32 s10, s56, s27
	s_add_i32 s12, s10, s26
	s_lshl_b32 s43, s12, 5
	s_and_b32 s10, s43, 0x3fffffe0
	s_lshr_b32 s50, s10, 4
	s_lshl_b64 s[10:11], s[50:51], 11
	s_and_b32 s50, s12, 0x1ffffff
	s_lshl_b64 s[12:13], s[50:51], 12
	s_cmp_lt_u32 s14, 2.0
	v_lshl_add_u64 v[204:205], v[86:87], 0, s[10:11]
	v_lshl_add_u64 v[202:203], v[88:89], 0, s[12:13]
	s_mov_b64 s[10:11], -1
	v_add_f32_e32 v228, 4.0, v227
	s_cbranch_scc1 .LBB0_1019
	global_load_dwordx2 v[166:167], v[204:205], off
	global_load_dwordx2 v[168:169], v[204:205], off offset:512
	global_load_dwordx2 v[164:165], v[204:205], off offset:1024
	global_load_dwordx2 v[162:163], v[204:205], off offset:1536
	global_load_dwordx2 v[160:161], v[204:205], off offset:2048
	global_load_dwordx2 v[158:159], v[204:205], off offset:2560
	global_load_dwordx2 v[156:157], v[204:205], off offset:3072
	global_load_dwordx2 v[154:155], v[204:205], off offset:3584
	global_load_dwordx2 v[106:107], v[202:203], off
	global_load_dwordx2 v[110:111], v[202:203], off offset:512
	global_load_dwordx2 v[112:113], v[202:203], off offset:1024
	global_load_dwordx2 v[116:117], v[202:203], off offset:1536
	global_load_dwordx2 v[136:137], v[202:203], off offset:2048
	global_load_dwordx2 v[134:135], v[202:203], off offset:2560
	global_load_dwordx2 v[114:115], v[202:203], off offset:3072
	global_load_dwordx2 v[108:109], v[202:203], off offset:3584
	s_waitcnt vmcnt(47)
	v_mfma_f32_16x16x32_fp8_fp8 v[2:5], v[196:197], v[78:79], 0
	v_mov_b64_e32 v[74:75], v[66:67]
	v_mov_b64_e32 v[70:71], v[62:63]
	v_mov_b64_e32 v[30:31], v[56:57]
	s_waitcnt vmcnt(43)
	v_mfma_f32_16x16x32_fp8_fp8 v[6:9], v[194:195], v[78:79], 0
	v_mov_b64_e32 v[26:27], v[52:53]
	v_mov_b64_e32 v[22:23], v[48:49]
	v_mov_b64_e32 v[18:19], v[44:45]
	v_mfma_f32_16x16x32_fp8_fp8 v[2:5], v[200:201], v[80:81], v[2:5]
	v_mov_b64_e32 v[14:15], v[40:41]
	v_mov_b32_e32 v133, v227
	v_mov_b64_e32 v[72:73], v[64:65]
	s_waitcnt vmcnt(42)
	v_mfma_f32_16x16x32_fp8_fp8 v[6:9], v[190:191], v[80:81], v[6:9]
	v_mov_b64_e32 v[68:69], v[60:61]
	v_mov_b64_e32 v[32:33], v[58:59]
	v_mov_b64_e32 v[28:29], v[54:55]
	v_mfma_f32_16x16x32_fp8_fp8 v[2:5], v[198:199], v[82:83], v[2:5]
	v_mov_b64_e32 v[24:25], v[50:51]
	v_mov_b64_e32 v[20:21], v[46:47]
	v_mov_b64_e32 v[16:17], v[42:43]
	s_waitcnt vmcnt(41)
	v_mfma_f32_16x16x32_fp8_fp8 v[6:9], v[188:189], v[82:83], v[6:9]
	v_mov_b32_e32 v34, v229
	v_mfma_f32_16x16x32_fp8_fp8 v[2:5], v[192:193], v[84:85], v[2:5]
	s_waitcnt vmcnt(40)
	v_mfma_f32_16x16x32_fp8_fp8 v[6:9], v[186:187], v[84:85], v[6:9]
	s_nop 5
	v_max_f32_e32 v0, v3, v3
	v_max_f32_e32 v10, v2, v2
	v_max_f32_e32 v0, v10, v0
	v_max_f32_e32 v10, v5, v5
	v_max_f32_e32 v11, v4, v4
	v_max_f32_e32 v10, v11, v10
	v_max_f32_e32 v11, v9, v9
	v_max_f32_e32 v12, v8, v8
	v_max_f32_e32 v11, v12, v11
	v_max3_f32 v11, v6, v7, v11
	v_max3_f32 v0, v0, v10, v11
	v_mov_b64_e32 v[10:11], v[36:37]
	v_cmp_gt_f32_e32 vcc, v0, v228
	v_mov_b64_e32 v[12:13], v[38:39]
	s_cbranch_vccz .LBB0_1018
	ds_bpermute_b32 v10, v225, v0
	v_max_f32_e32 v0, v0, v0
	s_waitcnt lgkmcnt(0)
	v_max_f32_e32 v10, v10, v10
	v_max_f32_e32 v0, v0, v10
	ds_bpermute_b32 v10, v224, v0
	s_waitcnt lgkmcnt(0)
	v_max3_f32 v133, v227, v0, v10
	v_sub_f32_e32 v0, v227, v133
	v_exp_f32_e32 v0, v0
	s_nop 0
	v_mul_f32_e32 v34, v229, v0
	v_pk_mul_f32 v[12:13], v[38:39], v[0:1] op_sel_hi:[1,0]
	v_pk_mul_f32 v[10:11], v[36:37], v[0:1] op_sel_hi:[1,0]
	v_pk_mul_f32 v[16:17], v[42:43], v[0:1] op_sel_hi:[1,0]
	v_pk_mul_f32 v[14:15], v[40:41], v[0:1] op_sel_hi:[1,0]
	v_pk_mul_f32 v[20:21], v[46:47], v[0:1] op_sel_hi:[1,0]
	v_pk_mul_f32 v[18:19], v[44:45], v[0:1] op_sel_hi:[1,0]
	v_pk_mul_f32 v[24:25], v[50:51], v[0:1] op_sel_hi:[1,0]
	v_pk_mul_f32 v[22:23], v[48:49], v[0:1] op_sel_hi:[1,0]
	v_pk_mul_f32 v[28:29], v[54:55], v[0:1] op_sel_hi:[1,0]
	v_pk_mul_f32 v[26:27], v[52:53], v[0:1] op_sel_hi:[1,0]
	v_pk_mul_f32 v[32:33], v[58:59], v[0:1] op_sel_hi:[1,0]
	v_pk_mul_f32 v[30:31], v[56:57], v[0:1] op_sel_hi:[1,0]
	v_pk_mul_f32 v[70:71], v[62:63], v[0:1] op_sel_hi:[1,0]
	v_pk_mul_f32 v[68:69], v[60:61], v[0:1] op_sel_hi:[1,0]
	v_pk_mul_f32 v[74:75], v[66:67], v[0:1] op_sel_hi:[1,0]
	v_pk_mul_f32 v[72:73], v[64:65], v[0:1] op_sel_hi:[1,0]
; template <bool SLC, bool NOMASK> ...
;     ...
;     f32x4 sa[2] = {(f32x4){0.f, 0.f, 0.f, 0.f}, (f32x4){0.f, 0.f, 0.f, 0.f}};
; #pragma unroll
;     for (int T = 0; T < 2; ++T)
; #pragma unroll
;         for (int s2 = 0; s2 < 4; ++s2) sa[T] = __builtin_amdgcn_mfma_f32_16x16x32_fp8_fp8(cur.k[T][s2], qf[s2], sa[T], 0, 0, 0);
;     float sc[8]; bool vd[8]; float mx = -1e30f;
;     const bool act = lo == 0 || !SLC;
;     if (NOMASK) {
; #pragma unroll
;         for (int j = 0; j < 8; ++j) { sc[j] = sa[j >> 2][j & 3]; vd[j] = act; }
;         mx = fmaxf(fmaxf(fmaxf(sc[0], sc[1]), fmaxf(sc[2], sc[3])), fmaxf(fmaxf(sc[4], sc[5]), fmaxf(sc[6], sc[7])));
;         mx = act ? mx : -1e30f;
;     } else {
; #pragma unroll
;         for (int T = 0; T < 2; ++T)
; #pragma unroll
;             for (int r = 0; r < 4; ++r) { const int p = pos0 + 16 * T + 4 * kq + r; const bool v = (p >= lo) & (p <= hi); const float x = sa[T][r];
;                 sc[4 * T + r] = x; vd[4 * T + r] = v; mx = v ? fmaxf(mx, x) : mx; }
;     }
;     if (__builtin_amdgcn_ballot_w64(mx > st.m + 4.f) != 0ull) {
;         mx = fmaxf(mx, __shfl_xor(mx, 16)); mx = fmaxf(mx, __shfl_xor(mx, 32));
;         const float mn = fmaxf(st.m, mx), alpha = __builtin_amdgcn_exp2f(st.m - mn); st.m = mn; st.l *= alpha;
; #pragma unroll
;         for (int j = 0; j < 8; ++j) st.o[j] = st.o[j] * alpha;
;     }
;     f32x4 pa, pb; float ps = 0.f;
;     const float mref = st.m - 4.f;
;     if (NOMASK) {
; #pragma unroll
;         for (int j = 0; j < 4; ++j) { pa[j] = __builtin_amdgcn_exp2f(sc[j] - mref); pb[j] = __builtin_amdgcn_exp2f(sc[4 + j] - mref); }
;         if (SLC) {
; #pragma unroll
;             for (int j = 0; j < 4; ++j) { pa[j] = act ? pa[j] : 0.f; pb[j] = act ? pb[j] : 0.f; }
;         }
; #pragma unroll
;         for (int j = 0; j < 4; ++j) ps += pa[j] + pb[j];
;     } else {
; #pragma unroll
;         for (int j = 0; j < 4; ++j) { pa[j] = vd[j] ? __builtin_amdgcn_exp2f(sc[j] - mref) : 0.f; pb[j] = vd[4 + j] ? __builtin_amdgcn_exp2f(sc[4 + j] - mref) : 0.f; ps += pa[j] + pb[j]; }
;     }
;     st.l += ps;
;     const u32x2 pw = pack8_fp8(pa, pb);
;     const i64_t pf = __builtin_bit_cast(i64_t, pw);
; #pragma unroll
;     for (int db = 0; db < 8; ++db) st.o[db] = __builtin_amdgcn_mfma_f32_16x16x32_fp8_fp8(cur.v[db], pf, st.o[db], 0, 0, 0);
.LBB0_1018:
	v_add_f32_e32 v230, -4.0, v133
	v_sub_f32_e32 v0, v2, v230
	v_exp_f32_e32 v231, v0
	v_sub_f32_e32 v0, v6, v230
	v_exp_f32_e32 v234, v0
	v_sub_f32_e32 v0, v3, v230
	v_exp_f32_e32 v2, v0
	v_sub_f32_e32 v0, v7, v230
	v_exp_f32_e32 v0, v0
	v_sub_f32_e32 v3, v4, v230
	v_exp_f32_e32 v235, v3
	v_sub_f32_e32 v3, v8, v230
	v_exp_f32_e32 v236, v3
	v_sub_f32_e32 v3, v5, v230
	v_exp_f32_e32 v4, v3
	v_sub_f32_e32 v3, v9, v230
	v_mov_b32_e32 v232, v1
	v_mov_b32_e32 v233, v1
	v_exp_f32_e32 v230, v3
	v_cvt_pk_fp8_f32 v232, v231, v2
	v_cvt_pk_fp8_f32 v233, v234, v0
	v_add_f32_e32 v3, v231, v234
	v_pk_add_f32 v[2:3], v[2:3], v[0:1]
	v_cvt_pk_fp8_f32 v232, v235, v4 op_sel:[0,0,1]
	v_cvt_pk_fp8_f32 v233, v236, v230 op_sel:[0,0,1]
	v_pk_add_f32 v[2:3], v[2:3], v[2:3] op_sel_hi:[0,1]
	v_add_f32_e32 v5, v235, v236
	v_mov_b32_e32 v231, v3
	v_pk_add_f32 v[2:3], v[4:5], v[230:231]
	s_waitcnt vmcnt(39)
	v_mfma_f32_16x16x32_fp8_fp8 v[6:9], v[170:171], v[232:233], v[10:13]
	v_add_f32_e32 v0, v2, v3
	v_add_f32_e32 v34, v0, v34
	s_mov_b64 s[10:11], 0
	s_waitcnt vmcnt(38)
	v_mfma_f32_16x16x32_fp8_fp8 v[10:13], v[172:173], v[232:233], v[14:17]
	s_waitcnt vmcnt(37)
	v_mfma_f32_16x16x32_fp8_fp8 v[14:17], v[174:175], v[232:233], v[18:21]
	s_waitcnt vmcnt(36)
	v_mfma_f32_16x16x32_fp8_fp8 v[18:21], v[176:177], v[232:233], v[22:25]
	s_waitcnt vmcnt(35)
	v_mfma_f32_16x16x32_fp8_fp8 v[22:25], v[184:185], v[232:233], v[26:29]
	s_waitcnt vmcnt(34)
	v_mfma_f32_16x16x32_fp8_fp8 v[26:29], v[182:183], v[232:233], v[30:33]
	s_waitcnt vmcnt(33)
	v_mfma_f32_16x16x32_fp8_fp8 v[30:33], v[180:181], v[232:233], v[68:71]
	s_waitcnt vmcnt(32)
	v_mfma_f32_16x16x32_fp8_fp8 v[2:5], v[178:179], v[232:233], v[72:75]
.LBB0_1019:
	s_and_b64 vcc, exec, s[10:11]
	s_cbranch_vccz .LBB0_1023
	global_load_dwordx2 v[166:167], v[204:205], off
	global_load_dwordx2 v[168:169], v[204:205], off offset:512
	global_load_dwordx2 v[164:165], v[204:205], off offset:1024
	global_load_dwordx2 v[162:163], v[204:205], off offset:1536
	global_load_dwordx2 v[160:161], v[204:205], off offset:2048
	global_load_dwordx2 v[158:159], v[204:205], off offset:2560
	global_load_dwordx2 v[156:157], v[204:205], off offset:3072
	global_load_dwordx2 v[154:155], v[204:205], off offset:3584
	global_load_dwordx2 v[106:107], v[202:203], off
	global_load_dwordx2 v[110:111], v[202:203], off offset:512
	global_load_dwordx2 v[112:113], v[202:203], off offset:1024
	global_load_dwordx2 v[116:117], v[202:203], off offset:1536
	global_load_dwordx2 v[136:137], v[202:203], off offset:2048
	global_load_dwordx2 v[134:135], v[202:203], off offset:2560
	global_load_dwordx2 v[114:115], v[202:203], off offset:3072
	global_load_dwordx2 v[108:109], v[202:203], off offset:3584
	s_waitcnt vmcnt(47)
	v_mfma_f32_16x16x32_fp8_fp8 v[2:5], v[196:197], v[78:79], 0
	v_or_b32_e32 v0, s57, v210
	v_cmp_ge_i32_e32 vcc, v0, v35
	v_cmp_le_i32_e64 s[10:11], v0, v132
	s_waitcnt vmcnt(46)
	v_mfma_f32_16x16x32_fp8_fp8 v[2:5], v[200:201], v[80:81], v[2:5]
	s_and_b64 s[16:17], vcc, s[10:11]
	v_or_b32_e32 v11, 1, v0
	v_cmp_ge_i32_e32 vcc, v11, v35
	s_waitcnt vmcnt(45)
	v_mfma_f32_16x16x32_fp8_fp8 v[2:5], v[198:199], v[82:83], v[2:5]
	v_cmp_lt_i32_e64 s[10:11], v0, v132
	s_and_b64 s[12:13], s[10:11], vcc
	s_waitcnt vmcnt(43)
	v_mfma_f32_16x16x32_fp8_fp8 v[6:9], v[194:195], v[78:79], 0
	v_mfma_f32_16x16x32_fp8_fp8 v[2:5], v[192:193], v[84:85], v[2:5]
	s_waitcnt vmcnt(42)
	v_mfma_f32_16x16x32_fp8_fp8 v[6:9], v[190:191], v[80:81], v[6:9]
	s_waitcnt vmcnt(41)
	v_mfma_f32_16x16x32_fp8_fp8 v[6:9], v[188:189], v[82:83], v[6:9]
	s_nop 3
	v_max_f32_e32 v10, v2, v2
	v_max_f32_e32 v10, 0xf149f2ca, v10
	v_cndmask_b32_e64 v10, v220, v10, s[16:17]
	v_max_f32_e32 v11, v3, v3
	v_max_f32_e32 v11, v10, v11
	v_cndmask_b32_e64 v10, v10, v11, s[12:13]
	v_or_b32_e32 v11, 2, v0
	v_cmp_ge_i32_e32 vcc, v11, v35
	v_cmp_le_i32_e64 s[10:11], v11, v132
	v_max_f32_e32 v11, v4, v4
	v_max_f32_e32 v11, v10, v11
	s_and_b64 s[14:15], vcc, s[10:11]
	s_waitcnt vmcnt(40)
	v_mfma_f32_16x16x32_fp8_fp8 v[6:9], v[186:187], v[84:85], v[6:9]
	v_cndmask_b32_e64 v10, v10, v11, s[14:15]
	v_or_b32_e32 v11, 3, v0
	v_cmp_ge_i32_e32 vcc, v11, v35
	v_cmp_le_i32_e64 s[10:11], v11, v132
	v_max_f32_e32 v11, v5, v5
	v_max_f32_e32 v11, v10, v11
	s_and_b64 s[10:11], vcc, s[10:11]
	v_cndmask_b32_e64 v10, v10, v11, s[10:11]
	v_or_b32_e32 v11, 16, v0
	v_cmp_ge_i32_e32 vcc, v11, v35
	v_cmp_le_i32_e64 s[18:19], v11, v132
	v_max_f32_e32 v11, v6, v6
	v_max_f32_e32 v11, v10, v11
	s_and_b64 s[24:25], vcc, s[18:19]
	v_cndmask_b32_e64 v10, v10, v11, s[24:25]
	v_or_b32_e32 v11, 17, v0
	v_cmp_ge_i32_e32 vcc, v11, v35
	v_cmp_le_i32_e64 s[18:19], v11, v132
	v_max_f32_e32 v11, v10, v10
	v_max_f32_e32 v12, v7, v7
	v_max_f32_e32 v11, v11, v12
	s_and_b64 s[20:21], vcc, s[18:19]
	v_cndmask_b32_e64 v10, v10, v11, s[20:21]
	v_or_b32_e32 v11, 18, v0
	v_cmp_ge_i32_e32 vcc, v11, v35
	v_cmp_le_i32_e64 s[18:19], v11, v132
	v_max_f32_e32 v11, v10, v10
	v_max_f32_e32 v12, v8, v8
	v_max_f32_e32 v11, v11, v12
	s_and_b64 s[22:23], vcc, s[18:19]
	v_cndmask_b32_e64 v10, v10, v11, s[22:23]
	v_or_b32_e32 v0, 19, v0
	v_cmp_ge_i32_e32 vcc, v0, v35
	v_cmp_le_i32_e64 s[18:19], v0, v132
	v_max_f32_e32 v0, v10, v10
	v_max_f32_e32 v11, v9, v9
	v_max_f32_e32 v0, v0, v11
	s_and_b64 s[18:19], vcc, s[18:19]
	v_cndmask_b32_e64 v0, v10, v0, s[18:19]
	v_cmp_gt_f32_e32 vcc, v0, v228
	s_cbranch_vccz .LBB0_1022
	ds_bpermute_b32 v10, v225, v0
	v_max_f32_e32 v0, v0, v0
	s_waitcnt lgkmcnt(0)
	v_max_f32_e32 v10, v10, v10
	v_max_f32_e32 v0, v0, v10
	ds_bpermute_b32 v10, v224, v0
	s_waitcnt lgkmcnt(0)
	v_max3_f32 v10, v227, v0, v10
	v_sub_f32_e32 v0, v227, v10
	v_exp_f32_e32 v0, v0
	v_mov_b32_e32 v227, v10
	v_mul_f32_e32 v229, v229, v0
	v_pk_mul_f32 v[38:39], v[38:39], v[0:1] op_sel_hi:[1,0]
	v_pk_mul_f32 v[36:37], v[36:37], v[0:1] op_sel_hi:[1,0]
	v_pk_mul_f32 v[42:43], v[42:43], v[0:1] op_sel_hi:[1,0]
	v_pk_mul_f32 v[40:41], v[40:41], v[0:1] op_sel_hi:[1,0]
	v_pk_mul_f32 v[46:47], v[46:47], v[0:1] op_sel_hi:[1,0]
	v_pk_mul_f32 v[44:45], v[44:45], v[0:1] op_sel_hi:[1,0]
	v_pk_mul_f32 v[50:51], v[50:51], v[0:1] op_sel_hi:[1,0]
	v_pk_mul_f32 v[48:49], v[48:49], v[0:1] op_sel_hi:[1,0]
	v_pk_mul_f32 v[54:55], v[54:55], v[0:1] op_sel_hi:[1,0]
	v_pk_mul_f32 v[52:53], v[52:53], v[0:1] op_sel_hi:[1,0]
	v_pk_mul_f32 v[58:59], v[58:59], v[0:1] op_sel_hi:[1,0]
	v_pk_mul_f32 v[56:57], v[56:57], v[0:1] op_sel_hi:[1,0]
	v_pk_mul_f32 v[62:63], v[62:63], v[0:1] op_sel_hi:[1,0]
	v_pk_mul_f32 v[60:61], v[60:61], v[0:1] op_sel_hi:[1,0]
	v_pk_mul_f32 v[66:67], v[66:67], v[0:1] op_sel_hi:[1,0]
	v_pk_mul_f32 v[64:65], v[64:65], v[0:1] op_sel_hi:[1,0]
; template <bool SLC, bool NOMASK> ...
;     ...
;     } else {
; #pragma unroll
;         for (int j = 0; j < 4; ++j) { pa[j] = vd[j] ? __builtin_amdgcn_exp2f(sc[j] - mref) : 0.f; pb[j] = vd[4 + j] ? __builtin_amdgcn_exp2f(sc[4 + j] - mref) : 0.f; ps += pa[j] + pb[j]; }
;     }
;     st.l += ps;
;     const u32x2 pw = pack8_fp8(pa, pb);
;     const i64_t pf = __builtin_bit_cast(i64_t, pw);
; #pragma unroll
;     for (int db = 0; db < 8; ++db) st.o[db] = __builtin_amdgcn_mfma_f32_16x16x32_fp8_fp8(cur.v[db], pf, st.o[db], 0, 0, 0);
.LBB0_1022:
	v_add_f32_e32 v0, -4.0, v227
	v_sub_f32_e32 v2, v2, v0
	v_exp_f32_e32 v2, v2
	v_sub_f32_e32 v6, v6, v0
	v_exp_f32_e32 v6, v6
	v_sub_f32_e32 v4, v4, v0
	v_cndmask_b32_e64 v26, 0, v2, s[16:17]
	v_sub_f32_e32 v2, v3, v0
	v_exp_f32_e32 v2, v2
	v_sub_f32_e32 v3, v7, v0
	v_exp_f32_e32 v3, v3
	v_cndmask_b32_e64 v27, 0, v6, s[24:25]
	v_sub_f32_e32 v6, v8, v0
	v_cndmask_b32_e64 v28, 0, v2, s[12:13]
	v_sub_f32_e32 v2, v5, v0
	v_sub_f32_e32 v0, v9, v0
	v_exp_f32_e32 v4, v4
	v_exp_f32_e32 v6, v6
	v_cndmask_b32_e64 v29, 0, v3, s[20:21]
	v_exp_f32_e32 v5, v2
	v_exp_f32_e32 v0, v0
	v_mov_b32_e32 v2, v1
	v_mov_b32_e32 v3, v1
	v_cvt_pk_fp8_f32 v2, v26, v28
	v_cvt_pk_fp8_f32 v3, v27, v29
	v_cndmask_b32_e64 v4, 0, v4, s[14:15]
	v_cndmask_b32_e64 v30, 0, v6, s[22:23]
	v_cndmask_b32_e64 v5, 0, v5, s[10:11]
	v_cndmask_b32_e64 v0, 0, v0, s[18:19]
	v_cvt_pk_fp8_f32 v2, v4, v5 op_sel:[0,0,1]
	v_cvt_pk_fp8_f32 v3, v30, v0 op_sel:[0,0,1]
	v_add_f32_e32 v26, v26, v27
	v_add_f32_e32 v31, 0, v26
	v_add_f32_e32 v32, v28, v29
	v_add_f32_e32 v31, v32, v31
	v_add_f32_e32 v4, v4, v30
	v_add_f32_e32 v4, v4, v31
	v_add_f32_e32 v0, v5, v0
	s_waitcnt vmcnt(39)
	v_mfma_f32_16x16x32_fp8_fp8 v[6:9], v[170:171], v[2:3], v[36:39]
	v_add_f32_e32 v0, v0, v4
	v_add_f32_e32 v34, v229, v0
	v_mov_b32_e32 v133, v227
	s_waitcnt vmcnt(38)
	v_mfma_f32_16x16x32_fp8_fp8 v[10:13], v[172:173], v[2:3], v[40:43]
	s_waitcnt vmcnt(37)
	v_mfma_f32_16x16x32_fp8_fp8 v[14:17], v[174:175], v[2:3], v[44:47]
	s_waitcnt vmcnt(36)
	v_mfma_f32_16x16x32_fp8_fp8 v[18:21], v[176:177], v[2:3], v[48:51]
	s_waitcnt vmcnt(35)
	v_mfma_f32_16x16x32_fp8_fp8 v[22:25], v[184:185], v[2:3], v[52:55]
	s_waitcnt vmcnt(34)
	v_mfma_f32_16x16x32_fp8_fp8 v[26:29], v[182:183], v[2:3], v[56:59]
	s_waitcnt vmcnt(33)
	v_mfma_f32_16x16x32_fp8_fp8 v[30:33], v[180:181], v[2:3], v[60:63]
	s_waitcnt vmcnt(32)
	v_mfma_f32_16x16x32_fp8_fp8 v[2:5], v[178:179], v[2:3], v[64:67]
